# baseline (speedup 1.0000x reference)
; DI unsigned cvtpk(float lo, float hi) { f32x2_t v = {lo, hi}; bf16x2_t b = __builtin_convertvector(v, bf16x2_t); return __builtin_bit_cast(unsigned, b); }
; DI float silu_f(float x) { return x * __builtin_amdgcn_rcpf(1.f + __expf(-x)); }
;     __device__ __forceinline__ void operator()(const f32x4 (&acc)[2][2][4][2], const Unit& u, int wr, int wc, int fr, int fq) const {
;         const int row0 = u.pm * BM + wr * 64 + fr, col0 = u.pn * 128 + wc * 32 + 8 * fq;
; #pragma unroll
;         for (int ai = 0; ai < 2; ++ai)
; #pragma unroll
;             for (int m = 0; m < 4; ++m) {
;                 bf16_t* rowp = H + (size_t)(row0 + ai * HALF + m * 16) * DFF + col0;
;                 float h[8];
; #pragma unroll
;                 for (int n = 0; n < 2; ++n)
; #pragma unroll
;                     for (int j = 0; j < 4; ++j) h[n * 4 + j] = silu_f(acc[ai][0][m][n][j]) * acc[ai][1][m][n][j];
;                 u32x4 w; w.x = cvtpk(h[0], h[1]); w.y = cvtpk(h[2], h[3]); w.z = cvtpk(h[4], h[5]); w.w = cvtpk(h[6], h[7]);
;                 *(u32x4*)rowp = w;
;             }
.LBB0_188:
	v_mul_f32_e32 v142, 0xbfb8aa3b, v126
	v_exp_f32_e32 v142, v142
	v_mul_f32_e32 v143, 0xbfb8aa3b, v127
	v_exp_f32_e32 v143, v143
	v_lshl_or_b32 v148, s78, 7, v145
	v_add_f32_e32 v142, 1.0, v142
	v_rcp_f32_e32 v150, v142
	v_add_f32_e32 v142, 1.0, v143
	v_rcp_f32_e32 v151, v142
	v_lshl_add_u32 v147, s79, 8, v1
	v_ashrrev_i32_e32 v149, 31, v148
	v_mov_b64_e32 v[142:143], s[50:51]
	v_pk_mul_f32 v[126:127], v[126:127], v[150:151]
	v_mul_f32_e32 v150, 0xbfb8aa3b, v128
	v_mul_f32_e32 v151, 0xbfb8aa3b, v129
	v_exp_f32_e32 v150, v150
	v_exp_f32_e32 v151, v151
	v_pk_mul_f32 v[122:123], v[122:123], v[126:127]
	v_mad_i64_i32 v[152:153], s[58:59], v147, s39, v[142:143]
	v_add_f32_e32 v126, 1.0, v150
	v_add_f32_e32 v127, 1.0, v151
	v_mul_f32_e32 v150, 0xbfb8aa3b, v118
	v_mul_f32_e32 v151, 0xbfb8aa3b, v119
	v_rcp_f32_e32 v126, v126
	v_rcp_f32_e32 v127, v127
	v_exp_f32_e32 v150, v150
	v_exp_f32_e32 v151, v151
	s_and_b64 vcc, exec, s[40:41]
	v_pk_mul_f32 v[126:127], v[128:129], v[126:127]
	v_add_f32_e32 v128, 1.0, v150
	v_add_f32_e32 v129, 1.0, v151
	v_mul_f32_e32 v150, 0xbfb8aa3b, v120
	v_mul_f32_e32 v151, 0xbfb8aa3b, v121
	v_exp_f32_e32 v150, v150
	v_exp_f32_e32 v151, v151
	v_rcp_f32_e32 v128, v128
	v_rcp_f32_e32 v129, v129
	v_add_f32_e32 v150, 1.0, v150
	v_add_f32_e32 v151, 1.0, v151
	v_rcp_f32_e32 v150, v150
	v_rcp_f32_e32 v151, v151
	v_pk_mul_f32 v[118:119], v[118:119], v[128:129]
	v_pk_mul_f32 v[124:125], v[124:125], v[126:127]
	v_pk_mul_f32 v[118:119], v[114:115], v[118:119]
	v_pk_mul_f32 v[114:115], v[120:121], v[150:151]
	v_cvt_pk_bf16_f32 v118, v118, v119
	v_pk_mul_f32 v[120:121], v[116:117], v[114:115]
	v_lshlrev_b64 v[114:115], 1, v[148:149]
	v_cvt_pk_bf16_f32 v119, v120, v121
	v_mul_f32_e32 v120, 0xbfb8aa3b, v110
	v_mul_f32_e32 v121, 0xbfb8aa3b, v111
	v_exp_f32_e32 v120, v120
	v_exp_f32_e32 v121, v121
	v_lshl_add_u64 v[126:127], v[152:153], 0, v[114:115]
	v_cvt_pk_bf16_f32 v116, v122, v123
	v_cvt_pk_bf16_f32 v117, v124, v125
	global_store_dwordx4 v[126:127], v[116:119], off nt
	s_mov_b64 s[40:41], -1
	s_nop 0
	v_add_f32_e32 v116, 1.0, v120
	v_add_f32_e32 v117, 1.0, v121
	v_rcp_f32_e32 v116, v116
	v_rcp_f32_e32 v117, v117
	v_or_b32_e32 v118, 16, v147
	v_mad_i64_i32 v[118:119], s[58:59], v118, s39, v[142:143]
	v_pk_mul_f32 v[110:111], v[110:111], v[116:117]
	v_mul_f32_e32 v116, 0xbfb8aa3b, v112
	v_mul_f32_e32 v117, 0xbfb8aa3b, v113
	v_exp_f32_e32 v116, v116
	v_exp_f32_e32 v117, v117
	v_pk_mul_f32 v[106:107], v[106:107], v[110:111]
	v_add_f32_e32 v110, 1.0, v116
	v_add_f32_e32 v111, 1.0, v117
	v_mul_f32_e32 v116, 0xbfb8aa3b, v102
	v_mul_f32_e32 v117, 0xbfb8aa3b, v103
	v_rcp_f32_e32 v110, v110
	v_rcp_f32_e32 v111, v111
	v_exp_f32_e32 v116, v116
	v_exp_f32_e32 v117, v117
	v_pk_mul_f32 v[110:111], v[112:113], v[110:111]
	v_add_f32_e32 v112, 1.0, v116
	v_add_f32_e32 v113, 1.0, v117
	v_mul_f32_e32 v116, 0xbfb8aa3b, v104
	v_mul_f32_e32 v117, 0xbfb8aa3b, v105
	v_exp_f32_e32 v116, v116
	v_exp_f32_e32 v117, v117
	v_rcp_f32_e32 v112, v112
	v_rcp_f32_e32 v113, v113
	v_add_f32_e32 v116, 1.0, v116
	v_add_f32_e32 v117, 1.0, v117
	v_rcp_f32_e32 v116, v116
	v_rcp_f32_e32 v117, v117
	v_pk_mul_f32 v[102:103], v[102:103], v[112:113]
	v_pk_mul_f32 v[108:109], v[108:109], v[110:111]
	v_pk_mul_f32 v[102:103], v[98:99], v[102:103]
	v_pk_mul_f32 v[98:99], v[104:105], v[116:117]
	v_lshl_add_u64 v[110:111], v[118:119], 0, v[114:115]
	v_pk_mul_f32 v[104:105], v[100:101], v[98:99]
	v_cvt_pk_bf16_f32 v100, v102, v103
	v_mul_f32_e32 v102, 0xbfb8aa3b, v94
	v_mul_f32_e32 v103, 0xbfb8aa3b, v95
	v_exp_f32_e32 v102, v102
	v_exp_f32_e32 v103, v103
	v_cvt_pk_bf16_f32 v98, v106, v107
	v_cvt_pk_bf16_f32 v99, v108, v109
	v_cvt_pk_bf16_f32 v101, v104, v105
	global_store_dwordx4 v[110:111], v[98:101], off nt
	s_nop 1
	v_add_f32_e32 v98, 1.0, v102
	v_add_f32_e32 v99, 1.0, v103
	v_rcp_f32_e32 v98, v98
	v_rcp_f32_e32 v99, v99
	v_or_b32_e32 v100, 32, v147
	v_mad_i64_i32 v[100:101], s[58:59], v100, s39, v[142:143]
	v_pk_mul_f32 v[94:95], v[94:95], v[98:99]
	v_mul_f32_e32 v98, 0xbfb8aa3b, v96
	v_mul_f32_e32 v99, 0xbfb8aa3b, v97
	v_exp_f32_e32 v98, v98
	v_exp_f32_e32 v99, v99
	v_pk_mul_f32 v[90:91], v[90:91], v[94:95]
	v_add_f32_e32 v94, 1.0, v98
	v_add_f32_e32 v95, 1.0, v99
	v_mul_f32_e32 v98, 0xbfb8aa3b, v86
	v_mul_f32_e32 v99, 0xbfb8aa3b, v87
	v_rcp_f32_e32 v94, v94
	v_rcp_f32_e32 v95, v95
	v_exp_f32_e32 v98, v98
	v_exp_f32_e32 v99, v99
	v_pk_mul_f32 v[94:95], v[96:97], v[94:95]
	v_add_f32_e32 v96, 1.0, v98
	v_add_f32_e32 v97, 1.0, v99
	v_mul_f32_e32 v98, 0xbfb8aa3b, v88
	v_mul_f32_e32 v99, 0xbfb8aa3b, v89
	v_exp_f32_e32 v98, v98
	v_exp_f32_e32 v99, v99
	v_rcp_f32_e32 v96, v96
	v_rcp_f32_e32 v97, v97
	v_add_f32_e32 v98, 1.0, v98
	v_add_f32_e32 v99, 1.0, v99
	v_rcp_f32_e32 v98, v98
	v_rcp_f32_e32 v99, v99
	v_pk_mul_f32 v[86:87], v[86:87], v[96:97]
	v_pk_mul_f32 v[92:93], v[92:93], v[94:95]
	v_pk_mul_f32 v[86:87], v[82:83], v[86:87]
	v_pk_mul_f32 v[82:83], v[88:89], v[98:99]
	v_lshl_add_u64 v[94:95], v[100:101], 0, v[114:115]
	v_pk_mul_f32 v[88:89], v[84:85], v[82:83]
	v_cvt_pk_bf16_f32 v84, v86, v87
	v_mul_f32_e32 v86, 0xbfb8aa3b, v78
	v_mul_f32_e32 v87, 0xbfb8aa3b, v79
	v_exp_f32_e32 v86, v86
	v_exp_f32_e32 v87, v87
	v_cvt_pk_bf16_f32 v82, v90, v91
	v_cvt_pk_bf16_f32 v83, v92, v93
	v_cvt_pk_bf16_f32 v85, v88, v89
	global_store_dwordx4 v[94:95], v[82:85], off nt
	s_nop 1
	v_add_f32_e32 v82, 1.0, v86
	v_add_f32_e32 v83, 1.0, v87
	v_rcp_f32_e32 v82, v82
	v_rcp_f32_e32 v83, v83
	v_or_b32_e32 v84, 48, v147
	v_mad_i64_i32 v[84:85], s[58:59], v84, s39, v[142:143]
	v_pk_mul_f32 v[78:79], v[78:79], v[82:83]
	v_mul_f32_e32 v82, 0xbfb8aa3b, v80
	v_mul_f32_e32 v83, 0xbfb8aa3b, v81
; DI unsigned cvtpk(float lo, float hi) { f32x2_t v = {lo, hi}; bf16x2_t b = __builtin_convertvector(v, bf16x2_t); return __builtin_bit_cast(unsigned, b); }
; DI float silu_f(float x) { return x * __builtin_amdgcn_rcpf(1.f + __expf(-x)); }
;     __device__ __forceinline__ void operator()(const f32x4 (&acc)[2][2][4][2], const Unit& u, int wr, int wc, int fr, int fq) const {
;     ...
;             for (int m = 0; m < 4; ++m) {
;                 bf16_t* rowp = H + (size_t)(row0 + ai * HALF + m * 16) * DFF + col0;
;                 float h[8];
; #pragma unroll
;                 for (int n = 0; n < 2; ++n)
; #pragma unroll
;                     for (int j = 0; j < 4; ++j) h[n * 4 + j] = silu_f(acc[ai][0][m][n][j]) * acc[ai][1][m][n][j];
;                 u32x4 w; w.x = cvtpk(h[0], h[1]); w.y = cvtpk(h[2], h[3]); w.z = cvtpk(h[4], h[5]); w.w = cvtpk(h[6], h[7]);
;                 *(u32x4*)rowp = w;
	v_exp_f32_e32 v82, v82
	v_exp_f32_e32 v83, v83
	v_pk_mul_f32 v[74:75], v[74:75], v[78:79]
	v_add_f32_e32 v78, 1.0, v82
	v_add_f32_e32 v79, 1.0, v83
	v_mul_f32_e32 v82, 0xbfb8aa3b, v70
	v_mul_f32_e32 v83, 0xbfb8aa3b, v71
	v_rcp_f32_e32 v78, v78
	v_rcp_f32_e32 v79, v79
	v_exp_f32_e32 v82, v82
	v_exp_f32_e32 v83, v83
	v_pk_mul_f32 v[78:79], v[80:81], v[78:79]
	v_add_f32_e32 v80, 1.0, v82
	v_add_f32_e32 v81, 1.0, v83
	v_mul_f32_e32 v82, 0xbfb8aa3b, v72
	v_mul_f32_e32 v83, 0xbfb8aa3b, v73
	v_exp_f32_e32 v82, v82
	v_exp_f32_e32 v83, v83
	v_rcp_f32_e32 v80, v80
	v_rcp_f32_e32 v81, v81
	v_add_f32_e32 v82, 1.0, v82
	v_add_f32_e32 v83, 1.0, v83
	v_rcp_f32_e32 v82, v82
	v_rcp_f32_e32 v83, v83
	v_pk_mul_f32 v[70:71], v[70:71], v[80:81]
	v_pk_mul_f32 v[76:77], v[76:77], v[78:79]
	v_pk_mul_f32 v[70:71], v[66:67], v[70:71]
	v_pk_mul_f32 v[66:67], v[72:73], v[82:83]
	v_lshl_add_u64 v[78:79], v[84:85], 0, v[114:115]
	v_pk_mul_f32 v[72:73], v[68:69], v[66:67]
	v_cvt_pk_bf16_f32 v68, v70, v71
	v_mul_f32_e32 v70, 0xbfb8aa3b, v62
	v_mul_f32_e32 v71, 0xbfb8aa3b, v63
	v_exp_f32_e32 v70, v70
	v_exp_f32_e32 v71, v71
	v_cvt_pk_bf16_f32 v66, v74, v75
	v_cvt_pk_bf16_f32 v67, v76, v77
	v_cvt_pk_bf16_f32 v69, v72, v73
	global_store_dwordx4 v[78:79], v[66:69], off nt
	s_nop 1
	v_add_f32_e32 v66, 1.0, v70
	v_add_f32_e32 v67, 1.0, v71
	v_rcp_f32_e32 v66, v66
	v_rcp_f32_e32 v67, v67
	v_add_u32_e32 v68, 0x80, v147
	v_mad_i64_i32 v[68:69], s[58:59], v68, s39, v[142:143]
	v_pk_mul_f32 v[62:63], v[62:63], v[66:67]
	v_mul_f32_e32 v66, 0xbfb8aa3b, v64
	v_mul_f32_e32 v67, 0xbfb8aa3b, v65
	v_exp_f32_e32 v66, v66
	v_exp_f32_e32 v67, v67
	v_pk_mul_f32 v[58:59], v[58:59], v[62:63]
	v_add_f32_e32 v62, 1.0, v66
	v_add_f32_e32 v63, 1.0, v67
	v_mul_f32_e32 v66, 0xbfb8aa3b, v54
	v_mul_f32_e32 v67, 0xbfb8aa3b, v55
	v_rcp_f32_e32 v62, v62
	v_rcp_f32_e32 v63, v63
	v_exp_f32_e32 v66, v66
	v_exp_f32_e32 v67, v67
	v_pk_mul_f32 v[62:63], v[64:65], v[62:63]
	v_add_f32_e32 v64, 1.0, v66
	v_add_f32_e32 v65, 1.0, v67
	v_mul_f32_e32 v66, 0xbfb8aa3b, v56
	v_mul_f32_e32 v67, 0xbfb8aa3b, v57
	v_exp_f32_e32 v66, v66
	v_exp_f32_e32 v67, v67
	v_rcp_f32_e32 v64, v64
	v_rcp_f32_e32 v65, v65
	v_add_f32_e32 v66, 1.0, v66
	v_add_f32_e32 v67, 1.0, v67
	v_rcp_f32_e32 v66, v66
	v_rcp_f32_e32 v67, v67
	v_pk_mul_f32 v[54:55], v[54:55], v[64:65]
	v_pk_mul_f32 v[60:61], v[60:61], v[62:63]
	v_pk_mul_f32 v[54:55], v[50:51], v[54:55]
	v_pk_mul_f32 v[50:51], v[56:57], v[66:67]
	v_lshl_add_u64 v[62:63], v[68:69], 0, v[114:115]
	v_pk_mul_f32 v[56:57], v[52:53], v[50:51]
	v_cvt_pk_bf16_f32 v52, v54, v55
	v_mul_f32_e32 v54, 0xbfb8aa3b, v46
	v_mul_f32_e32 v55, 0xbfb8aa3b, v47
	v_exp_f32_e32 v54, v54
	v_exp_f32_e32 v55, v55
	v_cvt_pk_bf16_f32 v50, v58, v59
	v_cvt_pk_bf16_f32 v51, v60, v61
	v_cvt_pk_bf16_f32 v53, v56, v57
	global_store_dwordx4 v[62:63], v[50:53], off nt
	s_nop 1
	v_add_f32_e32 v50, 1.0, v54
	v_add_f32_e32 v51, 1.0, v55
	v_rcp_f32_e32 v50, v50
	v_rcp_f32_e32 v51, v51
	v_add_u32_e32 v52, 0x90, v147
	v_mad_i64_i32 v[52:53], s[58:59], v52, s39, v[142:143]
	v_pk_mul_f32 v[46:47], v[46:47], v[50:51]
	v_mul_f32_e32 v50, 0xbfb8aa3b, v48
	v_mul_f32_e32 v51, 0xbfb8aa3b, v49
	v_exp_f32_e32 v50, v50
	v_exp_f32_e32 v51, v51
	v_pk_mul_f32 v[42:43], v[42:43], v[46:47]
	v_add_f32_e32 v46, 1.0, v50
	v_add_f32_e32 v47, 1.0, v51
	v_mul_f32_e32 v50, 0xbfb8aa3b, v38
	v_mul_f32_e32 v51, 0xbfb8aa3b, v39
	v_rcp_f32_e32 v46, v46
	v_rcp_f32_e32 v47, v47
	v_exp_f32_e32 v50, v50
	v_exp_f32_e32 v51, v51
	v_pk_mul_f32 v[46:47], v[48:49], v[46:47]
	v_add_f32_e32 v48, 1.0, v50
	v_add_f32_e32 v49, 1.0, v51
	v_mul_f32_e32 v50, 0xbfb8aa3b, v40
	v_mul_f32_e32 v51, 0xbfb8aa3b, v41
	v_exp_f32_e32 v50, v50
	v_exp_f32_e32 v51, v51
	v_rcp_f32_e32 v48, v48
	v_rcp_f32_e32 v49, v49
	v_add_f32_e32 v50, 1.0, v50
; #define PG8_BAR __builtin_amdgcn_s_barrier()
; DI unsigned cvtpk(float lo, float hi) { f32x2_t v = {lo, hi}; bf16x2_t b = __builtin_convertvector(v, bf16x2_t); return __builtin_bit_cast(unsigned, b); }
; DI float silu_f(float x) { return x * __builtin_amdgcn_rcpf(1.f + __expf(-x)); }
; template <class Epi, class Sched, bool ALIGN_EPI = false, bool SP2 = false>
; __device__ __forceinline__ void gemm_phase(PG8_LAS unsigned char* lds, const Gemm g, const Sched& S, const Epi& E) {
;     ...
;         if constexpr (ALIGN_EPI) { if (wr == 0) PG8_BAR; }
;         if constexpr (!Epi::AFTER_DRAIN) { E(acc, cur, wr, wc, fr, fq); S.done(cur); }
;         if (!has_next) break;
; #pragma unroll
;         for (int a = 0; a < 2; ++a)
; #pragma unroll
;             for (int b = 0; b < 2; ++b)
; #pragma unroll
;                 for (int m = 0; m < 4; ++m)
; #pragma unroll
;                     for (int n = 0; n < 2; ++n) acc[a][b][m][n] = (f32x4){0.f, 0.f, 0.f, 0.f};
;         cur = nxt; cA = nA; cB = nB; ++ui;
;         if constexpr (ALIGN_EPI) { if (wr == 1) PG8_BAR; }
;     }
;     __device__ __forceinline__ void operator()(const f32x4 (&acc)[2][2][4][2], const Unit& u, int wr, int wc, int fr, int fq) const {
;     ...
;             for (int m = 0; m < 4; ++m) {
;                 bf16_t* rowp = H + (size_t)(row0 + ai * HALF + m * 16) * DFF + col0;
;                 float h[8];
; #pragma unroll
;                 for (int n = 0; n < 2; ++n)
; #pragma unroll
;                     for (int j = 0; j < 4; ++j) h[n * 4 + j] = silu_f(acc[ai][0][m][n][j]) * acc[ai][1][m][n][j];
;                 u32x4 w; w.x = cvtpk(h[0], h[1]); w.y = cvtpk(h[2], h[3]); w.z = cvtpk(h[4], h[5]); w.w = cvtpk(h[6], h[7]);
;                 *(u32x4*)rowp = w;
	v_add_f32_e32 v51, 1.0, v51
	v_rcp_f32_e32 v50, v50
	v_rcp_f32_e32 v51, v51
	v_pk_mul_f32 v[38:39], v[38:39], v[48:49]
	v_pk_mul_f32 v[44:45], v[44:45], v[46:47]
	v_pk_mul_f32 v[38:39], v[34:35], v[38:39]
	v_pk_mul_f32 v[34:35], v[40:41], v[50:51]
	v_lshl_add_u64 v[46:47], v[52:53], 0, v[114:115]
	v_pk_mul_f32 v[40:41], v[36:37], v[34:35]
	v_cvt_pk_bf16_f32 v36, v38, v39
	v_mul_f32_e32 v38, 0xbfb8aa3b, v30
	v_mul_f32_e32 v39, 0xbfb8aa3b, v31
	v_exp_f32_e32 v38, v38
	v_exp_f32_e32 v39, v39
	v_cvt_pk_bf16_f32 v34, v42, v43
	v_cvt_pk_bf16_f32 v35, v44, v45
	v_cvt_pk_bf16_f32 v37, v40, v41
	global_store_dwordx4 v[46:47], v[34:37], off nt
	s_nop 1
	v_add_f32_e32 v34, 1.0, v38
	v_add_f32_e32 v35, 1.0, v39
	v_rcp_f32_e32 v34, v34
	v_rcp_f32_e32 v35, v35
	v_add_u32_e32 v36, 0xa0, v147
	v_mad_i64_i32 v[36:37], s[58:59], v36, s39, v[142:143]
	v_pk_mul_f32 v[30:31], v[30:31], v[34:35]
	v_mul_f32_e32 v34, 0xbfb8aa3b, v32
	v_mul_f32_e32 v35, 0xbfb8aa3b, v33
	v_exp_f32_e32 v34, v34
	v_exp_f32_e32 v35, v35
	v_pk_mul_f32 v[26:27], v[26:27], v[30:31]
	v_add_f32_e32 v30, 1.0, v34
	v_add_f32_e32 v31, 1.0, v35
	v_mul_f32_e32 v34, 0xbfb8aa3b, v22
	v_mul_f32_e32 v35, 0xbfb8aa3b, v23
	v_rcp_f32_e32 v30, v30
	v_rcp_f32_e32 v31, v31
	v_exp_f32_e32 v34, v34
	v_exp_f32_e32 v35, v35
	v_pk_mul_f32 v[30:31], v[32:33], v[30:31]
	v_add_f32_e32 v32, 1.0, v34
	v_add_f32_e32 v33, 1.0, v35
	v_mul_f32_e32 v34, 0xbfb8aa3b, v24
	v_mul_f32_e32 v35, 0xbfb8aa3b, v25
	v_exp_f32_e32 v34, v34
	v_exp_f32_e32 v35, v35
	v_rcp_f32_e32 v32, v32
	v_rcp_f32_e32 v33, v33
	v_add_f32_e32 v34, 1.0, v34
	v_add_f32_e32 v35, 1.0, v35
	v_rcp_f32_e32 v34, v34
	v_rcp_f32_e32 v35, v35
	v_pk_mul_f32 v[22:23], v[22:23], v[32:33]
	v_pk_mul_f32 v[28:29], v[28:29], v[30:31]
	v_pk_mul_f32 v[22:23], v[18:19], v[22:23]
	v_pk_mul_f32 v[18:19], v[24:25], v[34:35]
	v_lshl_add_u64 v[30:31], v[36:37], 0, v[114:115]
	v_pk_mul_f32 v[24:25], v[20:21], v[18:19]
	v_cvt_pk_bf16_f32 v20, v22, v23
	v_mul_f32_e32 v22, 0xbfb8aa3b, v14
	v_mul_f32_e32 v23, 0xbfb8aa3b, v15
	v_exp_f32_e32 v22, v22
	v_exp_f32_e32 v23, v23
	v_cvt_pk_bf16_f32 v18, v26, v27
	v_cvt_pk_bf16_f32 v19, v28, v29
	v_cvt_pk_bf16_f32 v21, v24, v25
	global_store_dwordx4 v[30:31], v[18:21], off nt
	s_nop 1
	v_add_f32_e32 v18, 1.0, v22
	v_add_f32_e32 v19, 1.0, v23
	v_rcp_f32_e32 v18, v18
	v_rcp_f32_e32 v19, v19
	v_add_u32_e32 v20, 0xb0, v147
	v_mad_i64_i32 v[20:21], s[58:59], v20, s39, v[142:143]
	v_pk_mul_f32 v[14:15], v[14:15], v[18:19]
	v_mul_f32_e32 v18, 0xbfb8aa3b, v16
	v_mul_f32_e32 v19, 0xbfb8aa3b, v17
	v_exp_f32_e32 v18, v18
	v_exp_f32_e32 v19, v19
	v_pk_mul_f32 v[10:11], v[10:11], v[14:15]
	v_add_f32_e32 v14, 1.0, v18
	v_add_f32_e32 v15, 1.0, v19
	v_mul_f32_e32 v18, 0xbfb8aa3b, v6
	v_mul_f32_e32 v19, 0xbfb8aa3b, v7
	v_rcp_f32_e32 v14, v14
	v_rcp_f32_e32 v15, v15
	v_exp_f32_e32 v18, v18
	v_exp_f32_e32 v19, v19
	v_pk_mul_f32 v[14:15], v[16:17], v[14:15]
	v_add_f32_e32 v16, 1.0, v18
	v_add_f32_e32 v17, 1.0, v19
	v_mul_f32_e32 v18, 0xbfb8aa3b, v8
	v_mul_f32_e32 v19, 0xbfb8aa3b, v9
	v_exp_f32_e32 v18, v18
	v_exp_f32_e32 v19, v19
	v_rcp_f32_e32 v16, v16
	v_rcp_f32_e32 v17, v17
	v_add_f32_e32 v18, 1.0, v18
	v_add_f32_e32 v19, 1.0, v19
	v_rcp_f32_e32 v18, v18
	v_rcp_f32_e32 v19, v19
	v_pk_mul_f32 v[6:7], v[6:7], v[16:17]
	v_pk_mul_f32 v[12:13], v[12:13], v[14:15]
	v_pk_mul_f32 v[6:7], v[2:3], v[6:7]
	v_pk_mul_f32 v[2:3], v[8:9], v[18:19]
	v_lshl_add_u64 v[14:15], v[20:21], 0, v[114:115]
	v_pk_mul_f32 v[8:9], v[4:5], v[2:3]
	v_cvt_pk_bf16_f32 v2, v10, v11
	v_cvt_pk_bf16_f32 v3, v12, v13
	v_cvt_pk_bf16_f32 v4, v6, v7
	v_cvt_pk_bf16_f32 v5, v8, v9
	global_store_dwordx4 v[14:15], v[2:5], off nt
	s_cbranch_vccnz .LBB0_171
	s_andn2_b64 vcc, exec, s[48:49]
	s_cbranch_vccnz .LBB0_170
	s_barrier
	s_branch .LBB0_170

;     __device__ __forceinline__ void operator()(const f32x4 (&acc)[2][2][4][2], const Unit& u, int wr, int wc, int fr, int fq) const {
;         const int row0 = u.pm * BM + wr * 64 + fr, col0 = u.pn * BM + wc * 32 + 4 * fq;
; #pragma unroll
;         for (int ai = 0; ai < 2; ++ai) {
;             f32x4 x[4][2][2];
; #pragma unroll
;             for (int m = 0; m < 4; ++m) { const size_t off = (size_t)(row0 + ai * HALF + m * 16) * DM + col0;
; #pragma unroll
;                 for (int bj = 0; bj < 2; ++bj)
; #pragma unroll
;                     for (int n = 0; n < 2; ++n) x[m][bj][n] = *(const f32x4*)(Yin + off + bj * HALF + n * 16); }
;             asm volatile("" ::: "memory");
; #pragma unroll
;             for (int m = 0; m < 4; ++m) { const size_t off = (size_t)(row0 + ai * HALF + m * 16) * DM + col0;
; #pragma unroll
;                 for (int bj = 0; bj < 2; ++bj)
; #pragma unroll
;                     for (int n = 0; n < 2; ++n) *(f32x4*)(Y + off + bj * HALF + n * 16) = x[m][bj][n] * ALPHA + acc[ai][bj][m][n] * s; }
;             asm volatile("" ::: "memory");
;         }
.LBB0_271:
	v_lshl_or_b32 v4, s8, 8, v163
	v_lshl_add_u32 v2, s9, 8, v1
	v_ashrrev_i32_e32 v5, 31, v4
	v_lshlrev_b64 v[94:95], 2, v[4:5]
	v_ashrrev_i32_e32 v3, 31, v2
	s_waitcnt lgkmcnt(0)
	v_lshl_add_u64 v[156:157], s[50:51], 0, v[94:95]
	v_lshlrev_b64 v[158:159], 12, v[2:3]
	v_lshl_add_u64 v[4:5], v[156:157], 0, v[158:159]
	global_load_dwordx4 v[166:169], v[4:5], off
	global_load_dwordx4 v[170:173], v[4:5], off offset:64
	global_load_dwordx4 v[174:177], v[4:5], off offset:512
	global_load_dwordx4 v[178:181], v[4:5], off offset:576
	v_or_b32_e32 v4, 16, v2
	v_ashrrev_i32_e32 v5, 31, v4
	v_lshlrev_b64 v[210:211], 12, v[4:5]
	v_lshl_add_u64 v[4:5], v[156:157], 0, v[210:211]
	global_load_dwordx4 v[182:185], v[4:5], off
	global_load_dwordx4 v[186:189], v[4:5], off offset:64
	global_load_dwordx4 v[190:193], v[4:5], off offset:512
	global_load_dwordx4 v[194:197], v[4:5], off offset:576
	v_or_b32_e32 v4, 32, v2
	v_ashrrev_i32_e32 v5, 31, v4
	v_or_b32_e32 v2, 48, v2
	v_lshlrev_b64 v[230:231], 12, v[4:5]
	v_ashrrev_i32_e32 v3, 31, v2
	v_lshl_add_u64 v[4:5], v[156:157], 0, v[230:231]
	v_lshlrev_b64 v[160:161], 12, v[2:3]
	global_load_dwordx4 v[198:201], v[4:5], off
	global_load_dwordx4 v[202:205], v[4:5], off offset:64
	global_load_dwordx4 v[206:209], v[4:5], off offset:512
	global_load_dwordx4 v[14:17], v[4:5], off offset:576
	v_lshl_add_u64 v[2:3], v[156:157], 0, v[160:161]
	global_load_dwordx4 v[226:229], v[2:3], off
	global_load_dwordx4 v[10:13], v[2:3], off offset:64
	global_load_dwordx4 v[6:9], v[2:3], off offset:512
	s_nop 0
	global_load_dwordx4 v[2:5], v[2:3], off offset:576
	s_mov_b64 s[8:9], 0x80000
	s_mov_b64 s[60:61], -1
	s_and_b64 vcc, exec, s[40:41]
	s_waitcnt vmcnt(0)
	v_pk_fma_f32 v[168:169], v[168:169], s[96:97], v[144:145] op_sel_hi:[1,0,1]
	v_pk_fma_f32 v[166:167], v[166:167], s[96:97], v[146:147] op_sel_hi:[1,0,1]
	v_lshl_add_u64 v[144:145], s[48:49], 0, v[158:159]
	v_pk_fma_f32 v[146:147], v[172:173], s[96:97], v[128:129] op_sel_hi:[1,0,1]
	v_lshl_add_u64 v[128:129], s[48:49], 0, v[210:211]
	v_lshl_add_u64 v[232:233], v[144:145], 0, v[94:95]
	v_pk_fma_f32 v[144:145], v[170:171], s[96:97], v[138:139] op_sel_hi:[1,0,1]
	v_pk_fma_f32 v[140:141], v[184:185], s[96:97], v[140:141] op_sel_hi:[1,0,1]
	v_pk_fma_f32 v[138:139], v[182:183], s[96:97], v[142:143] op_sel_hi:[1,0,1]
	v_lshl_add_u64 v[128:129], v[128:129], 0, v[94:95]
	global_store_dwordx4 v[128:129], v[138:141], off nt
	global_store_dwordx4 v[232:233], v[144:147], off offset:64 nt
	global_store_dwordx4 v[232:233], v[166:169], off nt
	v_pk_fma_f32 v[140:141], v[188:189], s[96:97], v[112:113] op_sel_hi:[1,0,1]
	v_pk_fma_f32 v[138:139], v[186:187], s[96:97], v[114:115] op_sel_hi:[1,0,1]
	v_pk_fma_f32 v[114:115], v[192:193], s[96:97], v[120:121] op_sel_hi:[1,0,1]
	v_pk_fma_f32 v[112:113], v[190:191], s[96:97], v[122:123] op_sel_hi:[1,0,1]
	global_store_dwordx4 v[128:129], v[112:115], off offset:512 nt
	v_pk_fma_f32 v[146:147], v[176:177], s[96:97], v[148:149] op_sel_hi:[1,0,1]
	v_pk_fma_f32 v[144:145], v[174:175], s[96:97], v[150:151] op_sel_hi:[1,0,1]
	v_pk_fma_f32 v[114:115], v[196:197], s[96:97], v[124:125] op_sel_hi:[1,0,1]
	v_pk_fma_f32 v[112:113], v[194:195], s[96:97], v[126:127] op_sel_hi:[1,0,1]
	global_store_dwordx4 v[128:129], v[112:115], off offset:576 nt
	v_pk_fma_f32 v[16:17], v[16:17], s[96:97], v[108:109] op_sel_hi:[1,0,1]
	v_pk_fma_f32 v[14:15], v[14:15], s[96:97], v[110:111] op_sel_hi:[1,0,1]
	v_pk_fma_f32 v[114:115], v[200:201], s[96:97], v[116:117] op_sel_hi:[1,0,1]
	v_lshl_add_u64 v[116:117], s[48:49], 0, v[230:231]
	v_pk_fma_f32 v[112:113], v[198:199], s[96:97], v[118:119] op_sel_hi:[1,0,1]
	v_lshl_add_u64 v[116:117], v[116:117], 0, v[94:95]
	global_store_dwordx4 v[116:117], v[112:115], off nt
	global_store_dwordx4 v[232:233], v[144:147], off offset:512 nt
	global_store_dwordx4 v[116:117], v[14:17], off offset:576 nt
	v_pk_fma_f32 v[114:115], v[204:205], s[96:97], v[96:97] op_sel_hi:[1,0,1]
	v_pk_fma_f32 v[112:113], v[202:203], s[96:97], v[98:99] op_sel_hi:[1,0,1]
	v_pk_fma_f32 v[98:99], v[208:209], s[96:97], v[104:105] op_sel_hi:[1,0,1]
	v_pk_fma_f32 v[96:97], v[206:207], s[96:97], v[106:107] op_sel_hi:[1,0,1]
	global_store_dwordx4 v[116:117], v[96:99], off offset:512 nt
	v_pk_fma_f32 v[146:147], v[180:181], s[96:97], v[152:153] op_sel_hi:[1,0,1]
	v_pk_fma_f32 v[144:145], v[178:179], s[96:97], v[154:155] op_sel_hi:[1,0,1]
	v_lshl_add_u64 v[96:97], s[48:49], 0, v[160:161]
	v_pk_fma_f32 v[16:17], v[228:229], s[96:97], v[100:101] op_sel_hi:[1,0,1]
	v_pk_fma_f32 v[14:15], v[226:227], s[96:97], v[102:103] op_sel_hi:[1,0,1]
	v_lshl_add_u64 v[96:97], v[96:97], 0, v[94:95]
	v_pk_fma_f32 v[12:13], v[12:13], s[96:97], v[92:93] op_sel_hi:[1,0,1]
	v_pk_fma_f32 v[10:11], v[10:11], s[96:97], v[90:91] op_sel_hi:[1,0,1]
	v_pk_fma_f32 v[8:9], v[8:9], s[96:97], v[88:89] op_sel_hi:[1,0,1]
	v_pk_fma_f32 v[6:7], v[6:7], s[96:97], v[86:87] op_sel_hi:[1,0,1]
	v_pk_fma_f32 v[4:5], v[4:5], s[96:97], v[84:85] op_sel_hi:[1,0,1]
	v_pk_fma_f32 v[2:3], v[2:3], s[96:97], v[82:83] op_sel_hi:[1,0,1]
	global_store_dwordx4 v[232:233], v[144:147], off offset:576 nt
	global_store_dwordx4 v[128:129], v[138:141], off offset:64 nt
	global_store_dwordx4 v[116:117], v[112:115], off offset:64 nt
	global_store_dwordx4 v[96:97], v[14:17], off nt
	global_store_dwordx4 v[96:97], v[10:13], off offset:64 nt
	global_store_dwordx4 v[96:97], v[6:9], off offset:512 nt
	global_store_dwordx4 v[96:97], v[2:5], off offset:576 nt
	v_lshl_add_u64 v[92:93], v[158:159], 0, s[8:9]
	s_mov_b64 s[8:9], 0x90000
	v_lshl_add_u64 v[2:3], v[156:157], 0, v[92:93]
	global_load_dwordx4 v[84:87], v[2:3], off
	global_load_dwordx4 v[88:91], v[2:3], off offset:64
	global_load_dwordx4 v[96:99], v[2:3], off offset:512
	global_load_dwordx4 v[100:103], v[2:3], off offset:576
	v_lshl_add_u64 v[128:129], v[158:159], 0, s[8:9]
	v_lshl_add_u64 v[2:3], v[156:157], 0, v[128:129]
	global_load_dwordx4 v[104:107], v[2:3], off
	global_load_dwordx4 v[108:111], v[2:3], off offset:64
	global_load_dwordx4 v[112:115], v[2:3], off offset:512
	global_load_dwordx4 v[116:119], v[2:3], off offset:576
	s_mov_b64 s[8:9], 0xa0000
	v_lshl_add_u64 v[146:147], v[158:159], 0, s[8:9]
	s_mov_b64 s[8:9], 0xb0000
	v_lshl_add_u64 v[2:3], v[156:157], 0, v[146:147]
	v_lshl_add_u64 v[82:83], v[158:159], 0, s[8:9]
	global_load_dwordx4 v[120:123], v[2:3], off
	global_load_dwordx4 v[124:127], v[2:3], off offset:64
	global_load_dwordx4 v[138:141], v[2:3], off offset:512
	global_load_dwordx4 v[14:17], v[2:3], off offset:576
	v_lshl_add_u64 v[2:3], v[156:157], 0, v[82:83]
	global_load_dwordx4 v[142:145], v[2:3], off
	global_load_dwordx4 v[10:13], v[2:3], off offset:64
	global_load_dwordx4 v[6:9], v[2:3], off offset:512
	s_nop 0
	global_load_dwordx4 v[2:5], v[2:3], off offset:576
	s_waitcnt vmcnt(15)
;     __device__ __forceinline__ void operator()(const f32x4 (&acc)[2][2][4][2], const Unit& u, int wr, int wc, int fr, int fq) const {
;     ...
;         for (int ai = 0; ai < 2; ++ai) {
;             f32x4 x[4][2][2];
; #pragma unroll
;             for (int m = 0; m < 4; ++m) { const size_t off = (size_t)(row0 + ai * HALF + m * 16) * DM + col0;
; #pragma unroll
;                 for (int bj = 0; bj < 2; ++bj)
; #pragma unroll
;                     for (int n = 0; n < 2; ++n) x[m][bj][n] = *(const f32x4*)(Yin + off + bj * HALF + n * 16); }
;             asm volatile("" ::: "memory");
; #pragma unroll
;             for (int m = 0; m < 4; ++m) { const size_t off = (size_t)(row0 + ai * HALF + m * 16) * DM + col0;
; #pragma unroll
;                 for (int bj = 0; bj < 2; ++bj)
; #pragma unroll
;                     for (int n = 0; n < 2; ++n) *(f32x4*)(Y + off + bj * HALF + n * 16) = x[m][bj][n] * ALPHA + acc[ai][bj][m][n] * s; }
;             asm volatile("" ::: "memory");
;         }
	v_pk_fma_f32 v[86:87], v[86:87], s[96:97], v[70:71] op_sel_hi:[1,0,1]
	v_lshl_add_u64 v[70:71], s[48:49], 0, v[92:93]
	v_pk_fma_f32 v[84:85], v[84:85], s[96:97], v[72:73] op_sel_hi:[1,0,1]
	v_lshl_add_u64 v[92:93], v[70:71], 0, v[94:95]
	s_waitcnt vmcnt(14)
	v_pk_fma_f32 v[72:73], v[90:91], s[96:97], v[62:63] op_sel_hi:[1,0,1]
	v_pk_fma_f32 v[70:71], v[88:89], s[96:97], v[64:65] op_sel_hi:[1,0,1]
	s_waitcnt vmcnt(13)
	v_pk_fma_f32 v[64:65], v[98:99], s[96:97], v[74:75] op_sel_hi:[1,0,1]
	v_pk_fma_f32 v[62:63], v[96:97], s[96:97], v[76:77] op_sel_hi:[1,0,1]
	global_store_dwordx4 v[92:93], v[62:65], off offset:512 nt
	global_store_dwordx4 v[92:93], v[84:87], off nt
	global_store_dwordx4 v[92:93], v[70:73], off offset:64 nt
	s_waitcnt vmcnt(15)
	v_pk_fma_f32 v[64:65], v[102:103], s[96:97], v[78:79] op_sel_hi:[1,0,1]
	v_pk_fma_f32 v[62:63], v[100:101], s[96:97], v[80:81] op_sel_hi:[1,0,1]
	global_store_dwordx4 v[92:93], v[62:65], off offset:576 nt
	s_waitcnt vmcnt(8)
	v_pk_fma_f32 v[16:17], v[16:17], s[96:97], v[42:43] op_sel_hi:[1,0,1]
	v_pk_fma_f32 v[14:15], v[14:15], s[96:97], v[44:45] op_sel_hi:[1,0,1]
	v_pk_fma_f32 v[64:65], v[106:107], s[96:97], v[66:67] op_sel_hi:[1,0,1]
	v_lshl_add_u64 v[66:67], s[48:49], 0, v[128:129]
	v_pk_fma_f32 v[62:63], v[104:105], s[96:97], v[68:69] op_sel_hi:[1,0,1]
	v_lshl_add_u64 v[66:67], v[66:67], 0, v[94:95]
	global_store_dwordx4 v[66:67], v[62:65], off nt
	s_waitcnt vmcnt(7)
	v_pk_fma_f32 v[12:13], v[12:13], s[96:97], v[26:27] op_sel_hi:[1,0,1]
	v_pk_fma_f32 v[10:11], v[10:11], s[96:97], v[24:25] op_sel_hi:[1,0,1]
	v_pk_fma_f32 v[64:65], v[110:111], s[96:97], v[46:47] op_sel_hi:[1,0,1]
	v_pk_fma_f32 v[62:63], v[108:109], s[96:97], v[48:49] op_sel_hi:[1,0,1]
	v_pk_fma_f32 v[48:49], v[114:115], s[96:97], v[54:55] op_sel_hi:[1,0,1]
	v_pk_fma_f32 v[46:47], v[112:113], s[96:97], v[56:57] op_sel_hi:[1,0,1]
	global_store_dwordx4 v[66:67], v[46:49], off offset:512 nt
	s_waitcnt vmcnt(7)
	v_pk_fma_f32 v[8:9], v[8:9], s[96:97], v[28:29] op_sel_hi:[1,0,1]
	v_pk_fma_f32 v[6:7], v[6:7], s[96:97], v[22:23] op_sel_hi:[1,0,1]
	v_pk_fma_f32 v[48:49], v[118:119], s[96:97], v[58:59] op_sel_hi:[1,0,1]
	v_pk_fma_f32 v[46:47], v[116:117], s[96:97], v[60:61] op_sel_hi:[1,0,1]
	global_store_dwordx4 v[66:67], v[46:49], off offset:576 nt
	s_waitcnt vmcnt(7)
	v_pk_fma_f32 v[4:5], v[4:5], s[96:97], v[20:21] op_sel_hi:[1,0,1]
	v_pk_fma_f32 v[2:3], v[2:3], s[96:97], v[18:19] op_sel_hi:[1,0,1]
	v_pk_fma_f32 v[48:49], v[122:123], s[96:97], v[50:51] op_sel_hi:[1,0,1]
	v_lshl_add_u64 v[50:51], s[48:49], 0, v[146:147]
	v_pk_fma_f32 v[46:47], v[120:121], s[96:97], v[52:53] op_sel_hi:[1,0,1]
	v_lshl_add_u64 v[50:51], v[50:51], 0, v[94:95]
	global_store_dwordx4 v[50:51], v[46:49], off nt
	global_store_dwordx4 v[50:51], v[14:17], off offset:576 nt
	global_store_dwordx4 v[66:67], v[62:65], off offset:64 nt
	v_pk_fma_f32 v[48:49], v[126:127], s[96:97], v[30:31] op_sel_hi:[1,0,1]
	v_pk_fma_f32 v[46:47], v[124:125], s[96:97], v[32:33] op_sel_hi:[1,0,1]
	v_pk_fma_f32 v[32:33], v[140:141], s[96:97], v[38:39] op_sel_hi:[1,0,1]
	v_pk_fma_f32 v[30:31], v[138:139], s[96:97], v[40:41] op_sel_hi:[1,0,1]
	global_store_dwordx4 v[50:51], v[30:33], off offset:512 nt
	v_pk_fma_f32 v[16:17], v[144:145], s[96:97], v[34:35] op_sel_hi:[1,0,1]
	v_pk_fma_f32 v[14:15], v[142:143], s[96:97], v[36:37] op_sel_hi:[1,0,1]
	v_lshl_add_u64 v[30:31], s[48:49], 0, v[82:83]
	v_lshl_add_u64 v[30:31], v[30:31], 0, v[94:95]
	global_store_dwordx4 v[50:51], v[46:49], off offset:64 nt
	global_store_dwordx4 v[30:31], v[14:17], off nt
	global_store_dwordx4 v[30:31], v[10:13], off offset:64 nt
	global_store_dwordx4 v[30:31], v[6:9], off offset:512 nt
	global_store_dwordx4 v[30:31], v[2:5], off offset:576 nt
	s_cbranch_vccnz .LBB0_254
	s_andn2_b64 vcc, exec, s[52:53]
	s_cbranch_vccnz .LBB0_253
	s_barrier
	s_branch .LBB0_253

;     __device__ __forceinline__ void operator()(const f32x4 (&acc)[2][2][4][2], const Unit& u, int wr, int wc, int fr, int fq) const {
;         const int row0 = u.pm * BM + wr * 64 + fr, col0 = u.pn * BM + wc * 32 + 4 * fq;
; #pragma unroll
;         for (int ai = 0; ai < 2; ++ai)
; #pragma unroll
;             for (int m = 0; m < 4; ++m) {
;                 float* rowp = O + (size_t)(row0 + ai * HALF + m * 16) * ldc + col0;
; #pragma unroll
;                 for (int bj = 0; bj < 2; ++bj)
; #pragma unroll
;                     for (int n = 0; n < 2; ++n) *(f32x4*)(rowp + bj * HALF + n * 16) = acc[ai][bj][m][n];
;             }
;     }
.LBB0_464:
	v_lshl_or_b32 v142, s72, 8, v139
	v_lshl_add_u32 v141, s73, 8, v1
	v_ashrrev_i32_e32 v143, 31, v142
	v_mov_b64_e32 v[144:145], s[50:51]
	s_movk_i32 s60, 0xc00
	v_mad_i64_i32 v[146:147], s[58:59], v141, s60, v[144:145]
	v_lshlrev_b64 v[142:143], 2, v[142:143]
	v_lshl_add_u64 v[146:147], v[146:147], 0, v[142:143]
	global_store_dwordx4 v[146:147], v[126:129], off nt
	global_store_dwordx4 v[146:147], v[122:125], off offset:64 nt
	global_store_dwordx4 v[146:147], v[118:121], off offset:512 nt
	global_store_dwordx4 v[146:147], v[114:117], off offset:576 nt
	s_and_b64 vcc, exec, s[40:41]
	s_mov_b64 s[40:41], -1
	v_or_b32_e32 v114, 16, v141
	v_mad_i64_i32 v[114:115], s[58:59], v114, s60, v[144:145]
	v_lshl_add_u64 v[114:115], v[114:115], 0, v[142:143]
	global_store_dwordx4 v[114:115], v[110:113], off nt
	global_store_dwordx4 v[114:115], v[106:109], off offset:64 nt
	global_store_dwordx4 v[114:115], v[102:105], off offset:512 nt
	global_store_dwordx4 v[114:115], v[98:101], off offset:576 nt
	s_nop 1
	v_or_b32_e32 v98, 32, v141
	v_mad_i64_i32 v[98:99], s[58:59], v98, s60, v[144:145]
	v_lshl_add_u64 v[98:99], v[98:99], 0, v[142:143]
	global_store_dwordx4 v[98:99], v[94:97], off nt
	global_store_dwordx4 v[98:99], v[90:93], off offset:64 nt
	global_store_dwordx4 v[98:99], v[86:89], off offset:512 nt
	global_store_dwordx4 v[98:99], v[82:85], off offset:576 nt
	s_nop 1
	v_or_b32_e32 v82, 48, v141
	v_mad_i64_i32 v[82:83], s[58:59], v82, s60, v[144:145]
	v_lshl_add_u64 v[82:83], v[82:83], 0, v[142:143]
	global_store_dwordx4 v[82:83], v[78:81], off nt
	global_store_dwordx4 v[82:83], v[74:77], off offset:64 nt
	global_store_dwordx4 v[82:83], v[70:73], off offset:512 nt
	global_store_dwordx4 v[82:83], v[66:69], off offset:576 nt
	s_nop 1
	v_add_u32_e32 v66, 0x80, v141
	v_mad_i64_i32 v[66:67], s[58:59], v66, s60, v[144:145]
	v_lshl_add_u64 v[66:67], v[66:67], 0, v[142:143]
	global_store_dwordx4 v[66:67], v[62:65], off nt
	global_store_dwordx4 v[66:67], v[58:61], off offset:64 nt
	global_store_dwordx4 v[66:67], v[54:57], off offset:512 nt
	global_store_dwordx4 v[66:67], v[50:53], off offset:576 nt
	s_nop 1
	v_add_u32_e32 v50, 0x90, v141
	v_mad_i64_i32 v[50:51], s[58:59], v50, s60, v[144:145]
	v_lshl_add_u64 v[50:51], v[50:51], 0, v[142:143]
	global_store_dwordx4 v[50:51], v[46:49], off nt
	global_store_dwordx4 v[50:51], v[42:45], off offset:64 nt
	global_store_dwordx4 v[50:51], v[38:41], off offset:512 nt
	global_store_dwordx4 v[50:51], v[34:37], off offset:576 nt
	s_nop 1
	v_add_u32_e32 v34, 0xa0, v141
	v_mad_i64_i32 v[34:35], s[58:59], v34, s60, v[144:145]
	v_lshl_add_u64 v[34:35], v[34:35], 0, v[142:143]
	global_store_dwordx4 v[34:35], v[30:33], off nt
	global_store_dwordx4 v[34:35], v[26:29], off offset:64 nt
	global_store_dwordx4 v[34:35], v[22:25], off offset:512 nt
	global_store_dwordx4 v[34:35], v[18:21], off offset:576 nt
	s_nop 1
	v_add_u32_e32 v18, 0xb0, v141
	v_mad_i64_i32 v[18:19], s[58:59], v18, s60, v[144:145]
	v_lshl_add_u64 v[18:19], v[18:19], 0, v[142:143]
	global_store_dwordx4 v[18:19], v[14:17], off nt
	global_store_dwordx4 v[18:19], v[10:13], off offset:64 nt
	global_store_dwordx4 v[18:19], v[6:9], off offset:512 nt
	global_store_dwordx4 v[18:19], v[2:5], off offset:576 nt
	s_cbranch_vccnz .LBB0_447
	s_andn2_b64 vcc, exec, s[48:49]
	s_cbranch_vccnz .LBB0_446
	s_barrier
	s_branch .LBB0_446

; DI unsigned cvtpk(float lo, float hi) { f32x2_t v = {lo, hi}; bf16x2_t b = __builtin_convertvector(v, bf16x2_t); return __builtin_bit_cast(unsigned, b); }
; __global__ void __launch_bounds__(NTHR, 2) mega_fwd(Params P) {
;     ...
;                 for (size_t e = t0; e < (size_t)8 * PAST * 32; e += tn) {
;                     const size_t row = e >> 5; const int c8 = (int)(e & 31) * 8; const int b = (int)(row >> 12), t = (int)(row & 4095);
;                     const f32x4 a = *(const f32x4*)(cck + row * 256 + c8), b4 = *(const f32x4*)(cck + row * 256 + c8 + 4);
;                     u32x4 w; w.x = cvtpk(a.x, a.y); w.y = cvtpk(a.z, a.w); w.z = cvtpk(b4.x, b4.y); w.w = cvtpk(b4.z, b4.w);
;                     *(u32x4*)(CKVB + ((size_t)MP + (size_t)b * SKV_S + t) * 256 + c8) = w;
;                 }
.LBB0_471:
	v_lshrrev_b64 v[10:11], 5, v[8:9]
	v_and_b32_e32 v20, 0xf8, v6
	v_lshlrev_b64 v[10:11], 10, v[10:11]
	v_lshl_add_u64 v[10:11], s[40:41], 0, v[10:11]
	v_lshlrev_b32_e32 v12, 2, v20
	v_mov_b32_e32 v13, v0
	v_lshl_add_u64 v[14:15], v[10:11], 0, v[12:13]
	global_load_dwordx4 v[10:13], v[14:15], off offset:16
	s_nop 0
	global_load_dwordx4 v[14:17], v[14:15], off
	v_alignbit_b32 v1, v9, v8, 5
	v_and_b32_e32 v18, 0xfff, v1
	v_mov_b32_e32 v19, v0
	v_alignbit_b32 v1, v9, v8, 17
	v_lshl_add_u64 v[8:9], v[8:9], 0, s[8:9]
	v_lshl_add_u64 v[6:7], v[6:7], 0, s[54:55]
	s_waitcnt vmcnt(0)
	v_cvt_pk_bf16_f32 v14, v14, v15
	v_cvt_pk_bf16_f32 v15, v16, v17
	v_cvt_pk_bf16_f32 v16, v10, v11
	v_mad_u64_u32 v[10:11], s[4:5], v1, s6, v[18:19]
	v_lshlrev_b64 v[10:11], 9, v[10:11]
	v_cvt_pk_bf16_f32 v17, v12, v13
	v_lshl_add_u64 v[10:11], s[50:51], 0, v[10:11]
	v_lshlrev_b32_e32 v12, 1, v20
	v_mov_b32_e32 v13, v0
	v_lshl_add_u64 v[10:11], v[10:11], 0, v[12:13]
	v_add_co_u32_e32 v10, vcc, 0x1000000, v10
	s_mov_b64 s[4:5], 0xfffff
	s_nop 0
	v_addc_co_u32_e32 v11, vcc, 0, v11, vcc
	v_cmp_lt_u64_e32 vcc, s[4:5], v[8:9]
	s_or_b64 s[52:53], vcc, s[52:53]
	global_store_dwordx4 v[10:11], v[14:17], off nt
	s_andn2_b64 exec, exec, s[52:53]
	s_cbranch_execnz .LBB0_471

; DI unsigned cvtpk(float lo, float hi) { f32x2_t v = {lo, hi}; bf16x2_t b = __builtin_convertvector(v, bf16x2_t); return __builtin_bit_cast(unsigned, b); }
; __global__ void __launch_bounds__(NTHR, 2) mega_fwd(Params P) {
;     ...
;                 for (size_t e = t0; e < (size_t)8 * PAST * 4; e += tn) {
;                     const size_t row = e >> 2; const int c8 = (int)(e & 3) * 8; const int b = (int)(row >> 12), t = (int)(row & 4095);
;                     const f32x4 a = *(const f32x4*)(ckr + row * 32 + c8), b4 = *(const f32x4*)(ckr + row * 32 + c8 + 4);
;                     u32x4 w; w.x = cvtpk(a.x, a.y); w.y = cvtpk(a.z, a.w); w.z = cvtpk(b4.x, b4.y); w.w = cvtpk(b4.z, b4.w);
;                     *(u32x4*)(KR + ((size_t)MP + (size_t)b * SKV_S + t) * 32 + c8) = w;
;                 }
.LBB0_474:
	v_lshrrev_b64 v[6:7], 2, v[2:3]
	v_and_b32_e32 v16, 24, v4
	v_lshlrev_b64 v[6:7], 7, v[6:7]
	v_lshl_add_u64 v[6:7], s[34:35], 0, v[6:7]
	v_lshlrev_b32_e32 v8, 2, v16
	v_mov_b32_e32 v9, v0
	v_lshl_add_u64 v[10:11], v[6:7], 0, v[8:9]
	global_load_dwordx4 v[6:9], v[10:11], off offset:16
	s_nop 0
	global_load_dwordx4 v[10:13], v[10:11], off
	v_alignbit_b32 v1, v3, v2, 2
	v_and_b32_e32 v14, 0xfff, v1
	v_mov_b32_e32 v15, v0
	v_alignbit_b32 v1, v3, v2, 14
	v_lshl_add_u64 v[2:3], v[2:3], 0, s[8:9]
	v_lshl_add_u64 v[4:5], v[4:5], 0, s[48:49]
	s_waitcnt vmcnt(0)
	v_cvt_pk_bf16_f32 v10, v10, v11
	v_cvt_pk_bf16_f32 v11, v12, v13
	v_cvt_pk_bf16_f32 v12, v6, v7
	v_mad_u64_u32 v[6:7], s[4:5], v1, s6, v[14:15]
	v_lshlrev_b64 v[6:7], 6, v[6:7]
	v_cvt_pk_bf16_f32 v13, v8, v9
	v_lshl_add_u64 v[6:7], s[46:47], 0, v[6:7]
	v_lshlrev_b32_e32 v8, 1, v16
	v_mov_b32_e32 v9, v0
	v_lshl_add_u64 v[6:7], v[6:7], 0, v[8:9]
	v_add_co_u32_e32 v6, vcc, 0x200000, v6
	s_mov_b64 s[4:5], 0x1ffff
	s_nop 0
	v_addc_co_u32_e32 v7, vcc, 0, v7, vcc
	v_cmp_lt_u64_e32 vcc, s[4:5], v[2:3]
	s_or_b64 s[42:43], vcc, s[42:43]
	global_store_dwordx4 v[6:7], v[10:13], off nt
	s_andn2_b64 exec, exec, s[42:43]
	s_cbranch_execnz .LBB0_474

; DI unsigned cvtpk(float lo, float hi) { f32x2_t v = {lo, hi}; bf16x2_t b = __builtin_convertvector(v, bf16x2_t); return __builtin_bit_cast(unsigned, b); }
;     __device__ __forceinline__ void operator()(const f32x4 (&acc)[2][2][4][2], const Unit& u, int wr, int wc, int fr, int fq) const {
;     ...
;                 const int row = row0 + ai * HALF + m * 16; const int pos = pos_of_row(row);
; #pragma unroll
;                 for (int bj = 0; bj < 2; ++bj) {
;                     const int g32 = u.pn * 8 + bj * 4 + wc;
;                     f32x4 a = acc[ai][bj][m][0], b = acc[ai][bj][m][1];
;                     if (g32 % 3 == 2) {
;                         const float2* t = tabM + (size_t)pos * 16 + 4 * fq;
; #pragma unroll
;                         for (int j = 0; j < 4; ++j) { const float2 cs = t[j]; const float x1 = a[j], x2 = b[j]; a[j] = x1 * cs.x - x2 * cs.y; b[j] = x2 * cs.x + x1 * cs.y; }
;                     }
;                     a = a * QSCALE; b = b * QSCALE;
;                     bf16_t* p = Q + (size_t)row * 768 + g32 * 32 + 4 * fq;
;                     u32x2 w0; w0.x = cvtpk(a[0], a[1]); w0.y = cvtpk(a[2], a[3]); *(u32x2*)p = w0;
;                     u32x2 w1; w1.x = cvtpk(b[0], b[1]); w1.y = cvtpk(b[2], b[3]); *(u32x2*)(p + 16) = w1;
.LBB0_657:
	v_pk_mul_f32 v[152:153], v[122:123], s[84:85] op_sel_hi:[1,0]
	v_mov_b64_e32 v[122:123], s[52:53]
	s_movk_i32 s9, 0x600
	s_lshl_b32 s62, s8, 5
	s_or_b32 s8, s8, 4
	v_pk_mul_f32 v[150:151], v[124:125], s[84:85] op_sel_hi:[1,0]
	v_mad_i64_i32 v[124:125], s[10:11], v149, s9, v[122:123]
	s_mul_hi_i32 s9, s8, 0x55555556
	s_lshr_b32 s10, s9, 31
	s_add_i32 s9, s9, s10
	s_ashr_i32 s63, s62, 31
	s_mul_i32 s9, s9, 3
	v_pk_mul_f32 v[128:129], v[128:129], s[84:85] op_sel_hi:[1,0]
	v_pk_mul_f32 v[126:127], v[126:127], s[84:85] op_sel_hi:[1,0]
	v_lshl_add_u64 v[154:155], s[62:63], 1, v[124:125]
	v_lshlrev_b32_e32 v122, 1, v134
	v_mov_b32_e32 v123, v0
	s_sub_i32 s9, s8, s9
	v_lshl_add_u64 v[154:155], v[154:155], 0, v[122:123]
	v_cvt_pk_bf16_f32 v126, v126, v127
	v_cvt_pk_bf16_f32 v127, v128, v129
	s_cmp_eq_u32 s9, 2
	global_store_dwordx2 v[154:155], v[126:127], off nt
	v_cvt_pk_bf16_f32 v126, v152, v153
	v_cvt_pk_bf16_f32 v127, v150, v151
	s_cselect_b64 s[66:67], -1, 0
	s_cmp_lg_u32 s9, 2
	global_store_dwordx2 v[154:155], v[126:127], off offset:32 nt
	s_cbranch_scc1 .LBB0_659
	v_mov_b32_e32 v143, v0
	v_lshl_add_u64 v[142:143], v[136:137], 0, v[142:143]
	global_load_dwordx4 v[126:129], v[142:143], off
	global_load_dwordx4 v[150:153], v[142:143], off offset:16
	s_waitcnt vmcnt(0)
	v_mov_b32_e32 v142, v126
	v_mul_f32_e32 v126, v120, v150
	v_mul_f32_e32 v154, v116, v151
	v_mul_f32_e32 v150, v116, v150
	v_mul_f32_e32 v156, v120, v151
	v_mov_b32_e32 v116, v121
	v_mov_b32_e32 v120, v117
	v_mov_b32_e32 v143, v128
	v_mov_b32_e32 v128, v127
	v_pk_mul_f32 v[116:117], v[116:117], v[152:153]
	v_pk_mul_f32 v[120:121], v[120:121], v[152:153]
	v_pk_mul_f32 v[158:159], v[118:119], v[128:129]
	v_pk_mul_f32 v[128:129], v[114:115], v[128:129]
	v_mov_b32_e32 v127, v116
	v_mov_b32_e32 v155, v117
	v_mov_b32_e32 v151, v120
	v_mov_b32_e32 v157, v121
	v_pk_fma_f32 v[118:119], v[118:119], v[142:143], v[128:129] neg_lo:[0,0,1] neg_hi:[0,0,1]
	v_pk_fma_f32 v[114:115], v[114:115], v[142:143], v[158:159]
	v_pk_add_f32 v[120:121], v[126:127], v[154:155] neg_lo:[0,1] neg_hi:[0,1]
	v_pk_add_f32 v[116:117], v[150:151], v[156:157]
.LBB0_659:
	s_lshl_b32 s64, s8, 5
	s_ashr_i32 s65, s64, 31
	v_pk_mul_f32 v[116:117], v[116:117], s[84:85] op_sel_hi:[1,0]
	v_pk_mul_f32 v[114:115], v[114:115], s[84:85] op_sel_hi:[1,0]
	v_lshl_add_u64 v[124:125], s[64:65], 1, v[124:125]
	v_lshl_add_u64 v[124:125], v[124:125], 0, v[122:123]
	v_cvt_pk_bf16_f32 v114, v114, v115
	v_cvt_pk_bf16_f32 v115, v116, v117
	v_or_b32_e32 v116, 16, v149
	s_movk_i32 s8, 0x1fdf
	global_store_dwordx2 v[124:125], v[114:115], off offset:32 nt
	v_bitop3_b32 v114, v149, s8, 16 bitop3:0xc8
	v_cmp_gt_i32_e32 vcc, s89, v116
	v_pk_mul_f32 v[120:121], v[120:121], s[84:85] op_sel_hi:[1,0]
	v_pk_mul_f32 v[118:119], v[118:119], s[84:85] op_sel_hi:[1,0]
	v_cndmask_b32_e32 v114, v145, v114, vcc
	v_lshlrev_b32_e32 v114, 4, v114
	v_cndmask_b32_e64 v115, 0, 1, s[44:45]
	v_cvt_pk_bf16_f32 v118, v118, v119
	v_cvt_pk_bf16_f32 v119, v120, v121
	v_cmp_ne_u32_e64 s[42:43], 1, v115
	s_andn2_b64 vcc, exec, s[44:45]
	v_lshlrev_b32_e32 v114, 3, v114
	global_store_dwordx2 v[124:125], v[118:119], off nt
	s_cbranch_vccnz .LBB0_661
	v_mov_b32_e32 v115, v0
	v_lshl_add_u64 v[124:125], v[136:137], 0, v[114:115]
	global_load_dwordx4 v[118:121], v[124:125], off
	s_nop 0
	global_load_dwordx4 v[124:127], v[124:125], off offset:16
	s_waitcnt vmcnt(0)
	v_mov_b32_e32 v128, v118
	v_mul_f32_e32 v118, v112, v124
	v_mul_f32_e32 v142, v108, v125
	v_mul_f32_e32 v124, v108, v124
	v_mul_f32_e32 v150, v112, v125
	v_mov_b32_e32 v108, v113
	v_mov_b32_e32 v112, v109
	v_mov_b32_e32 v129, v120
	v_mov_b32_e32 v120, v119
	v_pk_mul_f32 v[108:109], v[108:109], v[126:127]
	v_pk_mul_f32 v[112:113], v[112:113], v[126:127]
	v_pk_mul_f32 v[152:153], v[110:111], v[120:121]
	v_pk_mul_f32 v[120:121], v[106:107], v[120:121]
	v_mov_b32_e32 v119, v108
	v_mov_b32_e32 v143, v109
	v_mov_b32_e32 v125, v112
	v_mov_b32_e32 v151, v113
	v_pk_fma_f32 v[110:111], v[110:111], v[128:129], v[120:121] neg_lo:[0,0,1] neg_hi:[0,0,1]
	v_pk_fma_f32 v[106:107], v[106:107], v[128:129], v[152:153]
	v_pk_add_f32 v[112:113], v[118:119], v[142:143] neg_lo:[0,1] neg_hi:[0,1]
	v_pk_add_f32 v[108:109], v[124:125], v[150:151]
.LBB0_661:
	v_pk_mul_f32 v[118:119], v[106:107], s[84:85] op_sel_hi:[1,0]
	v_mov_b64_e32 v[106:107], s[52:53]
	s_movk_i32 s8, 0x600
	v_mad_i64_i32 v[106:107], s[8:9], v116, s8, v[106:107]
	v_pk_mul_f32 v[112:113], v[112:113], s[84:85] op_sel_hi:[1,0]
	v_pk_mul_f32 v[110:111], v[110:111], s[84:85] op_sel_hi:[1,0]
	v_lshl_add_u64 v[116:117], s[62:63], 1, v[106:107]
	v_mov_b32_e32 v123, v0
	v_pk_mul_f32 v[108:109], v[108:109], s[84:85] op_sel_hi:[1,0]
	v_lshl_add_u64 v[116:117], v[116:117], 0, v[122:123]
	v_cvt_pk_bf16_f32 v110, v110, v111
	v_cvt_pk_bf16_f32 v111, v112, v113
	global_store_dwordx2 v[116:117], v[110:111], off nt
	v_cvt_pk_bf16_f32 v111, v108, v109
	v_cndmask_b32_e64 v108, 0, 1, s[66:67]
	v_cvt_pk_bf16_f32 v110, v118, v119
	v_cmp_ne_u32_e64 s[44:45], 1, v108
	s_andn2_b64 vcc, exec, s[66:67]
	global_store_dwordx2 v[116:117], v[110:111], off offset:32 nt
	s_cbranch_vccnz .LBB0_663
	v_mov_b32_e32 v115, v0
	v_lshl_add_u64 v[112:113], v[136:137], 0, v[114:115]
	global_load_dwordx4 v[108:111], v[112:113], off
	s_nop 0
	global_load_dwordx4 v[112:115], v[112:113], off offset:16
	s_waitcnt vmcnt(0)
	v_mov_b32_e32 v116, v108
	v_mul_f32_e32 v108, v104, v112
	v_mul_f32_e32 v118, v100, v113
	v_mul_f32_e32 v112, v100, v112
	v_mul_f32_e32 v120, v104, v113
	v_mov_b32_e32 v100, v105
	v_mov_b32_e32 v104, v101
	v_mov_b32_e32 v117, v110
	v_mov_b32_e32 v110, v109
	v_pk_mul_f32 v[100:101], v[100:101], v[114:115]
	v_pk_mul_f32 v[104:105], v[104:105], v[114:115]
	v_pk_mul_f32 v[124:125], v[102:103], v[110:111]
	v_pk_mul_f32 v[110:111], v[98:99], v[110:111]
	v_mov_b32_e32 v109, v100
	v_mov_b32_e32 v119, v101
	v_mov_b32_e32 v113, v104
	v_mov_b32_e32 v121, v105
	v_pk_fma_f32 v[102:103], v[102:103], v[116:117], v[110:111] neg_lo:[0,0,1] neg_hi:[0,0,1]
	v_pk_fma_f32 v[98:99], v[98:99], v[116:117], v[124:125]
	v_pk_add_f32 v[104:105], v[108:109], v[118:119] neg_lo:[0,1] neg_hi:[0,1]
	v_pk_add_f32 v[100:101], v[112:113], v[120:121]
; DI unsigned cvtpk(float lo, float hi) { f32x2_t v = {lo, hi}; bf16x2_t b = __builtin_convertvector(v, bf16x2_t); return __builtin_bit_cast(unsigned, b); }
;     __device__ __forceinline__ void operator()(const f32x4 (&acc)[2][2][4][2], const Unit& u, int wr, int wc, int fr, int fq) const {
;     ...
;                 const int row = row0 + ai * HALF + m * 16; const int pos = pos_of_row(row);
; #pragma unroll
;                 for (int bj = 0; bj < 2; ++bj) {
;                     const int g32 = u.pn * 8 + bj * 4 + wc;
;                     f32x4 a = acc[ai][bj][m][0], b = acc[ai][bj][m][1];
;                     if (g32 % 3 == 2) {
;                         const float2* t = tabM + (size_t)pos * 16 + 4 * fq;
; #pragma unroll
;                         for (int j = 0; j < 4; ++j) { const float2 cs = t[j]; const float x1 = a[j], x2 = b[j]; a[j] = x1 * cs.x - x2 * cs.y; b[j] = x2 * cs.x + x1 * cs.y; }
;                     }
;                     a = a * QSCALE; b = b * QSCALE;
;                     bf16_t* p = Q + (size_t)row * 768 + g32 * 32 + 4 * fq;
;                     u32x2 w0; w0.x = cvtpk(a[0], a[1]); w0.y = cvtpk(a[2], a[3]); *(u32x2*)p = w0;
;                     u32x2 w1; w1.x = cvtpk(b[0], b[1]); w1.y = cvtpk(b[2], b[3]); *(u32x2*)(p + 16) = w1;
.LBB0_663:
	s_nop 0
	v_pk_mul_f32 v[100:101], v[100:101], s[84:85] op_sel_hi:[1,0]
	v_pk_mul_f32 v[98:99], v[98:99], s[84:85] op_sel_hi:[1,0]
	v_lshl_add_u64 v[106:107], s[64:65], 1, v[106:107]
	v_lshl_add_u64 v[106:107], v[106:107], 0, v[122:123]
	v_cvt_pk_bf16_f32 v98, v98, v99
	v_cvt_pk_bf16_f32 v99, v100, v101
	v_or_b32_e32 v100, 32, v149
	s_movk_i32 s8, 0x1fef
	global_store_dwordx2 v[106:107], v[98:99], off offset:32 nt
	v_bitop3_b32 v98, v149, s8, 32 bitop3:0xc8
	v_cmp_gt_i32_e32 vcc, s89, v100
	v_pk_mul_f32 v[104:105], v[104:105], s[84:85] op_sel_hi:[1,0]
	v_pk_mul_f32 v[102:103], v[102:103], s[84:85] op_sel_hi:[1,0]
	v_cndmask_b32_e32 v98, v146, v98, vcc
	v_lshlrev_b32_e32 v98, 4, v98
	v_cvt_pk_bf16_f32 v102, v102, v103
	v_cvt_pk_bf16_f32 v103, v104, v105
	s_and_b64 vcc, exec, s[42:43]
	v_lshlrev_b32_e32 v98, 3, v98
	global_store_dwordx2 v[106:107], v[102:103], off nt
	s_cbranch_vccnz .LBB0_665
	v_mov_b32_e32 v99, v0
	v_lshl_add_u64 v[106:107], v[136:137], 0, v[98:99]
	global_load_dwordx4 v[102:105], v[106:107], off
	s_nop 0
	global_load_dwordx4 v[106:109], v[106:107], off offset:16
	s_waitcnt vmcnt(0)
	v_mov_b32_e32 v110, v102
	v_mul_f32_e32 v102, v96, v106
	v_mul_f32_e32 v112, v92, v107
	v_mul_f32_e32 v106, v92, v106
	v_mul_f32_e32 v114, v96, v107
	v_mov_b32_e32 v92, v97
	v_mov_b32_e32 v96, v93
	v_mov_b32_e32 v111, v104
	v_mov_b32_e32 v104, v103
	v_pk_mul_f32 v[92:93], v[92:93], v[108:109]
	v_pk_mul_f32 v[96:97], v[96:97], v[108:109]
	v_pk_mul_f32 v[116:117], v[94:95], v[104:105]
	v_pk_mul_f32 v[104:105], v[90:91], v[104:105]
	v_mov_b32_e32 v103, v92
	v_mov_b32_e32 v113, v93
	v_mov_b32_e32 v107, v96
	v_mov_b32_e32 v115, v97
	v_pk_fma_f32 v[94:95], v[94:95], v[110:111], v[104:105] neg_lo:[0,0,1] neg_hi:[0,0,1]
	v_pk_fma_f32 v[90:91], v[90:91], v[110:111], v[116:117]
	v_pk_add_f32 v[96:97], v[102:103], v[112:113] neg_lo:[0,1] neg_hi:[0,1]
	v_pk_add_f32 v[92:93], v[106:107], v[114:115]
.LBB0_665:
	v_pk_mul_f32 v[102:103], v[90:91], s[84:85] op_sel_hi:[1,0]
	v_mov_b64_e32 v[90:91], s[52:53]
	s_movk_i32 s8, 0x600
	v_mad_i64_i32 v[90:91], s[8:9], v100, s8, v[90:91]
	v_pk_mul_f32 v[96:97], v[96:97], s[84:85] op_sel_hi:[1,0]
	v_pk_mul_f32 v[94:95], v[94:95], s[84:85] op_sel_hi:[1,0]
	v_lshl_add_u64 v[100:101], s[62:63], 1, v[90:91]
	v_mov_b32_e32 v123, v0
	v_pk_mul_f32 v[92:93], v[92:93], s[84:85] op_sel_hi:[1,0]
	v_lshl_add_u64 v[100:101], v[100:101], 0, v[122:123]
	v_cvt_pk_bf16_f32 v94, v94, v95
	v_cvt_pk_bf16_f32 v95, v96, v97
	global_store_dwordx2 v[100:101], v[94:95], off nt
	v_cvt_pk_bf16_f32 v94, v102, v103
	v_cvt_pk_bf16_f32 v95, v92, v93
	s_and_b64 vcc, exec, s[44:45]
	global_store_dwordx2 v[100:101], v[94:95], off offset:32 nt
	s_cbranch_vccnz .LBB0_667
	v_mov_b32_e32 v99, v0
	v_lshl_add_u64 v[96:97], v[136:137], 0, v[98:99]
	global_load_dwordx4 v[92:95], v[96:97], off
	s_nop 0
	global_load_dwordx4 v[96:99], v[96:97], off offset:16
	s_waitcnt vmcnt(0)
	v_mov_b32_e32 v100, v92
	v_mul_f32_e32 v92, v88, v96
	v_mul_f32_e32 v102, v84, v97
	v_mul_f32_e32 v96, v84, v96
	v_mul_f32_e32 v104, v88, v97
	v_mov_b32_e32 v84, v89
	v_mov_b32_e32 v88, v85
	v_mov_b32_e32 v101, v94
	v_mov_b32_e32 v94, v93
	v_pk_mul_f32 v[84:85], v[84:85], v[98:99]
	v_pk_mul_f32 v[88:89], v[88:89], v[98:99]
	v_pk_mul_f32 v[106:107], v[86:87], v[94:95]
	v_pk_mul_f32 v[94:95], v[82:83], v[94:95]
	v_mov_b32_e32 v93, v84
	v_mov_b32_e32 v103, v85
	v_mov_b32_e32 v97, v88
	v_mov_b32_e32 v105, v89
	v_pk_fma_f32 v[86:87], v[86:87], v[100:101], v[94:95] neg_lo:[0,0,1] neg_hi:[0,0,1]
	v_pk_fma_f32 v[82:83], v[82:83], v[100:101], v[106:107]
	v_pk_add_f32 v[88:89], v[92:93], v[102:103] neg_lo:[0,1] neg_hi:[0,1]
	v_pk_add_f32 v[84:85], v[96:97], v[104:105]
.LBB0_667:
	s_nop 0
	v_pk_mul_f32 v[84:85], v[84:85], s[84:85] op_sel_hi:[1,0]
	v_pk_mul_f32 v[82:83], v[82:83], s[84:85] op_sel_hi:[1,0]
	v_lshl_add_u64 v[90:91], s[64:65], 1, v[90:91]
	v_lshl_add_u64 v[90:91], v[90:91], 0, v[122:123]
	v_cvt_pk_bf16_f32 v82, v82, v83
	v_cvt_pk_bf16_f32 v83, v84, v85
	v_or_b32_e32 v84, 48, v149
	s_movk_i32 s8, 0x1fff
	global_store_dwordx2 v[90:91], v[82:83], off offset:32 nt
	v_bitop3_b32 v82, v149, s8, 48 bitop3:0xc8
	v_cmp_gt_i32_e32 vcc, s89, v84
	v_pk_mul_f32 v[88:89], v[88:89], s[84:85] op_sel_hi:[1,0]
	v_pk_mul_f32 v[86:87], v[86:87], s[84:85] op_sel_hi:[1,0]
	v_cndmask_b32_e32 v82, v147, v82, vcc
	v_lshlrev_b32_e32 v82, 4, v82
	v_cvt_pk_bf16_f32 v86, v86, v87
	v_cvt_pk_bf16_f32 v87, v88, v89
	s_and_b64 vcc, exec, s[42:43]
	v_lshlrev_b32_e32 v82, 3, v82
	global_store_dwordx2 v[90:91], v[86:87], off nt
	s_cbranch_vccnz .LBB0_669
	v_mov_b32_e32 v83, v0
	v_lshl_add_u64 v[90:91], v[136:137], 0, v[82:83]
	global_load_dwordx4 v[86:89], v[90:91], off
	s_nop 0
	global_load_dwordx4 v[90:93], v[90:91], off offset:16
	s_waitcnt vmcnt(0)
	v_mov_b32_e32 v94, v86
	v_mul_f32_e32 v86, v80, v90
	v_mul_f32_e32 v96, v76, v91
	v_mul_f32_e32 v90, v76, v90
	v_mul_f32_e32 v98, v80, v91
	v_mov_b32_e32 v76, v81
	v_mov_b32_e32 v80, v77
	v_mov_b32_e32 v95, v88
	v_mov_b32_e32 v88, v87
	v_pk_mul_f32 v[76:77], v[76:77], v[92:93]
	v_pk_mul_f32 v[80:81], v[80:81], v[92:93]
	v_pk_mul_f32 v[100:101], v[78:79], v[88:89]
	v_pk_mul_f32 v[88:89], v[74:75], v[88:89]
	v_mov_b32_e32 v87, v76
	v_mov_b32_e32 v97, v77
	v_mov_b32_e32 v91, v80
	v_mov_b32_e32 v99, v81
	v_pk_fma_f32 v[78:79], v[78:79], v[94:95], v[88:89] neg_lo:[0,0,1] neg_hi:[0,0,1]
	v_pk_fma_f32 v[74:75], v[74:75], v[94:95], v[100:101]
	v_pk_add_f32 v[80:81], v[86:87], v[96:97] neg_lo:[0,1] neg_hi:[0,1]
	v_pk_add_f32 v[76:77], v[90:91], v[98:99]
; DI unsigned cvtpk(float lo, float hi) { f32x2_t v = {lo, hi}; bf16x2_t b = __builtin_convertvector(v, bf16x2_t); return __builtin_bit_cast(unsigned, b); }
;     __device__ __forceinline__ void operator()(const f32x4 (&acc)[2][2][4][2], const Unit& u, int wr, int wc, int fr, int fq) const {
;     ...
;                 const int row = row0 + ai * HALF + m * 16; const int pos = pos_of_row(row);
; #pragma unroll
;                 for (int bj = 0; bj < 2; ++bj) {
;                     const int g32 = u.pn * 8 + bj * 4 + wc;
;                     f32x4 a = acc[ai][bj][m][0], b = acc[ai][bj][m][1];
;                     if (g32 % 3 == 2) {
;                         const float2* t = tabM + (size_t)pos * 16 + 4 * fq;
; #pragma unroll
;                         for (int j = 0; j < 4; ++j) { const float2 cs = t[j]; const float x1 = a[j], x2 = b[j]; a[j] = x1 * cs.x - x2 * cs.y; b[j] = x2 * cs.x + x1 * cs.y; }
;                     }
;                     a = a * QSCALE; b = b * QSCALE;
;                     bf16_t* p = Q + (size_t)row * 768 + g32 * 32 + 4 * fq;
;                     u32x2 w0; w0.x = cvtpk(a[0], a[1]); w0.y = cvtpk(a[2], a[3]); *(u32x2*)p = w0;
;                     u32x2 w1; w1.x = cvtpk(b[0], b[1]); w1.y = cvtpk(b[2], b[3]); *(u32x2*)(p + 16) = w1;
.LBB0_669:
	v_pk_mul_f32 v[86:87], v[74:75], s[84:85] op_sel_hi:[1,0]
	v_mov_b64_e32 v[74:75], s[52:53]
	s_movk_i32 s8, 0x600
	v_mad_i64_i32 v[74:75], s[8:9], v84, s8, v[74:75]
	v_pk_mul_f32 v[80:81], v[80:81], s[84:85] op_sel_hi:[1,0]
	v_pk_mul_f32 v[78:79], v[78:79], s[84:85] op_sel_hi:[1,0]
	v_lshl_add_u64 v[84:85], s[62:63], 1, v[74:75]
	v_mov_b32_e32 v123, v0
	v_pk_mul_f32 v[76:77], v[76:77], s[84:85] op_sel_hi:[1,0]
	v_lshl_add_u64 v[84:85], v[84:85], 0, v[122:123]
	v_cvt_pk_bf16_f32 v78, v78, v79
	v_cvt_pk_bf16_f32 v79, v80, v81
	global_store_dwordx2 v[84:85], v[78:79], off nt
	v_cvt_pk_bf16_f32 v78, v86, v87
	v_cvt_pk_bf16_f32 v79, v76, v77
	s_and_b64 vcc, exec, s[44:45]
	global_store_dwordx2 v[84:85], v[78:79], off offset:32 nt
	s_cbranch_vccnz .LBB0_671
	v_mov_b32_e32 v83, v0
	v_lshl_add_u64 v[80:81], v[136:137], 0, v[82:83]
	global_load_dwordx4 v[76:79], v[80:81], off
	s_nop 0
	global_load_dwordx4 v[80:83], v[80:81], off offset:16
	s_waitcnt vmcnt(0)
	v_mov_b32_e32 v84, v76
	v_mul_f32_e32 v76, v72, v80
	v_mul_f32_e32 v86, v68, v81
	v_mul_f32_e32 v80, v68, v80
	v_mul_f32_e32 v88, v72, v81
	v_mov_b32_e32 v68, v73
	v_mov_b32_e32 v72, v69
	v_mov_b32_e32 v85, v78
	v_mov_b32_e32 v78, v77
	v_pk_mul_f32 v[68:69], v[68:69], v[82:83]
	v_pk_mul_f32 v[72:73], v[72:73], v[82:83]
	v_pk_mul_f32 v[90:91], v[70:71], v[78:79]
	v_pk_mul_f32 v[78:79], v[66:67], v[78:79]
	v_mov_b32_e32 v77, v68
	v_mov_b32_e32 v87, v69
	v_mov_b32_e32 v81, v72
	v_mov_b32_e32 v89, v73
	v_pk_fma_f32 v[70:71], v[70:71], v[84:85], v[78:79] neg_lo:[0,0,1] neg_hi:[0,0,1]
	v_pk_fma_f32 v[66:67], v[66:67], v[84:85], v[90:91]
	v_pk_add_f32 v[72:73], v[76:77], v[86:87] neg_lo:[0,1] neg_hi:[0,1]
	v_pk_add_f32 v[68:69], v[80:81], v[88:89]
.LBB0_671:
	s_nop 0
	v_pk_mul_f32 v[68:69], v[68:69], s[84:85] op_sel_hi:[1,0]
	v_pk_mul_f32 v[66:67], v[66:67], s[84:85] op_sel_hi:[1,0]
	v_lshl_add_u64 v[74:75], s[64:65], 1, v[74:75]
	v_lshl_add_u64 v[74:75], v[74:75], 0, v[122:123]
	v_cvt_pk_bf16_f32 v66, v66, v67
	v_cvt_pk_bf16_f32 v67, v68, v69
	v_add_u32_e32 v68, 0x80, v149
	s_movk_i32 s8, 0x7f80
	global_store_dwordx2 v[74:75], v[66:67], off offset:32 nt
	v_and_b32_e32 v66, 0x1fcf, v68
	v_cmp_gt_i32_e32 vcc, s8, v149
	v_pk_mul_f32 v[72:73], v[72:73], s[84:85] op_sel_hi:[1,0]
	v_pk_mul_f32 v[70:71], v[70:71], s[84:85] op_sel_hi:[1,0]
	v_cndmask_b32_e32 v66, v144, v66, vcc
	v_lshlrev_b32_e32 v66, 4, v66
	v_cvt_pk_bf16_f32 v70, v70, v71
	v_cvt_pk_bf16_f32 v71, v72, v73
	s_and_b64 vcc, exec, s[42:43]
	v_lshlrev_b32_e32 v66, 3, v66
	global_store_dwordx2 v[74:75], v[70:71], off nt
	s_cbranch_vccnz .LBB0_673
	v_mov_b32_e32 v67, v0
	v_lshl_add_u64 v[74:75], v[136:137], 0, v[66:67]
	global_load_dwordx4 v[70:73], v[74:75], off
	s_nop 0
	global_load_dwordx4 v[74:77], v[74:75], off offset:16
	s_waitcnt vmcnt(0)
	v_mov_b32_e32 v78, v70
	v_mul_f32_e32 v70, v64, v74
	v_mul_f32_e32 v80, v60, v75
	v_mul_f32_e32 v74, v60, v74
	v_mul_f32_e32 v82, v64, v75
	v_mov_b32_e32 v60, v65
	v_mov_b32_e32 v64, v61
	v_mov_b32_e32 v79, v72
	v_mov_b32_e32 v72, v71
	v_pk_mul_f32 v[60:61], v[60:61], v[76:77]
	v_pk_mul_f32 v[64:65], v[64:65], v[76:77]
	v_pk_mul_f32 v[84:85], v[62:63], v[72:73]
	v_pk_mul_f32 v[72:73], v[58:59], v[72:73]
	v_mov_b32_e32 v71, v60
	v_mov_b32_e32 v81, v61
	v_mov_b32_e32 v75, v64
	v_mov_b32_e32 v83, v65
	v_pk_fma_f32 v[62:63], v[62:63], v[78:79], v[72:73] neg_lo:[0,0,1] neg_hi:[0,0,1]
	v_pk_fma_f32 v[58:59], v[58:59], v[78:79], v[84:85]
	v_pk_add_f32 v[64:65], v[70:71], v[80:81] neg_lo:[0,1] neg_hi:[0,1]
	v_pk_add_f32 v[60:61], v[74:75], v[82:83]
.LBB0_673:
	v_pk_mul_f32 v[70:71], v[58:59], s[84:85] op_sel_hi:[1,0]
	v_mov_b64_e32 v[58:59], s[52:53]
	s_movk_i32 s8, 0x600
	v_mad_i64_i32 v[58:59], s[8:9], v68, s8, v[58:59]
	v_pk_mul_f32 v[64:65], v[64:65], s[84:85] op_sel_hi:[1,0]
	v_pk_mul_f32 v[62:63], v[62:63], s[84:85] op_sel_hi:[1,0]
	v_lshl_add_u64 v[68:69], s[62:63], 1, v[58:59]
	v_mov_b32_e32 v123, v0
	v_pk_mul_f32 v[60:61], v[60:61], s[84:85] op_sel_hi:[1,0]
	v_lshl_add_u64 v[68:69], v[68:69], 0, v[122:123]
	v_cvt_pk_bf16_f32 v62, v62, v63
	v_cvt_pk_bf16_f32 v63, v64, v65
	global_store_dwordx2 v[68:69], v[62:63], off nt
	v_cvt_pk_bf16_f32 v62, v70, v71
	v_cvt_pk_bf16_f32 v63, v60, v61
	s_and_b64 vcc, exec, s[44:45]
	global_store_dwordx2 v[68:69], v[62:63], off offset:32 nt
	s_cbranch_vccnz .LBB0_675
	v_mov_b32_e32 v67, v0
	v_lshl_add_u64 v[64:65], v[136:137], 0, v[66:67]
	global_load_dwordx4 v[60:63], v[64:65], off
	s_nop 0
	global_load_dwordx4 v[64:67], v[64:65], off offset:16
	s_waitcnt vmcnt(0)
	v_mov_b32_e32 v68, v60
	v_mul_f32_e32 v60, v56, v64
	v_mul_f32_e32 v70, v52, v65
	v_mul_f32_e32 v64, v52, v64
	v_mul_f32_e32 v72, v56, v65
	v_mov_b32_e32 v52, v57
	v_mov_b32_e32 v56, v53
	v_mov_b32_e32 v69, v62
	v_mov_b32_e32 v62, v61
	v_pk_mul_f32 v[52:53], v[52:53], v[66:67]
	v_pk_mul_f32 v[56:57], v[56:57], v[66:67]
	v_pk_mul_f32 v[74:75], v[54:55], v[62:63]
	v_pk_mul_f32 v[62:63], v[50:51], v[62:63]
	v_mov_b32_e32 v61, v52
	v_mov_b32_e32 v71, v53
	v_mov_b32_e32 v65, v56
	v_mov_b32_e32 v73, v57
	v_pk_fma_f32 v[54:55], v[54:55], v[68:69], v[62:63] neg_lo:[0,0,1] neg_hi:[0,0,1]
	v_pk_fma_f32 v[50:51], v[50:51], v[68:69], v[74:75]
	v_pk_add_f32 v[56:57], v[60:61], v[70:71] neg_lo:[0,1] neg_hi:[0,1]
	v_pk_add_f32 v[52:53], v[64:65], v[72:73]
; DI unsigned cvtpk(float lo, float hi) { f32x2_t v = {lo, hi}; bf16x2_t b = __builtin_convertvector(v, bf16x2_t); return __builtin_bit_cast(unsigned, b); }
;     __device__ __forceinline__ void operator()(const f32x4 (&acc)[2][2][4][2], const Unit& u, int wr, int wc, int fr, int fq) const {
;     ...
;                 const int row = row0 + ai * HALF + m * 16; const int pos = pos_of_row(row);
; #pragma unroll
;                 for (int bj = 0; bj < 2; ++bj) {
;                     const int g32 = u.pn * 8 + bj * 4 + wc;
;                     f32x4 a = acc[ai][bj][m][0], b = acc[ai][bj][m][1];
;                     if (g32 % 3 == 2) {
;                         const float2* t = tabM + (size_t)pos * 16 + 4 * fq;
; #pragma unroll
;                         for (int j = 0; j < 4; ++j) { const float2 cs = t[j]; const float x1 = a[j], x2 = b[j]; a[j] = x1 * cs.x - x2 * cs.y; b[j] = x2 * cs.x + x1 * cs.y; }
;                     }
;                     a = a * QSCALE; b = b * QSCALE;
;                     bf16_t* p = Q + (size_t)row * 768 + g32 * 32 + 4 * fq;
;                     u32x2 w0; w0.x = cvtpk(a[0], a[1]); w0.y = cvtpk(a[2], a[3]); *(u32x2*)p = w0;
;                     u32x2 w1; w1.x = cvtpk(b[0], b[1]); w1.y = cvtpk(b[2], b[3]); *(u32x2*)(p + 16) = w1;
.LBB0_675:
	s_nop 0
	v_pk_mul_f32 v[52:53], v[52:53], s[84:85] op_sel_hi:[1,0]
	v_pk_mul_f32 v[50:51], v[50:51], s[84:85] op_sel_hi:[1,0]
	v_lshl_add_u64 v[58:59], s[64:65], 1, v[58:59]
	v_lshl_add_u64 v[58:59], v[58:59], 0, v[122:123]
	v_cvt_pk_bf16_f32 v50, v50, v51
	v_cvt_pk_bf16_f32 v51, v52, v53
	v_add_u32_e32 v52, 0x90, v149
	s_movk_i32 s8, 0x7f70
	global_store_dwordx2 v[58:59], v[50:51], off offset:32 nt
	v_and_b32_e32 v50, 0x1fdf, v52
	v_cmp_gt_i32_e32 vcc, s8, v149
	v_pk_mul_f32 v[56:57], v[56:57], s[84:85] op_sel_hi:[1,0]
	v_pk_mul_f32 v[54:55], v[54:55], s[84:85] op_sel_hi:[1,0]
	v_cndmask_b32_e32 v50, v145, v50, vcc
	v_lshlrev_b32_e32 v50, 4, v50
	v_cvt_pk_bf16_f32 v54, v54, v55
	v_cvt_pk_bf16_f32 v55, v56, v57
	s_and_b64 vcc, exec, s[42:43]
	v_lshlrev_b32_e32 v50, 3, v50
	global_store_dwordx2 v[58:59], v[54:55], off nt
	s_cbranch_vccnz .LBB0_677
	v_mov_b32_e32 v51, v0
	v_lshl_add_u64 v[58:59], v[136:137], 0, v[50:51]
	global_load_dwordx4 v[54:57], v[58:59], off
	s_nop 0
	global_load_dwordx4 v[58:61], v[58:59], off offset:16
	s_waitcnt vmcnt(0)
	v_mov_b32_e32 v62, v54
	v_mul_f32_e32 v54, v48, v58
	v_mul_f32_e32 v64, v44, v59
	v_mul_f32_e32 v58, v44, v58
	v_mul_f32_e32 v66, v48, v59
	v_mov_b32_e32 v44, v49
	v_mov_b32_e32 v48, v45
	v_mov_b32_e32 v63, v56
	v_mov_b32_e32 v56, v55
	v_pk_mul_f32 v[44:45], v[44:45], v[60:61]
	v_pk_mul_f32 v[48:49], v[48:49], v[60:61]
	v_pk_mul_f32 v[68:69], v[46:47], v[56:57]
	v_pk_mul_f32 v[56:57], v[42:43], v[56:57]
	v_mov_b32_e32 v55, v44
	v_mov_b32_e32 v65, v45
	v_mov_b32_e32 v59, v48
	v_mov_b32_e32 v67, v49
	v_pk_fma_f32 v[46:47], v[46:47], v[62:63], v[56:57] neg_lo:[0,0,1] neg_hi:[0,0,1]
	v_pk_fma_f32 v[42:43], v[42:43], v[62:63], v[68:69]
	v_pk_add_f32 v[48:49], v[54:55], v[64:65] neg_lo:[0,1] neg_hi:[0,1]
	v_pk_add_f32 v[44:45], v[58:59], v[66:67]
.LBB0_677:
	v_pk_mul_f32 v[54:55], v[42:43], s[84:85] op_sel_hi:[1,0]
	v_mov_b64_e32 v[42:43], s[52:53]
	s_movk_i32 s8, 0x600
	v_mad_i64_i32 v[42:43], s[8:9], v52, s8, v[42:43]
	v_pk_mul_f32 v[48:49], v[48:49], s[84:85] op_sel_hi:[1,0]
	v_pk_mul_f32 v[46:47], v[46:47], s[84:85] op_sel_hi:[1,0]
	v_lshl_add_u64 v[52:53], s[62:63], 1, v[42:43]
	v_mov_b32_e32 v123, v0
	v_pk_mul_f32 v[44:45], v[44:45], s[84:85] op_sel_hi:[1,0]
	v_lshl_add_u64 v[52:53], v[52:53], 0, v[122:123]
	v_cvt_pk_bf16_f32 v46, v46, v47
	v_cvt_pk_bf16_f32 v47, v48, v49
	global_store_dwordx2 v[52:53], v[46:47], off nt
	v_cvt_pk_bf16_f32 v46, v54, v55
	v_cvt_pk_bf16_f32 v47, v44, v45
	s_and_b64 vcc, exec, s[44:45]
	global_store_dwordx2 v[52:53], v[46:47], off offset:32 nt
	s_cbranch_vccnz .LBB0_679
	v_mov_b32_e32 v51, v0
	v_lshl_add_u64 v[48:49], v[136:137], 0, v[50:51]
	global_load_dwordx4 v[44:47], v[48:49], off
	s_nop 0
	global_load_dwordx4 v[48:51], v[48:49], off offset:16
	s_waitcnt vmcnt(0)
	v_mov_b32_e32 v52, v44
	v_mul_f32_e32 v44, v40, v48
	v_mul_f32_e32 v54, v36, v49
	v_mul_f32_e32 v48, v36, v48
	v_mul_f32_e32 v56, v40, v49
	v_mov_b32_e32 v36, v41
	v_mov_b32_e32 v40, v37
	v_mov_b32_e32 v53, v46
	v_mov_b32_e32 v46, v45
	v_pk_mul_f32 v[36:37], v[36:37], v[50:51]
	v_pk_mul_f32 v[40:41], v[40:41], v[50:51]
	v_pk_mul_f32 v[58:59], v[38:39], v[46:47]
	v_pk_mul_f32 v[46:47], v[34:35], v[46:47]
	v_mov_b32_e32 v45, v36
	v_mov_b32_e32 v55, v37
	v_mov_b32_e32 v49, v40
	v_mov_b32_e32 v57, v41
	v_pk_fma_f32 v[38:39], v[38:39], v[52:53], v[46:47] neg_lo:[0,0,1] neg_hi:[0,0,1]
	v_pk_fma_f32 v[34:35], v[34:35], v[52:53], v[58:59]
	v_pk_add_f32 v[40:41], v[44:45], v[54:55] neg_lo:[0,1] neg_hi:[0,1]
	v_pk_add_f32 v[36:37], v[48:49], v[56:57]
.LBB0_679:
	s_nop 0
	v_pk_mul_f32 v[36:37], v[36:37], s[84:85] op_sel_hi:[1,0]
	v_pk_mul_f32 v[34:35], v[34:35], s[84:85] op_sel_hi:[1,0]
	v_lshl_add_u64 v[42:43], s[64:65], 1, v[42:43]
	v_lshl_add_u64 v[42:43], v[42:43], 0, v[122:123]
	v_cvt_pk_bf16_f32 v34, v34, v35
	v_cvt_pk_bf16_f32 v35, v36, v37
	v_add_u32_e32 v36, 0xa0, v149
	s_movk_i32 s8, 0x7f60
	global_store_dwordx2 v[42:43], v[34:35], off offset:32 nt
	v_and_b32_e32 v34, 0x1fef, v36
	v_cmp_gt_i32_e32 vcc, s8, v149
	v_pk_mul_f32 v[40:41], v[40:41], s[84:85] op_sel_hi:[1,0]
	v_pk_mul_f32 v[38:39], v[38:39], s[84:85] op_sel_hi:[1,0]
	v_cndmask_b32_e32 v34, v146, v34, vcc
	v_lshlrev_b32_e32 v34, 4, v34
	v_cvt_pk_bf16_f32 v38, v38, v39
	v_cvt_pk_bf16_f32 v39, v40, v41
	s_and_b64 vcc, exec, s[42:43]
	v_lshlrev_b32_e32 v34, 3, v34
	global_store_dwordx2 v[42:43], v[38:39], off nt
	s_cbranch_vccnz .LBB0_681
	v_mov_b32_e32 v35, v0
	v_lshl_add_u64 v[42:43], v[136:137], 0, v[34:35]
	global_load_dwordx4 v[38:41], v[42:43], off
	s_nop 0
	global_load_dwordx4 v[42:45], v[42:43], off offset:16
	s_waitcnt vmcnt(0)
	v_mov_b32_e32 v46, v38
	v_mul_f32_e32 v38, v32, v42
	v_mul_f32_e32 v48, v28, v43
	v_mul_f32_e32 v42, v28, v42
	v_mul_f32_e32 v50, v32, v43
	v_mov_b32_e32 v28, v33
	v_mov_b32_e32 v32, v29
	v_mov_b32_e32 v47, v40
	v_mov_b32_e32 v40, v39
	v_pk_mul_f32 v[28:29], v[28:29], v[44:45]
	v_pk_mul_f32 v[32:33], v[32:33], v[44:45]
	v_pk_mul_f32 v[52:53], v[30:31], v[40:41]
	v_pk_mul_f32 v[40:41], v[26:27], v[40:41]
	v_mov_b32_e32 v39, v28
	v_mov_b32_e32 v49, v29
	v_mov_b32_e32 v43, v32
	v_mov_b32_e32 v51, v33
	v_pk_fma_f32 v[30:31], v[30:31], v[46:47], v[40:41] neg_lo:[0,0,1] neg_hi:[0,0,1]
	v_pk_fma_f32 v[26:27], v[26:27], v[46:47], v[52:53]
	v_pk_add_f32 v[32:33], v[38:39], v[48:49] neg_lo:[0,1] neg_hi:[0,1]
	v_pk_add_f32 v[28:29], v[42:43], v[50:51]
; #define PG8_BAR __builtin_amdgcn_s_barrier()
; DI unsigned cvtpk(float lo, float hi) { f32x2_t v = {lo, hi}; bf16x2_t b = __builtin_convertvector(v, bf16x2_t); return __builtin_bit_cast(unsigned, b); }
; template <class Epi, class Sched, bool ALIGN_EPI = false, bool SP2 = false>
; __device__ __forceinline__ void gemm_phase(PG8_LAS unsigned char* lds, const Gemm g, const Sched& S, const Epi& E) {
;     ...
;         if constexpr (ALIGN_EPI) { if (wr == 0) PG8_BAR; }
;         if constexpr (!Epi::AFTER_DRAIN) { E(acc, cur, wr, wc, fr, fq); S.done(cur); }
;         if (!has_next) break;
; #pragma unroll
;         for (int a = 0; a < 2; ++a)
; #pragma unroll
;             for (int b = 0; b < 2; ++b)
; #pragma unroll
;                 for (int m = 0; m < 4; ++m)
; #pragma unroll
;                     for (int n = 0; n < 2; ++n) acc[a][b][m][n] = (f32x4){0.f, 0.f, 0.f, 0.f};
;         cur = nxt; cA = nA; cB = nB; ++ui;
;         if constexpr (ALIGN_EPI) { if (wr == 1) PG8_BAR; }
;     __device__ __forceinline__ void operator()(const f32x4 (&acc)[2][2][4][2], const Unit& u, int wr, int wc, int fr, int fq) const {
;     ...
;                 const int row = row0 + ai * HALF + m * 16; const int pos = pos_of_row(row);
; #pragma unroll
;                 for (int bj = 0; bj < 2; ++bj) {
;                     const int g32 = u.pn * 8 + bj * 4 + wc;
;                     f32x4 a = acc[ai][bj][m][0], b = acc[ai][bj][m][1];
;                     if (g32 % 3 == 2) {
;                         const float2* t = tabM + (size_t)pos * 16 + 4 * fq;
; #pragma unroll
;                         for (int j = 0; j < 4; ++j) { const float2 cs = t[j]; const float x1 = a[j], x2 = b[j]; a[j] = x1 * cs.x - x2 * cs.y; b[j] = x2 * cs.x + x1 * cs.y; }
;                     }
;                     a = a * QSCALE; b = b * QSCALE;
;                     bf16_t* p = Q + (size_t)row * 768 + g32 * 32 + 4 * fq;
;                     u32x2 w0; w0.x = cvtpk(a[0], a[1]); w0.y = cvtpk(a[2], a[3]); *(u32x2*)p = w0;
;                     u32x2 w1; w1.x = cvtpk(b[0], b[1]); w1.y = cvtpk(b[2], b[3]); *(u32x2*)(p + 16) = w1;
.LBB0_681:
	v_pk_mul_f32 v[38:39], v[26:27], s[84:85] op_sel_hi:[1,0]
	v_mov_b64_e32 v[26:27], s[52:53]
	s_movk_i32 s8, 0x600
	v_mad_i64_i32 v[26:27], s[8:9], v36, s8, v[26:27]
	v_pk_mul_f32 v[32:33], v[32:33], s[84:85] op_sel_hi:[1,0]
	v_pk_mul_f32 v[30:31], v[30:31], s[84:85] op_sel_hi:[1,0]
	v_lshl_add_u64 v[36:37], s[62:63], 1, v[26:27]
	v_mov_b32_e32 v123, v0
	v_pk_mul_f32 v[28:29], v[28:29], s[84:85] op_sel_hi:[1,0]
	v_lshl_add_u64 v[36:37], v[36:37], 0, v[122:123]
	v_cvt_pk_bf16_f32 v30, v30, v31
	v_cvt_pk_bf16_f32 v31, v32, v33
	global_store_dwordx2 v[36:37], v[30:31], off nt
	v_cvt_pk_bf16_f32 v30, v38, v39
	v_cvt_pk_bf16_f32 v31, v28, v29
	s_and_b64 vcc, exec, s[44:45]
	global_store_dwordx2 v[36:37], v[30:31], off offset:32 nt
	s_cbranch_vccnz .LBB0_683
	v_mov_b32_e32 v35, v0
	v_lshl_add_u64 v[32:33], v[136:137], 0, v[34:35]
	global_load_dwordx4 v[28:31], v[32:33], off
	s_nop 0
	global_load_dwordx4 v[32:35], v[32:33], off offset:16
	s_waitcnt vmcnt(0)
	v_mov_b32_e32 v36, v28
	v_mul_f32_e32 v28, v24, v32
	v_mul_f32_e32 v38, v20, v33
	v_mul_f32_e32 v32, v20, v32
	v_mul_f32_e32 v40, v24, v33
	v_mov_b32_e32 v20, v25
	v_mov_b32_e32 v24, v21
	v_mov_b32_e32 v37, v30
	v_mov_b32_e32 v30, v29
	v_pk_mul_f32 v[20:21], v[20:21], v[34:35]
	v_pk_mul_f32 v[24:25], v[24:25], v[34:35]
	v_pk_mul_f32 v[42:43], v[22:23], v[30:31]
	v_pk_mul_f32 v[30:31], v[18:19], v[30:31]
	v_mov_b32_e32 v29, v20
	v_mov_b32_e32 v39, v21
	v_mov_b32_e32 v33, v24
	v_mov_b32_e32 v41, v25
	v_pk_fma_f32 v[22:23], v[22:23], v[36:37], v[30:31] neg_lo:[0,0,1] neg_hi:[0,0,1]
	v_pk_fma_f32 v[18:19], v[18:19], v[36:37], v[42:43]
	v_pk_add_f32 v[24:25], v[28:29], v[38:39] neg_lo:[0,1] neg_hi:[0,1]
	v_pk_add_f32 v[20:21], v[32:33], v[40:41]
.LBB0_683:
	s_nop 0
	v_pk_mul_f32 v[20:21], v[20:21], s[84:85] op_sel_hi:[1,0]
	v_pk_mul_f32 v[18:19], v[18:19], s[84:85] op_sel_hi:[1,0]
	v_lshl_add_u64 v[26:27], s[64:65], 1, v[26:27]
	v_lshl_add_u64 v[26:27], v[26:27], 0, v[122:123]
	v_cvt_pk_bf16_f32 v18, v18, v19
	v_cvt_pk_bf16_f32 v19, v20, v21
	v_add_u32_e32 v20, 0xb0, v149
	s_movk_i32 s8, 0x7f50
	global_store_dwordx2 v[26:27], v[18:19], off offset:32 nt
	v_and_b32_e32 v18, 0x1fff, v20
	v_cmp_gt_i32_e32 vcc, s8, v149
	v_pk_mul_f32 v[24:25], v[24:25], s[84:85] op_sel_hi:[1,0]
	v_pk_mul_f32 v[22:23], v[22:23], s[84:85] op_sel_hi:[1,0]
	v_cndmask_b32_e32 v18, v147, v18, vcc
	v_lshlrev_b32_e32 v18, 4, v18
	v_cvt_pk_bf16_f32 v22, v22, v23
	v_cvt_pk_bf16_f32 v23, v24, v25
	s_and_b64 vcc, exec, s[42:43]
	v_lshlrev_b32_e32 v18, 3, v18
	global_store_dwordx2 v[26:27], v[22:23], off nt
	s_cbranch_vccnz .LBB0_685
	v_mov_b32_e32 v19, v0
	v_lshl_add_u64 v[26:27], v[136:137], 0, v[18:19]
	global_load_dwordx4 v[22:25], v[26:27], off
	s_nop 0
	global_load_dwordx4 v[26:29], v[26:27], off offset:16
	s_waitcnt vmcnt(0)
	v_mov_b32_e32 v30, v22
	v_mul_f32_e32 v22, v16, v26
	v_mul_f32_e32 v32, v12, v27
	v_mul_f32_e32 v26, v12, v26
	v_mul_f32_e32 v34, v16, v27
	v_mov_b32_e32 v12, v17
	v_mov_b32_e32 v16, v13
	v_mov_b32_e32 v31, v24
	v_mov_b32_e32 v24, v23
	v_pk_mul_f32 v[12:13], v[12:13], v[28:29]
	v_pk_mul_f32 v[16:17], v[16:17], v[28:29]
	v_pk_mul_f32 v[36:37], v[14:15], v[24:25]
	v_pk_mul_f32 v[24:25], v[10:11], v[24:25]
	v_mov_b32_e32 v23, v12
	v_mov_b32_e32 v33, v13
	v_mov_b32_e32 v27, v16
	v_mov_b32_e32 v35, v17
	v_pk_fma_f32 v[14:15], v[14:15], v[30:31], v[24:25] neg_lo:[0,0,1] neg_hi:[0,0,1]
	v_pk_fma_f32 v[10:11], v[10:11], v[30:31], v[36:37]
	v_pk_add_f32 v[16:17], v[22:23], v[32:33] neg_lo:[0,1] neg_hi:[0,1]
	v_pk_add_f32 v[12:13], v[26:27], v[34:35]
.LBB0_685:
	v_pk_mul_f32 v[22:23], v[10:11], s[84:85] op_sel_hi:[1,0]
	v_mov_b64_e32 v[10:11], s[52:53]
	s_movk_i32 s8, 0x600
	v_mad_i64_i32 v[10:11], s[8:9], v20, s8, v[10:11]
	v_pk_mul_f32 v[16:17], v[16:17], s[84:85] op_sel_hi:[1,0]
	v_pk_mul_f32 v[14:15], v[14:15], s[84:85] op_sel_hi:[1,0]
	v_lshl_add_u64 v[20:21], s[62:63], 1, v[10:11]
	v_mov_b32_e32 v123, v0
	v_pk_mul_f32 v[12:13], v[12:13], s[84:85] op_sel_hi:[1,0]
	v_lshl_add_u64 v[20:21], v[20:21], 0, v[122:123]
	v_cvt_pk_bf16_f32 v14, v14, v15
	v_cvt_pk_bf16_f32 v15, v16, v17
	global_store_dwordx2 v[20:21], v[14:15], off nt
	v_cvt_pk_bf16_f32 v14, v22, v23
	v_cvt_pk_bf16_f32 v15, v12, v13
	s_and_b64 vcc, exec, s[44:45]
	global_store_dwordx2 v[20:21], v[14:15], off offset:32 nt
	s_cbranch_vccnz .LBB0_687
	v_mov_b32_e32 v19, v0
	v_lshl_add_u64 v[16:17], v[136:137], 0, v[18:19]
	global_load_dwordx4 v[12:15], v[16:17], off
	s_nop 0
	global_load_dwordx4 v[16:19], v[16:17], off offset:16
	s_waitcnt vmcnt(0)
	v_mov_b32_e32 v20, v12
	v_mul_f32_e32 v12, v8, v16
	v_mul_f32_e32 v22, v4, v17
	v_mul_f32_e32 v16, v4, v16
	v_mul_f32_e32 v24, v8, v17
	v_mov_b32_e32 v4, v9
	v_mov_b32_e32 v8, v5
	v_mov_b32_e32 v21, v14
	v_mov_b32_e32 v14, v13
	v_pk_mul_f32 v[4:5], v[4:5], v[18:19]
	v_pk_mul_f32 v[8:9], v[8:9], v[18:19]
	v_pk_mul_f32 v[26:27], v[6:7], v[14:15]
	v_pk_mul_f32 v[14:15], v[2:3], v[14:15]
	v_mov_b32_e32 v13, v4
	v_mov_b32_e32 v23, v5
	v_mov_b32_e32 v17, v8
	v_mov_b32_e32 v25, v9
	v_pk_fma_f32 v[6:7], v[6:7], v[20:21], v[14:15] neg_lo:[0,0,1] neg_hi:[0,0,1]
	v_pk_fma_f32 v[2:3], v[2:3], v[20:21], v[26:27]
	v_pk_add_f32 v[8:9], v[12:13], v[22:23] neg_lo:[0,1] neg_hi:[0,1]
	v_pk_add_f32 v[4:5], v[16:17], v[24:25]
.LBB0_687:
	v_pk_mul_f32 v[8:9], v[8:9], s[84:85] op_sel_hi:[1,0]
	v_pk_mul_f32 v[6:7], v[6:7], s[84:85] op_sel_hi:[1,0]
	v_pk_mul_f32 v[4:5], v[4:5], s[84:85] op_sel_hi:[1,0]
	v_pk_mul_f32 v[2:3], v[2:3], s[84:85] op_sel_hi:[1,0]
	v_lshl_add_u64 v[10:11], s[64:65], 1, v[10:11]
	v_lshl_add_u64 v[10:11], v[10:11], 0, v[122:123]
	v_cvt_pk_bf16_f32 v6, v6, v7
	v_cvt_pk_bf16_f32 v7, v8, v9
	v_cvt_pk_bf16_f32 v2, v2, v3
	v_cvt_pk_bf16_f32 v3, v4, v5
	s_and_b64 vcc, exec, s[40:41]
	s_mov_b64 s[40:41], -1
	global_store_dwordx2 v[10:11], v[6:7], off nt
	global_store_dwordx2 v[10:11], v[2:3], off offset:32 nt
	s_cbranch_vccnz .LBB0_639
	s_andn2_b64 vcc, exec, s[50:51]
	s_cbranch_vccnz .LBB0_638
	s_barrier
	s_branch .LBB0_638

; DI unsigned cvtpk(float lo, float hi) { f32x2_t v = {lo, hi}; bf16x2_t b = __builtin_convertvector(v, bf16x2_t); return __builtin_bit_cast(unsigned, b); }
;     __device__ __forceinline__ void operator()(const f32x4 (&acc)[2][2][4][2], const Unit& u, int wr, int wc, int fr, int fq) const {
;     ...
;                 const int row = row0 + ai * HALF + m * 16;
; #pragma unroll
;                 for (int bj = 0; bj < 2; ++bj) {
;                     const int head = 2 * u.pn + bj;
;                     const f32x4 v0 = acc[ai][bj][m][0], v1 = acc[ai][bj][m][1];
;                     const unsigned w0 = cvtpk(v0[0], v0[1]), w1 = cvtpk(v0[2], v0[3]), w2 = cvtpk(v1[0], v1[1]), w3 = cvtpk(v1[2], v1[3]);
;                     if (wc < 2) {
;                         u32x4 w; w.x = w0; w.y = w1; w.z = w2; w.w = w3;
;                         *(u32x4*)(KN + (size_t)row * 512 + 64 * head + 32 * wc + 8 * fq) = w;
;                     } else {
;                         bf16_t* p = VT + ((size_t)(row >> 6) * 8 + head) * 4096 + (32 * (wc - 2) + 8 * fq) * 64 + (row & 63);
;                         p[0 * 64] = (bf16_t)(w0 & 0xffffu); p[1 * 64] = (bf16_t)(w0 >> 16); p[2 * 64] = (bf16_t)(w1 & 0xffffu); p[3 * 64] = (bf16_t)(w1 >> 16);
;                         p[4 * 64] = (bf16_t)(w2 & 0xffffu); p[5 * 64] = (bf16_t)(w2 >> 16); p[6 * 64] = (bf16_t)(w3 & 0xffffu); p[7 * 64] = (bf16_t)(w3 >> 16);
;                     }
.LBB0_718:
	s_lshl_b32 s11, s11, 8
	s_add_i32 s11, s11, s81
	s_ashr_i32 s42, s11, 6
	s_ashr_i32 s43, s42, 31
	s_lshl_b32 s66, s72, 1
	s_lshl_b64 s[68:69], s[42:43], 16
	v_cvt_pk_bf16_f32 v122, v122, v123
	v_cvt_pk_bf16_f32 v123, v124, v125
	v_cvt_pk_bf16_f32 v124, v126, v127
	v_cvt_pk_bf16_f32 v125, v128, v129
	s_mov_b64 s[42:43], -1
	s_and_b64 vcc, exec, s[58:59]
	v_lshlrev_b32_e32 v126, 1, v138
	s_cbranch_vccz .LBB0_720
	s_ashr_i32 s67, s66, 31
	s_add_u32 s64, s52, s68
	s_addc_u32 s65, s53, s69
	s_lshl_b64 s[42:43], s[66:67], 13
	s_add_u32 s42, s64, s42
	s_addc_u32 s43, s65, s43
	v_lshl_add_u64 v[128:129], v[142:143], 1, s[42:43]
	v_mov_b32_e32 v127, v0
	v_lshl_add_u64 v[128:129], v[128:129], 0, v[126:127]
	global_store_short v[128:129], v122, off nt
	global_store_short_d16_hi v[128:129], v122, off offset:128 nt
	global_store_short v[128:129], v123, off offset:256 nt
	global_store_short_d16_hi v[128:129], v123, off offset:384 nt
	global_store_short v[128:129], v124, off offset:512 nt
	global_store_short_d16_hi v[128:129], v124, off offset:640 nt
	global_store_short v[128:129], v125, off offset:768 nt
	global_store_short_d16_hi v[128:129], v125, off offset:896 nt
	s_mov_b64 s[42:43], 0
.LBB0_720:
	v_or_b32_e32 v148, s11, v138
	v_ashrrev_i32_e32 v149, 31, v148
	v_lshlrev_b64 v[128:129], 10, v[148:149]
	s_andn2_b64 vcc, exec, s[42:43]
	v_lshl_add_u64 v[150:151], s[50:51], 0, v[128:129]
	v_lshlrev_b32_e32 v128, 1, v140
	s_cbranch_vccnz .LBB0_722
	s_lshl_b32 s42, s72, 7
	s_ashr_i32 s43, s42, 31
	v_lshl_add_u64 v[152:153], s[42:43], 1, v[150:151]
	s_lshl_b32 s92, s82, 1
	v_lshl_add_u64 v[152:153], v[152:153], 0, s[92:93]
	v_mov_b32_e32 v129, v0
	v_lshl_add_u64 v[152:153], v[152:153], 0, v[128:129]
	global_store_dwordx4 v[152:153], v[122:125], off nt
.LBB0_722:
	v_cvt_pk_bf16_f32 v118, v118, v119
	v_cvt_pk_bf16_f32 v119, v120, v121
	v_cvt_pk_bf16_f32 v120, v114, v115
	v_cndmask_b32_e64 v114, 0, 1, s[58:59]
	s_or_b32 s64, s66, 1
	v_cvt_pk_bf16_f32 v121, v116, v117
	v_cmp_ne_u32_e64 s[42:43], 1, v114
	s_andn2_b64 vcc, exec, s[58:59]
	s_mov_b64 s[70:71], -1
	s_cbranch_vccnz .LBB0_724
	s_ashr_i32 s65, s64, 31
	s_add_u32 s11, s52, s68
	s_addc_u32 s67, s53, s69
	s_lshl_b64 s[70:71], s[64:65], 13
	s_add_u32 s70, s11, s70
	s_addc_u32 s71, s67, s71
	v_lshl_add_u64 v[114:115], v[142:143], 1, s[70:71]
	v_mov_b32_e32 v127, v0
	v_lshl_add_u64 v[114:115], v[114:115], 0, v[126:127]
	s_mov_b64 s[70:71], 0
	global_store_short v[114:115], v118, off nt
	global_store_short_d16_hi v[114:115], v118, off offset:128 nt
	global_store_short v[114:115], v119, off offset:256 nt
	global_store_short_d16_hi v[114:115], v119, off offset:384 nt
	global_store_short v[114:115], v120, off offset:512 nt
	global_store_short_d16_hi v[114:115], v120, off offset:640 nt
	global_store_short v[114:115], v121, off offset:768 nt
	global_store_short_d16_hi v[114:115], v121, off offset:896 nt
.LBB0_724:
	s_andn2_b64 vcc, exec, s[70:71]
	s_cbranch_vccnz .LBB0_726
	s_lshl_b32 s70, s64, 6
	s_ashr_i32 s71, s70, 31
	v_lshl_add_u64 v[114:115], s[70:71], 1, v[150:151]
	s_lshl_b32 s92, s82, 1
	v_lshl_add_u64 v[114:115], v[114:115], 0, s[92:93]
	v_mov_b32_e32 v129, v0
	v_lshl_add_u64 v[114:115], v[114:115], 0, v[128:129]
	global_store_dwordx4 v[114:115], v[118:121], off nt
.LBB0_726:
	v_cvt_pk_bf16_f32 v110, v110, v111
	v_cvt_pk_bf16_f32 v111, v112, v113
	v_cvt_pk_bf16_f32 v112, v106, v107
	v_cvt_pk_bf16_f32 v113, v108, v109
	s_and_b64 vcc, exec, s[42:43]
	s_mov_b64 s[70:71], -1
	s_cbranch_vccnz .LBB0_728
	s_ashr_i32 s67, s66, 31
	s_add_u32 s11, s52, s68
	s_addc_u32 s65, s53, s69
	s_lshl_b64 s[70:71], s[66:67], 13
	s_add_u32 s70, s11, s70
	s_addc_u32 s71, s65, s71
	v_lshl_add_u64 v[106:107], v[142:143], 1, s[70:71]
	v_mov_b32_e32 v127, v0
	v_lshl_add_u64 v[106:107], v[106:107], 0, v[126:127]
	s_mov_b64 s[70:71], 0
	global_store_short v[106:107], v110, off offset:32 nt
	global_store_short_d16_hi v[106:107], v110, off offset:160 nt
	global_store_short v[106:107], v111, off offset:288 nt
	global_store_short_d16_hi v[106:107], v111, off offset:416 nt
	global_store_short v[106:107], v112, off offset:544 nt
	global_store_short_d16_hi v[106:107], v112, off offset:672 nt
	global_store_short v[106:107], v113, off offset:800 nt
	global_store_short_d16_hi v[106:107], v113, off offset:928 nt
.LBB0_728:
	v_or_b32_e32 v106, 16, v148
	v_ashrrev_i32_e32 v107, 31, v106
	v_lshlrev_b64 v[106:107], 10, v[106:107]
	s_andn2_b64 vcc, exec, s[70:71]
	v_lshl_add_u64 v[106:107], s[50:51], 0, v[106:107]
	s_cbranch_vccnz .LBB0_730
	s_lshl_b32 s70, s72, 7
	s_ashr_i32 s71, s70, 31
	v_lshl_add_u64 v[108:109], s[70:71], 1, v[106:107]
	s_lshl_b32 s92, s82, 1
	v_lshl_add_u64 v[108:109], v[108:109], 0, s[92:93]
	v_mov_b32_e32 v129, v0
	v_lshl_add_u64 v[108:109], v[108:109], 0, v[128:129]
	global_store_dwordx4 v[108:109], v[110:113], off nt
.LBB0_730:
	v_cvt_pk_bf16_f32 v102, v102, v103
	v_cvt_pk_bf16_f32 v103, v104, v105
	v_cvt_pk_bf16_f32 v104, v98, v99
	v_cvt_pk_bf16_f32 v105, v100, v101
	s_and_b64 vcc, exec, s[42:43]
	s_mov_b64 s[70:71], -1
	s_cbranch_vccnz .LBB0_732
	s_ashr_i32 s65, s64, 31
	s_add_u32 s11, s52, s68
	s_addc_u32 s67, s53, s69
	s_lshl_b64 s[70:71], s[64:65], 13
	s_add_u32 s70, s11, s70
	s_addc_u32 s71, s67, s71
	v_lshl_add_u64 v[98:99], v[142:143], 1, s[70:71]
	v_mov_b32_e32 v127, v0
	v_lshl_add_u64 v[98:99], v[98:99], 0, v[126:127]
	s_mov_b64 s[70:71], 0
	global_store_short v[98:99], v102, off offset:32 nt
	global_store_short_d16_hi v[98:99], v102, off offset:160 nt
	global_store_short v[98:99], v103, off offset:288 nt
	global_store_short_d16_hi v[98:99], v103, off offset:416 nt
	global_store_short v[98:99], v104, off offset:544 nt
	global_store_short_d16_hi v[98:99], v104, off offset:672 nt
	global_store_short v[98:99], v105, off offset:800 nt
	global_store_short_d16_hi v[98:99], v105, off offset:928 nt
; DI unsigned cvtpk(float lo, float hi) { f32x2_t v = {lo, hi}; bf16x2_t b = __builtin_convertvector(v, bf16x2_t); return __builtin_bit_cast(unsigned, b); }
;     __device__ __forceinline__ void operator()(const f32x4 (&acc)[2][2][4][2], const Unit& u, int wr, int wc, int fr, int fq) const {
;     ...
;                 const int row = row0 + ai * HALF + m * 16;
; #pragma unroll
;                 for (int bj = 0; bj < 2; ++bj) {
;                     const int head = 2 * u.pn + bj;
;                     const f32x4 v0 = acc[ai][bj][m][0], v1 = acc[ai][bj][m][1];
;                     const unsigned w0 = cvtpk(v0[0], v0[1]), w1 = cvtpk(v0[2], v0[3]), w2 = cvtpk(v1[0], v1[1]), w3 = cvtpk(v1[2], v1[3]);
;                     if (wc < 2) {
;                         u32x4 w; w.x = w0; w.y = w1; w.z = w2; w.w = w3;
;                         *(u32x4*)(KN + (size_t)row * 512 + 64 * head + 32 * wc + 8 * fq) = w;
;                     } else {
;                         bf16_t* p = VT + ((size_t)(row >> 6) * 8 + head) * 4096 + (32 * (wc - 2) + 8 * fq) * 64 + (row & 63);
;                         p[0 * 64] = (bf16_t)(w0 & 0xffffu); p[1 * 64] = (bf16_t)(w0 >> 16); p[2 * 64] = (bf16_t)(w1 & 0xffffu); p[3 * 64] = (bf16_t)(w1 >> 16);
;                         p[4 * 64] = (bf16_t)(w2 & 0xffffu); p[5 * 64] = (bf16_t)(w2 >> 16); p[6 * 64] = (bf16_t)(w3 & 0xffffu); p[7 * 64] = (bf16_t)(w3 >> 16);
;                     }
.LBB0_732:
	s_andn2_b64 vcc, exec, s[70:71]
	s_cbranch_vccnz .LBB0_734
	s_lshl_b32 s70, s64, 6
	s_ashr_i32 s71, s70, 31
	v_lshl_add_u64 v[98:99], s[70:71], 1, v[106:107]
	s_lshl_b32 s92, s82, 1
	v_lshl_add_u64 v[98:99], v[98:99], 0, s[92:93]
	v_mov_b32_e32 v129, v0
	v_lshl_add_u64 v[98:99], v[98:99], 0, v[128:129]
	global_store_dwordx4 v[98:99], v[102:105], off nt
.LBB0_734:
	v_cvt_pk_bf16_f32 v94, v94, v95
	v_cvt_pk_bf16_f32 v95, v96, v97
	v_cvt_pk_bf16_f32 v96, v90, v91
	v_cvt_pk_bf16_f32 v97, v92, v93
	s_and_b64 vcc, exec, s[42:43]
	s_mov_b64 s[70:71], -1
	s_cbranch_vccnz .LBB0_736
	s_ashr_i32 s67, s66, 31
	s_add_u32 s11, s52, s68
	s_addc_u32 s65, s53, s69
	s_lshl_b64 s[70:71], s[66:67], 13
	s_add_u32 s70, s11, s70
	s_addc_u32 s71, s65, s71
	v_lshl_add_u64 v[90:91], v[142:143], 1, s[70:71]
	v_mov_b32_e32 v127, v0
	v_lshl_add_u64 v[90:91], v[90:91], 0, v[126:127]
	s_mov_b64 s[70:71], 0
	global_store_short v[90:91], v94, off offset:64 nt
	global_store_short_d16_hi v[90:91], v94, off offset:192 nt
	global_store_short v[90:91], v95, off offset:320 nt
	global_store_short_d16_hi v[90:91], v95, off offset:448 nt
	global_store_short v[90:91], v96, off offset:576 nt
	global_store_short_d16_hi v[90:91], v96, off offset:704 nt
	global_store_short v[90:91], v97, off offset:832 nt
	global_store_short_d16_hi v[90:91], v97, off offset:960 nt
.LBB0_736:
	v_or_b32_e32 v90, 32, v148
	v_ashrrev_i32_e32 v91, 31, v90
	v_lshlrev_b64 v[90:91], 10, v[90:91]
	s_andn2_b64 vcc, exec, s[70:71]
	v_lshl_add_u64 v[90:91], s[50:51], 0, v[90:91]
	s_cbranch_vccnz .LBB0_738
	s_lshl_b32 s70, s72, 7
	s_ashr_i32 s71, s70, 31
	v_lshl_add_u64 v[92:93], s[70:71], 1, v[90:91]
	s_lshl_b32 s92, s82, 1
	v_lshl_add_u64 v[92:93], v[92:93], 0, s[92:93]
	v_mov_b32_e32 v129, v0
	v_lshl_add_u64 v[92:93], v[92:93], 0, v[128:129]
	global_store_dwordx4 v[92:93], v[94:97], off nt
.LBB0_738:
	v_cvt_pk_bf16_f32 v86, v86, v87
	v_cvt_pk_bf16_f32 v87, v88, v89
	v_cvt_pk_bf16_f32 v88, v82, v83
	v_cvt_pk_bf16_f32 v89, v84, v85
	s_and_b64 vcc, exec, s[42:43]
	s_mov_b64 s[70:71], -1
	s_cbranch_vccnz .LBB0_740
	s_ashr_i32 s65, s64, 31
	s_add_u32 s11, s52, s68
	s_addc_u32 s67, s53, s69
	s_lshl_b64 s[70:71], s[64:65], 13
	s_add_u32 s70, s11, s70
	s_addc_u32 s71, s67, s71
	v_lshl_add_u64 v[82:83], v[142:143], 1, s[70:71]
	v_mov_b32_e32 v127, v0
	v_lshl_add_u64 v[82:83], v[82:83], 0, v[126:127]
	s_mov_b64 s[70:71], 0
	global_store_short v[82:83], v86, off offset:64 nt
	global_store_short_d16_hi v[82:83], v86, off offset:192 nt
	global_store_short v[82:83], v87, off offset:320 nt
	global_store_short_d16_hi v[82:83], v87, off offset:448 nt
	global_store_short v[82:83], v88, off offset:576 nt
	global_store_short_d16_hi v[82:83], v88, off offset:704 nt
	global_store_short v[82:83], v89, off offset:832 nt
	global_store_short_d16_hi v[82:83], v89, off offset:960 nt
.LBB0_740:
	s_andn2_b64 vcc, exec, s[70:71]
	s_cbranch_vccnz .LBB0_742
	s_lshl_b32 s70, s64, 6
	s_ashr_i32 s71, s70, 31
	v_lshl_add_u64 v[82:83], s[70:71], 1, v[90:91]
	s_lshl_b32 s92, s82, 1
	v_lshl_add_u64 v[82:83], v[82:83], 0, s[92:93]
	v_mov_b32_e32 v129, v0
	v_lshl_add_u64 v[82:83], v[82:83], 0, v[128:129]
	global_store_dwordx4 v[82:83], v[86:89], off nt
.LBB0_742:
	v_cvt_pk_bf16_f32 v78, v78, v79
	v_cvt_pk_bf16_f32 v79, v80, v81
	v_cvt_pk_bf16_f32 v80, v74, v75
	v_cvt_pk_bf16_f32 v81, v76, v77
	s_and_b64 vcc, exec, s[42:43]
	s_mov_b64 s[70:71], -1
	s_cbranch_vccnz .LBB0_744
	s_ashr_i32 s67, s66, 31
	s_add_u32 s11, s52, s68
	s_addc_u32 s65, s53, s69
	s_lshl_b64 s[70:71], s[66:67], 13
	s_add_u32 s70, s11, s70
	s_addc_u32 s71, s65, s71
	v_lshl_add_u64 v[74:75], v[142:143], 1, s[70:71]
	v_mov_b32_e32 v127, v0
	v_lshl_add_u64 v[74:75], v[74:75], 0, v[126:127]
	s_mov_b64 s[70:71], 0
	global_store_short v[74:75], v78, off offset:96 nt
	global_store_short_d16_hi v[74:75], v78, off offset:224 nt
	global_store_short v[74:75], v79, off offset:352 nt
	global_store_short_d16_hi v[74:75], v79, off offset:480 nt
	global_store_short v[74:75], v80, off offset:608 nt
	global_store_short_d16_hi v[74:75], v80, off offset:736 nt
	global_store_short v[74:75], v81, off offset:864 nt
	global_store_short_d16_hi v[74:75], v81, off offset:992 nt
.LBB0_744:
	v_or_b32_e32 v74, 48, v148
	v_ashrrev_i32_e32 v75, 31, v74
	v_lshlrev_b64 v[74:75], 10, v[74:75]
	s_andn2_b64 vcc, exec, s[70:71]
	v_lshl_add_u64 v[74:75], s[50:51], 0, v[74:75]
	s_cbranch_vccnz .LBB0_746
	s_lshl_b32 s70, s72, 7
	s_ashr_i32 s71, s70, 31
	v_lshl_add_u64 v[76:77], s[70:71], 1, v[74:75]
	s_lshl_b32 s92, s82, 1
	v_lshl_add_u64 v[76:77], v[76:77], 0, s[92:93]
	v_mov_b32_e32 v129, v0
	v_lshl_add_u64 v[76:77], v[76:77], 0, v[128:129]
	global_store_dwordx4 v[76:77], v[78:81], off nt
.LBB0_746:
	v_cvt_pk_bf16_f32 v70, v70, v71
	v_cvt_pk_bf16_f32 v71, v72, v73
	v_cvt_pk_bf16_f32 v72, v66, v67
	v_cvt_pk_bf16_f32 v73, v68, v69
	s_and_b64 vcc, exec, s[42:43]
	s_mov_b64 s[70:71], -1
	s_cbranch_vccnz .LBB0_748
	s_ashr_i32 s65, s64, 31
	s_add_u32 s11, s52, s68
	s_addc_u32 s67, s53, s69
	s_lshl_b64 s[68:69], s[64:65], 13
	s_add_u32 s68, s11, s68
	s_addc_u32 s69, s67, s69
	v_lshl_add_u64 v[66:67], v[142:143], 1, s[68:69]
	v_mov_b32_e32 v127, v0
	v_lshl_add_u64 v[66:67], v[66:67], 0, v[126:127]
	s_mov_b64 s[70:71], 0
	global_store_short v[66:67], v70, off offset:96 nt
	global_store_short_d16_hi v[66:67], v70, off offset:224 nt
	global_store_short v[66:67], v71, off offset:352 nt
	global_store_short_d16_hi v[66:67], v71, off offset:480 nt
	global_store_short v[66:67], v72, off offset:608 nt
	global_store_short_d16_hi v[66:67], v72, off offset:736 nt
	global_store_short v[66:67], v73, off offset:864 nt
	global_store_short_d16_hi v[66:67], v73, off offset:992 nt
; DI unsigned cvtpk(float lo, float hi) { f32x2_t v = {lo, hi}; bf16x2_t b = __builtin_convertvector(v, bf16x2_t); return __builtin_bit_cast(unsigned, b); }
;     __device__ __forceinline__ void operator()(const f32x4 (&acc)[2][2][4][2], const Unit& u, int wr, int wc, int fr, int fq) const {
;     ...
;                 const int row = row0 + ai * HALF + m * 16;
; #pragma unroll
;                 for (int bj = 0; bj < 2; ++bj) {
;                     const int head = 2 * u.pn + bj;
;                     const f32x4 v0 = acc[ai][bj][m][0], v1 = acc[ai][bj][m][1];
;                     const unsigned w0 = cvtpk(v0[0], v0[1]), w1 = cvtpk(v0[2], v0[3]), w2 = cvtpk(v1[0], v1[1]), w3 = cvtpk(v1[2], v1[3]);
;                     if (wc < 2) {
;                         u32x4 w; w.x = w0; w.y = w1; w.z = w2; w.w = w3;
;                         *(u32x4*)(KN + (size_t)row * 512 + 64 * head + 32 * wc + 8 * fq) = w;
;                     } else {
;                         bf16_t* p = VT + ((size_t)(row >> 6) * 8 + head) * 4096 + (32 * (wc - 2) + 8 * fq) * 64 + (row & 63);
;                         p[0 * 64] = (bf16_t)(w0 & 0xffffu); p[1 * 64] = (bf16_t)(w0 >> 16); p[2 * 64] = (bf16_t)(w1 & 0xffffu); p[3 * 64] = (bf16_t)(w1 >> 16);
;                         p[4 * 64] = (bf16_t)(w2 & 0xffffu); p[5 * 64] = (bf16_t)(w2 >> 16); p[6 * 64] = (bf16_t)(w3 & 0xffffu); p[7 * 64] = (bf16_t)(w3 >> 16);
;                     }
.LBB0_748:
	s_andn2_b64 vcc, exec, s[70:71]
	s_cbranch_vccnz .LBB0_750
	s_lshl_b32 s68, s64, 6
	s_ashr_i32 s69, s68, 31
	v_lshl_add_u64 v[66:67], s[68:69], 1, v[74:75]
	s_lshl_b32 s92, s82, 1
	v_lshl_add_u64 v[66:67], v[66:67], 0, s[92:93]
	v_mov_b32_e32 v129, v0
	v_lshl_add_u64 v[66:67], v[66:67], 0, v[128:129]
	global_store_dwordx4 v[66:67], v[70:73], off nt
.LBB0_750:
	v_add_u32_e32 v66, 0x80, v148
	v_ashrrev_i32_e32 v68, 6, v66
	v_ashrrev_i32_e32 v69, 31, v68
	v_lshlrev_b64 v[68:69], 16, v[68:69]
	v_cvt_pk_bf16_f32 v62, v62, v63
	v_cvt_pk_bf16_f32 v63, v64, v65
	v_cvt_pk_bf16_f32 v64, v58, v59
	v_cvt_pk_bf16_f32 v65, v60, v61
	s_mov_b64 s[68:69], -1
	s_and_b64 vcc, exec, s[42:43]
	v_lshl_add_u64 v[58:59], s[52:53], 0, v[68:69]
	s_cbranch_vccnz .LBB0_752
	s_ashr_i32 s67, s66, 31
	s_lshl_b64 s[68:69], s[66:67], 13
	v_lshl_add_u64 v[60:61], v[58:59], 0, s[68:69]
	v_lshl_add_u64 v[60:61], v[142:143], 1, v[60:61]
	v_mov_b32_e32 v127, v0
	v_lshl_add_u64 v[60:61], v[60:61], 0, v[126:127]
	s_mov_b64 s[68:69], 0
	global_store_short v[60:61], v62, off nt
	global_store_short_d16_hi v[60:61], v62, off offset:128 nt
	global_store_short v[60:61], v63, off offset:256 nt
	global_store_short_d16_hi v[60:61], v63, off offset:384 nt
	global_store_short v[60:61], v64, off offset:512 nt
	global_store_short_d16_hi v[60:61], v64, off offset:640 nt
	global_store_short v[60:61], v65, off offset:768 nt
	global_store_short_d16_hi v[60:61], v65, off offset:896 nt
.LBB0_752:
	v_ashrrev_i32_e32 v67, 31, v66
	v_lshlrev_b64 v[60:61], 10, v[66:67]
	s_andn2_b64 vcc, exec, s[68:69]
	v_lshl_add_u64 v[60:61], s[50:51], 0, v[60:61]
	s_cbranch_vccnz .LBB0_754
	s_lshl_b32 s68, s72, 7
	s_ashr_i32 s69, s68, 31
	v_lshl_add_u64 v[66:67], s[68:69], 1, v[60:61]
	s_lshl_b32 s92, s82, 1
	v_lshl_add_u64 v[66:67], v[66:67], 0, s[92:93]
	v_mov_b32_e32 v129, v0
	v_lshl_add_u64 v[66:67], v[66:67], 0, v[128:129]
	global_store_dwordx4 v[66:67], v[62:65], off nt
.LBB0_754:
	v_cvt_pk_bf16_f32 v54, v54, v55
	v_cvt_pk_bf16_f32 v55, v56, v57
	v_cvt_pk_bf16_f32 v56, v50, v51
	v_cvt_pk_bf16_f32 v57, v52, v53
	s_and_b64 vcc, exec, s[42:43]
	s_mov_b64 s[68:69], -1
	s_cbranch_vccnz .LBB0_756
	s_ashr_i32 s65, s64, 31
	s_lshl_b64 s[68:69], s[64:65], 13
	v_lshl_add_u64 v[50:51], v[58:59], 0, s[68:69]
	v_lshl_add_u64 v[50:51], v[142:143], 1, v[50:51]
	v_mov_b32_e32 v127, v0
	v_lshl_add_u64 v[50:51], v[50:51], 0, v[126:127]
	s_mov_b64 s[68:69], 0
	global_store_short v[50:51], v54, off nt
	global_store_short_d16_hi v[50:51], v54, off offset:128 nt
	global_store_short v[50:51], v55, off offset:256 nt
	global_store_short_d16_hi v[50:51], v55, off offset:384 nt
	global_store_short v[50:51], v56, off offset:512 nt
	global_store_short_d16_hi v[50:51], v56, off offset:640 nt
	global_store_short v[50:51], v57, off offset:768 nt
	global_store_short_d16_hi v[50:51], v57, off offset:896 nt
.LBB0_756:
	s_andn2_b64 vcc, exec, s[68:69]
	s_cbranch_vccnz .LBB0_758
	s_lshl_b32 s68, s64, 6
	s_ashr_i32 s69, s68, 31
	v_lshl_add_u64 v[50:51], s[68:69], 1, v[60:61]
	s_lshl_b32 s92, s82, 1
	v_lshl_add_u64 v[50:51], v[50:51], 0, s[92:93]
	v_mov_b32_e32 v129, v0
	v_lshl_add_u64 v[50:51], v[50:51], 0, v[128:129]
	global_store_dwordx4 v[50:51], v[54:57], off nt
.LBB0_758:
	v_cvt_pk_bf16_f32 v46, v46, v47
	v_cvt_pk_bf16_f32 v47, v48, v49
	v_cvt_pk_bf16_f32 v48, v42, v43
	v_cvt_pk_bf16_f32 v49, v44, v45
	s_and_b64 vcc, exec, s[42:43]
	s_mov_b64 s[68:69], -1
	s_cbranch_vccnz .LBB0_760
	s_ashr_i32 s67, s66, 31
	s_lshl_b64 s[68:69], s[66:67], 13
	v_lshl_add_u64 v[42:43], v[58:59], 0, s[68:69]
	v_lshl_add_u64 v[42:43], v[142:143], 1, v[42:43]
	v_mov_b32_e32 v127, v0
	v_lshl_add_u64 v[42:43], v[42:43], 0, v[126:127]
	s_mov_b64 s[68:69], 0
	global_store_short v[42:43], v46, off offset:32 nt
	global_store_short_d16_hi v[42:43], v46, off offset:160 nt
	global_store_short v[42:43], v47, off offset:288 nt
	global_store_short_d16_hi v[42:43], v47, off offset:416 nt
	global_store_short v[42:43], v48, off offset:544 nt
	global_store_short_d16_hi v[42:43], v48, off offset:672 nt
	global_store_short v[42:43], v49, off offset:800 nt
	global_store_short_d16_hi v[42:43], v49, off offset:928 nt
.LBB0_760:
	v_lshlrev_b64 v[42:43], 10, v[148:149]
	s_mov_b64 s[70:71], 0x24000
	v_lshl_add_u64 v[42:43], v[42:43], 0, s[70:71]
	s_andn2_b64 vcc, exec, s[68:69]
	v_lshl_add_u64 v[42:43], s[50:51], 0, v[42:43]
	s_cbranch_vccnz .LBB0_762
	s_lshl_b32 s68, s72, 7
	s_ashr_i32 s69, s68, 31
	v_lshl_add_u64 v[44:45], s[68:69], 1, v[42:43]
	s_lshl_b32 s92, s82, 1
	v_lshl_add_u64 v[44:45], v[44:45], 0, s[92:93]
	v_mov_b32_e32 v129, v0
	v_lshl_add_u64 v[44:45], v[44:45], 0, v[128:129]
	global_store_dwordx4 v[44:45], v[46:49], off nt
.LBB0_762:
	v_cvt_pk_bf16_f32 v38, v38, v39
	v_cvt_pk_bf16_f32 v39, v40, v41
	v_cvt_pk_bf16_f32 v40, v34, v35
	v_cvt_pk_bf16_f32 v41, v36, v37
	s_and_b64 vcc, exec, s[42:43]
	s_mov_b64 s[68:69], -1
	s_cbranch_vccnz .LBB0_764
	s_ashr_i32 s65, s64, 31
	s_lshl_b64 s[68:69], s[64:65], 13
	v_lshl_add_u64 v[34:35], v[58:59], 0, s[68:69]
	v_lshl_add_u64 v[34:35], v[142:143], 1, v[34:35]
	v_mov_b32_e32 v127, v0
	v_lshl_add_u64 v[34:35], v[34:35], 0, v[126:127]
	s_mov_b64 s[68:69], 0
	global_store_short v[34:35], v38, off offset:32 nt
	global_store_short_d16_hi v[34:35], v38, off offset:160 nt
	global_store_short v[34:35], v39, off offset:288 nt
	global_store_short_d16_hi v[34:35], v39, off offset:416 nt
	global_store_short v[34:35], v40, off offset:544 nt
	global_store_short_d16_hi v[34:35], v40, off offset:672 nt
	global_store_short v[34:35], v41, off offset:800 nt
	global_store_short_d16_hi v[34:35], v41, off offset:928 nt
; DI unsigned cvtpk(float lo, float hi) { f32x2_t v = {lo, hi}; bf16x2_t b = __builtin_convertvector(v, bf16x2_t); return __builtin_bit_cast(unsigned, b); }
;     __device__ __forceinline__ void operator()(const f32x4 (&acc)[2][2][4][2], const Unit& u, int wr, int wc, int fr, int fq) const {
;     ...
;                 const int row = row0 + ai * HALF + m * 16;
; #pragma unroll
;                 for (int bj = 0; bj < 2; ++bj) {
;                     const int head = 2 * u.pn + bj;
;                     const f32x4 v0 = acc[ai][bj][m][0], v1 = acc[ai][bj][m][1];
;                     const unsigned w0 = cvtpk(v0[0], v0[1]), w1 = cvtpk(v0[2], v0[3]), w2 = cvtpk(v1[0], v1[1]), w3 = cvtpk(v1[2], v1[3]);
;                     if (wc < 2) {
;                         u32x4 w; w.x = w0; w.y = w1; w.z = w2; w.w = w3;
;                         *(u32x4*)(KN + (size_t)row * 512 + 64 * head + 32 * wc + 8 * fq) = w;
;                     } else {
;                         bf16_t* p = VT + ((size_t)(row >> 6) * 8 + head) * 4096 + (32 * (wc - 2) + 8 * fq) * 64 + (row & 63);
;                         p[0 * 64] = (bf16_t)(w0 & 0xffffu); p[1 * 64] = (bf16_t)(w0 >> 16); p[2 * 64] = (bf16_t)(w1 & 0xffffu); p[3 * 64] = (bf16_t)(w1 >> 16);
;                         p[4 * 64] = (bf16_t)(w2 & 0xffffu); p[5 * 64] = (bf16_t)(w2 >> 16); p[6 * 64] = (bf16_t)(w3 & 0xffffu); p[7 * 64] = (bf16_t)(w3 >> 16);
;                     }
.LBB0_764:
	s_andn2_b64 vcc, exec, s[68:69]
	s_cbranch_vccnz .LBB0_766
	s_lshl_b32 s68, s64, 6
	s_ashr_i32 s69, s68, 31
	v_lshl_add_u64 v[34:35], s[68:69], 1, v[42:43]
	s_lshl_b32 s92, s82, 1
	v_lshl_add_u64 v[34:35], v[34:35], 0, s[92:93]
	v_mov_b32_e32 v129, v0
	v_lshl_add_u64 v[34:35], v[34:35], 0, v[128:129]
	global_store_dwordx4 v[34:35], v[38:41], off nt
.LBB0_766:
	v_cvt_pk_bf16_f32 v30, v30, v31
	v_cvt_pk_bf16_f32 v31, v32, v33
	v_cvt_pk_bf16_f32 v32, v26, v27
	v_cvt_pk_bf16_f32 v33, v28, v29
	s_and_b64 vcc, exec, s[42:43]
	s_mov_b64 s[68:69], -1
	s_cbranch_vccnz .LBB0_768
	s_ashr_i32 s67, s66, 31
	s_lshl_b64 s[68:69], s[66:67], 13
	v_lshl_add_u64 v[26:27], v[58:59], 0, s[68:69]
	v_lshl_add_u64 v[26:27], v[142:143], 1, v[26:27]
	v_mov_b32_e32 v127, v0
	v_lshl_add_u64 v[26:27], v[26:27], 0, v[126:127]
	s_mov_b64 s[68:69], 0
	global_store_short v[26:27], v30, off offset:64 nt
	global_store_short_d16_hi v[26:27], v30, off offset:192 nt
	global_store_short v[26:27], v31, off offset:320 nt
	global_store_short_d16_hi v[26:27], v31, off offset:448 nt
	global_store_short v[26:27], v32, off offset:576 nt
	global_store_short_d16_hi v[26:27], v32, off offset:704 nt
	global_store_short v[26:27], v33, off offset:832 nt
	global_store_short_d16_hi v[26:27], v33, off offset:960 nt
.LBB0_768:
	v_lshlrev_b64 v[26:27], 10, v[148:149]
	s_mov_b64 s[70:71], 0x28000
	v_lshl_add_u64 v[26:27], v[26:27], 0, s[70:71]
	s_andn2_b64 vcc, exec, s[68:69]
	v_lshl_add_u64 v[26:27], s[50:51], 0, v[26:27]
	s_cbranch_vccnz .LBB0_770
	s_lshl_b32 s68, s72, 7
	s_ashr_i32 s69, s68, 31
	v_lshl_add_u64 v[28:29], s[68:69], 1, v[26:27]
	s_lshl_b32 s92, s82, 1
	v_lshl_add_u64 v[28:29], v[28:29], 0, s[92:93]
	v_mov_b32_e32 v129, v0
	v_lshl_add_u64 v[28:29], v[28:29], 0, v[128:129]
	global_store_dwordx4 v[28:29], v[30:33], off nt
.LBB0_770:
	v_cvt_pk_bf16_f32 v22, v22, v23
	v_cvt_pk_bf16_f32 v23, v24, v25
	v_cvt_pk_bf16_f32 v24, v18, v19
	v_cvt_pk_bf16_f32 v25, v20, v21
	s_and_b64 vcc, exec, s[42:43]
	s_mov_b64 s[68:69], -1
	s_cbranch_vccnz .LBB0_772
	s_ashr_i32 s65, s64, 31
	s_lshl_b64 s[68:69], s[64:65], 13
	v_lshl_add_u64 v[18:19], v[58:59], 0, s[68:69]
	v_lshl_add_u64 v[18:19], v[142:143], 1, v[18:19]
	v_mov_b32_e32 v127, v0
	v_lshl_add_u64 v[18:19], v[18:19], 0, v[126:127]
	s_mov_b64 s[68:69], 0
	global_store_short v[18:19], v22, off offset:64 nt
	global_store_short_d16_hi v[18:19], v22, off offset:192 nt
	global_store_short v[18:19], v23, off offset:320 nt
	global_store_short_d16_hi v[18:19], v23, off offset:448 nt
	global_store_short v[18:19], v24, off offset:576 nt
	global_store_short_d16_hi v[18:19], v24, off offset:704 nt
	global_store_short v[18:19], v25, off offset:832 nt
	global_store_short_d16_hi v[18:19], v25, off offset:960 nt
.LBB0_772:
	s_andn2_b64 vcc, exec, s[68:69]
	s_cbranch_vccnz .LBB0_774
	s_lshl_b32 s68, s64, 6
	s_ashr_i32 s69, s68, 31
	v_lshl_add_u64 v[18:19], s[68:69], 1, v[26:27]
	s_lshl_b32 s92, s82, 1
	v_lshl_add_u64 v[18:19], v[18:19], 0, s[92:93]
	v_mov_b32_e32 v129, v0
	v_lshl_add_u64 v[18:19], v[18:19], 0, v[128:129]
	global_store_dwordx4 v[18:19], v[22:25], off nt
.LBB0_774:
	v_cvt_pk_bf16_f32 v14, v14, v15
	v_cvt_pk_bf16_f32 v15, v16, v17
	v_cvt_pk_bf16_f32 v16, v10, v11
	v_cvt_pk_bf16_f32 v17, v12, v13
	s_and_b64 vcc, exec, s[42:43]
	s_mov_b64 s[68:69], -1
	s_cbranch_vccnz .LBB0_776
	s_ashr_i32 s67, s66, 31
	s_lshl_b64 s[66:67], s[66:67], 13
	v_lshl_add_u64 v[10:11], v[58:59], 0, s[66:67]
	v_lshl_add_u64 v[10:11], v[142:143], 1, v[10:11]
	v_mov_b32_e32 v127, v0
	v_lshl_add_u64 v[10:11], v[10:11], 0, v[126:127]
	s_mov_b64 s[68:69], 0
	global_store_short v[10:11], v14, off offset:96 nt
	global_store_short_d16_hi v[10:11], v14, off offset:224 nt
	global_store_short v[10:11], v15, off offset:352 nt
	global_store_short_d16_hi v[10:11], v15, off offset:480 nt
	global_store_short v[10:11], v16, off offset:608 nt
	global_store_short_d16_hi v[10:11], v16, off offset:736 nt
	global_store_short v[10:11], v17, off offset:864 nt
	global_store_short_d16_hi v[10:11], v17, off offset:992 nt
.LBB0_776:
	v_lshlrev_b64 v[10:11], 10, v[148:149]
	s_mov_b64 s[66:67], 0x2c000
	v_lshl_add_u64 v[10:11], v[10:11], 0, s[66:67]
	s_andn2_b64 vcc, exec, s[68:69]
	v_lshl_add_u64 v[10:11], s[50:51], 0, v[10:11]
	s_cbranch_vccnz .LBB0_778
	s_lshl_b32 s66, s72, 7
	s_ashr_i32 s67, s66, 31
	v_lshl_add_u64 v[12:13], s[66:67], 1, v[10:11]
	s_lshl_b32 s92, s82, 1
	v_lshl_add_u64 v[12:13], v[12:13], 0, s[92:93]
	v_mov_b32_e32 v129, v0
	v_lshl_add_u64 v[12:13], v[12:13], 0, v[128:129]
	global_store_dwordx4 v[12:13], v[14:17], off nt
.LBB0_778:
	v_cvt_pk_bf16_f32 v6, v6, v7
	v_cvt_pk_bf16_f32 v7, v8, v9
	v_cvt_pk_bf16_f32 v8, v2, v3
	v_cvt_pk_bf16_f32 v9, v4, v5
	s_and_b64 vcc, exec, s[42:43]
	s_mov_b64 s[42:43], -1
	s_cbranch_vccnz .LBB0_781
	s_ashr_i32 s65, s64, 31
	s_lshl_b64 s[42:43], s[64:65], 13
	v_lshl_add_u64 v[2:3], v[58:59], 0, s[42:43]
	v_lshl_add_u64 v[2:3], v[142:143], 1, v[2:3]
	v_mov_b32_e32 v127, v0
	v_lshl_add_u64 v[2:3], v[2:3], 0, v[126:127]
	global_store_short v[2:3], v6, off offset:96 nt
	global_store_short_d16_hi v[2:3], v6, off offset:224 nt
	global_store_short v[2:3], v7, off offset:352 nt
	global_store_short_d16_hi v[2:3], v7, off offset:480 nt
	global_store_short v[2:3], v8, off offset:608 nt
	global_store_short_d16_hi v[2:3], v8, off offset:736 nt
	global_store_short v[2:3], v9, off offset:864 nt
	global_store_short_d16_hi v[2:3], v9, off offset:992 nt
	s_cbranch_execz .LBB0_782

; template <class Epi, class Sched, bool ALIGN_EPI = false, bool SP2 = false>
; __device__ __forceinline__ void gemm_phase(PG8_LAS unsigned char* lds, const Gemm g, const Sched& S, const Epi& E) {
;     ...
;     for (;;) {
;         const bool has_next = S.next(ui + 1, nxt);
;         const char* nA = has_next ? (const char*)g.A + (size_t)nxt.pm * tstep : cA; const char* nB = has_next ? (const char*)g.Bt + (size_t)nxt.pn * tstep : cB;
;         for (int t = 0; t < nt; t += 2) {
;     __device__ __forceinline__ void operator()(const f32x4 (&acc)[2][2][4][2], const Unit& u, int wr, int wc, int fr, int fq) const {
;     ...
;                         u32x4 w; w.x = w0; w.y = w1; w.z = w2; w.w = w3;
;                         *(u32x4*)(KN + (size_t)row * 512 + 64 * head + 32 * wc + 8 * fq) = w;
.LBB0_782:
	s_lshl_b32 s42, s64, 6
	s_ashr_i32 s43, s42, 31
	v_lshl_add_u64 v[2:3], s[42:43], 1, v[10:11]
	s_lshl_b32 s92, s82, 1
	v_lshl_add_u64 v[2:3], v[2:3], 0, s[92:93]
	v_mov_b32_e32 v129, v0
	v_lshl_add_u64 v[2:3], v[2:3], 0, v[128:129]
	global_store_dwordx4 v[2:3], v[6:9], off nt
	s_and_b64 vcc, exec, s[40:41]
	s_mov_b64 s[40:41], -1
	s_cbranch_vccnz .LBB0_702

; DI unsigned cvtpk(float lo, float hi) { f32x2_t v = {lo, hi}; bf16x2_t b = __builtin_convertvector(v, bf16x2_t); return __builtin_bit_cast(unsigned, b); }
;     __device__ __forceinline__ void operator()(const f32x4 (&acc)[2][2][4][2], const Unit& u, int wr, int wc, int fr, int fq) const {
;     ...
;                 const int row = row0 + ai * HALF + m * 16; const int pos = pos_of_row(row);
;                 const int cidx = 4 * u.pm + 2 * ai + wr, t = 16 * m + fr;
; #pragma unroll
;                 for (int bj = 0; bj < 2; ++bj) {
;                     const int g32 = u.pn * 8 + bj * 4 + wc;
;                     f32x4 a = acc[ai][bj][m][0], b = acc[ai][bj][m][1];
;                     if (rope) {
;                         const float2* tb = tabR + (size_t)pos * 32 + 16 * (g32 & 1) + 4 * fq;
; #pragma unroll
;                         for (int j = 0; j < 4; ++j) { const float2 cs = tb[j]; const float x1 = a[j], x2 = b[j]; a[j] = x1 * cs.x - x2 * cs.y; b[j] = x2 * cs.x + x1 * cs.y; }
;                     }
;                     a = a * sc; b = b * sc;
;                     bf16_t* p = PST + (((size_t)cidx * 4 + m) * NIN_SCAN + g32 * 32 + 4 * fq) * 16 + fr;
;                     const unsigned w0 = cvtpk(a[0], a[1]), w1 = cvtpk(a[2], a[3]), w2 = cvtpk(b[0], b[1]), w3 = cvtpk(b[2], b[3]);
;                     p[0 * 16] = (bf16_t)(w0 & 0xffffu); p[1 * 16] = (bf16_t)(w0 >> 16); p[2 * 16] = (bf16_t)(w1 & 0xffffu); p[3 * 16] = (bf16_t)(w1 >> 16);
;                     p[16 * 16] = (bf16_t)(w2 & 0xffffu); p[17 * 16] = (bf16_t)(w2 >> 16); p[18 * 16] = (bf16_t)(w3 & 0xffffu); p[19 * 16] = (bf16_t)(w3 >> 16);
.LBB0_1012:
	s_lshl_b32 s9, s9, 2
	s_add_i32 s9, s9, s64
	s_lshl_b32 s8, s8, 8
	s_mul_hi_i32 s63, s9, 0x3000
	s_mul_i32 s62, s9, 0x3000
	s_or_b32 s58, s8, s71
	v_mov_b32_e32 v151, s63
	v_or_b32_e32 v150, s62, v134
	s_ashr_i32 s59, s58, 31
	v_lshl_add_u64 v[160:161], v[150:151], 0, s[58:59]
	v_pk_mul_f32 v[126:127], v[148:149], v[126:127] op_sel_hi:[0,1]
	v_pk_mul_f32 v[122:123], v[148:149], v[122:123] op_sel_hi:[0,1]
	v_lshlrev_b64 v[160:161], 5, v[160:161]
	v_pk_mul_f32 v[128:129], v[148:149], v[128:129] op_sel_hi:[0,1]
	v_pk_mul_f32 v[124:125], v[148:149], v[124:125] op_sel_hi:[0,1]
	v_lshl_add_u64 v[160:161], v[140:141], 0, v[160:161]
	v_cvt_pk_bf16_f32 v126, v126, v127
	v_cvt_pk_bf16_f32 v122, v122, v123
	v_cvt_pk_bf16_f32 v127, v128, v129
	v_cvt_pk_bf16_f32 v123, v124, v125
	global_store_short v[160:161], v126, off nt
	global_store_short_d16_hi v[160:161], v126, off offset:32 nt
	global_store_short v[160:161], v127, off offset:64 nt
	global_store_short_d16_hi v[160:161], v127, off offset:96 nt
	global_store_short v[160:161], v122, off offset:512 nt
	global_store_short_d16_hi v[160:161], v122, off offset:544 nt
	global_store_short v[160:161], v123, off offset:576 nt
	v_cndmask_b32_e64 v122, 0, 1, s[60:61]
	v_cmp_ne_u32_e64 s[42:43], 1, v122
	s_andn2_b64 vcc, exec, s[60:61]
	global_store_short_d16_hi v[160:161], v123, off offset:608 nt
	s_cbranch_vccnz .LBB0_1014
	global_load_dwordx4 v[122:125], v[152:153], off
	global_load_dwordx4 v[126:129], v[152:153], off offset:16
	s_waitcnt vmcnt(0)
	v_mov_b32_e32 v152, v122
	v_mul_f32_e32 v122, v120, v126
	v_mul_f32_e32 v160, v116, v127
	v_mul_f32_e32 v126, v116, v126
	v_mul_f32_e32 v162, v120, v127
	v_mov_b32_e32 v116, v121
	v_mov_b32_e32 v120, v117
	v_mov_b32_e32 v153, v124
	v_mov_b32_e32 v124, v123
	v_pk_mul_f32 v[116:117], v[116:117], v[128:129]
	v_pk_mul_f32 v[120:121], v[120:121], v[128:129]
	v_pk_mul_f32 v[164:165], v[118:119], v[124:125]
	v_pk_mul_f32 v[124:125], v[114:115], v[124:125]
	v_mov_b32_e32 v123, v116
	v_mov_b32_e32 v161, v117
	v_mov_b32_e32 v127, v120
	v_mov_b32_e32 v163, v121
	v_pk_fma_f32 v[118:119], v[118:119], v[152:153], v[124:125] neg_lo:[0,0,1] neg_hi:[0,0,1]
	v_pk_fma_f32 v[114:115], v[114:115], v[152:153], v[164:165]
	v_pk_add_f32 v[120:121], v[122:123], v[160:161] neg_lo:[0,1] neg_hi:[0,1]
	v_pk_add_f32 v[116:117], v[126:127], v[162:163]
.LBB0_1014:
	s_or_b32 s60, s58, 0x80
	s_ashr_i32 s61, s60, 31
	v_mov_b32_e32 v149, v148
	v_mov_b32_e32 v122, v148
	v_mov_b32_e32 v123, v148
	v_lshl_add_u64 v[124:125], v[150:151], 0, s[60:61]
	v_pk_mul_f32 v[118:119], v[148:149], v[118:119]
	v_pk_mul_f32 v[116:117], v[122:123], v[116:117]
	v_pk_mul_f32 v[114:115], v[148:149], v[114:115]
	v_lshlrev_b64 v[124:125], 5, v[124:125]
	v_pk_mul_f32 v[120:121], v[122:123], v[120:121]
	v_lshl_add_u64 v[124:125], v[140:141], 0, v[124:125]
	v_cvt_pk_bf16_f32 v118, v118, v119
	v_cvt_pk_bf16_f32 v114, v114, v115
	v_cvt_pk_bf16_f32 v115, v116, v117
	s_movk_i32 s8, 0x1fdf
	v_cvt_pk_bf16_f32 v119, v120, v121
	global_store_short v[124:125], v118, off nt
	global_store_short_d16_hi v[124:125], v118, off offset:32 nt
	global_store_short v[124:125], v119, off offset:64 nt
	global_store_short_d16_hi v[124:125], v119, off offset:96 nt
	global_store_short v[124:125], v114, off offset:512 nt
	global_store_short_d16_hi v[124:125], v114, off offset:544 nt
	global_store_short v[124:125], v115, off offset:576 nt
	global_store_short_d16_hi v[124:125], v115, off offset:608 nt
	v_or_b32_e32 v114, 16, v159
	v_bitop3_b32 v115, v159, s8, 16 bitop3:0xc8
	s_mov_b32 s8, 0x8000
	v_cmp_gt_i32_e32 vcc, s8, v114
	s_nop 1
	v_cndmask_b32_e32 v114, v155, v115, vcc
	v_lshlrev_b32_e32 v114, 8, v114
	v_mov_b32_e32 v115, v0
	s_and_b64 vcc, exec, s[42:43]
	v_lshl_add_u64 v[114:115], v[142:143], 0, v[114:115]
	s_cbranch_vccnz .LBB0_1016
	global_load_dwordx4 v[116:119], v[114:115], off
	global_load_dwordx4 v[124:127], v[114:115], off offset:16
	s_waitcnt vmcnt(0)
	v_mov_b32_e32 v120, v116
	v_mul_f32_e32 v116, v112, v124
	v_mul_f32_e32 v128, v108, v125
	v_mul_f32_e32 v124, v108, v124
	v_mul_f32_e32 v152, v112, v125
	v_mov_b32_e32 v108, v113
	v_mov_b32_e32 v112, v109
	v_mov_b32_e32 v121, v118
	v_mov_b32_e32 v118, v117
	v_pk_mul_f32 v[108:109], v[108:109], v[126:127]
	v_pk_mul_f32 v[112:113], v[112:113], v[126:127]
	v_pk_mul_f32 v[160:161], v[110:111], v[118:119]
	v_pk_mul_f32 v[118:119], v[106:107], v[118:119]
	v_mov_b32_e32 v117, v108
	v_mov_b32_e32 v129, v109
	v_mov_b32_e32 v125, v112
	v_mov_b32_e32 v153, v113
	v_pk_fma_f32 v[110:111], v[110:111], v[120:121], v[118:119] neg_lo:[0,0,1] neg_hi:[0,0,1]
	v_pk_fma_f32 v[106:107], v[106:107], v[120:121], v[160:161]
	v_pk_add_f32 v[112:113], v[116:117], v[128:129] neg_lo:[0,1] neg_hi:[0,1]
	v_pk_add_f32 v[108:109], v[124:125], v[152:153]
; DI unsigned cvtpk(float lo, float hi) { f32x2_t v = {lo, hi}; bf16x2_t b = __builtin_convertvector(v, bf16x2_t); return __builtin_bit_cast(unsigned, b); }
;     __device__ __forceinline__ void operator()(const f32x4 (&acc)[2][2][4][2], const Unit& u, int wr, int wc, int fr, int fq) const {
;     ...
;                 const int row = row0 + ai * HALF + m * 16; const int pos = pos_of_row(row);
;                 const int cidx = 4 * u.pm + 2 * ai + wr, t = 16 * m + fr;
; #pragma unroll
;                 for (int bj = 0; bj < 2; ++bj) {
;                     const int g32 = u.pn * 8 + bj * 4 + wc;
;                     f32x4 a = acc[ai][bj][m][0], b = acc[ai][bj][m][1];
;                     if (rope) {
;                         const float2* tb = tabR + (size_t)pos * 32 + 16 * (g32 & 1) + 4 * fq;
; #pragma unroll
;                         for (int j = 0; j < 4; ++j) { const float2 cs = tb[j]; const float x1 = a[j], x2 = b[j]; a[j] = x1 * cs.x - x2 * cs.y; b[j] = x2 * cs.x + x1 * cs.y; }
;                     }
;                     a = a * sc; b = b * sc;
;                     bf16_t* p = PST + (((size_t)cidx * 4 + m) * NIN_SCAN + g32 * 32 + 4 * fq) * 16 + fr;
;                     const unsigned w0 = cvtpk(a[0], a[1]), w1 = cvtpk(a[2], a[3]), w2 = cvtpk(b[0], b[1]), w3 = cvtpk(b[2], b[3]);
;                     p[0 * 16] = (bf16_t)(w0 & 0xffffu); p[1 * 16] = (bf16_t)(w0 >> 16); p[2 * 16] = (bf16_t)(w1 & 0xffffu); p[3 * 16] = (bf16_t)(w1 >> 16);
;                     p[16 * 16] = (bf16_t)(w2 & 0xffffu); p[17 * 16] = (bf16_t)(w2 >> 16); p[18 * 16] = (bf16_t)(w3 & 0xffffu); p[19 * 16] = (bf16_t)(w3 >> 16);
.LBB0_1016:
	v_or_b32_e32 v150, 0xc00, v150
	v_lshl_add_u64 v[116:117], v[150:151], 0, s[58:59]
	v_pk_mul_f32 v[110:111], v[148:149], v[110:111]
	v_pk_mul_f32 v[108:109], v[122:123], v[108:109]
	v_pk_mul_f32 v[106:107], v[148:149], v[106:107]
	v_lshlrev_b64 v[116:117], 5, v[116:117]
	v_pk_mul_f32 v[112:113], v[122:123], v[112:113]
	v_lshl_add_u64 v[116:117], v[140:141], 0, v[116:117]
	v_cvt_pk_bf16_f32 v110, v110, v111
	v_cvt_pk_bf16_f32 v106, v106, v107
	v_cvt_pk_bf16_f32 v107, v108, v109
	s_and_b64 vcc, exec, s[42:43]
	v_cvt_pk_bf16_f32 v111, v112, v113
	global_store_short v[116:117], v110, off nt
	global_store_short_d16_hi v[116:117], v110, off offset:32 nt
	global_store_short v[116:117], v111, off offset:64 nt
	global_store_short_d16_hi v[116:117], v111, off offset:96 nt
	global_store_short v[116:117], v106, off offset:512 nt
	global_store_short_d16_hi v[116:117], v106, off offset:544 nt
	global_store_short v[116:117], v107, off offset:576 nt
	global_store_short_d16_hi v[116:117], v107, off offset:608 nt
	s_cbranch_vccnz .LBB0_1018
	global_load_dwordx4 v[106:109], v[114:115], off
	global_load_dwordx4 v[110:113], v[114:115], off offset:16
	s_waitcnt vmcnt(0)
	v_mov_b32_e32 v114, v106
	v_mul_f32_e32 v106, v104, v110
	v_mul_f32_e32 v116, v100, v111
	v_mul_f32_e32 v110, v100, v110
	v_mul_f32_e32 v118, v104, v111
	v_mov_b32_e32 v100, v105
	v_mov_b32_e32 v104, v101
	v_mov_b32_e32 v115, v108
	v_mov_b32_e32 v108, v107
	v_pk_mul_f32 v[100:101], v[100:101], v[112:113]
	v_pk_mul_f32 v[104:105], v[104:105], v[112:113]
	v_pk_mul_f32 v[120:121], v[102:103], v[108:109]
	v_pk_mul_f32 v[108:109], v[98:99], v[108:109]
	v_mov_b32_e32 v107, v100
	v_mov_b32_e32 v117, v101
	v_mov_b32_e32 v111, v104
	v_mov_b32_e32 v119, v105
	v_pk_fma_f32 v[102:103], v[102:103], v[114:115], v[108:109] neg_lo:[0,0,1] neg_hi:[0,0,1]
	v_pk_fma_f32 v[98:99], v[98:99], v[114:115], v[120:121]
	v_pk_add_f32 v[104:105], v[106:107], v[116:117] neg_lo:[0,1] neg_hi:[0,1]
	v_pk_add_f32 v[100:101], v[110:111], v[118:119]
.LBB0_1018:
	v_mov_b32_e32 v106, v148
	v_mov_b32_e32 v107, v148
	v_lshl_add_u64 v[108:109], v[150:151], 0, s[60:61]
	v_pk_mul_f32 v[102:103], v[148:149], v[102:103]
	v_pk_mul_f32 v[100:101], v[106:107], v[100:101]
	v_pk_mul_f32 v[98:99], v[148:149], v[98:99]
	v_lshlrev_b64 v[108:109], 5, v[108:109]
	v_pk_mul_f32 v[104:105], v[106:107], v[104:105]
	v_lshl_add_u64 v[108:109], v[140:141], 0, v[108:109]
	v_cvt_pk_bf16_f32 v102, v102, v103
	v_cvt_pk_bf16_f32 v98, v98, v99
	v_cvt_pk_bf16_f32 v99, v100, v101
	s_movk_i32 s8, 0x1fef
	v_cvt_pk_bf16_f32 v103, v104, v105
	global_store_short v[108:109], v102, off nt
	global_store_short_d16_hi v[108:109], v102, off offset:32 nt
	global_store_short v[108:109], v103, off offset:64 nt
	global_store_short_d16_hi v[108:109], v103, off offset:96 nt
	global_store_short v[108:109], v98, off offset:512 nt
	global_store_short_d16_hi v[108:109], v98, off offset:544 nt
	global_store_short v[108:109], v99, off offset:576 nt
	global_store_short_d16_hi v[108:109], v99, off offset:608 nt
	v_or_b32_e32 v98, 32, v159
	v_bitop3_b32 v99, v159, s8, 32 bitop3:0xc8
	s_mov_b32 s8, 0x8000
	v_cmp_gt_i32_e32 vcc, s8, v98
	s_nop 1
	v_cndmask_b32_e32 v98, v156, v99, vcc
	v_lshlrev_b32_e32 v98, 8, v98
	v_mov_b32_e32 v99, v0
	s_and_b64 vcc, exec, s[42:43]
	v_lshl_add_u64 v[100:101], v[142:143], 0, v[98:99]
	s_cbranch_vccnz .LBB0_1020
	global_load_dwordx4 v[102:105], v[100:101], off
	global_load_dwordx4 v[108:111], v[100:101], off offset:16
	s_waitcnt vmcnt(0)
	v_mov_b32_e32 v98, v102
	v_mul_f32_e32 v102, v96, v108
	v_mul_f32_e32 v112, v92, v109
	v_mul_f32_e32 v108, v92, v108
	v_mul_f32_e32 v114, v96, v109
	v_mov_b32_e32 v92, v97
	v_mov_b32_e32 v96, v93
	v_mov_b32_e32 v99, v104
	v_mov_b32_e32 v104, v103
	v_pk_mul_f32 v[92:93], v[92:93], v[110:111]
	v_pk_mul_f32 v[96:97], v[96:97], v[110:111]
	v_pk_mul_f32 v[116:117], v[94:95], v[104:105]
	v_pk_mul_f32 v[104:105], v[90:91], v[104:105]
	v_mov_b32_e32 v103, v92
	v_mov_b32_e32 v113, v93
	v_mov_b32_e32 v109, v96
	v_mov_b32_e32 v115, v97
	v_pk_fma_f32 v[94:95], v[94:95], v[98:99], v[104:105] neg_lo:[0,0,1] neg_hi:[0,0,1]
	v_pk_fma_f32 v[90:91], v[90:91], v[98:99], v[116:117]
	v_pk_add_f32 v[96:97], v[102:103], v[112:113] neg_lo:[0,1] neg_hi:[0,1]
	v_pk_add_f32 v[92:93], v[108:109], v[114:115]
.LBB0_1020:
	v_lshl_add_u64 v[98:99], s[62:63], 0, v[136:137]
	v_lshl_add_u64 v[102:103], v[98:99], 0, s[58:59]
	v_pk_mul_f32 v[94:95], v[148:149], v[94:95]
	v_pk_mul_f32 v[92:93], v[106:107], v[92:93]
	v_pk_mul_f32 v[90:91], v[148:149], v[90:91]
	v_lshlrev_b64 v[102:103], 5, v[102:103]
	v_pk_mul_f32 v[96:97], v[106:107], v[96:97]
	v_lshl_add_u64 v[102:103], v[140:141], 0, v[102:103]
	v_cvt_pk_bf16_f32 v94, v94, v95
	v_cvt_pk_bf16_f32 v90, v90, v91
	v_cvt_pk_bf16_f32 v91, v92, v93
	s_and_b64 vcc, exec, s[42:43]
	v_cvt_pk_bf16_f32 v95, v96, v97
	global_store_short v[102:103], v94, off nt
	global_store_short_d16_hi v[102:103], v94, off offset:32 nt
	global_store_short v[102:103], v95, off offset:64 nt
	global_store_short_d16_hi v[102:103], v95, off offset:96 nt
	global_store_short v[102:103], v90, off offset:512 nt
	global_store_short_d16_hi v[102:103], v90, off offset:544 nt
	global_store_short v[102:103], v91, off offset:576 nt
	global_store_short_d16_hi v[102:103], v91, off offset:608 nt
	s_cbranch_vccnz .LBB0_1022
	global_load_dwordx4 v[90:93], v[100:101], off
	global_load_dwordx4 v[94:97], v[100:101], off offset:16
	s_waitcnt vmcnt(0)
	v_mov_b32_e32 v100, v90
	v_mul_f32_e32 v90, v88, v94
	v_mul_f32_e32 v102, v84, v95
	v_mul_f32_e32 v94, v84, v94
	v_mul_f32_e32 v104, v88, v95
	v_mov_b32_e32 v84, v89
	v_mov_b32_e32 v88, v85
	v_mov_b32_e32 v101, v92
	v_mov_b32_e32 v92, v91
	v_pk_mul_f32 v[84:85], v[84:85], v[96:97]
	v_pk_mul_f32 v[88:89], v[88:89], v[96:97]
	v_pk_mul_f32 v[106:107], v[86:87], v[92:93]
	v_pk_mul_f32 v[92:93], v[82:83], v[92:93]
	v_mov_b32_e32 v91, v84
	v_mov_b32_e32 v103, v85
	v_mov_b32_e32 v95, v88
	v_mov_b32_e32 v105, v89
	v_pk_fma_f32 v[86:87], v[86:87], v[100:101], v[92:93] neg_lo:[0,0,1] neg_hi:[0,0,1]
	v_pk_fma_f32 v[82:83], v[82:83], v[100:101], v[106:107]
	v_pk_add_f32 v[88:89], v[90:91], v[102:103] neg_lo:[0,1] neg_hi:[0,1]
	v_pk_add_f32 v[84:85], v[94:95], v[104:105]
; DI unsigned cvtpk(float lo, float hi) { f32x2_t v = {lo, hi}; bf16x2_t b = __builtin_convertvector(v, bf16x2_t); return __builtin_bit_cast(unsigned, b); }
;     __device__ __forceinline__ void operator()(const f32x4 (&acc)[2][2][4][2], const Unit& u, int wr, int wc, int fr, int fq) const {
;     ...
;                 const int row = row0 + ai * HALF + m * 16; const int pos = pos_of_row(row);
;                 const int cidx = 4 * u.pm + 2 * ai + wr, t = 16 * m + fr;
; #pragma unroll
;                 for (int bj = 0; bj < 2; ++bj) {
;                     const int g32 = u.pn * 8 + bj * 4 + wc;
;                     f32x4 a = acc[ai][bj][m][0], b = acc[ai][bj][m][1];
;                     if (rope) {
;                         const float2* tb = tabR + (size_t)pos * 32 + 16 * (g32 & 1) + 4 * fq;
; #pragma unroll
;                         for (int j = 0; j < 4; ++j) { const float2 cs = tb[j]; const float x1 = a[j], x2 = b[j]; a[j] = x1 * cs.x - x2 * cs.y; b[j] = x2 * cs.x + x1 * cs.y; }
;                     }
;                     a = a * sc; b = b * sc;
;                     bf16_t* p = PST + (((size_t)cidx * 4 + m) * NIN_SCAN + g32 * 32 + 4 * fq) * 16 + fr;
;                     const unsigned w0 = cvtpk(a[0], a[1]), w1 = cvtpk(a[2], a[3]), w2 = cvtpk(b[0], b[1]), w3 = cvtpk(b[2], b[3]);
;                     p[0 * 16] = (bf16_t)(w0 & 0xffffu); p[1 * 16] = (bf16_t)(w0 >> 16); p[2 * 16] = (bf16_t)(w1 & 0xffffu); p[3 * 16] = (bf16_t)(w1 >> 16);
;                     p[16 * 16] = (bf16_t)(w2 & 0xffffu); p[17 * 16] = (bf16_t)(w2 >> 16); p[18 * 16] = (bf16_t)(w3 & 0xffffu); p[19 * 16] = (bf16_t)(w3 >> 16);
.LBB0_1022:
	v_mov_b32_e32 v90, v148
	v_mov_b32_e32 v91, v148
	v_lshl_add_u64 v[92:93], v[98:99], 0, s[60:61]
	v_pk_mul_f32 v[86:87], v[148:149], v[86:87]
	v_pk_mul_f32 v[84:85], v[90:91], v[84:85]
	v_pk_mul_f32 v[82:83], v[148:149], v[82:83]
	v_lshlrev_b64 v[92:93], 5, v[92:93]
	v_pk_mul_f32 v[88:89], v[90:91], v[88:89]
	v_lshl_add_u64 v[92:93], v[140:141], 0, v[92:93]
	v_cvt_pk_bf16_f32 v86, v86, v87
	v_cvt_pk_bf16_f32 v82, v82, v83
	v_cvt_pk_bf16_f32 v83, v84, v85
	s_movk_i32 s8, 0x1fff
	v_cvt_pk_bf16_f32 v87, v88, v89
	global_store_short v[92:93], v86, off nt
	global_store_short_d16_hi v[92:93], v86, off offset:32 nt
	global_store_short v[92:93], v87, off offset:64 nt
	global_store_short_d16_hi v[92:93], v87, off offset:96 nt
	global_store_short v[92:93], v82, off offset:512 nt
	global_store_short_d16_hi v[92:93], v82, off offset:544 nt
	global_store_short v[92:93], v83, off offset:576 nt
	global_store_short_d16_hi v[92:93], v83, off offset:608 nt
	v_or_b32_e32 v82, 48, v159
	v_bitop3_b32 v83, v159, s8, 48 bitop3:0xc8
	s_mov_b32 s8, 0x8000
	v_cmp_gt_i32_e32 vcc, s8, v82
	s_nop 1
	v_cndmask_b32_e32 v82, v157, v83, vcc
	v_lshlrev_b32_e32 v82, 8, v82
	v_mov_b32_e32 v83, v0
	s_and_b64 vcc, exec, s[42:43]
	v_lshl_add_u64 v[84:85], v[142:143], 0, v[82:83]
	s_cbranch_vccnz .LBB0_1024
	global_load_dwordx4 v[86:89], v[84:85], off
	global_load_dwordx4 v[92:95], v[84:85], off offset:16
	s_waitcnt vmcnt(0)
	v_mov_b32_e32 v82, v86
	v_mul_f32_e32 v86, v80, v92
	v_mul_f32_e32 v96, v76, v93
	v_mul_f32_e32 v92, v76, v92
	v_mul_f32_e32 v98, v80, v93
	v_mov_b32_e32 v76, v81
	v_mov_b32_e32 v80, v77
	v_mov_b32_e32 v83, v88
	v_mov_b32_e32 v88, v87
	v_pk_mul_f32 v[76:77], v[76:77], v[94:95]
	v_pk_mul_f32 v[80:81], v[80:81], v[94:95]
	v_pk_mul_f32 v[100:101], v[78:79], v[88:89]
	v_pk_mul_f32 v[88:89], v[74:75], v[88:89]
	v_mov_b32_e32 v87, v76
	v_mov_b32_e32 v97, v77
	v_mov_b32_e32 v93, v80
	v_mov_b32_e32 v99, v81
	v_pk_fma_f32 v[78:79], v[78:79], v[82:83], v[88:89] neg_lo:[0,0,1] neg_hi:[0,0,1]
	v_pk_fma_f32 v[74:75], v[74:75], v[82:83], v[100:101]
	v_pk_add_f32 v[80:81], v[86:87], v[96:97] neg_lo:[0,1] neg_hi:[0,1]
	v_pk_add_f32 v[76:77], v[92:93], v[98:99]
.LBB0_1024:
	v_lshl_add_u64 v[82:83], s[62:63], 0, v[138:139]
	v_lshl_add_u64 v[86:87], v[82:83], 0, s[58:59]
	v_pk_mul_f32 v[78:79], v[148:149], v[78:79]
	v_pk_mul_f32 v[76:77], v[90:91], v[76:77]
	v_pk_mul_f32 v[74:75], v[148:149], v[74:75]
	v_lshlrev_b64 v[86:87], 5, v[86:87]
	v_pk_mul_f32 v[80:81], v[90:91], v[80:81]
	v_lshl_add_u64 v[86:87], v[140:141], 0, v[86:87]
	v_cvt_pk_bf16_f32 v78, v78, v79
	v_cvt_pk_bf16_f32 v74, v74, v75
	v_cvt_pk_bf16_f32 v75, v76, v77
	s_and_b64 vcc, exec, s[42:43]
	v_cvt_pk_bf16_f32 v79, v80, v81
	global_store_short v[86:87], v78, off nt
	global_store_short_d16_hi v[86:87], v78, off offset:32 nt
	global_store_short v[86:87], v79, off offset:64 nt
	global_store_short_d16_hi v[86:87], v79, off offset:96 nt
	global_store_short v[86:87], v74, off offset:512 nt
	global_store_short_d16_hi v[86:87], v74, off offset:544 nt
	global_store_short v[86:87], v75, off offset:576 nt
	global_store_short_d16_hi v[86:87], v75, off offset:608 nt
	s_cbranch_vccnz .LBB0_1026
	global_load_dwordx4 v[74:77], v[84:85], off
	global_load_dwordx4 v[78:81], v[84:85], off offset:16
	s_waitcnt vmcnt(0)
	v_mov_b32_e32 v84, v74
	v_mul_f32_e32 v74, v72, v78
	v_mul_f32_e32 v86, v68, v79
	v_mul_f32_e32 v78, v68, v78
	v_mul_f32_e32 v88, v72, v79
	v_mov_b32_e32 v68, v73
	v_mov_b32_e32 v72, v69
	v_mov_b32_e32 v85, v76
	v_mov_b32_e32 v76, v75
	v_pk_mul_f32 v[68:69], v[68:69], v[80:81]
	v_pk_mul_f32 v[72:73], v[72:73], v[80:81]
	v_pk_mul_f32 v[90:91], v[70:71], v[76:77]
	v_pk_mul_f32 v[76:77], v[66:67], v[76:77]
	v_mov_b32_e32 v75, v68
	v_mov_b32_e32 v87, v69
	v_mov_b32_e32 v79, v72
	v_mov_b32_e32 v89, v73
	v_pk_fma_f32 v[70:71], v[70:71], v[84:85], v[76:77] neg_lo:[0,0,1] neg_hi:[0,0,1]
	v_pk_fma_f32 v[66:67], v[66:67], v[84:85], v[90:91]
	v_pk_add_f32 v[72:73], v[74:75], v[86:87] neg_lo:[0,1] neg_hi:[0,1]
	v_pk_add_f32 v[68:69], v[78:79], v[88:89]
.LBB0_1026:
	v_lshl_add_u64 v[76:77], v[82:83], 0, s[60:61]
	v_mov_b32_e32 v74, v148
	v_mov_b32_e32 v75, v148
	v_pk_mul_f32 v[70:71], v[148:149], v[70:71]
	v_pk_mul_f32 v[66:67], v[148:149], v[66:67]
	v_lshlrev_b64 v[76:77], 5, v[76:77]
	v_pk_mul_f32 v[72:73], v[74:75], v[72:73]
	v_pk_mul_f32 v[68:69], v[74:75], v[68:69]
	v_lshl_add_u64 v[76:77], v[140:141], 0, v[76:77]
	v_cvt_pk_bf16_f32 v70, v70, v71
	v_cvt_pk_bf16_f32 v66, v66, v67
	v_cvt_pk_bf16_f32 v71, v72, v73
	v_cvt_pk_bf16_f32 v67, v68, v69
	global_store_short v[76:77], v70, off nt
	global_store_short_d16_hi v[76:77], v70, off offset:32 nt
	global_store_short v[76:77], v71, off offset:64 nt
	global_store_short_d16_hi v[76:77], v71, off offset:96 nt
	global_store_short v[76:77], v66, off offset:512 nt
	global_store_short_d16_hi v[76:77], v66, off offset:544 nt
	global_store_short v[76:77], v67, off offset:576 nt
	global_store_short_d16_hi v[76:77], v67, off offset:608 nt
	v_add_u32_e32 v66, 0x80, v159
	s_movk_i32 s8, 0x7f80
	v_and_b32_e32 v66, 0x1fcf, v66
	v_cmp_gt_i32_e32 vcc, s8, v159
	v_mov_b32_e32 v67, v0
	s_nop 0
	v_cndmask_b32_e32 v66, v154, v66, vcc
	v_lshlrev_b32_e32 v66, 8, v66
	s_and_b64 vcc, exec, s[42:43]
	v_lshl_add_u64 v[68:69], v[142:143], 0, v[66:67]
	s_cbranch_vccnz .LBB0_1028
	global_load_dwordx4 v[70:73], v[68:69], off
	global_load_dwordx4 v[76:79], v[68:69], off offset:16
	s_waitcnt vmcnt(0)
	v_mov_b32_e32 v66, v70
	v_mul_f32_e32 v70, v64, v76
	v_mul_f32_e32 v80, v60, v77
	v_mul_f32_e32 v76, v60, v76
	v_mul_f32_e32 v82, v64, v77
	v_mov_b32_e32 v60, v65
	v_mov_b32_e32 v64, v61
	v_mov_b32_e32 v67, v72
	v_mov_b32_e32 v72, v71
	v_pk_mul_f32 v[60:61], v[60:61], v[78:79]
	v_pk_mul_f32 v[64:65], v[64:65], v[78:79]
	v_pk_mul_f32 v[84:85], v[62:63], v[72:73]
	v_pk_mul_f32 v[72:73], v[58:59], v[72:73]
	v_mov_b32_e32 v71, v60
	v_mov_b32_e32 v81, v61
	v_mov_b32_e32 v77, v64
	v_mov_b32_e32 v83, v65
	v_pk_fma_f32 v[62:63], v[62:63], v[66:67], v[72:73] neg_lo:[0,0,1] neg_hi:[0,0,1]
	v_pk_fma_f32 v[58:59], v[58:59], v[66:67], v[84:85]
	v_pk_add_f32 v[64:65], v[70:71], v[80:81] neg_lo:[0,1] neg_hi:[0,1]
	v_pk_add_f32 v[60:61], v[76:77], v[82:83]
; DI unsigned cvtpk(float lo, float hi) { f32x2_t v = {lo, hi}; bf16x2_t b = __builtin_convertvector(v, bf16x2_t); return __builtin_bit_cast(unsigned, b); }
;     __device__ __forceinline__ void operator()(const f32x4 (&acc)[2][2][4][2], const Unit& u, int wr, int wc, int fr, int fq) const {
;     ...
;                 const int row = row0 + ai * HALF + m * 16; const int pos = pos_of_row(row);
;                 const int cidx = 4 * u.pm + 2 * ai + wr, t = 16 * m + fr;
; #pragma unroll
;                 for (int bj = 0; bj < 2; ++bj) {
;                     const int g32 = u.pn * 8 + bj * 4 + wc;
;                     f32x4 a = acc[ai][bj][m][0], b = acc[ai][bj][m][1];
;                     if (rope) {
;                         const float2* tb = tabR + (size_t)pos * 32 + 16 * (g32 & 1) + 4 * fq;
; #pragma unroll
;                         for (int j = 0; j < 4; ++j) { const float2 cs = tb[j]; const float x1 = a[j], x2 = b[j]; a[j] = x1 * cs.x - x2 * cs.y; b[j] = x2 * cs.x + x1 * cs.y; }
;                     }
;                     a = a * sc; b = b * sc;
;                     bf16_t* p = PST + (((size_t)cidx * 4 + m) * NIN_SCAN + g32 * 32 + 4 * fq) * 16 + fr;
;                     const unsigned w0 = cvtpk(a[0], a[1]), w1 = cvtpk(a[2], a[3]), w2 = cvtpk(b[0], b[1]), w3 = cvtpk(b[2], b[3]);
;                     p[0 * 16] = (bf16_t)(w0 & 0xffffu); p[1 * 16] = (bf16_t)(w0 >> 16); p[2 * 16] = (bf16_t)(w1 & 0xffffu); p[3 * 16] = (bf16_t)(w1 >> 16);
;                     p[16 * 16] = (bf16_t)(w2 & 0xffffu); p[17 * 16] = (bf16_t)(w2 >> 16); p[18 * 16] = (bf16_t)(w3 & 0xffffu); p[19 * 16] = (bf16_t)(w3 >> 16);
.LBB0_1028:
	s_add_i32 s8, s9, 2
	s_mul_hi_i32 s63, s8, 0x3000
	s_mul_i32 s62, s8, 0x3000
	v_mov_b32_e32 v67, s63
	v_or_b32_e32 v66, s62, v134
	v_lshl_add_u64 v[70:71], v[66:67], 0, s[58:59]
	v_pk_mul_f32 v[62:63], v[148:149], v[62:63]
	v_pk_mul_f32 v[60:61], v[74:75], v[60:61]
	v_pk_mul_f32 v[58:59], v[148:149], v[58:59]
	v_lshlrev_b64 v[70:71], 5, v[70:71]
	v_pk_mul_f32 v[64:65], v[74:75], v[64:65]
	v_lshl_add_u64 v[70:71], v[140:141], 0, v[70:71]
	v_cvt_pk_bf16_f32 v62, v62, v63
	v_cvt_pk_bf16_f32 v58, v58, v59
	v_cvt_pk_bf16_f32 v59, v60, v61
	s_and_b64 vcc, exec, s[42:43]
	v_cvt_pk_bf16_f32 v63, v64, v65
	global_store_short v[70:71], v62, off nt
	global_store_short_d16_hi v[70:71], v62, off offset:32 nt
	global_store_short v[70:71], v63, off offset:64 nt
	global_store_short_d16_hi v[70:71], v63, off offset:96 nt
	global_store_short v[70:71], v58, off offset:512 nt
	global_store_short_d16_hi v[70:71], v58, off offset:544 nt
	global_store_short v[70:71], v59, off offset:576 nt
	global_store_short_d16_hi v[70:71], v59, off offset:608 nt
	s_cbranch_vccnz .LBB0_1030
	global_load_dwordx4 v[58:61], v[68:69], off
	global_load_dwordx4 v[62:65], v[68:69], off offset:16
	s_waitcnt vmcnt(0)
	v_mov_b32_e32 v68, v58
	v_mul_f32_e32 v58, v56, v62
	v_mul_f32_e32 v70, v52, v63
	v_mul_f32_e32 v62, v52, v62
	v_mul_f32_e32 v72, v56, v63
	v_mov_b32_e32 v52, v57
	v_mov_b32_e32 v56, v53
	v_mov_b32_e32 v69, v60
	v_mov_b32_e32 v60, v59
	v_pk_mul_f32 v[52:53], v[52:53], v[64:65]
	v_pk_mul_f32 v[56:57], v[56:57], v[64:65]
	v_pk_mul_f32 v[74:75], v[54:55], v[60:61]
	v_pk_mul_f32 v[60:61], v[50:51], v[60:61]
	v_mov_b32_e32 v59, v52
	v_mov_b32_e32 v71, v53
	v_mov_b32_e32 v63, v56
	v_mov_b32_e32 v73, v57
	v_pk_fma_f32 v[54:55], v[54:55], v[68:69], v[60:61] neg_lo:[0,0,1] neg_hi:[0,0,1]
	v_pk_fma_f32 v[50:51], v[50:51], v[68:69], v[74:75]
	v_pk_add_f32 v[56:57], v[58:59], v[70:71] neg_lo:[0,1] neg_hi:[0,1]
	v_pk_add_f32 v[52:53], v[62:63], v[72:73]
.LBB0_1030:
	v_lshl_add_u64 v[60:61], v[66:67], 0, s[60:61]
	v_mov_b32_e32 v58, v148
	v_mov_b32_e32 v59, v148
	v_pk_mul_f32 v[54:55], v[148:149], v[54:55]
	v_pk_mul_f32 v[50:51], v[148:149], v[50:51]
	v_lshlrev_b64 v[60:61], 5, v[60:61]
	v_pk_mul_f32 v[56:57], v[58:59], v[56:57]
	v_pk_mul_f32 v[52:53], v[58:59], v[52:53]
	v_lshl_add_u64 v[60:61], v[140:141], 0, v[60:61]
	v_cvt_pk_bf16_f32 v54, v54, v55
	v_cvt_pk_bf16_f32 v50, v50, v51
	v_cvt_pk_bf16_f32 v55, v56, v57
	v_cvt_pk_bf16_f32 v51, v52, v53
	global_store_short v[60:61], v54, off nt
	global_store_short_d16_hi v[60:61], v54, off offset:32 nt
	global_store_short v[60:61], v55, off offset:64 nt
	global_store_short_d16_hi v[60:61], v55, off offset:96 nt
	global_store_short v[60:61], v50, off offset:512 nt
	global_store_short_d16_hi v[60:61], v50, off offset:544 nt
	global_store_short v[60:61], v51, off offset:576 nt
	global_store_short_d16_hi v[60:61], v51, off offset:608 nt
	v_add_u32_e32 v50, 0x90, v159
	s_movk_i32 s8, 0x7f70
	v_and_b32_e32 v50, 0x1fdf, v50
	v_cmp_gt_i32_e32 vcc, s8, v159
	v_mov_b32_e32 v51, v0
	s_nop 0
	v_cndmask_b32_e32 v50, v155, v50, vcc
	v_lshlrev_b32_e32 v50, 8, v50
	s_and_b64 vcc, exec, s[42:43]
	v_lshl_add_u64 v[50:51], v[142:143], 0, v[50:51]
	s_cbranch_vccnz .LBB0_1032
	global_load_dwordx4 v[52:55], v[50:51], off
	global_load_dwordx4 v[60:63], v[50:51], off offset:16
	s_waitcnt vmcnt(0)
	v_mov_b32_e32 v56, v52
	v_mul_f32_e32 v52, v48, v60
	v_mul_f32_e32 v64, v44, v61
	v_mul_f32_e32 v60, v44, v60
	v_mul_f32_e32 v68, v48, v61
	v_mov_b32_e32 v44, v49
	v_mov_b32_e32 v48, v45
	v_mov_b32_e32 v57, v54
	v_mov_b32_e32 v54, v53
	v_pk_mul_f32 v[44:45], v[44:45], v[62:63]
	v_pk_mul_f32 v[48:49], v[48:49], v[62:63]
	v_pk_mul_f32 v[70:71], v[46:47], v[54:55]
	v_pk_mul_f32 v[54:55], v[42:43], v[54:55]
	v_mov_b32_e32 v53, v44
	v_mov_b32_e32 v65, v45
	v_mov_b32_e32 v61, v48
	v_mov_b32_e32 v69, v49
	v_pk_fma_f32 v[46:47], v[46:47], v[56:57], v[54:55] neg_lo:[0,0,1] neg_hi:[0,0,1]
	v_pk_fma_f32 v[42:43], v[42:43], v[56:57], v[70:71]
	v_pk_add_f32 v[48:49], v[52:53], v[64:65] neg_lo:[0,1] neg_hi:[0,1]
	v_pk_add_f32 v[44:45], v[60:61], v[68:69]
.LBB0_1032:
	v_or_b32_e32 v66, 0xc00, v66
	v_lshl_add_u64 v[52:53], v[66:67], 0, s[58:59]
	v_pk_mul_f32 v[46:47], v[148:149], v[46:47]
	v_pk_mul_f32 v[44:45], v[58:59], v[44:45]
	v_pk_mul_f32 v[42:43], v[148:149], v[42:43]
	v_lshlrev_b64 v[52:53], 5, v[52:53]
	v_pk_mul_f32 v[48:49], v[58:59], v[48:49]
	v_lshl_add_u64 v[52:53], v[140:141], 0, v[52:53]
	v_cvt_pk_bf16_f32 v46, v46, v47
	v_cvt_pk_bf16_f32 v42, v42, v43
	v_cvt_pk_bf16_f32 v43, v44, v45
	s_and_b64 vcc, exec, s[42:43]
	v_cvt_pk_bf16_f32 v47, v48, v49
	global_store_short v[52:53], v46, off nt
	global_store_short_d16_hi v[52:53], v46, off offset:32 nt
	global_store_short v[52:53], v47, off offset:64 nt
	global_store_short_d16_hi v[52:53], v47, off offset:96 nt
	global_store_short v[52:53], v42, off offset:512 nt
	global_store_short_d16_hi v[52:53], v42, off offset:544 nt
	global_store_short v[52:53], v43, off offset:576 nt
	global_store_short_d16_hi v[52:53], v43, off offset:608 nt
	s_cbranch_vccnz .LBB0_1034
	global_load_dwordx4 v[42:45], v[50:51], off
	global_load_dwordx4 v[46:49], v[50:51], off offset:16
	s_waitcnt vmcnt(0)
	v_mov_b32_e32 v50, v42
	v_mul_f32_e32 v42, v40, v46
	v_mul_f32_e32 v52, v36, v47
	v_mul_f32_e32 v46, v36, v46
	v_mul_f32_e32 v54, v40, v47
	v_mov_b32_e32 v36, v41
	v_mov_b32_e32 v40, v37
	v_mov_b32_e32 v51, v44
	v_mov_b32_e32 v44, v43
	v_pk_mul_f32 v[36:37], v[36:37], v[48:49]
	v_pk_mul_f32 v[40:41], v[40:41], v[48:49]
	v_pk_mul_f32 v[56:57], v[38:39], v[44:45]
	v_pk_mul_f32 v[44:45], v[34:35], v[44:45]
	v_mov_b32_e32 v43, v36
	v_mov_b32_e32 v53, v37
	v_mov_b32_e32 v47, v40
	v_mov_b32_e32 v55, v41
	v_pk_fma_f32 v[38:39], v[38:39], v[50:51], v[44:45] neg_lo:[0,0,1] neg_hi:[0,0,1]
	v_pk_fma_f32 v[34:35], v[34:35], v[50:51], v[56:57]
	v_pk_add_f32 v[40:41], v[42:43], v[52:53] neg_lo:[0,1] neg_hi:[0,1]
	v_pk_add_f32 v[36:37], v[46:47], v[54:55]
; DI unsigned cvtpk(float lo, float hi) { f32x2_t v = {lo, hi}; bf16x2_t b = __builtin_convertvector(v, bf16x2_t); return __builtin_bit_cast(unsigned, b); }
;     __device__ __forceinline__ void operator()(const f32x4 (&acc)[2][2][4][2], const Unit& u, int wr, int wc, int fr, int fq) const {
;     ...
;                 const int row = row0 + ai * HALF + m * 16; const int pos = pos_of_row(row);
;                 const int cidx = 4 * u.pm + 2 * ai + wr, t = 16 * m + fr;
; #pragma unroll
;                 for (int bj = 0; bj < 2; ++bj) {
;                     const int g32 = u.pn * 8 + bj * 4 + wc;
;                     f32x4 a = acc[ai][bj][m][0], b = acc[ai][bj][m][1];
;                     if (rope) {
;                         const float2* tb = tabR + (size_t)pos * 32 + 16 * (g32 & 1) + 4 * fq;
; #pragma unroll
;                         for (int j = 0; j < 4; ++j) { const float2 cs = tb[j]; const float x1 = a[j], x2 = b[j]; a[j] = x1 * cs.x - x2 * cs.y; b[j] = x2 * cs.x + x1 * cs.y; }
;                     }
;                     a = a * sc; b = b * sc;
;                     bf16_t* p = PST + (((size_t)cidx * 4 + m) * NIN_SCAN + g32 * 32 + 4 * fq) * 16 + fr;
;                     const unsigned w0 = cvtpk(a[0], a[1]), w1 = cvtpk(a[2], a[3]), w2 = cvtpk(b[0], b[1]), w3 = cvtpk(b[2], b[3]);
;                     p[0 * 16] = (bf16_t)(w0 & 0xffffu); p[1 * 16] = (bf16_t)(w0 >> 16); p[2 * 16] = (bf16_t)(w1 & 0xffffu); p[3 * 16] = (bf16_t)(w1 >> 16);
;                     p[16 * 16] = (bf16_t)(w2 & 0xffffu); p[17 * 16] = (bf16_t)(w2 >> 16); p[18 * 16] = (bf16_t)(w3 & 0xffffu); p[19 * 16] = (bf16_t)(w3 >> 16);
.LBB0_1034:
	v_lshl_add_u64 v[44:45], v[66:67], 0, s[60:61]
	v_mov_b32_e32 v42, v148
	v_mov_b32_e32 v43, v148
	v_pk_mul_f32 v[38:39], v[148:149], v[38:39]
	v_pk_mul_f32 v[34:35], v[148:149], v[34:35]
	v_lshlrev_b64 v[44:45], 5, v[44:45]
	v_pk_mul_f32 v[40:41], v[42:43], v[40:41]
	v_pk_mul_f32 v[36:37], v[42:43], v[36:37]
	v_lshl_add_u64 v[44:45], v[140:141], 0, v[44:45]
	v_cvt_pk_bf16_f32 v38, v38, v39
	v_cvt_pk_bf16_f32 v34, v34, v35
	v_cvt_pk_bf16_f32 v39, v40, v41
	v_cvt_pk_bf16_f32 v35, v36, v37
	global_store_short v[44:45], v38, off nt
	global_store_short_d16_hi v[44:45], v38, off offset:32 nt
	global_store_short v[44:45], v39, off offset:64 nt
	global_store_short_d16_hi v[44:45], v39, off offset:96 nt
	global_store_short v[44:45], v34, off offset:512 nt
	global_store_short_d16_hi v[44:45], v34, off offset:544 nt
	global_store_short v[44:45], v35, off offset:576 nt
	global_store_short_d16_hi v[44:45], v35, off offset:608 nt
	v_add_u32_e32 v34, 0xa0, v159
	s_movk_i32 s8, 0x7f60
	v_and_b32_e32 v34, 0x1fef, v34
	v_cmp_gt_i32_e32 vcc, s8, v159
	v_mov_b32_e32 v35, v0
	s_nop 0
	v_cndmask_b32_e32 v34, v156, v34, vcc
	v_lshlrev_b32_e32 v34, 8, v34
	s_and_b64 vcc, exec, s[42:43]
	v_lshl_add_u64 v[36:37], v[142:143], 0, v[34:35]
	s_cbranch_vccnz .LBB0_1036
	global_load_dwordx4 v[38:41], v[36:37], off
	global_load_dwordx4 v[44:47], v[36:37], off offset:16
	s_waitcnt vmcnt(0)
	v_mov_b32_e32 v34, v38
	v_mul_f32_e32 v38, v32, v44
	v_mul_f32_e32 v48, v28, v45
	v_mul_f32_e32 v44, v28, v44
	v_mul_f32_e32 v50, v32, v45
	v_mov_b32_e32 v28, v33
	v_mov_b32_e32 v32, v29
	v_mov_b32_e32 v35, v40
	v_mov_b32_e32 v40, v39
	v_pk_mul_f32 v[28:29], v[28:29], v[46:47]
	v_pk_mul_f32 v[32:33], v[32:33], v[46:47]
	v_pk_mul_f32 v[52:53], v[30:31], v[40:41]
	v_pk_mul_f32 v[40:41], v[26:27], v[40:41]
	v_mov_b32_e32 v39, v28
	v_mov_b32_e32 v49, v29
	v_mov_b32_e32 v45, v32
	v_mov_b32_e32 v51, v33
	v_pk_fma_f32 v[30:31], v[30:31], v[34:35], v[40:41] neg_lo:[0,0,1] neg_hi:[0,0,1]
	v_pk_fma_f32 v[26:27], v[26:27], v[34:35], v[52:53]
	v_pk_add_f32 v[32:33], v[38:39], v[48:49] neg_lo:[0,1] neg_hi:[0,1]
	v_pk_add_f32 v[28:29], v[44:45], v[50:51]
.LBB0_1036:
	v_lshl_add_u64 v[34:35], s[62:63], 0, v[136:137]
	v_lshl_add_u64 v[38:39], v[34:35], 0, s[58:59]
	v_pk_mul_f32 v[30:31], v[148:149], v[30:31]
	v_pk_mul_f32 v[28:29], v[42:43], v[28:29]
	v_pk_mul_f32 v[26:27], v[148:149], v[26:27]
	v_lshlrev_b64 v[38:39], 5, v[38:39]
	v_pk_mul_f32 v[32:33], v[42:43], v[32:33]
	v_lshl_add_u64 v[38:39], v[140:141], 0, v[38:39]
	v_cvt_pk_bf16_f32 v30, v30, v31
	v_cvt_pk_bf16_f32 v26, v26, v27
	v_cvt_pk_bf16_f32 v27, v28, v29
	s_and_b64 vcc, exec, s[42:43]
	v_cvt_pk_bf16_f32 v31, v32, v33
	global_store_short v[38:39], v30, off nt
	global_store_short_d16_hi v[38:39], v30, off offset:32 nt
	global_store_short v[38:39], v31, off offset:64 nt
	global_store_short_d16_hi v[38:39], v31, off offset:96 nt
	global_store_short v[38:39], v26, off offset:512 nt
	global_store_short_d16_hi v[38:39], v26, off offset:544 nt
	global_store_short v[38:39], v27, off offset:576 nt
	global_store_short_d16_hi v[38:39], v27, off offset:608 nt
	s_cbranch_vccnz .LBB0_1038
	global_load_dwordx4 v[26:29], v[36:37], off
	global_load_dwordx4 v[30:33], v[36:37], off offset:16
	s_waitcnt vmcnt(0)
	v_mov_b32_e32 v36, v26
	v_mul_f32_e32 v26, v24, v30
	v_mul_f32_e32 v38, v20, v31
	v_mul_f32_e32 v30, v20, v30
	v_mul_f32_e32 v40, v24, v31
	v_mov_b32_e32 v20, v25
	v_mov_b32_e32 v24, v21
	v_mov_b32_e32 v37, v28
	v_mov_b32_e32 v28, v27
	v_pk_mul_f32 v[20:21], v[20:21], v[32:33]
	v_pk_mul_f32 v[24:25], v[24:25], v[32:33]
	v_pk_mul_f32 v[42:43], v[22:23], v[28:29]
	v_pk_mul_f32 v[28:29], v[18:19], v[28:29]
	v_mov_b32_e32 v27, v20
	v_mov_b32_e32 v39, v21
	v_mov_b32_e32 v31, v24
	v_mov_b32_e32 v41, v25
	v_pk_fma_f32 v[22:23], v[22:23], v[36:37], v[28:29] neg_lo:[0,0,1] neg_hi:[0,0,1]
	v_pk_fma_f32 v[18:19], v[18:19], v[36:37], v[42:43]
	v_pk_add_f32 v[24:25], v[26:27], v[38:39] neg_lo:[0,1] neg_hi:[0,1]
	v_pk_add_f32 v[20:21], v[30:31], v[40:41]
; #define PG8_BAR __builtin_amdgcn_s_barrier()
; template <class Epi, class Sched, bool ALIGN_EPI = false, bool SP2 = false>
; __device__ __forceinline__ void gemm_phase(PG8_LAS unsigned char* lds, const Gemm g, const Sched& S, const Epi& E) {
;     ...
;         if constexpr (ALIGN_EPI) { if (wr == 0) PG8_BAR; }
;         if constexpr (!Epi::AFTER_DRAIN) { E(acc, cur, wr, wc, fr, fq); S.done(cur); }
;         if (!has_next) break;
; #pragma unroll
;         for (int a = 0; a < 2; ++a)
; #pragma unroll
;             for (int b = 0; b < 2; ++b)
; #pragma unroll
;                 for (int m = 0; m < 4; ++m)
; #pragma unroll
;                     for (int n = 0; n < 2; ++n) acc[a][b][m][n] = (f32x4){0.f, 0.f, 0.f, 0.f};
;         cur = nxt; cA = nA; cB = nB; ++ui;
;         if constexpr (ALIGN_EPI) { if (wr == 1) PG8_BAR; }
;     __device__ __forceinline__ void operator()(const f32x4 (&acc)[2][2][4][2], const Unit& u, int wr, int wc, int fr, int fq) const {
;     ...
;                 const int row = row0 + ai * HALF + m * 16; const int pos = pos_of_row(row);
;                 const int cidx = 4 * u.pm + 2 * ai + wr, t = 16 * m + fr;
; #pragma unroll
;                 for (int bj = 0; bj < 2; ++bj) {
;                     const int g32 = u.pn * 8 + bj * 4 + wc;
;                     f32x4 a = acc[ai][bj][m][0], b = acc[ai][bj][m][1];
;                     if (rope) {
;                         const float2* tb = tabR + (size_t)pos * 32 + 16 * (g32 & 1) + 4 * fq;
; #pragma unroll
;                         for (int j = 0; j < 4; ++j) { const float2 cs = tb[j]; const float x1 = a[j], x2 = b[j]; a[j] = x1 * cs.x - x2 * cs.y; b[j] = x2 * cs.x + x1 * cs.y; }
;                     }
;                     a = a * sc; b = b * sc;
;                     bf16_t* p = PST + (((size_t)cidx * 4 + m) * NIN_SCAN + g32 * 32 + 4 * fq) * 16 + fr;
;                     const unsigned w0 = cvtpk(a[0], a[1]), w1 = cvtpk(a[2], a[3]), w2 = cvtpk(b[0], b[1]), w3 = cvtpk(b[2], b[3]);
;                     p[0 * 16] = (bf16_t)(w0 & 0xffffu); p[1 * 16] = (bf16_t)(w0 >> 16); p[2 * 16] = (bf16_t)(w1 & 0xffffu); p[3 * 16] = (bf16_t)(w1 >> 16);
;                     p[16 * 16] = (bf16_t)(w2 & 0xffffu); p[17 * 16] = (bf16_t)(w2 >> 16); p[18 * 16] = (bf16_t)(w3 & 0xffffu); p[19 * 16] = (bf16_t)(w3 >> 16);
.LBB0_1038:
	v_lshl_add_u64 v[28:29], v[34:35], 0, s[60:61]
	v_mov_b32_e32 v26, v148
	v_mov_b32_e32 v27, v148
	v_pk_mul_f32 v[22:23], v[148:149], v[22:23]
	v_pk_mul_f32 v[18:19], v[148:149], v[18:19]
	v_lshlrev_b64 v[28:29], 5, v[28:29]
	v_pk_mul_f32 v[24:25], v[26:27], v[24:25]
	v_pk_mul_f32 v[20:21], v[26:27], v[20:21]
	v_lshl_add_u64 v[28:29], v[140:141], 0, v[28:29]
	v_cvt_pk_bf16_f32 v22, v22, v23
	v_cvt_pk_bf16_f32 v18, v18, v19
	v_cvt_pk_bf16_f32 v23, v24, v25
	v_cvt_pk_bf16_f32 v19, v20, v21
	global_store_short v[28:29], v22, off nt
	global_store_short_d16_hi v[28:29], v22, off offset:32 nt
	global_store_short v[28:29], v23, off offset:64 nt
	global_store_short_d16_hi v[28:29], v23, off offset:96 nt
	global_store_short v[28:29], v18, off offset:512 nt
	global_store_short_d16_hi v[28:29], v18, off offset:544 nt
	global_store_short v[28:29], v19, off offset:576 nt
	global_store_short_d16_hi v[28:29], v19, off offset:608 nt
	v_add_u32_e32 v18, 0xb0, v159
	s_movk_i32 s8, 0x7f50
	v_and_b32_e32 v18, 0x1fff, v18
	v_cmp_gt_i32_e32 vcc, s8, v159
	v_mov_b32_e32 v19, v0
	s_nop 0
	v_cndmask_b32_e32 v18, v157, v18, vcc
	v_lshlrev_b32_e32 v18, 8, v18
	s_and_b64 vcc, exec, s[42:43]
	v_lshl_add_u64 v[20:21], v[142:143], 0, v[18:19]
	s_cbranch_vccnz .LBB0_1040
	global_load_dwordx4 v[22:25], v[20:21], off
	global_load_dwordx4 v[28:31], v[20:21], off offset:16
	s_waitcnt vmcnt(0)
	v_mov_b32_e32 v18, v22
	v_mul_f32_e32 v22, v16, v28
	v_mul_f32_e32 v32, v12, v29
	v_mul_f32_e32 v28, v12, v28
	v_mul_f32_e32 v34, v16, v29
	v_mov_b32_e32 v12, v17
	v_mov_b32_e32 v16, v13
	v_mov_b32_e32 v19, v24
	v_mov_b32_e32 v24, v23
	v_pk_mul_f32 v[12:13], v[12:13], v[30:31]
	v_pk_mul_f32 v[16:17], v[16:17], v[30:31]
	v_pk_mul_f32 v[36:37], v[14:15], v[24:25]
	v_pk_mul_f32 v[24:25], v[10:11], v[24:25]
	v_mov_b32_e32 v23, v12
	v_mov_b32_e32 v33, v13
	v_mov_b32_e32 v29, v16
	v_mov_b32_e32 v35, v17
	v_pk_fma_f32 v[14:15], v[14:15], v[18:19], v[24:25] neg_lo:[0,0,1] neg_hi:[0,0,1]
	v_pk_fma_f32 v[10:11], v[10:11], v[18:19], v[36:37]
	v_pk_add_f32 v[16:17], v[22:23], v[32:33] neg_lo:[0,1] neg_hi:[0,1]
	v_pk_add_f32 v[12:13], v[28:29], v[34:35]
.LBB0_1040:
	v_lshl_add_u64 v[18:19], s[62:63], 0, v[138:139]
	v_lshl_add_u64 v[22:23], v[18:19], 0, s[58:59]
	v_pk_mul_f32 v[14:15], v[148:149], v[14:15]
	v_pk_mul_f32 v[12:13], v[26:27], v[12:13]
	v_pk_mul_f32 v[10:11], v[148:149], v[10:11]
	v_lshlrev_b64 v[22:23], 5, v[22:23]
	v_pk_mul_f32 v[16:17], v[26:27], v[16:17]
	v_lshl_add_u64 v[22:23], v[140:141], 0, v[22:23]
	v_cvt_pk_bf16_f32 v14, v14, v15
	v_cvt_pk_bf16_f32 v10, v10, v11
	v_cvt_pk_bf16_f32 v11, v12, v13
	s_and_b64 vcc, exec, s[42:43]
	v_cvt_pk_bf16_f32 v15, v16, v17
	global_store_short v[22:23], v14, off nt
	global_store_short_d16_hi v[22:23], v14, off offset:32 nt
	global_store_short v[22:23], v15, off offset:64 nt
	global_store_short_d16_hi v[22:23], v15, off offset:96 nt
	global_store_short v[22:23], v10, off offset:512 nt
	global_store_short_d16_hi v[22:23], v10, off offset:544 nt
	global_store_short v[22:23], v11, off offset:576 nt
	global_store_short_d16_hi v[22:23], v11, off offset:608 nt
	s_cbranch_vccnz .LBB0_1042
	global_load_dwordx4 v[10:13], v[20:21], off
	global_load_dwordx4 v[14:17], v[20:21], off offset:16
	s_waitcnt vmcnt(0)
	v_mov_b32_e32 v20, v10
	v_mul_f32_e32 v10, v8, v14
	v_mul_f32_e32 v22, v4, v15
	v_mul_f32_e32 v14, v4, v14
	v_mul_f32_e32 v24, v8, v15
	v_mov_b32_e32 v4, v9
	v_mov_b32_e32 v8, v5
	v_mov_b32_e32 v21, v12
	v_mov_b32_e32 v12, v11
	v_pk_mul_f32 v[4:5], v[4:5], v[16:17]
	v_pk_mul_f32 v[8:9], v[8:9], v[16:17]
	v_pk_mul_f32 v[26:27], v[6:7], v[12:13]
	v_pk_mul_f32 v[12:13], v[2:3], v[12:13]
	v_mov_b32_e32 v11, v4
	v_mov_b32_e32 v23, v5
	v_mov_b32_e32 v15, v8
	v_mov_b32_e32 v25, v9
	v_pk_fma_f32 v[6:7], v[6:7], v[20:21], v[12:13] neg_lo:[0,0,1] neg_hi:[0,0,1]
	v_pk_fma_f32 v[2:3], v[2:3], v[20:21], v[26:27]
	v_pk_add_f32 v[8:9], v[10:11], v[22:23] neg_lo:[0,1] neg_hi:[0,1]
	v_pk_add_f32 v[4:5], v[14:15], v[24:25]
.LBB0_1042:
	v_mov_b32_e32 v10, v148
	v_mov_b32_e32 v11, v148
	v_pk_mul_f32 v[8:9], v[10:11], v[8:9]
	v_pk_mul_f32 v[4:5], v[10:11], v[4:5]
	v_lshl_add_u64 v[10:11], v[18:19], 0, s[60:61]
	v_pk_mul_f32 v[6:7], v[148:149], v[6:7]
	v_lshlrev_b64 v[10:11], 5, v[10:11]
	v_pk_mul_f32 v[2:3], v[148:149], v[2:3]
	v_lshl_add_u64 v[10:11], v[140:141], 0, v[10:11]
	v_cvt_pk_bf16_f32 v6, v6, v7
	s_and_b64 vcc, exec, s[40:41]
	s_mov_b64 s[40:41], -1
	v_cvt_pk_bf16_f32 v7, v8, v9
	v_cvt_pk_bf16_f32 v2, v2, v3
	v_cvt_pk_bf16_f32 v3, v4, v5
	global_store_short v[10:11], v6, off nt
	global_store_short_d16_hi v[10:11], v6, off offset:32 nt
	global_store_short v[10:11], v7, off offset:64 nt
	global_store_short_d16_hi v[10:11], v7, off offset:96 nt
	global_store_short v[10:11], v2, off offset:512 nt
	global_store_short_d16_hi v[10:11], v2, off offset:544 nt
	global_store_short v[10:11], v3, off offset:576 nt
	global_store_short_d16_hi v[10:11], v3, off offset:608 nt
	s_cbranch_vccnz .LBB0_990
	s_andn2_b64 vcc, exec, s[48:49]
	s_cbranch_vccnz .LBB0_989
	s_barrier
	s_branch .LBB0_989

; DI void gla_gate_items(unsigned char* lds, const float* GLR, unsigned short* LA, int first, int stride, int nitems, const float* wgate, const float* bgate) {
;     ...
;         for (int j = 0; j < 16; j += 2) {
;             float la[2];
; #pragma unroll
;             for (int q = 0; q < 2; ++q) {
;                 const f32x4* gr = (const f32x4*)(GLRS + (16 * rg + j + q) * 16); float x = bg;
; #pragma unroll
;                 for (int i = 0; i < 4; ++i) { const f32x4 gv = gr[i]; x += gv.x * wg[4 * i] + gv.y * wg[4 * i + 1] + gv.z * wg[4 * i + 2] + gv.w * wg[4 * i + 3]; }
;                 la[q] = -(fmaxf(-x, 0.f) + __logf(1.f + __expf(-fabsf(x)))) * (1.f / 16.f);
;             }
;             const _Float16 h0 = (_Float16)la[0], h1 = (_Float16)la[1];
;             pk[j >> 1] = (unsigned)__builtin_bit_cast(unsigned short, h0) | ((unsigned)__builtin_bit_cast(unsigned short, h1) << 16);
.LBB0_1053:
	s_or_b64 exec, exec, s[42:43]
	ds_read_b128 v[6:9], v1
	ds_read_b128 v[10:13], v1 offset:16
	ds_read_b128 v[34:37], v1 offset:32
	ds_read_b128 v[42:45], v1 offset:48
	s_ashr_i32 s50, s6, 2
	s_waitcnt lgkmcnt(3)
	v_mov_b32_e32 v38, v6
	s_waitcnt lgkmcnt(2)
	v_mov_b32_e32 v39, v10
	v_mov_b32_e32 v10, v7
	v_pk_mul_f32 v[6:7], v[16:17], v[10:11]
	v_mov_b32_e32 v10, v8
	v_pk_fma_f32 v[6:7], v[14:15], v[38:39], v[6:7]
	v_mov_b32_e32 v11, v12
	v_pk_fma_f32 v[6:7], v[18:19], v[10:11], v[6:7]
	v_mov_b32_e32 v12, v9
	v_pk_fma_f32 v[6:7], v[20:21], v[12:13], v[6:7]
	s_mov_b32 s6, 0xbfb8aa3b
	v_add_f32_e32 v6, v40, v6
	v_add_f32_e32 v10, v6, v7
	s_waitcnt lgkmcnt(0)
	v_mov_b32_e32 v7, v42
	v_mov_b32_e32 v42, v35
	v_mov_b32_e32 v6, v34
	v_pk_mul_f32 v[8:9], v[24:25], v[42:43]
	s_mov_b32 s7, 0x800000
	v_pk_fma_f32 v[6:7], v[22:23], v[6:7], v[8:9]
	v_mov_b32_e32 v8, v36
	v_mov_b32_e32 v9, v44
	v_pk_fma_f32 v[6:7], v[26:27], v[8:9], v[6:7]
	v_mov_b32_e32 v44, v37
	v_pk_fma_f32 v[6:7], v[28:29], v[44:45], v[6:7]
	s_mov_b32 s8, 0x3f317217
	v_add_f32_e32 v6, v10, v6
	v_add_f32_e32 v7, v6, v7
	v_max_f32_e64 v6, -v7, 0
	v_mul_f32_e64 v7, |v7|, s6
	v_exp_f32_e32 v7, v7
	ds_read_b128 v[10:13], v1 offset:64
	ds_read_b128 v[34:37], v1 offset:80
	s_mov_b32 s9, 0x7f800000
	s_mov_b32 s10, 0xbd800000
	v_add_f32_e32 v7, 1.0, v7
	v_cmp_gt_f32_e32 vcc, s7, v7
	s_waitcnt lgkmcnt(0)
	v_mov_b32_e32 v39, v34
	v_mov_b32_e32 v34, v11
	v_cndmask_b32_e64 v8, 0, 32, vcc
	v_ldexp_f32 v7, v7, v8
	v_log_f32_e32 v7, v7
	v_mov_b32_e32 v38, v10
	v_pk_mul_f32 v[10:11], v[16:17], v[34:35]
	v_mov_b32_e32 v34, v12
	v_mul_f32_e32 v8, 0x3f317217, v7
	v_fma_f32 v8, v7, s8, -v8
	v_fmac_f32_e32 v8, 0x3377d1cf, v7
	v_pk_fma_f32 v[10:11], v[14:15], v[38:39], v[10:11]
	v_mov_b32_e32 v35, v36
	v_fmac_f32_e32 v8, 0x3f317217, v7
	v_cmp_lt_f32_e64 s[42:43], |v7|, s9
	v_pk_fma_f32 v[10:11], v[18:19], v[34:35], v[10:11]
	v_mov_b32_e32 v36, v13
	v_cndmask_b32_e64 v7, v7, v8, s[42:43]
	v_cndmask_b32_e32 v8, 0, v222, vcc
	v_pk_fma_f32 v[10:11], v[20:21], v[36:37], v[10:11]
	v_sub_f32_e32 v8, v7, v8
	v_add_f32_e32 v7, v40, v10
	v_add_f32_e32 v7, v7, v11
	ds_read_b128 v[10:13], v1 offset:96
	ds_read_b128 v[34:37], v1 offset:112
	s_ashr_i32 s51, s50, 31
	s_waitcnt lgkmcnt(1)
	v_mov_b32_e32 v38, v10
	s_waitcnt lgkmcnt(0)
	v_mov_b32_e32 v39, v34
	v_mov_b32_e32 v34, v11
	v_pk_mul_f32 v[10:11], v[24:25], v[34:35]
	v_mov_b32_e32 v34, v12
	v_pk_fma_f32 v[10:11], v[22:23], v[38:39], v[10:11]
	v_mov_b32_e32 v35, v36
	v_pk_fma_f32 v[10:11], v[26:27], v[34:35], v[10:11]
	v_mov_b32_e32 v36, v13
	v_pk_fma_f32 v[10:11], v[28:29], v[36:37], v[10:11]
	ds_read_b128 v[34:37], v1 offset:128
	ds_read_b128 v[42:45], v1 offset:144
	v_add_f32_e32 v7, v7, v10
	v_add_f32_e32 v7, v7, v11
	v_max_f32_e64 v10, -v7, 0
	v_mul_f32_e64 v7, |v7|, s6
	v_exp_f32_e32 v7, v7
	s_waitcnt lgkmcnt(0)
	v_mov_b32_e32 v39, v42
	v_mov_b32_e32 v42, v35
	v_mov_b32_e32 v38, v34
	v_add_f32_e32 v7, 1.0, v7
	v_cmp_gt_f32_e32 vcc, s7, v7
	v_pk_mul_f32 v[34:35], v[16:17], v[42:43]
	s_nop 0
	v_cndmask_b32_e64 v9, 0, 32, vcc
	v_ldexp_f32 v7, v7, v9
	v_log_f32_e32 v7, v7
	v_pk_fma_f32 v[34:35], v[14:15], v[38:39], v[34:35]
	v_mov_b32_e32 v38, v36
	v_mov_b32_e32 v39, v44
	v_mul_f32_e32 v9, 0x3f317217, v7
	v_fma_f32 v9, v7, s8, -v9
	v_fmac_f32_e32 v9, 0x3377d1cf, v7
	v_fmac_f32_e32 v9, 0x3f317217, v7
	v_cmp_lt_f32_e64 s[42:43], |v7|, s9
	v_pk_fma_f32 v[34:35], v[18:19], v[38:39], v[34:35]
	v_mov_b32_e32 v44, v37
	v_cndmask_b32_e64 v7, v7, v9, s[42:43]
	v_cndmask_b32_e32 v9, 0, v222, vcc
	v_pk_fma_f32 v[34:35], v[20:21], v[44:45], v[34:35]
	v_sub_f32_e32 v12, v7, v9
	v_add_f32_e32 v7, v40, v34
	v_add_f32_e32 v7, v7, v35
	ds_read_b128 v[34:37], v1 offset:160
	ds_read_b128 v[42:45], v1 offset:176
	s_waitcnt lgkmcnt(1)
	v_mov_b32_e32 v38, v34
	s_waitcnt lgkmcnt(0)
	v_mov_b32_e32 v39, v42
	v_mov_b32_e32 v42, v35
	v_pk_mul_f32 v[34:35], v[24:25], v[42:43]
	s_nop 0
	v_pk_fma_f32 v[34:35], v[22:23], v[38:39], v[34:35]
	v_mov_b32_e32 v38, v36
	v_mov_b32_e32 v39, v44
	v_pk_fma_f32 v[34:35], v[26:27], v[38:39], v[34:35]
	v_mov_b32_e32 v44, v37
	v_pk_fma_f32 v[34:35], v[28:29], v[44:45], v[34:35]
	s_nop 0
	v_add_f32_e32 v7, v7, v34
	v_add_f32_e32 v9, v7, v35
	v_max_f32_e64 v7, -v9, 0
	v_mul_f32_e64 v9, |v9|, s6
	v_exp_f32_e32 v9, v9
	ds_read_b128 v[34:37], v1 offset:192
	ds_read_b128 v[42:45], v1 offset:208
	v_add_f32_e32 v9, 1.0, v9
	v_cmp_gt_f32_e32 vcc, s7, v9
	s_waitcnt lgkmcnt(0)
	v_mov_b32_e32 v39, v42
	v_mov_b32_e32 v42, v35
	v_cndmask_b32_e64 v11, 0, 32, vcc
	v_ldexp_f32 v9, v9, v11
	v_log_f32_e32 v9, v9
	v_mov_b32_e32 v38, v34
	v_pk_mul_f32 v[34:35], v[16:17], v[42:43]
	v_mul_f32_e32 v11, 0x3f317217, v9
	v_fma_f32 v11, v9, s8, -v11
	v_fmac_f32_e32 v11, 0x3377d1cf, v9
	v_pk_fma_f32 v[34:35], v[14:15], v[38:39], v[34:35]
	v_mov_b32_e32 v38, v36
	v_mov_b32_e32 v39, v44
	v_fmac_f32_e32 v11, 0x3f317217, v9
	v_cmp_lt_f32_e64 s[42:43], |v9|, s9
	v_pk_fma_f32 v[34:35], v[18:19], v[38:39], v[34:35]
	v_mov_b32_e32 v44, v37
	v_cndmask_b32_e64 v9, v9, v11, s[42:43]
	v_cndmask_b32_e32 v11, 0, v222, vcc
	v_pk_fma_f32 v[34:35], v[20:21], v[44:45], v[34:35]
	v_sub_f32_e32 v9, v9, v11
	v_add_f32_e32 v11, v40, v34
	v_add_f32_e32 v11, v11, v35
	ds_read_b128 v[34:37], v1 offset:224
	ds_read_b128 v[42:45], v1 offset:240
	v_pk_add_f32 v[6:7], v[6:7], v[8:9]
	s_waitcnt lgkmcnt(1)
	v_mov_b32_e32 v38, v34
	s_waitcnt lgkmcnt(0)
; DI void gla_gate_items(unsigned char* lds, const float* GLR, unsigned short* LA, int first, int stride, int nitems, const float* wgate, const float* bgate) {
;     ...
;         for (int j = 0; j < 16; j += 2) {
;             float la[2];
; #pragma unroll
;             for (int q = 0; q < 2; ++q) {
;                 const f32x4* gr = (const f32x4*)(GLRS + (16 * rg + j + q) * 16); float x = bg;
; #pragma unroll
;                 for (int i = 0; i < 4; ++i) { const f32x4 gv = gr[i]; x += gv.x * wg[4 * i] + gv.y * wg[4 * i + 1] + gv.z * wg[4 * i + 2] + gv.w * wg[4 * i + 3]; }
;                 la[q] = -(fmaxf(-x, 0.f) + __logf(1.f + __expf(-fabsf(x)))) * (1.f / 16.f);
;             }
;             const _Float16 h0 = (_Float16)la[0], h1 = (_Float16)la[1];
;             pk[j >> 1] = (unsigned)__builtin_bit_cast(unsigned short, h0) | ((unsigned)__builtin_bit_cast(unsigned short, h1) << 16);
	v_mov_b32_e32 v39, v42
	v_mov_b32_e32 v42, v35
	v_pk_mul_f32 v[34:35], v[24:25], v[42:43]
	v_pk_mul_f32 v[6:7], v[6:7], s[10:11] op_sel_hi:[1,0]
	v_pk_fma_f32 v[34:35], v[22:23], v[38:39], v[34:35]
	v_mov_b32_e32 v38, v36
	v_mov_b32_e32 v39, v44
	v_pk_fma_f32 v[34:35], v[26:27], v[38:39], v[34:35]
	v_mov_b32_e32 v44, v37
	v_pk_fma_f32 v[34:35], v[28:29], v[44:45], v[34:35]
	v_cvt_pk_f16_f32 v6, v6, v7
	v_add_f32_e32 v11, v11, v34
	v_add_f32_e32 v13, v11, v35
	v_max_f32_e64 v11, -v13, 0
	v_mul_f32_e64 v13, |v13|, s6
	v_exp_f32_e32 v13, v13
	s_nop 0
	v_add_f32_e32 v13, 1.0, v13
	v_cmp_gt_f32_e32 vcc, s7, v13
	s_nop 1
	v_cndmask_b32_e64 v34, 0, 32, vcc
	v_ldexp_f32 v13, v13, v34
	v_log_f32_e32 v13, v13
	s_nop 0
	v_mul_f32_e32 v34, 0x3f317217, v13
	v_fma_f32 v34, v13, s8, -v34
	v_fmac_f32_e32 v34, 0x3377d1cf, v13
	v_fmac_f32_e32 v34, 0x3f317217, v13
	v_cmp_lt_f32_e64 s[42:43], |v13|, s9
	s_nop 1
	v_cndmask_b32_e64 v13, v13, v34, s[42:43]
	v_cndmask_b32_e32 v34, 0, v222, vcc
	v_sub_f32_e32 v13, v13, v34
	v_pk_add_f32 v[8:9], v[10:11], v[12:13]
	s_nop 0
	v_pk_mul_f32 v[8:9], v[8:9], s[10:11] op_sel_hi:[1,0]
	s_nop 0
	v_cvt_pk_f16_f32 v7, v8, v9
	v_and_b32_e32 v8, 0xffff0000, v7
	v_lshlrev_b32_e32 v9, 16, v7
	v_or_b32_sdwa v7, v8, v6 dst_sel:DWORD dst_unused:UNUSED_PAD src0_sel:DWORD src1_sel:WORD_1
	v_or_b32_sdwa v6, v9, v6 dst_sel:DWORD dst_unused:UNUSED_PAD src0_sel:DWORD src1_sel:WORD_0
	ds_read_b128 v[8:11], v1 offset:256
	ds_read_b128 v[34:37], v1 offset:272
	s_waitcnt lgkmcnt(1)
	v_mov_b32_e32 v12, v8
	s_waitcnt lgkmcnt(0)
	v_mov_b32_e32 v13, v34
	v_mov_b32_e32 v34, v9
	v_pk_mul_f32 v[8:9], v[16:17], v[34:35]
	s_nop 0
	v_pk_fma_f32 v[8:9], v[14:15], v[12:13], v[8:9]
	v_mov_b32_e32 v12, v10
	v_mov_b32_e32 v13, v36
	v_pk_fma_f32 v[8:9], v[18:19], v[12:13], v[8:9]
	v_mov_b32_e32 v36, v11
	v_pk_fma_f32 v[8:9], v[20:21], v[36:37], v[8:9]
	s_nop 0
	v_add_f32_e32 v8, v40, v8
	v_add_f32_e32 v38, v8, v9
	ds_read_b128 v[8:11], v1 offset:288
	ds_read_b128 v[34:37], v1 offset:304
	s_waitcnt lgkmcnt(1)
	v_mov_b32_e32 v12, v8
	s_waitcnt lgkmcnt(0)
	v_mov_b32_e32 v13, v34
	v_mov_b32_e32 v34, v9
	v_pk_mul_f32 v[8:9], v[24:25], v[34:35]
	s_nop 0
	v_pk_fma_f32 v[8:9], v[22:23], v[12:13], v[8:9]
	v_mov_b32_e32 v12, v10
	v_mov_b32_e32 v13, v36
	v_pk_fma_f32 v[8:9], v[26:27], v[12:13], v[8:9]
	v_mov_b32_e32 v36, v11
	v_pk_fma_f32 v[8:9], v[28:29], v[36:37], v[8:9]
	ds_read_b128 v[34:37], v1 offset:320
	ds_read_b128 v[42:45], v1 offset:336
	v_add_f32_e32 v8, v38, v8
	v_add_f32_e32 v9, v8, v9
	v_max_f32_e64 v8, -v9, 0
	v_mul_f32_e64 v9, |v9|, s6
	v_exp_f32_e32 v9, v9
	s_waitcnt lgkmcnt(0)
	v_mov_b32_e32 v13, v42
	v_mov_b32_e32 v42, v35
	v_mov_b32_e32 v12, v34
	v_add_f32_e32 v9, 1.0, v9
	v_cmp_gt_f32_e32 vcc, s7, v9
	v_pk_mul_f32 v[34:35], v[16:17], v[42:43]
	s_nop 0
	v_cndmask_b32_e64 v10, 0, 32, vcc
	v_ldexp_f32 v9, v9, v10
	v_log_f32_e32 v9, v9
	v_pk_fma_f32 v[12:13], v[14:15], v[12:13], v[34:35]
	v_mov_b32_e32 v34, v36
	v_mov_b32_e32 v35, v44
	v_mul_f32_e32 v10, 0x3f317217, v9
	v_pk_fma_f32 v[12:13], v[18:19], v[34:35], v[12:13]
	v_mov_b32_e32 v44, v37
	v_fma_f32 v10, v9, s8, -v10
	v_pk_fma_f32 v[12:13], v[20:21], v[44:45], v[12:13]
	ds_read_b128 v[34:37], v1 offset:352
	ds_read_b128 v[42:45], v1 offset:368
	v_fmac_f32_e32 v10, 0x3377d1cf, v9
	v_fmac_f32_e32 v10, 0x3f317217, v9
	v_cmp_lt_f32_e64 s[42:43], |v9|, s9
	s_nop 1
	v_cndmask_b32_e64 v9, v9, v10, s[42:43]
	v_cndmask_b32_e32 v10, 0, v222, vcc
	v_sub_f32_e32 v10, v9, v10
	v_add_f32_e32 v9, v40, v12
	v_add_f32_e32 v9, v9, v13
	s_waitcnt lgkmcnt(0)
	v_mov_b32_e32 v13, v42
	v_mov_b32_e32 v42, v35
	v_mov_b32_e32 v12, v34
	v_pk_mul_f32 v[34:35], v[24:25], v[42:43]
	s_nop 0
	v_pk_fma_f32 v[12:13], v[22:23], v[12:13], v[34:35]
	v_mov_b32_e32 v34, v36
	v_mov_b32_e32 v35, v44
	v_pk_fma_f32 v[12:13], v[26:27], v[34:35], v[12:13]
	v_mov_b32_e32 v44, v37
	v_pk_fma_f32 v[12:13], v[28:29], v[44:45], v[12:13]
	ds_read_b128 v[36:39], v1 offset:384
	ds_read_b128 v[42:45], v1 offset:400
	v_add_f32_e32 v9, v9, v12
	v_add_f32_e32 v9, v9, v13
	v_max_f32_e64 v12, -v9, 0
	v_mul_f32_e64 v9, |v9|, s6
	v_exp_f32_e32 v9, v9
	s_waitcnt lgkmcnt(0)
	v_mov_b32_e32 v47, v42
	v_mov_b32_e32 v42, v37
	v_mov_b32_e32 v46, v36
	v_add_f32_e32 v9, 1.0, v9
	v_cmp_gt_f32_e32 vcc, s7, v9
	v_pk_mul_f32 v[36:37], v[16:17], v[42:43]
	v_mov_b32_e32 v42, v38
	v_cndmask_b32_e64 v11, 0, 32, vcc
	v_ldexp_f32 v9, v9, v11
	v_log_f32_e32 v9, v9
	v_pk_fma_f32 v[36:37], v[14:15], v[46:47], v[36:37]
	v_mov_b32_e32 v43, v44
	v_pk_fma_f32 v[36:37], v[18:19], v[42:43], v[36:37]
	v_mul_f32_e32 v11, 0x3f317217, v9
	v_fma_f32 v11, v9, s8, -v11
	v_fmac_f32_e32 v11, 0x3377d1cf, v9
	v_fmac_f32_e32 v11, 0x3f317217, v9
	v_cmp_lt_f32_e64 s[42:43], |v9|, s9
	v_mov_b32_e32 v44, v39
	v_pk_fma_f32 v[36:37], v[20:21], v[44:45], v[36:37]
	v_cndmask_b32_e64 v9, v9, v11, s[42:43]
	v_cndmask_b32_e32 v11, 0, v222, vcc
	v_sub_f32_e32 v34, v9, v11
	v_add_f32_e32 v9, v40, v36
	v_add_f32_e32 v9, v9, v37
	ds_read_b128 v[36:39], v1 offset:416
	ds_read_b128 v[42:45], v1 offset:432
	s_waitcnt lgkmcnt(1)
	v_mov_b32_e32 v46, v36
	s_waitcnt lgkmcnt(0)
	v_mov_b32_e32 v47, v42
	v_mov_b32_e32 v42, v37
	v_pk_mul_f32 v[36:37], v[24:25], v[42:43]
	v_mov_b32_e32 v42, v38
	v_pk_fma_f32 v[36:37], v[22:23], v[46:47], v[36:37]
	v_mov_b32_e32 v43, v44
	v_pk_fma_f32 v[36:37], v[26:27], v[42:43], v[36:37]
	v_mov_b32_e32 v44, v39
	v_pk_fma_f32 v[36:37], v[28:29], v[44:45], v[36:37]
	s_nop 0
	v_add_f32_e32 v9, v9, v36
	v_add_f32_e32 v11, v9, v37
	v_max_f32_e64 v9, -v11, 0
	v_mul_f32_e64 v11, |v11|, s6
	v_exp_f32_e32 v11, v11
	ds_read_b128 v[36:39], v1 offset:448
	ds_read_b128 v[42:45], v1 offset:464
	v_add_f32_e32 v11, 1.0, v11
	v_cmp_gt_f32_e32 vcc, s7, v11
	s_waitcnt lgkmcnt(0)
; DI void gla_gate_items(unsigned char* lds, const float* GLR, unsigned short* LA, int first, int stride, int nitems, const float* wgate, const float* bgate) {
;     ...
;         for (int j = 0; j < 16; j += 2) {
;             float la[2];
; #pragma unroll
;             for (int q = 0; q < 2; ++q) {
;                 const f32x4* gr = (const f32x4*)(GLRS + (16 * rg + j + q) * 16); float x = bg;
; #pragma unroll
;                 for (int i = 0; i < 4; ++i) { const f32x4 gv = gr[i]; x += gv.x * wg[4 * i] + gv.y * wg[4 * i + 1] + gv.z * wg[4 * i + 2] + gv.w * wg[4 * i + 3]; }
;                 la[q] = -(fmaxf(-x, 0.f) + __logf(1.f + __expf(-fabsf(x)))) * (1.f / 16.f);
;             }
;             const _Float16 h0 = (_Float16)la[0], h1 = (_Float16)la[1];
;             pk[j >> 1] = (unsigned)__builtin_bit_cast(unsigned short, h0) | ((unsigned)__builtin_bit_cast(unsigned short, h1) << 16);
	v_mov_b32_e32 v47, v42
	v_mov_b32_e32 v42, v37
	v_cndmask_b32_e64 v13, 0, 32, vcc
	v_ldexp_f32 v11, v11, v13
	v_log_f32_e32 v11, v11
	v_mov_b32_e32 v46, v36
	v_pk_mul_f32 v[36:37], v[16:17], v[42:43]
	v_mov_b32_e32 v42, v38
	v_mul_f32_e32 v13, 0x3f317217, v11
	v_fma_f32 v13, v11, s8, -v13
	v_fmac_f32_e32 v13, 0x3377d1cf, v11
	v_pk_fma_f32 v[36:37], v[14:15], v[46:47], v[36:37]
	v_mov_b32_e32 v43, v44
	v_fmac_f32_e32 v13, 0x3f317217, v11
	v_cmp_lt_f32_e64 s[42:43], |v11|, s9
	v_pk_fma_f32 v[36:37], v[18:19], v[42:43], v[36:37]
	v_mov_b32_e32 v44, v39
	v_cndmask_b32_e64 v11, v11, v13, s[42:43]
	v_cndmask_b32_e32 v13, 0, v222, vcc
	v_pk_fma_f32 v[36:37], v[20:21], v[44:45], v[36:37]
	v_sub_f32_e32 v11, v11, v13
	v_add_f32_e32 v13, v40, v36
	v_add_f32_e32 v13, v13, v37
	ds_read_b128 v[36:39], v1 offset:480
	ds_read_b128 v[42:45], v1 offset:496
	v_pk_add_f32 v[8:9], v[8:9], v[10:11]
	s_waitcnt lgkmcnt(1)
	v_mov_b32_e32 v46, v36
	s_waitcnt lgkmcnt(0)
	v_mov_b32_e32 v47, v42
	v_mov_b32_e32 v42, v37
	v_pk_mul_f32 v[36:37], v[24:25], v[42:43]
	v_mov_b32_e32 v42, v38
	v_pk_fma_f32 v[36:37], v[22:23], v[46:47], v[36:37]
	v_mov_b32_e32 v43, v44
	v_pk_fma_f32 v[36:37], v[26:27], v[42:43], v[36:37]
	v_mov_b32_e32 v44, v39
	v_pk_fma_f32 v[36:37], v[28:29], v[44:45], v[36:37]
	v_pk_mul_f32 v[8:9], v[8:9], s[10:11] op_sel_hi:[1,0]
	v_add_f32_e32 v13, v13, v36
	v_add_f32_e32 v35, v13, v37
	v_max_f32_e64 v13, -v35, 0
	v_mul_f32_e64 v35, |v35|, s6
	v_exp_f32_e32 v35, v35
	v_cvt_pk_f16_f32 v8, v8, v9
	v_add_f32_e32 v35, 1.0, v35
	v_cmp_gt_f32_e32 vcc, s7, v35
	s_nop 1
	v_cndmask_b32_e64 v36, 0, 32, vcc
	v_ldexp_f32 v35, v35, v36
	v_log_f32_e32 v35, v35
	s_nop 0
	v_mul_f32_e32 v36, 0x3f317217, v35
	v_fma_f32 v36, v35, s8, -v36
	v_fmac_f32_e32 v36, 0x3377d1cf, v35
	v_fmac_f32_e32 v36, 0x3f317217, v35
	v_cmp_lt_f32_e64 s[42:43], |v35|, s9
	s_nop 1
	v_cndmask_b32_e64 v35, v35, v36, s[42:43]
	v_cndmask_b32_e32 v36, 0, v222, vcc
	v_sub_f32_e32 v35, v35, v36
	v_pk_add_f32 v[10:11], v[12:13], v[34:35]
	s_nop 0
	v_pk_mul_f32 v[10:11], v[10:11], s[10:11] op_sel_hi:[1,0]
	s_nop 0
	v_cvt_pk_f16_f32 v9, v10, v11
	v_and_b32_e32 v10, 0xffff0000, v9
	v_lshlrev_b32_e32 v11, 16, v9
	v_or_b32_sdwa v9, v10, v8 dst_sel:DWORD dst_unused:UNUSED_PAD src0_sel:DWORD src1_sel:WORD_1
	v_or_b32_sdwa v8, v11, v8 dst_sel:DWORD dst_unused:UNUSED_PAD src0_sel:DWORD src1_sel:WORD_0
	ds_read_b128 v[10:13], v1 offset:512
	ds_read_b128 v[34:37], v1 offset:528
	s_waitcnt lgkmcnt(1)
	v_mov_b32_e32 v38, v10
	s_waitcnt lgkmcnt(0)
	v_mov_b32_e32 v39, v34
	v_mov_b32_e32 v34, v11
	v_pk_mul_f32 v[10:11], v[16:17], v[34:35]
	v_mov_b32_e32 v34, v12
	v_pk_fma_f32 v[10:11], v[14:15], v[38:39], v[10:11]
	v_mov_b32_e32 v35, v36
	v_pk_fma_f32 v[10:11], v[18:19], v[34:35], v[10:11]
	v_mov_b32_e32 v36, v13
	v_pk_fma_f32 v[10:11], v[20:21], v[36:37], v[10:11]
	s_nop 0
	v_add_f32_e32 v10, v40, v10
	v_add_f32_e32 v42, v10, v11
	ds_read_b128 v[10:13], v1 offset:544
	ds_read_b128 v[34:37], v1 offset:560
	s_waitcnt lgkmcnt(1)
	v_mov_b32_e32 v38, v10
	s_waitcnt lgkmcnt(0)
	v_mov_b32_e32 v39, v34
	v_mov_b32_e32 v34, v11
	v_pk_mul_f32 v[10:11], v[24:25], v[34:35]
	v_mov_b32_e32 v34, v12
	v_pk_fma_f32 v[10:11], v[22:23], v[38:39], v[10:11]
	v_mov_b32_e32 v35, v36
	v_pk_fma_f32 v[10:11], v[26:27], v[34:35], v[10:11]
	v_mov_b32_e32 v36, v13
	v_pk_fma_f32 v[10:11], v[28:29], v[36:37], v[10:11]
	s_nop 0
	v_add_f32_e32 v10, v42, v10
	v_add_f32_e32 v11, v10, v11
	v_max_f32_e64 v10, -v11, 0
	v_mul_f32_e64 v11, |v11|, s6
	v_exp_f32_e32 v11, v11
	ds_read_b128 v[34:37], v1 offset:576
	ds_read_b128 v[42:45], v1 offset:592
	v_add_f32_e32 v11, 1.0, v11
	v_cmp_gt_f32_e32 vcc, s7, v11
	s_waitcnt lgkmcnt(0)
	v_mov_b32_e32 v39, v42
	v_mov_b32_e32 v42, v35
	v_cndmask_b32_e64 v12, 0, 32, vcc
	v_ldexp_f32 v11, v11, v12
	v_log_f32_e32 v11, v11
	v_mov_b32_e32 v38, v34
	v_pk_mul_f32 v[34:35], v[16:17], v[42:43]
	v_mul_f32_e32 v12, 0x3f317217, v11
	v_fma_f32 v12, v11, s8, -v12
	v_fmac_f32_e32 v12, 0x3377d1cf, v11
	v_pk_fma_f32 v[34:35], v[14:15], v[38:39], v[34:35]
	v_mov_b32_e32 v38, v36
	v_mov_b32_e32 v39, v44
	v_fmac_f32_e32 v12, 0x3f317217, v11
	v_cmp_lt_f32_e64 s[42:43], |v11|, s9
	v_pk_fma_f32 v[34:35], v[18:19], v[38:39], v[34:35]
	v_mov_b32_e32 v44, v37
	v_cndmask_b32_e64 v11, v11, v12, s[42:43]
	v_cndmask_b32_e32 v12, 0, v222, vcc
	v_pk_fma_f32 v[34:35], v[20:21], v[44:45], v[34:35]
	v_sub_f32_e32 v12, v11, v12
	v_add_f32_e32 v11, v40, v34
	v_add_f32_e32 v11, v11, v35
	ds_read_b128 v[34:37], v1 offset:608
	ds_read_b128 v[42:45], v1 offset:624
	s_waitcnt lgkmcnt(1)
	v_mov_b32_e32 v38, v34
	s_waitcnt lgkmcnt(0)
	v_mov_b32_e32 v39, v42
	v_mov_b32_e32 v42, v35
	v_pk_mul_f32 v[34:35], v[24:25], v[42:43]
	s_nop 0
	v_pk_fma_f32 v[34:35], v[22:23], v[38:39], v[34:35]
	v_mov_b32_e32 v38, v36
	v_mov_b32_e32 v39, v44
	v_pk_fma_f32 v[34:35], v[26:27], v[38:39], v[34:35]
	v_mov_b32_e32 v44, v37
	v_pk_fma_f32 v[34:35], v[28:29], v[44:45], v[34:35]
	ds_read_b128 v[42:45], v1 offset:640
	ds_read_b128 v[46:49], v1 offset:656
	v_add_f32_e32 v11, v11, v34
	v_add_f32_e32 v11, v11, v35
	v_max_f32_e64 v34, -v11, 0
	v_mul_f32_e64 v11, |v11|, s6
	v_exp_f32_e32 v11, v11
	s_waitcnt lgkmcnt(0)
; DI void gla_gate_items(unsigned char* lds, const float* GLR, unsigned short* LA, int first, int stride, int nitems, const float* wgate, const float* bgate) {
;     ...
;         for (int j = 0; j < 16; j += 2) {
;             float la[2];
; #pragma unroll
;             for (int q = 0; q < 2; ++q) {
;                 const f32x4* gr = (const f32x4*)(GLRS + (16 * rg + j + q) * 16); float x = bg;
; #pragma unroll
;                 for (int i = 0; i < 4; ++i) { const f32x4 gv = gr[i]; x += gv.x * wg[4 * i] + gv.y * wg[4 * i + 1] + gv.z * wg[4 * i + 2] + gv.w * wg[4 * i + 3]; }
;                 la[q] = -(fmaxf(-x, 0.f) + __logf(1.f + __expf(-fabsf(x)))) * (1.f / 16.f);
;             }
;             const _Float16 h0 = (_Float16)la[0], h1 = (_Float16)la[1];
;             pk[j >> 1] = (unsigned)__builtin_bit_cast(unsigned short, h0) | ((unsigned)__builtin_bit_cast(unsigned short, h1) << 16);
	v_mov_b32_e32 v39, v46
	v_mov_b32_e32 v46, v43
	v_mov_b32_e32 v38, v42
	v_add_f32_e32 v11, 1.0, v11
	v_cmp_gt_f32_e32 vcc, s7, v11
	v_pk_mul_f32 v[42:43], v[16:17], v[46:47]
	s_nop 0
	v_cndmask_b32_e64 v13, 0, 32, vcc
	v_ldexp_f32 v11, v11, v13
	v_log_f32_e32 v11, v11
	v_pk_fma_f32 v[38:39], v[14:15], v[38:39], v[42:43]
	v_mov_b32_e32 v42, v44
	v_mov_b32_e32 v43, v48
	v_mul_f32_e32 v13, 0x3f317217, v11
	v_pk_fma_f32 v[38:39], v[18:19], v[42:43], v[38:39]
	v_mov_b32_e32 v48, v45
	v_fma_f32 v13, v11, s8, -v13
	v_pk_fma_f32 v[38:39], v[20:21], v[48:49], v[38:39]
	ds_read_b128 v[42:45], v1 offset:672
	ds_read_b128 v[46:49], v1 offset:688
	v_fmac_f32_e32 v13, 0x3377d1cf, v11
	v_fmac_f32_e32 v13, 0x3f317217, v11
	v_cmp_lt_f32_e64 s[42:43], |v11|, s9
	s_nop 1
	v_cndmask_b32_e64 v11, v11, v13, s[42:43]
	v_cndmask_b32_e32 v13, 0, v222, vcc
	v_sub_f32_e32 v36, v11, v13
	v_add_f32_e32 v11, v40, v38
	v_add_f32_e32 v11, v11, v39
	s_waitcnt lgkmcnt(0)
	v_mov_b32_e32 v39, v46
	v_mov_b32_e32 v46, v43
	v_mov_b32_e32 v38, v42
	v_pk_mul_f32 v[42:43], v[24:25], v[46:47]
	s_nop 0
	v_pk_fma_f32 v[38:39], v[22:23], v[38:39], v[42:43]
	v_mov_b32_e32 v42, v44
	v_mov_b32_e32 v43, v48
	v_pk_fma_f32 v[38:39], v[26:27], v[42:43], v[38:39]
	v_mov_b32_e32 v48, v45
	v_pk_fma_f32 v[38:39], v[28:29], v[48:49], v[38:39]
	ds_read_b128 v[42:45], v1 offset:704
	ds_read_b128 v[46:49], v1 offset:720
	v_add_f32_e32 v11, v11, v38
	v_add_f32_e32 v13, v11, v39
	v_max_f32_e64 v11, -v13, 0
	v_mul_f32_e64 v13, |v13|, s6
	v_exp_f32_e32 v13, v13
	s_waitcnt lgkmcnt(0)
	v_mov_b32_e32 v39, v46
	v_mov_b32_e32 v46, v43
	v_mov_b32_e32 v38, v42
	v_add_f32_e32 v13, 1.0, v13
	v_cmp_gt_f32_e32 vcc, s7, v13
	v_pk_mul_f32 v[42:43], v[16:17], v[46:47]
	s_nop 0
	v_cndmask_b32_e64 v35, 0, 32, vcc
	v_ldexp_f32 v13, v13, v35
	v_log_f32_e32 v13, v13
	v_pk_fma_f32 v[38:39], v[14:15], v[38:39], v[42:43]
	v_mov_b32_e32 v42, v44
	v_mov_b32_e32 v43, v48
	v_mul_f32_e32 v35, 0x3f317217, v13
	v_pk_fma_f32 v[38:39], v[18:19], v[42:43], v[38:39]
	v_mov_b32_e32 v48, v45
	v_fma_f32 v35, v13, s8, -v35
	v_pk_fma_f32 v[38:39], v[20:21], v[48:49], v[38:39]
	ds_read_b128 v[42:45], v1 offset:736
	ds_read_b128 v[46:49], v1 offset:752
	v_fmac_f32_e32 v35, 0x3377d1cf, v13
	v_fmac_f32_e32 v35, 0x3f317217, v13
	v_cmp_lt_f32_e64 s[42:43], |v13|, s9
	s_nop 1
	v_cndmask_b32_e64 v13, v13, v35, s[42:43]
	v_cndmask_b32_e32 v35, 0, v222, vcc
	v_sub_f32_e32 v13, v13, v35
	v_add_f32_e32 v35, v40, v38
	v_add_f32_e32 v35, v35, v39
	s_waitcnt lgkmcnt(0)
	v_mov_b32_e32 v39, v46
	v_mov_b32_e32 v46, v43
	v_mov_b32_e32 v38, v42
	v_pk_mul_f32 v[42:43], v[24:25], v[46:47]
	v_pk_add_f32 v[10:11], v[10:11], v[12:13]
	v_pk_fma_f32 v[38:39], v[22:23], v[38:39], v[42:43]
	v_mov_b32_e32 v42, v44
	v_mov_b32_e32 v43, v48
	v_pk_fma_f32 v[38:39], v[26:27], v[42:43], v[38:39]
	v_mov_b32_e32 v48, v45
	v_pk_fma_f32 v[38:39], v[28:29], v[48:49], v[38:39]
	v_pk_mul_f32 v[10:11], v[10:11], s[10:11] op_sel_hi:[1,0]
	v_add_f32_e32 v35, v35, v38
	v_add_f32_e32 v37, v35, v39
	v_max_f32_e64 v35, -v37, 0
	v_mul_f32_e64 v37, |v37|, s6
	v_exp_f32_e32 v37, v37
	v_cvt_pk_f16_f32 v10, v10, v11
	v_add_f32_e32 v37, 1.0, v37
	v_cmp_gt_f32_e32 vcc, s7, v37
	s_nop 1
	v_cndmask_b32_e64 v38, 0, 32, vcc
	v_ldexp_f32 v37, v37, v38
	v_log_f32_e32 v37, v37
	s_nop 0
	v_mul_f32_e32 v38, 0x3f317217, v37
	v_fma_f32 v38, v37, s8, -v38
	v_fmac_f32_e32 v38, 0x3377d1cf, v37
	v_fmac_f32_e32 v38, 0x3f317217, v37
	v_cmp_lt_f32_e64 s[42:43], |v37|, s9
	s_nop 1
	v_cndmask_b32_e64 v37, v37, v38, s[42:43]
	v_cndmask_b32_e32 v38, 0, v222, vcc
	v_sub_f32_e32 v37, v37, v38
	v_pk_add_f32 v[12:13], v[34:35], v[36:37]
	ds_read_b128 v[34:37], v1 offset:768
	ds_read_b128 v[42:45], v1 offset:784
	v_pk_mul_f32 v[12:13], v[12:13], s[10:11] op_sel_hi:[1,0]
	s_nop 0
	v_cvt_pk_f16_f32 v11, v12, v13
	v_and_b32_e32 v12, 0xffff0000, v11
	v_lshlrev_b32_e32 v13, 16, v11
	v_or_b32_sdwa v11, v12, v10 dst_sel:DWORD dst_unused:UNUSED_PAD src0_sel:DWORD src1_sel:WORD_1
	v_or_b32_sdwa v10, v13, v10 dst_sel:DWORD dst_unused:UNUSED_PAD src0_sel:DWORD src1_sel:WORD_0
	s_waitcnt lgkmcnt(0)
	v_mov_b32_e32 v13, v42
	v_mov_b32_e32 v42, v35
	v_mov_b32_e32 v12, v34
	v_pk_mul_f32 v[34:35], v[16:17], v[42:43]
	s_nop 0
	v_pk_fma_f32 v[12:13], v[14:15], v[12:13], v[34:35]
	v_mov_b32_e32 v34, v36
	v_mov_b32_e32 v35, v44
	v_pk_fma_f32 v[12:13], v[18:19], v[34:35], v[12:13]
	v_mov_b32_e32 v44, v37
	v_pk_fma_f32 v[12:13], v[20:21], v[44:45], v[12:13]
	ds_read_b128 v[34:37], v1 offset:800
	ds_read_b128 v[42:45], v1 offset:816
	v_add_f32_e32 v12, v40, v12
	v_add_f32_e32 v38, v12, v13
	s_waitcnt lgkmcnt(1)
	v_mov_b32_e32 v12, v34
	s_waitcnt lgkmcnt(0)
	v_mov_b32_e32 v13, v42
	v_mov_b32_e32 v42, v35
	v_pk_mul_f32 v[34:35], v[24:25], v[42:43]
	s_nop 0
	v_pk_fma_f32 v[12:13], v[22:23], v[12:13], v[34:35]
	v_mov_b32_e32 v34, v36
	v_mov_b32_e32 v35, v44
	v_pk_fma_f32 v[12:13], v[26:27], v[34:35], v[12:13]
	v_mov_b32_e32 v44, v37
	v_pk_fma_f32 v[12:13], v[28:29], v[44:45], v[12:13]
	s_nop 0
	v_add_f32_e32 v12, v38, v12
	v_add_f32_e32 v13, v12, v13
	v_max_f32_e64 v12, -v13, 0
	v_mul_f32_e64 v13, |v13|, s6
	v_exp_f32_e32 v13, v13
	ds_read_b128 v[36:39], v1 offset:832
	ds_read_b128 v[42:45], v1 offset:848
	v_add_f32_e32 v13, 1.0, v13
	v_cmp_gt_f32_e32 vcc, s7, v13
	s_waitcnt lgkmcnt(0)
; DI void gla_gate_items(unsigned char* lds, const float* GLR, unsigned short* LA, int first, int stride, int nitems, const float* wgate, const float* bgate) {
;     ...
; #pragma unroll
;         for (int j = 0; j < 16; j += 2) {
;             float la[2];
; #pragma unroll
;             for (int q = 0; q < 2; ++q) {
;                 const f32x4* gr = (const f32x4*)(GLRS + (16 * rg + j + q) * 16); float x = bg;
; #pragma unroll
;                 for (int i = 0; i < 4; ++i) { const f32x4 gv = gr[i]; x += gv.x * wg[4 * i] + gv.y * wg[4 * i + 1] + gv.z * wg[4 * i + 2] + gv.w * wg[4 * i + 3]; }
;                 la[q] = -(fmaxf(-x, 0.f) + __logf(1.f + __expf(-fabsf(x)))) * (1.f / 16.f);
;             }
;             const _Float16 h0 = (_Float16)la[0], h1 = (_Float16)la[1];
;             pk[j >> 1] = (unsigned)__builtin_bit_cast(unsigned short, h0) | ((unsigned)__builtin_bit_cast(unsigned short, h1) << 16);
;         }
;         u32x4* dst = (u32x4*)(LA + ((((size_t)cidx * 4 + h) * 4 + rg) * 128 + dcol) * 16);
;         dst[0] = (u32x4){pk[0], pk[1], pk[2], pk[3]}; dst[1] = (u32x4){pk[4], pk[5], pk[6], pk[7]};
	v_mov_b32_e32 v47, v42
	v_mov_b32_e32 v42, v37
	v_cndmask_b32_e64 v34, 0, 32, vcc
	v_ldexp_f32 v13, v13, v34
	v_log_f32_e32 v13, v13
	v_mov_b32_e32 v46, v36
	v_pk_mul_f32 v[36:37], v[16:17], v[42:43]
	v_mov_b32_e32 v42, v38
	v_mul_f32_e32 v34, 0x3f317217, v13
	v_fma_f32 v34, v13, s8, -v34
	v_fmac_f32_e32 v34, 0x3377d1cf, v13
	v_pk_fma_f32 v[36:37], v[14:15], v[46:47], v[36:37]
	v_mov_b32_e32 v43, v44
	v_fmac_f32_e32 v34, 0x3f317217, v13
	v_cmp_lt_f32_e64 s[42:43], |v13|, s9
	v_pk_fma_f32 v[36:37], v[18:19], v[42:43], v[36:37]
	v_mov_b32_e32 v44, v39
	v_cndmask_b32_e64 v13, v13, v34, s[42:43]
	v_cndmask_b32_e32 v34, 0, v222, vcc
	v_pk_fma_f32 v[36:37], v[20:21], v[44:45], v[36:37]
	v_sub_f32_e32 v34, v13, v34
	v_add_f32_e32 v13, v40, v36
	v_add_f32_e32 v13, v13, v37
	ds_read_b128 v[36:39], v1 offset:864
	ds_read_b128 v[42:45], v1 offset:880
	s_waitcnt lgkmcnt(1)
	v_mov_b32_e32 v46, v36
	s_waitcnt lgkmcnt(0)
	v_mov_b32_e32 v47, v42
	v_mov_b32_e32 v42, v37
	v_pk_mul_f32 v[36:37], v[24:25], v[42:43]
	v_mov_b32_e32 v42, v38
	v_pk_fma_f32 v[36:37], v[22:23], v[46:47], v[36:37]
	v_mov_b32_e32 v43, v44
	v_pk_fma_f32 v[36:37], v[26:27], v[42:43], v[36:37]
	v_mov_b32_e32 v44, v39
	v_pk_fma_f32 v[36:37], v[28:29], v[44:45], v[36:37]
	ds_read_b128 v[42:45], v1 offset:896
	ds_read_b128 v[46:49], v1 offset:912
	v_add_f32_e32 v13, v13, v36
	v_add_f32_e32 v13, v13, v37
	v_max_f32_e64 v36, -v13, 0
	v_mul_f32_e64 v13, |v13|, s6
	v_exp_f32_e32 v13, v13
	s_waitcnt lgkmcnt(0)
	v_mov_b32_e32 v51, v46
	v_mov_b32_e32 v46, v43
	v_mov_b32_e32 v50, v42
	v_add_f32_e32 v13, 1.0, v13
	v_cmp_gt_f32_e32 vcc, s7, v13
	v_pk_mul_f32 v[42:43], v[16:17], v[46:47]
	v_mov_b32_e32 v46, v44
	v_cndmask_b32_e64 v35, 0, 32, vcc
	v_ldexp_f32 v13, v13, v35
	v_log_f32_e32 v13, v13
	v_pk_fma_f32 v[42:43], v[14:15], v[50:51], v[42:43]
	v_mov_b32_e32 v47, v48
	v_pk_fma_f32 v[42:43], v[18:19], v[46:47], v[42:43]
	v_mul_f32_e32 v35, 0x3f317217, v13
	v_fma_f32 v35, v13, s8, -v35
	v_fmac_f32_e32 v35, 0x3377d1cf, v13
	v_fmac_f32_e32 v35, 0x3f317217, v13
	v_cmp_lt_f32_e64 s[42:43], |v13|, s9
	v_mov_b32_e32 v48, v45
	v_pk_fma_f32 v[42:43], v[20:21], v[48:49], v[42:43]
	v_cndmask_b32_e64 v13, v13, v35, s[42:43]
	v_cndmask_b32_e32 v35, 0, v222, vcc
	v_sub_f32_e32 v38, v13, v35
	v_add_f32_e32 v13, v40, v42
	v_add_f32_e32 v13, v13, v43
	ds_read_b128 v[42:45], v1 offset:928
	ds_read_b128 v[46:49], v1 offset:944
	s_waitcnt lgkmcnt(1)
	v_mov_b32_e32 v50, v42
	s_waitcnt lgkmcnt(0)
	v_mov_b32_e32 v51, v46
	v_mov_b32_e32 v46, v43
	v_pk_mul_f32 v[42:43], v[24:25], v[46:47]
	v_mov_b32_e32 v46, v44
	v_pk_fma_f32 v[42:43], v[22:23], v[50:51], v[42:43]
	v_mov_b32_e32 v47, v48
	v_pk_fma_f32 v[42:43], v[26:27], v[46:47], v[42:43]
	v_mov_b32_e32 v48, v45
	v_pk_fma_f32 v[42:43], v[28:29], v[48:49], v[42:43]
	s_nop 0
	v_add_f32_e32 v13, v13, v42
	v_add_f32_e32 v35, v13, v43
	v_max_f32_e64 v13, -v35, 0
	v_mul_f32_e64 v35, |v35|, s6
	v_exp_f32_e32 v35, v35
	ds_read_b128 v[42:45], v1 offset:960
	ds_read_b128 v[46:49], v1 offset:976
	v_add_f32_e32 v35, 1.0, v35
	v_cmp_gt_f32_e32 vcc, s7, v35
	s_waitcnt lgkmcnt(0)
	v_mov_b32_e32 v51, v46
	v_mov_b32_e32 v46, v43
	v_cndmask_b32_e64 v37, 0, 32, vcc
	v_ldexp_f32 v35, v35, v37
	v_log_f32_e32 v35, v35
	v_mov_b32_e32 v50, v42
	v_pk_mul_f32 v[42:43], v[16:17], v[46:47]
	v_mov_b32_e32 v46, v44
	v_mul_f32_e32 v37, 0x3f317217, v35
	v_fma_f32 v37, v35, s8, -v37
	v_fmac_f32_e32 v37, 0x3377d1cf, v35
	v_pk_fma_f32 v[42:43], v[14:15], v[50:51], v[42:43]
	v_mov_b32_e32 v47, v48
	v_fmac_f32_e32 v37, 0x3f317217, v35
	v_cmp_lt_f32_e64 s[42:43], |v35|, s9
	v_pk_fma_f32 v[42:43], v[18:19], v[46:47], v[42:43]
	v_mov_b32_e32 v48, v45
	v_cndmask_b32_e64 v35, v35, v37, s[42:43]
	v_cndmask_b32_e32 v37, 0, v222, vcc
	v_pk_fma_f32 v[42:43], v[20:21], v[48:49], v[42:43]
	v_sub_f32_e32 v35, v35, v37
	v_add_f32_e32 v37, v40, v42
	v_add_f32_e32 v37, v37, v43
	ds_read_b128 v[42:45], v1 offset:992
	ds_read_b128 v[46:49], v1 offset:1008
	v_pk_add_f32 v[12:13], v[12:13], v[34:35]
	s_waitcnt lgkmcnt(1)
	v_mov_b32_e32 v50, v42
	s_waitcnt lgkmcnt(0)
	v_mov_b32_e32 v51, v46
	v_mov_b32_e32 v46, v43
	v_pk_mul_f32 v[42:43], v[24:25], v[46:47]
	v_mov_b32_e32 v46, v44
	v_pk_fma_f32 v[42:43], v[22:23], v[50:51], v[42:43]
	v_mov_b32_e32 v47, v48
	v_pk_fma_f32 v[42:43], v[26:27], v[46:47], v[42:43]
	v_mov_b32_e32 v48, v45
	v_pk_fma_f32 v[42:43], v[28:29], v[48:49], v[42:43]
	v_pk_mul_f32 v[12:13], v[12:13], s[10:11] op_sel_hi:[1,0]
	v_add_f32_e32 v37, v37, v42
	v_add_f32_e32 v39, v37, v43
	v_max_f32_e64 v37, -v39, 0
	v_mul_f32_e64 v39, |v39|, s6
	v_exp_f32_e32 v39, v39
	v_cvt_pk_f16_f32 v12, v12, v13
	v_add_f32_e32 v39, 1.0, v39
	v_cmp_gt_f32_e32 vcc, s7, v39
	s_lshl_b64 s[6:7], s[50:51], 16
	s_nop 0
	v_cndmask_b32_e64 v42, 0, 32, vcc
	v_ldexp_f32 v39, v39, v42
	v_log_f32_e32 v39, v39
	s_nop 0
	v_mul_f32_e32 v42, 0x3f317217, v39
	v_fma_f32 v42, v39, s8, -v42
	v_fmac_f32_e32 v42, 0x3377d1cf, v39
	v_fmac_f32_e32 v42, 0x3f317217, v39
	v_cmp_lt_f32_e64 s[42:43], |v39|, s9
	s_nop 1
	v_cndmask_b32_e64 v39, v39, v42, s[42:43]
	v_cndmask_b32_e32 v42, 0, v222, vcc
	v_sub_f32_e32 v39, v39, v42
	v_pk_add_f32 v[34:35], v[36:37], v[38:39]
	s_andn2_b64 vcc, exec, s[48:49]
	v_pk_mul_f32 v[34:35], v[34:35], s[10:11] op_sel_hi:[1,0]
	s_nop 0
	v_cvt_pk_f16_f32 v13, v34, v35
	v_and_b32_e32 v34, 0xffff0000, v13
	v_lshlrev_b32_e32 v35, 16, v13
	v_or_b32_sdwa v13, v34, v12 dst_sel:DWORD dst_unused:UNUSED_PAD src0_sel:DWORD src1_sel:WORD_1
	v_or_b32_sdwa v12, v35, v12 dst_sel:DWORD dst_unused:UNUSED_PAD src0_sel:DWORD src1_sel:WORD_0
	v_lshl_add_u64 v[34:35], v[32:33], 0, s[6:7]
	s_mov_b32 s6, s5
	global_store_dwordx4 v[34:35], v[6:9], off nt
	global_store_dwordx4 v[34:35], v[10:13], off offset:16 nt
	s_cbranch_vccz .LBB0_1058

; DI void gla_gate_items(unsigned char* lds, const float* GLR, unsigned short* LA, int first, int stride, int nitems, const float* wgate, const float* bgate) {
;     ...
;     for (int it = first; it < nitems; it += stride) {
;         const int cidx = it >> 2;
;         __syncthreads();
;         if (tid < 256) *(f32x4*)(GLRS + 4 * tid) = nxt;
;         __syncthreads();
;         if (it + stride < nitems && tid < 256) nxt = *(const f32x4*)(GLR + (size_t)((it + stride) >> 2) * 64 * 16 + 4 * tid);
;         unsigned pk[8];
; #pragma unroll
;         for (int j = 0; j < 16; j += 2) {
;             float la[2];
; #pragma unroll
;             for (int q = 0; q < 2; ++q) {
;                 const f32x4* gr = (const f32x4*)(GLRS + (16 * rg + j + q) * 16); float x = bg;
; #pragma unroll
;                 for (int i = 0; i < 4; ++i) { const f32x4 gv = gr[i]; x += gv.x * wg[4 * i] + gv.y * wg[4 * i + 1] + gv.z * wg[4 * i + 2] + gv.w * wg[4 * i + 3]; }
;                 la[q] = -(fmaxf(-x, 0.f) + __logf(1.f + __expf(-fabsf(x)))) * (1.f / 16.f);
.LBB0_1067:
	s_or_b64 exec, exec, s[42:43]
	ds_read_b128 v[6:9], v1
	ds_read_b128 v[10:13], v1 offset:16
	ds_read_b128 v[34:37], v1 offset:32
	ds_read_b128 v[42:45], v1 offset:48
	s_mov_b32 s5, 0xbfb8aa3b
	s_waitcnt lgkmcnt(3)
	v_mov_b32_e32 v38, v6
	s_waitcnt lgkmcnt(2)
	v_mov_b32_e32 v39, v10
	v_mov_b32_e32 v10, v7
	s_waitcnt vmcnt(11)
	v_pk_mul_f32 v[6:7], v[16:17], v[10:11]
	v_mov_b32_e32 v10, v8
	v_pk_fma_f32 v[6:7], v[14:15], v[38:39], v[6:7]
	v_mov_b32_e32 v11, v12
	s_waitcnt vmcnt(10)
	v_pk_fma_f32 v[6:7], v[18:19], v[10:11], v[6:7]
	v_mov_b32_e32 v12, v9
	s_waitcnt vmcnt(9)
	v_pk_fma_f32 v[6:7], v[20:21], v[12:13], v[6:7]
	s_mov_b32 s6, 0x800000
	s_waitcnt vmcnt(0)
	v_add_f32_e32 v6, v40, v6
	v_add_f32_e32 v10, v6, v7
	s_waitcnt lgkmcnt(0)
	v_mov_b32_e32 v7, v42
	v_mov_b32_e32 v42, v35
	v_mov_b32_e32 v6, v34
	v_pk_mul_f32 v[8:9], v[24:25], v[42:43]
	s_mov_b32 s7, 0x3f317217
	v_pk_fma_f32 v[6:7], v[22:23], v[6:7], v[8:9]
	v_mov_b32_e32 v8, v36
	v_mov_b32_e32 v9, v44
	v_pk_fma_f32 v[6:7], v[26:27], v[8:9], v[6:7]
	v_mov_b32_e32 v44, v37
	v_pk_fma_f32 v[6:7], v[28:29], v[44:45], v[6:7]
	s_mov_b32 s8, 0x7f800000
	v_add_f32_e32 v6, v10, v6
	v_add_f32_e32 v7, v6, v7
	v_max_f32_e64 v6, -v7, 0
	v_mul_f32_e64 v7, |v7|, s5
	v_exp_f32_e32 v7, v7
	ds_read_b128 v[10:13], v1 offset:64
	ds_read_b128 v[34:37], v1 offset:80
	s_mov_b32 s10, 0xbd800000
	v_add_f32_e32 v7, 1.0, v7
	v_cmp_gt_f32_e32 vcc, s6, v7
	s_waitcnt lgkmcnt(0)
	v_mov_b32_e32 v39, v34
	v_mov_b32_e32 v34, v11
	v_cndmask_b32_e64 v8, 0, 32, vcc
	v_ldexp_f32 v7, v7, v8
	v_log_f32_e32 v7, v7
	v_mov_b32_e32 v38, v10
	v_pk_mul_f32 v[10:11], v[16:17], v[34:35]
	v_mov_b32_e32 v34, v12
	v_mul_f32_e32 v8, 0x3f317217, v7
	v_fma_f32 v8, v7, s7, -v8
	v_fmac_f32_e32 v8, 0x3377d1cf, v7
	v_pk_fma_f32 v[10:11], v[14:15], v[38:39], v[10:11]
	v_mov_b32_e32 v35, v36
	v_fmac_f32_e32 v8, 0x3f317217, v7
	v_cmp_lt_f32_e64 s[42:43], |v7|, s8
	v_pk_fma_f32 v[10:11], v[18:19], v[34:35], v[10:11]
	v_mov_b32_e32 v36, v13
	v_cndmask_b32_e64 v7, v7, v8, s[42:43]
	v_cndmask_b32_e32 v8, 0, v222, vcc
	v_pk_fma_f32 v[10:11], v[20:21], v[36:37], v[10:11]
	v_sub_f32_e32 v8, v7, v8
	v_add_f32_e32 v7, v40, v10
	v_add_f32_e32 v7, v7, v11
	ds_read_b128 v[10:13], v1 offset:96
	ds_read_b128 v[34:37], v1 offset:112
	s_waitcnt lgkmcnt(1)
	v_mov_b32_e32 v38, v10
	s_waitcnt lgkmcnt(0)
	v_mov_b32_e32 v39, v34
	v_mov_b32_e32 v34, v11
	v_pk_mul_f32 v[10:11], v[24:25], v[34:35]
	v_mov_b32_e32 v34, v12
	v_pk_fma_f32 v[10:11], v[22:23], v[38:39], v[10:11]
	v_mov_b32_e32 v35, v36
	v_pk_fma_f32 v[10:11], v[26:27], v[34:35], v[10:11]
	v_mov_b32_e32 v36, v13
	v_pk_fma_f32 v[10:11], v[28:29], v[36:37], v[10:11]
	ds_read_b128 v[34:37], v1 offset:128
	ds_read_b128 v[42:45], v1 offset:144
	v_add_f32_e32 v7, v7, v10
	v_add_f32_e32 v7, v7, v11
	v_max_f32_e64 v10, -v7, 0
	v_mul_f32_e64 v7, |v7|, s5
	v_exp_f32_e32 v7, v7
	s_waitcnt lgkmcnt(0)
	v_mov_b32_e32 v39, v42
	v_mov_b32_e32 v42, v35
	v_mov_b32_e32 v38, v34
	v_add_f32_e32 v7, 1.0, v7
	v_cmp_gt_f32_e32 vcc, s6, v7
	v_pk_mul_f32 v[34:35], v[16:17], v[42:43]
	s_nop 0
	v_cndmask_b32_e64 v9, 0, 32, vcc
	v_ldexp_f32 v7, v7, v9
	v_log_f32_e32 v7, v7
	v_pk_fma_f32 v[34:35], v[14:15], v[38:39], v[34:35]
	v_mov_b32_e32 v38, v36
	v_mov_b32_e32 v39, v44
	v_mul_f32_e32 v9, 0x3f317217, v7
	v_fma_f32 v9, v7, s7, -v9
	v_fmac_f32_e32 v9, 0x3377d1cf, v7
	v_fmac_f32_e32 v9, 0x3f317217, v7
	v_cmp_lt_f32_e64 s[42:43], |v7|, s8
	v_pk_fma_f32 v[34:35], v[18:19], v[38:39], v[34:35]
	v_mov_b32_e32 v44, v37
	v_cndmask_b32_e64 v7, v7, v9, s[42:43]
	v_cndmask_b32_e32 v9, 0, v222, vcc
	v_pk_fma_f32 v[34:35], v[20:21], v[44:45], v[34:35]
	v_sub_f32_e32 v12, v7, v9
	v_add_f32_e32 v7, v40, v34
	v_add_f32_e32 v7, v7, v35
	ds_read_b128 v[34:37], v1 offset:160
	ds_read_b128 v[42:45], v1 offset:176
	s_waitcnt lgkmcnt(1)
	v_mov_b32_e32 v38, v34
	s_waitcnt lgkmcnt(0)
	v_mov_b32_e32 v39, v42
	v_mov_b32_e32 v42, v35
	v_pk_mul_f32 v[34:35], v[24:25], v[42:43]
	s_nop 0
	v_pk_fma_f32 v[34:35], v[22:23], v[38:39], v[34:35]
	v_mov_b32_e32 v38, v36
	v_mov_b32_e32 v39, v44
	v_pk_fma_f32 v[34:35], v[26:27], v[38:39], v[34:35]
	v_mov_b32_e32 v44, v37
	v_pk_fma_f32 v[34:35], v[28:29], v[44:45], v[34:35]
	s_nop 0
	v_add_f32_e32 v7, v7, v34
	v_add_f32_e32 v9, v7, v35
	v_max_f32_e64 v7, -v9, 0
	v_mul_f32_e64 v9, |v9|, s5
	v_exp_f32_e32 v9, v9
	ds_read_b128 v[34:37], v1 offset:192
	ds_read_b128 v[42:45], v1 offset:208
	v_add_f32_e32 v9, 1.0, v9
	v_cmp_gt_f32_e32 vcc, s6, v9
	s_waitcnt lgkmcnt(0)
	v_mov_b32_e32 v39, v42
	v_mov_b32_e32 v42, v35
	v_cndmask_b32_e64 v11, 0, 32, vcc
	v_ldexp_f32 v9, v9, v11
	v_log_f32_e32 v9, v9
	v_mov_b32_e32 v38, v34
	v_pk_mul_f32 v[34:35], v[16:17], v[42:43]
	v_mul_f32_e32 v11, 0x3f317217, v9
	v_fma_f32 v11, v9, s7, -v11
	v_fmac_f32_e32 v11, 0x3377d1cf, v9
	v_pk_fma_f32 v[34:35], v[14:15], v[38:39], v[34:35]
	v_mov_b32_e32 v38, v36
	v_mov_b32_e32 v39, v44
	v_fmac_f32_e32 v11, 0x3f317217, v9
	v_cmp_lt_f32_e64 s[42:43], |v9|, s8
	v_pk_fma_f32 v[34:35], v[18:19], v[38:39], v[34:35]
	v_mov_b32_e32 v44, v37
	v_cndmask_b32_e64 v9, v9, v11, s[42:43]
	v_cndmask_b32_e32 v11, 0, v222, vcc
	v_pk_fma_f32 v[34:35], v[20:21], v[44:45], v[34:35]
	v_sub_f32_e32 v9, v9, v11
	v_add_f32_e32 v11, v40, v34
	v_add_f32_e32 v11, v11, v35
	ds_read_b128 v[34:37], v1 offset:224
	ds_read_b128 v[42:45], v1 offset:240
	v_pk_add_f32 v[6:7], v[6:7], v[8:9]
	s_waitcnt lgkmcnt(1)
	v_mov_b32_e32 v38, v34
	s_waitcnt lgkmcnt(0)
; DI void gla_gate_items(unsigned char* lds, const float* GLR, unsigned short* LA, int first, int stride, int nitems, const float* wgate, const float* bgate) {
;     ...
;         for (int j = 0; j < 16; j += 2) {
;             float la[2];
; #pragma unroll
;             for (int q = 0; q < 2; ++q) {
;                 const f32x4* gr = (const f32x4*)(GLRS + (16 * rg + j + q) * 16); float x = bg;
; #pragma unroll
;                 for (int i = 0; i < 4; ++i) { const f32x4 gv = gr[i]; x += gv.x * wg[4 * i] + gv.y * wg[4 * i + 1] + gv.z * wg[4 * i + 2] + gv.w * wg[4 * i + 3]; }
;                 la[q] = -(fmaxf(-x, 0.f) + __logf(1.f + __expf(-fabsf(x)))) * (1.f / 16.f);
;             }
;             const _Float16 h0 = (_Float16)la[0], h1 = (_Float16)la[1];
;             pk[j >> 1] = (unsigned)__builtin_bit_cast(unsigned short, h0) | ((unsigned)__builtin_bit_cast(unsigned short, h1) << 16);
	v_mov_b32_e32 v39, v42
	v_mov_b32_e32 v42, v35
	v_pk_mul_f32 v[34:35], v[24:25], v[42:43]
	v_pk_mul_f32 v[6:7], v[6:7], s[10:11] op_sel_hi:[1,0]
	v_pk_fma_f32 v[34:35], v[22:23], v[38:39], v[34:35]
	v_mov_b32_e32 v38, v36
	v_mov_b32_e32 v39, v44
	v_pk_fma_f32 v[34:35], v[26:27], v[38:39], v[34:35]
	v_mov_b32_e32 v44, v37
	v_pk_fma_f32 v[34:35], v[28:29], v[44:45], v[34:35]
	v_cvt_pk_f16_f32 v6, v6, v7
	v_add_f32_e32 v11, v11, v34
	v_add_f32_e32 v13, v11, v35
	v_max_f32_e64 v11, -v13, 0
	v_mul_f32_e64 v13, |v13|, s5
	v_exp_f32_e32 v13, v13
	s_nop 0
	v_add_f32_e32 v13, 1.0, v13
	v_cmp_gt_f32_e32 vcc, s6, v13
	s_nop 1
	v_cndmask_b32_e64 v34, 0, 32, vcc
	v_ldexp_f32 v13, v13, v34
	v_log_f32_e32 v13, v13
	s_nop 0
	v_mul_f32_e32 v34, 0x3f317217, v13
	v_fma_f32 v34, v13, s7, -v34
	v_fmac_f32_e32 v34, 0x3377d1cf, v13
	v_fmac_f32_e32 v34, 0x3f317217, v13
	v_cmp_lt_f32_e64 s[42:43], |v13|, s8
	s_nop 1
	v_cndmask_b32_e64 v13, v13, v34, s[42:43]
	v_cndmask_b32_e32 v34, 0, v222, vcc
	v_sub_f32_e32 v13, v13, v34
	v_pk_add_f32 v[8:9], v[10:11], v[12:13]
	s_nop 0
	v_pk_mul_f32 v[8:9], v[8:9], s[10:11] op_sel_hi:[1,0]
	s_nop 0
	v_cvt_pk_f16_f32 v7, v8, v9
	v_and_b32_e32 v8, 0xffff0000, v7
	v_lshlrev_b32_e32 v9, 16, v7
	v_or_b32_sdwa v7, v8, v6 dst_sel:DWORD dst_unused:UNUSED_PAD src0_sel:DWORD src1_sel:WORD_1
	v_or_b32_sdwa v6, v9, v6 dst_sel:DWORD dst_unused:UNUSED_PAD src0_sel:DWORD src1_sel:WORD_0
	ds_read_b128 v[8:11], v1 offset:256
	ds_read_b128 v[34:37], v1 offset:272
	s_waitcnt lgkmcnt(1)
	v_mov_b32_e32 v12, v8
	s_waitcnt lgkmcnt(0)
	v_mov_b32_e32 v13, v34
	v_mov_b32_e32 v34, v9
	v_pk_mul_f32 v[8:9], v[16:17], v[34:35]
	s_nop 0
	v_pk_fma_f32 v[8:9], v[14:15], v[12:13], v[8:9]
	v_mov_b32_e32 v12, v10
	v_mov_b32_e32 v13, v36
	v_pk_fma_f32 v[8:9], v[18:19], v[12:13], v[8:9]
	v_mov_b32_e32 v36, v11
	v_pk_fma_f32 v[8:9], v[20:21], v[36:37], v[8:9]
	s_nop 0
	v_add_f32_e32 v8, v40, v8
	v_add_f32_e32 v38, v8, v9
	ds_read_b128 v[8:11], v1 offset:288
	ds_read_b128 v[34:37], v1 offset:304
	s_waitcnt lgkmcnt(1)
	v_mov_b32_e32 v12, v8
	s_waitcnt lgkmcnt(0)
	v_mov_b32_e32 v13, v34
	v_mov_b32_e32 v34, v9
	v_pk_mul_f32 v[8:9], v[24:25], v[34:35]
	s_nop 0
	v_pk_fma_f32 v[8:9], v[22:23], v[12:13], v[8:9]
	v_mov_b32_e32 v12, v10
	v_mov_b32_e32 v13, v36
	v_pk_fma_f32 v[8:9], v[26:27], v[12:13], v[8:9]
	v_mov_b32_e32 v36, v11
	v_pk_fma_f32 v[8:9], v[28:29], v[36:37], v[8:9]
	ds_read_b128 v[34:37], v1 offset:320
	ds_read_b128 v[42:45], v1 offset:336
	v_add_f32_e32 v8, v38, v8
	v_add_f32_e32 v9, v8, v9
	v_max_f32_e64 v8, -v9, 0
	v_mul_f32_e64 v9, |v9|, s5
	v_exp_f32_e32 v9, v9
	s_waitcnt lgkmcnt(0)
	v_mov_b32_e32 v13, v42
	v_mov_b32_e32 v42, v35
	v_mov_b32_e32 v12, v34
	v_add_f32_e32 v9, 1.0, v9
	v_cmp_gt_f32_e32 vcc, s6, v9
	v_pk_mul_f32 v[34:35], v[16:17], v[42:43]
	s_nop 0
	v_cndmask_b32_e64 v10, 0, 32, vcc
	v_ldexp_f32 v9, v9, v10
	v_log_f32_e32 v9, v9
	v_pk_fma_f32 v[12:13], v[14:15], v[12:13], v[34:35]
	v_mov_b32_e32 v34, v36
	v_mov_b32_e32 v35, v44
	v_mul_f32_e32 v10, 0x3f317217, v9
	v_pk_fma_f32 v[12:13], v[18:19], v[34:35], v[12:13]
	v_mov_b32_e32 v44, v37
	v_fma_f32 v10, v9, s7, -v10
	v_pk_fma_f32 v[12:13], v[20:21], v[44:45], v[12:13]
	ds_read_b128 v[34:37], v1 offset:352
	ds_read_b128 v[42:45], v1 offset:368
	v_fmac_f32_e32 v10, 0x3377d1cf, v9
	v_fmac_f32_e32 v10, 0x3f317217, v9
	v_cmp_lt_f32_e64 s[42:43], |v9|, s8
	s_nop 1
	v_cndmask_b32_e64 v9, v9, v10, s[42:43]
	v_cndmask_b32_e32 v10, 0, v222, vcc
	v_sub_f32_e32 v10, v9, v10
	v_add_f32_e32 v9, v40, v12
	v_add_f32_e32 v9, v9, v13
	s_waitcnt lgkmcnt(0)
	v_mov_b32_e32 v13, v42
	v_mov_b32_e32 v42, v35
	v_mov_b32_e32 v12, v34
	v_pk_mul_f32 v[34:35], v[24:25], v[42:43]
	s_nop 0
	v_pk_fma_f32 v[12:13], v[22:23], v[12:13], v[34:35]
	v_mov_b32_e32 v34, v36
	v_mov_b32_e32 v35, v44
	v_pk_fma_f32 v[12:13], v[26:27], v[34:35], v[12:13]
	v_mov_b32_e32 v44, v37
	v_pk_fma_f32 v[12:13], v[28:29], v[44:45], v[12:13]
	ds_read_b128 v[36:39], v1 offset:384
	ds_read_b128 v[42:45], v1 offset:400
	v_add_f32_e32 v9, v9, v12
	v_add_f32_e32 v9, v9, v13
	v_max_f32_e64 v12, -v9, 0
	v_mul_f32_e64 v9, |v9|, s5
	v_exp_f32_e32 v9, v9
	s_waitcnt lgkmcnt(0)
	v_mov_b32_e32 v47, v42
	v_mov_b32_e32 v42, v37
	v_mov_b32_e32 v46, v36
	v_add_f32_e32 v9, 1.0, v9
	v_cmp_gt_f32_e32 vcc, s6, v9
	v_pk_mul_f32 v[36:37], v[16:17], v[42:43]
	v_mov_b32_e32 v42, v38
	v_cndmask_b32_e64 v11, 0, 32, vcc
	v_ldexp_f32 v9, v9, v11
	v_log_f32_e32 v9, v9
	v_pk_fma_f32 v[36:37], v[14:15], v[46:47], v[36:37]
	v_mov_b32_e32 v43, v44
	v_pk_fma_f32 v[36:37], v[18:19], v[42:43], v[36:37]
	v_mul_f32_e32 v11, 0x3f317217, v9
	v_fma_f32 v11, v9, s7, -v11
	v_fmac_f32_e32 v11, 0x3377d1cf, v9
	v_fmac_f32_e32 v11, 0x3f317217, v9
	v_cmp_lt_f32_e64 s[42:43], |v9|, s8
	v_mov_b32_e32 v44, v39
	v_pk_fma_f32 v[36:37], v[20:21], v[44:45], v[36:37]
	v_cndmask_b32_e64 v9, v9, v11, s[42:43]
	v_cndmask_b32_e32 v11, 0, v222, vcc
	v_sub_f32_e32 v34, v9, v11
	v_add_f32_e32 v9, v40, v36
	v_add_f32_e32 v9, v9, v37
	ds_read_b128 v[36:39], v1 offset:416
	ds_read_b128 v[42:45], v1 offset:432
	s_waitcnt lgkmcnt(1)
	v_mov_b32_e32 v46, v36
	s_waitcnt lgkmcnt(0)
	v_mov_b32_e32 v47, v42
	v_mov_b32_e32 v42, v37
	v_pk_mul_f32 v[36:37], v[24:25], v[42:43]
	v_mov_b32_e32 v42, v38
	v_pk_fma_f32 v[36:37], v[22:23], v[46:47], v[36:37]
	v_mov_b32_e32 v43, v44
	v_pk_fma_f32 v[36:37], v[26:27], v[42:43], v[36:37]
	v_mov_b32_e32 v44, v39
	v_pk_fma_f32 v[36:37], v[28:29], v[44:45], v[36:37]
	s_nop 0
	v_add_f32_e32 v9, v9, v36
	v_add_f32_e32 v11, v9, v37
	v_max_f32_e64 v9, -v11, 0
	v_mul_f32_e64 v11, |v11|, s5
	v_exp_f32_e32 v11, v11
	ds_read_b128 v[36:39], v1 offset:448
	ds_read_b128 v[42:45], v1 offset:464
	v_add_f32_e32 v11, 1.0, v11
	v_cmp_gt_f32_e32 vcc, s6, v11
	s_waitcnt lgkmcnt(0)
; DI void gla_gate_items(unsigned char* lds, const float* GLR, unsigned short* LA, int first, int stride, int nitems, const float* wgate, const float* bgate) {
;     ...
;         for (int j = 0; j < 16; j += 2) {
;             float la[2];
; #pragma unroll
;             for (int q = 0; q < 2; ++q) {
;                 const f32x4* gr = (const f32x4*)(GLRS + (16 * rg + j + q) * 16); float x = bg;
; #pragma unroll
;                 for (int i = 0; i < 4; ++i) { const f32x4 gv = gr[i]; x += gv.x * wg[4 * i] + gv.y * wg[4 * i + 1] + gv.z * wg[4 * i + 2] + gv.w * wg[4 * i + 3]; }
;                 la[q] = -(fmaxf(-x, 0.f) + __logf(1.f + __expf(-fabsf(x)))) * (1.f / 16.f);
;             }
;             const _Float16 h0 = (_Float16)la[0], h1 = (_Float16)la[1];
;             pk[j >> 1] = (unsigned)__builtin_bit_cast(unsigned short, h0) | ((unsigned)__builtin_bit_cast(unsigned short, h1) << 16);
	v_mov_b32_e32 v47, v42
	v_mov_b32_e32 v42, v37
	v_cndmask_b32_e64 v13, 0, 32, vcc
	v_ldexp_f32 v11, v11, v13
	v_log_f32_e32 v11, v11
	v_mov_b32_e32 v46, v36
	v_pk_mul_f32 v[36:37], v[16:17], v[42:43]
	v_mov_b32_e32 v42, v38
	v_mul_f32_e32 v13, 0x3f317217, v11
	v_fma_f32 v13, v11, s7, -v13
	v_fmac_f32_e32 v13, 0x3377d1cf, v11
	v_pk_fma_f32 v[36:37], v[14:15], v[46:47], v[36:37]
	v_mov_b32_e32 v43, v44
	v_fmac_f32_e32 v13, 0x3f317217, v11
	v_cmp_lt_f32_e64 s[42:43], |v11|, s8
	v_pk_fma_f32 v[36:37], v[18:19], v[42:43], v[36:37]
	v_mov_b32_e32 v44, v39
	v_cndmask_b32_e64 v11, v11, v13, s[42:43]
	v_cndmask_b32_e32 v13, 0, v222, vcc
	v_pk_fma_f32 v[36:37], v[20:21], v[44:45], v[36:37]
	v_sub_f32_e32 v11, v11, v13
	v_add_f32_e32 v13, v40, v36
	v_add_f32_e32 v13, v13, v37
	ds_read_b128 v[36:39], v1 offset:480
	ds_read_b128 v[42:45], v1 offset:496
	v_pk_add_f32 v[8:9], v[8:9], v[10:11]
	s_waitcnt lgkmcnt(1)
	v_mov_b32_e32 v46, v36
	s_waitcnt lgkmcnt(0)
	v_mov_b32_e32 v47, v42
	v_mov_b32_e32 v42, v37
	v_pk_mul_f32 v[36:37], v[24:25], v[42:43]
	v_mov_b32_e32 v42, v38
	v_pk_fma_f32 v[36:37], v[22:23], v[46:47], v[36:37]
	v_mov_b32_e32 v43, v44
	v_pk_fma_f32 v[36:37], v[26:27], v[42:43], v[36:37]
	v_mov_b32_e32 v44, v39
	v_pk_fma_f32 v[36:37], v[28:29], v[44:45], v[36:37]
	v_pk_mul_f32 v[8:9], v[8:9], s[10:11] op_sel_hi:[1,0]
	v_add_f32_e32 v13, v13, v36
	v_add_f32_e32 v35, v13, v37
	v_max_f32_e64 v13, -v35, 0
	v_mul_f32_e64 v35, |v35|, s5
	v_exp_f32_e32 v35, v35
	v_cvt_pk_f16_f32 v8, v8, v9
	v_add_f32_e32 v35, 1.0, v35
	v_cmp_gt_f32_e32 vcc, s6, v35
	s_nop 1
	v_cndmask_b32_e64 v36, 0, 32, vcc
	v_ldexp_f32 v35, v35, v36
	v_log_f32_e32 v35, v35
	s_nop 0
	v_mul_f32_e32 v36, 0x3f317217, v35
	v_fma_f32 v36, v35, s7, -v36
	v_fmac_f32_e32 v36, 0x3377d1cf, v35
	v_fmac_f32_e32 v36, 0x3f317217, v35
	v_cmp_lt_f32_e64 s[42:43], |v35|, s8
	s_nop 1
	v_cndmask_b32_e64 v35, v35, v36, s[42:43]
	v_cndmask_b32_e32 v36, 0, v222, vcc
	v_sub_f32_e32 v35, v35, v36
	v_pk_add_f32 v[10:11], v[12:13], v[34:35]
	s_nop 0
	v_pk_mul_f32 v[10:11], v[10:11], s[10:11] op_sel_hi:[1,0]
	s_nop 0
	v_cvt_pk_f16_f32 v9, v10, v11
	v_and_b32_e32 v10, 0xffff0000, v9
	v_lshlrev_b32_e32 v11, 16, v9
	v_or_b32_sdwa v9, v10, v8 dst_sel:DWORD dst_unused:UNUSED_PAD src0_sel:DWORD src1_sel:WORD_1
	v_or_b32_sdwa v8, v11, v8 dst_sel:DWORD dst_unused:UNUSED_PAD src0_sel:DWORD src1_sel:WORD_0
	ds_read_b128 v[10:13], v1 offset:512
	ds_read_b128 v[34:37], v1 offset:528
	s_waitcnt lgkmcnt(1)
	v_mov_b32_e32 v38, v10
	s_waitcnt lgkmcnt(0)
	v_mov_b32_e32 v39, v34
	v_mov_b32_e32 v34, v11
	v_pk_mul_f32 v[10:11], v[16:17], v[34:35]
	v_mov_b32_e32 v34, v12
	v_pk_fma_f32 v[10:11], v[14:15], v[38:39], v[10:11]
	v_mov_b32_e32 v35, v36
	v_pk_fma_f32 v[10:11], v[18:19], v[34:35], v[10:11]
	v_mov_b32_e32 v36, v13
	v_pk_fma_f32 v[10:11], v[20:21], v[36:37], v[10:11]
	s_nop 0
	v_add_f32_e32 v10, v40, v10
	v_add_f32_e32 v42, v10, v11
	ds_read_b128 v[10:13], v1 offset:544
	ds_read_b128 v[34:37], v1 offset:560
	s_waitcnt lgkmcnt(1)
	v_mov_b32_e32 v38, v10
	s_waitcnt lgkmcnt(0)
	v_mov_b32_e32 v39, v34
	v_mov_b32_e32 v34, v11
	v_pk_mul_f32 v[10:11], v[24:25], v[34:35]
	v_mov_b32_e32 v34, v12
	v_pk_fma_f32 v[10:11], v[22:23], v[38:39], v[10:11]
	v_mov_b32_e32 v35, v36
	v_pk_fma_f32 v[10:11], v[26:27], v[34:35], v[10:11]
	v_mov_b32_e32 v36, v13
	v_pk_fma_f32 v[10:11], v[28:29], v[36:37], v[10:11]
	s_nop 0
	v_add_f32_e32 v10, v42, v10
	v_add_f32_e32 v11, v10, v11
	v_max_f32_e64 v10, -v11, 0
	v_mul_f32_e64 v11, |v11|, s5
	v_exp_f32_e32 v11, v11
	ds_read_b128 v[34:37], v1 offset:576
	ds_read_b128 v[42:45], v1 offset:592
	v_add_f32_e32 v11, 1.0, v11
	v_cmp_gt_f32_e32 vcc, s6, v11
	s_waitcnt lgkmcnt(0)
	v_mov_b32_e32 v39, v42
	v_mov_b32_e32 v42, v35
	v_cndmask_b32_e64 v12, 0, 32, vcc
	v_ldexp_f32 v11, v11, v12
	v_log_f32_e32 v11, v11
	v_mov_b32_e32 v38, v34
	v_pk_mul_f32 v[34:35], v[16:17], v[42:43]
	v_mul_f32_e32 v12, 0x3f317217, v11
	v_fma_f32 v12, v11, s7, -v12
	v_fmac_f32_e32 v12, 0x3377d1cf, v11
	v_pk_fma_f32 v[34:35], v[14:15], v[38:39], v[34:35]
	v_mov_b32_e32 v38, v36
	v_mov_b32_e32 v39, v44
	v_fmac_f32_e32 v12, 0x3f317217, v11
	v_cmp_lt_f32_e64 s[42:43], |v11|, s8
	v_pk_fma_f32 v[34:35], v[18:19], v[38:39], v[34:35]
	v_mov_b32_e32 v44, v37
	v_cndmask_b32_e64 v11, v11, v12, s[42:43]
	v_cndmask_b32_e32 v12, 0, v222, vcc
	v_pk_fma_f32 v[34:35], v[20:21], v[44:45], v[34:35]
	v_sub_f32_e32 v12, v11, v12
	v_add_f32_e32 v11, v40, v34
	v_add_f32_e32 v11, v11, v35
	ds_read_b128 v[34:37], v1 offset:608
	ds_read_b128 v[42:45], v1 offset:624
	s_waitcnt lgkmcnt(1)
	v_mov_b32_e32 v38, v34
	s_waitcnt lgkmcnt(0)
	v_mov_b32_e32 v39, v42
	v_mov_b32_e32 v42, v35
	v_pk_mul_f32 v[34:35], v[24:25], v[42:43]
	s_nop 0
	v_pk_fma_f32 v[34:35], v[22:23], v[38:39], v[34:35]
	v_mov_b32_e32 v38, v36
	v_mov_b32_e32 v39, v44
	v_pk_fma_f32 v[34:35], v[26:27], v[38:39], v[34:35]
	v_mov_b32_e32 v44, v37
	v_pk_fma_f32 v[34:35], v[28:29], v[44:45], v[34:35]
	ds_read_b128 v[42:45], v1 offset:640
	ds_read_b128 v[46:49], v1 offset:656
	v_add_f32_e32 v11, v11, v34
	v_add_f32_e32 v11, v11, v35
	v_max_f32_e64 v34, -v11, 0
	v_mul_f32_e64 v11, |v11|, s5
	v_exp_f32_e32 v11, v11
	s_waitcnt lgkmcnt(0)
; DI void gla_gate_items(unsigned char* lds, const float* GLR, unsigned short* LA, int first, int stride, int nitems, const float* wgate, const float* bgate) {
;     ...
;         for (int j = 0; j < 16; j += 2) {
;             float la[2];
; #pragma unroll
;             for (int q = 0; q < 2; ++q) {
;                 const f32x4* gr = (const f32x4*)(GLRS + (16 * rg + j + q) * 16); float x = bg;
; #pragma unroll
;                 for (int i = 0; i < 4; ++i) { const f32x4 gv = gr[i]; x += gv.x * wg[4 * i] + gv.y * wg[4 * i + 1] + gv.z * wg[4 * i + 2] + gv.w * wg[4 * i + 3]; }
;                 la[q] = -(fmaxf(-x, 0.f) + __logf(1.f + __expf(-fabsf(x)))) * (1.f / 16.f);
;             }
;             const _Float16 h0 = (_Float16)la[0], h1 = (_Float16)la[1];
;             pk[j >> 1] = (unsigned)__builtin_bit_cast(unsigned short, h0) | ((unsigned)__builtin_bit_cast(unsigned short, h1) << 16);
	v_mov_b32_e32 v39, v46
	v_mov_b32_e32 v46, v43
	v_mov_b32_e32 v38, v42
	v_add_f32_e32 v11, 1.0, v11
	v_cmp_gt_f32_e32 vcc, s6, v11
	v_pk_mul_f32 v[42:43], v[16:17], v[46:47]
	s_nop 0
	v_cndmask_b32_e64 v13, 0, 32, vcc
	v_ldexp_f32 v11, v11, v13
	v_log_f32_e32 v11, v11
	v_pk_fma_f32 v[38:39], v[14:15], v[38:39], v[42:43]
	v_mov_b32_e32 v42, v44
	v_mov_b32_e32 v43, v48
	v_mul_f32_e32 v13, 0x3f317217, v11
	v_pk_fma_f32 v[38:39], v[18:19], v[42:43], v[38:39]
	v_mov_b32_e32 v48, v45
	v_fma_f32 v13, v11, s7, -v13
	v_pk_fma_f32 v[38:39], v[20:21], v[48:49], v[38:39]
	ds_read_b128 v[42:45], v1 offset:672
	ds_read_b128 v[46:49], v1 offset:688
	v_fmac_f32_e32 v13, 0x3377d1cf, v11
	v_fmac_f32_e32 v13, 0x3f317217, v11
	v_cmp_lt_f32_e64 s[42:43], |v11|, s8
	s_nop 1
	v_cndmask_b32_e64 v11, v11, v13, s[42:43]
	v_cndmask_b32_e32 v13, 0, v222, vcc
	v_sub_f32_e32 v36, v11, v13
	v_add_f32_e32 v11, v40, v38
	v_add_f32_e32 v11, v11, v39
	s_waitcnt lgkmcnt(0)
	v_mov_b32_e32 v39, v46
	v_mov_b32_e32 v46, v43
	v_mov_b32_e32 v38, v42
	v_pk_mul_f32 v[42:43], v[24:25], v[46:47]
	s_nop 0
	v_pk_fma_f32 v[38:39], v[22:23], v[38:39], v[42:43]
	v_mov_b32_e32 v42, v44
	v_mov_b32_e32 v43, v48
	v_pk_fma_f32 v[38:39], v[26:27], v[42:43], v[38:39]
	v_mov_b32_e32 v48, v45
	v_pk_fma_f32 v[38:39], v[28:29], v[48:49], v[38:39]
	ds_read_b128 v[42:45], v1 offset:704
	ds_read_b128 v[46:49], v1 offset:720
	v_add_f32_e32 v11, v11, v38
	v_add_f32_e32 v13, v11, v39
	v_max_f32_e64 v11, -v13, 0
	v_mul_f32_e64 v13, |v13|, s5
	v_exp_f32_e32 v13, v13
	s_waitcnt lgkmcnt(0)
	v_mov_b32_e32 v39, v46
	v_mov_b32_e32 v46, v43
	v_mov_b32_e32 v38, v42
	v_add_f32_e32 v13, 1.0, v13
	v_cmp_gt_f32_e32 vcc, s6, v13
	v_pk_mul_f32 v[42:43], v[16:17], v[46:47]
	s_nop 0
	v_cndmask_b32_e64 v35, 0, 32, vcc
	v_ldexp_f32 v13, v13, v35
	v_log_f32_e32 v13, v13
	v_pk_fma_f32 v[38:39], v[14:15], v[38:39], v[42:43]
	v_mov_b32_e32 v42, v44
	v_mov_b32_e32 v43, v48
	v_mul_f32_e32 v35, 0x3f317217, v13
	v_pk_fma_f32 v[38:39], v[18:19], v[42:43], v[38:39]
	v_mov_b32_e32 v48, v45
	v_fma_f32 v35, v13, s7, -v35
	v_pk_fma_f32 v[38:39], v[20:21], v[48:49], v[38:39]
	ds_read_b128 v[42:45], v1 offset:736
	ds_read_b128 v[46:49], v1 offset:752
	v_fmac_f32_e32 v35, 0x3377d1cf, v13
	v_fmac_f32_e32 v35, 0x3f317217, v13
	v_cmp_lt_f32_e64 s[42:43], |v13|, s8
	s_nop 1
	v_cndmask_b32_e64 v13, v13, v35, s[42:43]
	v_cndmask_b32_e32 v35, 0, v222, vcc
	v_sub_f32_e32 v13, v13, v35
	v_add_f32_e32 v35, v40, v38
	v_add_f32_e32 v35, v35, v39
	s_waitcnt lgkmcnt(0)
	v_mov_b32_e32 v39, v46
	v_mov_b32_e32 v46, v43
	v_mov_b32_e32 v38, v42
	v_pk_mul_f32 v[42:43], v[24:25], v[46:47]
	v_pk_add_f32 v[10:11], v[10:11], v[12:13]
	v_pk_fma_f32 v[38:39], v[22:23], v[38:39], v[42:43]
	v_mov_b32_e32 v42, v44
	v_mov_b32_e32 v43, v48
	v_pk_fma_f32 v[38:39], v[26:27], v[42:43], v[38:39]
	v_mov_b32_e32 v48, v45
	v_pk_fma_f32 v[38:39], v[28:29], v[48:49], v[38:39]
	v_pk_mul_f32 v[10:11], v[10:11], s[10:11] op_sel_hi:[1,0]
	v_add_f32_e32 v35, v35, v38
	v_add_f32_e32 v37, v35, v39
	v_max_f32_e64 v35, -v37, 0
	v_mul_f32_e64 v37, |v37|, s5
	v_exp_f32_e32 v37, v37
	v_cvt_pk_f16_f32 v10, v10, v11
	v_add_f32_e32 v37, 1.0, v37
	v_cmp_gt_f32_e32 vcc, s6, v37
	s_nop 1
	v_cndmask_b32_e64 v38, 0, 32, vcc
	v_ldexp_f32 v37, v37, v38
	v_log_f32_e32 v37, v37
	s_nop 0
	v_mul_f32_e32 v38, 0x3f317217, v37
	v_fma_f32 v38, v37, s7, -v38
	v_fmac_f32_e32 v38, 0x3377d1cf, v37
	v_fmac_f32_e32 v38, 0x3f317217, v37
	v_cmp_lt_f32_e64 s[42:43], |v37|, s8
	s_nop 1
	v_cndmask_b32_e64 v37, v37, v38, s[42:43]
	v_cndmask_b32_e32 v38, 0, v222, vcc
	v_sub_f32_e32 v37, v37, v38
	v_pk_add_f32 v[12:13], v[34:35], v[36:37]
	ds_read_b128 v[34:37], v1 offset:768
	ds_read_b128 v[42:45], v1 offset:784
	v_pk_mul_f32 v[12:13], v[12:13], s[10:11] op_sel_hi:[1,0]
	s_nop 0
	v_cvt_pk_f16_f32 v11, v12, v13
	v_and_b32_e32 v12, 0xffff0000, v11
	v_lshlrev_b32_e32 v13, 16, v11
	v_or_b32_sdwa v11, v12, v10 dst_sel:DWORD dst_unused:UNUSED_PAD src0_sel:DWORD src1_sel:WORD_1
	v_or_b32_sdwa v10, v13, v10 dst_sel:DWORD dst_unused:UNUSED_PAD src0_sel:DWORD src1_sel:WORD_0
	s_waitcnt lgkmcnt(0)
	v_mov_b32_e32 v13, v42
	v_mov_b32_e32 v42, v35
	v_mov_b32_e32 v12, v34
	v_pk_mul_f32 v[34:35], v[16:17], v[42:43]
	s_nop 0
	v_pk_fma_f32 v[12:13], v[14:15], v[12:13], v[34:35]
	v_mov_b32_e32 v34, v36
	v_mov_b32_e32 v35, v44
	v_pk_fma_f32 v[12:13], v[18:19], v[34:35], v[12:13]
	v_mov_b32_e32 v44, v37
	v_pk_fma_f32 v[12:13], v[20:21], v[44:45], v[12:13]
	ds_read_b128 v[34:37], v1 offset:800
	ds_read_b128 v[42:45], v1 offset:816
	v_add_f32_e32 v12, v40, v12
	v_add_f32_e32 v38, v12, v13
	s_waitcnt lgkmcnt(1)
	v_mov_b32_e32 v12, v34
	s_waitcnt lgkmcnt(0)
	v_mov_b32_e32 v13, v42
	v_mov_b32_e32 v42, v35
	v_pk_mul_f32 v[34:35], v[24:25], v[42:43]
	s_nop 0
	v_pk_fma_f32 v[12:13], v[22:23], v[12:13], v[34:35]
	v_mov_b32_e32 v34, v36
	v_mov_b32_e32 v35, v44
	v_pk_fma_f32 v[12:13], v[26:27], v[34:35], v[12:13]
	v_mov_b32_e32 v44, v37
	v_pk_fma_f32 v[12:13], v[28:29], v[44:45], v[12:13]
	s_nop 0
	v_add_f32_e32 v12, v38, v12
	v_add_f32_e32 v13, v12, v13
	v_max_f32_e64 v12, -v13, 0
	v_mul_f32_e64 v13, |v13|, s5
	v_exp_f32_e32 v13, v13
	ds_read_b128 v[36:39], v1 offset:832
	ds_read_b128 v[42:45], v1 offset:848
	v_add_f32_e32 v13, 1.0, v13
	v_cmp_gt_f32_e32 vcc, s6, v13
	s_waitcnt lgkmcnt(0)
; DI void gla_gate_items(unsigned char* lds, const float* GLR, unsigned short* LA, int first, int stride, int nitems, const float* wgate, const float* bgate) {
;     ...
;         for (int j = 0; j < 16; j += 2) {
;             float la[2];
; #pragma unroll
;             for (int q = 0; q < 2; ++q) {
;                 const f32x4* gr = (const f32x4*)(GLRS + (16 * rg + j + q) * 16); float x = bg;
; #pragma unroll
;                 for (int i = 0; i < 4; ++i) { const f32x4 gv = gr[i]; x += gv.x * wg[4 * i] + gv.y * wg[4 * i + 1] + gv.z * wg[4 * i + 2] + gv.w * wg[4 * i + 3]; }
;                 la[q] = -(fmaxf(-x, 0.f) + __logf(1.f + __expf(-fabsf(x)))) * (1.f / 16.f);
;             }
;             const _Float16 h0 = (_Float16)la[0], h1 = (_Float16)la[1];
;             pk[j >> 1] = (unsigned)__builtin_bit_cast(unsigned short, h0) | ((unsigned)__builtin_bit_cast(unsigned short, h1) << 16);
;         }
;         u32x4* dst = (u32x4*)(LA + ((((size_t)cidx * 4 + h) * 4 + rg) * 128 + dcol) * 16);
;         dst[0] = (u32x4){pk[0], pk[1], pk[2], pk[3]}; dst[1] = (u32x4){pk[4], pk[5], pk[6], pk[7]};
	v_mov_b32_e32 v47, v42
	v_mov_b32_e32 v42, v37
	v_cndmask_b32_e64 v34, 0, 32, vcc
	v_ldexp_f32 v13, v13, v34
	v_log_f32_e32 v13, v13
	v_mov_b32_e32 v46, v36
	v_pk_mul_f32 v[36:37], v[16:17], v[42:43]
	v_mov_b32_e32 v42, v38
	v_mul_f32_e32 v34, 0x3f317217, v13
	v_fma_f32 v34, v13, s7, -v34
	v_fmac_f32_e32 v34, 0x3377d1cf, v13
	v_pk_fma_f32 v[36:37], v[14:15], v[46:47], v[36:37]
	v_mov_b32_e32 v43, v44
	v_fmac_f32_e32 v34, 0x3f317217, v13
	v_cmp_lt_f32_e64 s[42:43], |v13|, s8
	v_pk_fma_f32 v[36:37], v[18:19], v[42:43], v[36:37]
	v_mov_b32_e32 v44, v39
	v_cndmask_b32_e64 v13, v13, v34, s[42:43]
	v_cndmask_b32_e32 v34, 0, v222, vcc
	v_pk_fma_f32 v[36:37], v[20:21], v[44:45], v[36:37]
	v_sub_f32_e32 v34, v13, v34
	v_add_f32_e32 v13, v40, v36
	v_add_f32_e32 v13, v13, v37
	ds_read_b128 v[36:39], v1 offset:864
	ds_read_b128 v[42:45], v1 offset:880
	s_waitcnt lgkmcnt(1)
	v_mov_b32_e32 v46, v36
	s_waitcnt lgkmcnt(0)
	v_mov_b32_e32 v47, v42
	v_mov_b32_e32 v42, v37
	v_pk_mul_f32 v[36:37], v[24:25], v[42:43]
	v_mov_b32_e32 v42, v38
	v_pk_fma_f32 v[36:37], v[22:23], v[46:47], v[36:37]
	v_mov_b32_e32 v43, v44
	v_pk_fma_f32 v[36:37], v[26:27], v[42:43], v[36:37]
	v_mov_b32_e32 v44, v39
	v_pk_fma_f32 v[36:37], v[28:29], v[44:45], v[36:37]
	ds_read_b128 v[42:45], v1 offset:896
	ds_read_b128 v[46:49], v1 offset:912
	v_add_f32_e32 v13, v13, v36
	v_add_f32_e32 v13, v13, v37
	v_max_f32_e64 v36, -v13, 0
	v_mul_f32_e64 v13, |v13|, s5
	v_exp_f32_e32 v13, v13
	s_waitcnt lgkmcnt(0)
	v_mov_b32_e32 v51, v46
	v_mov_b32_e32 v46, v43
	v_mov_b32_e32 v50, v42
	v_add_f32_e32 v13, 1.0, v13
	v_cmp_gt_f32_e32 vcc, s6, v13
	v_pk_mul_f32 v[42:43], v[16:17], v[46:47]
	v_mov_b32_e32 v46, v44
	v_cndmask_b32_e64 v35, 0, 32, vcc
	v_ldexp_f32 v13, v13, v35
	v_log_f32_e32 v13, v13
	v_pk_fma_f32 v[42:43], v[14:15], v[50:51], v[42:43]
	v_mov_b32_e32 v47, v48
	v_pk_fma_f32 v[42:43], v[18:19], v[46:47], v[42:43]
	v_mul_f32_e32 v35, 0x3f317217, v13
	v_fma_f32 v35, v13, s7, -v35
	v_fmac_f32_e32 v35, 0x3377d1cf, v13
	v_fmac_f32_e32 v35, 0x3f317217, v13
	v_cmp_lt_f32_e64 s[42:43], |v13|, s8
	v_mov_b32_e32 v48, v45
	v_pk_fma_f32 v[42:43], v[20:21], v[48:49], v[42:43]
	v_cndmask_b32_e64 v13, v13, v35, s[42:43]
	v_cndmask_b32_e32 v35, 0, v222, vcc
	v_sub_f32_e32 v38, v13, v35
	v_add_f32_e32 v13, v40, v42
	v_add_f32_e32 v13, v13, v43
	ds_read_b128 v[42:45], v1 offset:928
	ds_read_b128 v[46:49], v1 offset:944
	s_waitcnt lgkmcnt(1)
	v_mov_b32_e32 v50, v42
	s_waitcnt lgkmcnt(0)
	v_mov_b32_e32 v51, v46
	v_mov_b32_e32 v46, v43
	v_pk_mul_f32 v[42:43], v[24:25], v[46:47]
	v_mov_b32_e32 v46, v44
	v_pk_fma_f32 v[42:43], v[22:23], v[50:51], v[42:43]
	v_mov_b32_e32 v47, v48
	v_pk_fma_f32 v[42:43], v[26:27], v[46:47], v[42:43]
	v_mov_b32_e32 v48, v45
	v_pk_fma_f32 v[42:43], v[28:29], v[48:49], v[42:43]
	s_nop 0
	v_add_f32_e32 v13, v13, v42
	v_add_f32_e32 v35, v13, v43
	v_max_f32_e64 v13, -v35, 0
	v_mul_f32_e64 v35, |v35|, s5
	v_exp_f32_e32 v35, v35
	ds_read_b128 v[42:45], v1 offset:960
	ds_read_b128 v[46:49], v1 offset:976
	v_add_f32_e32 v35, 1.0, v35
	v_cmp_gt_f32_e32 vcc, s6, v35
	s_waitcnt lgkmcnt(0)
	v_mov_b32_e32 v51, v46
	v_mov_b32_e32 v46, v43
	v_cndmask_b32_e64 v37, 0, 32, vcc
	v_ldexp_f32 v35, v35, v37
	v_log_f32_e32 v35, v35
	v_mov_b32_e32 v50, v42
	v_pk_mul_f32 v[42:43], v[16:17], v[46:47]
	v_mov_b32_e32 v46, v44
	v_mul_f32_e32 v37, 0x3f317217, v35
	v_fma_f32 v37, v35, s7, -v37
	v_fmac_f32_e32 v37, 0x3377d1cf, v35
	v_pk_fma_f32 v[42:43], v[14:15], v[50:51], v[42:43]
	v_mov_b32_e32 v47, v48
	v_fmac_f32_e32 v37, 0x3f317217, v35
	v_cmp_lt_f32_e64 s[42:43], |v35|, s8
	v_pk_fma_f32 v[42:43], v[18:19], v[46:47], v[42:43]
	v_mov_b32_e32 v48, v45
	v_cndmask_b32_e64 v35, v35, v37, s[42:43]
	v_cndmask_b32_e32 v37, 0, v222, vcc
	v_pk_fma_f32 v[42:43], v[20:21], v[48:49], v[42:43]
	v_sub_f32_e32 v35, v35, v37
	v_add_f32_e32 v37, v40, v42
	v_add_f32_e32 v37, v37, v43
	ds_read_b128 v[42:45], v1 offset:992
	ds_read_b128 v[46:49], v1 offset:1008
	v_pk_add_f32 v[12:13], v[12:13], v[34:35]
	s_waitcnt lgkmcnt(1)
	v_mov_b32_e32 v50, v42
	s_waitcnt lgkmcnt(0)
	v_mov_b32_e32 v51, v46
	v_mov_b32_e32 v46, v43
	v_pk_mul_f32 v[42:43], v[24:25], v[46:47]
	v_mov_b32_e32 v46, v44
	v_pk_fma_f32 v[42:43], v[22:23], v[50:51], v[42:43]
	v_mov_b32_e32 v47, v48
	v_pk_fma_f32 v[42:43], v[26:27], v[46:47], v[42:43]
	v_mov_b32_e32 v48, v45
	v_pk_fma_f32 v[42:43], v[28:29], v[48:49], v[42:43]
	v_pk_mul_f32 v[12:13], v[12:13], s[10:11] op_sel_hi:[1,0]
	v_add_f32_e32 v37, v37, v42
	v_add_f32_e32 v39, v37, v43
	v_max_f32_e64 v37, -v39, 0
	v_mul_f32_e64 v39, |v39|, s5
	v_exp_f32_e32 v39, v39
	v_cvt_pk_f16_f32 v12, v12, v13
	s_mov_b32 s5, s4
	v_add_f32_e32 v39, 1.0, v39
	v_cmp_gt_f32_e32 vcc, s6, v39
	s_nop 1
	v_cndmask_b32_e64 v42, 0, 32, vcc
	v_ldexp_f32 v39, v39, v42
	v_log_f32_e32 v39, v39
	s_nop 0
	v_mul_f32_e32 v42, 0x3f317217, v39
	v_fma_f32 v42, v39, s7, -v42
	v_fmac_f32_e32 v42, 0x3377d1cf, v39
	v_fmac_f32_e32 v42, 0x3f317217, v39
	v_cmp_lt_f32_e64 s[42:43], |v39|, s8
	s_mov_b64 s[6:7], 0x3a0000
	s_nop 0
	v_cndmask_b32_e64 v39, v39, v42, s[42:43]
	v_cndmask_b32_e32 v42, 0, v222, vcc
	v_sub_f32_e32 v39, v39, v42
	v_pk_add_f32 v[34:35], v[36:37], v[38:39]
	s_and_b64 vcc, exec, s[34:35]
	v_pk_mul_f32 v[34:35], v[34:35], s[10:11] op_sel_hi:[1,0]
	s_nop 0
	v_cvt_pk_f16_f32 v13, v34, v35
	v_and_b32_e32 v34, 0xffff0000, v13
	v_lshlrev_b32_e32 v35, 16, v13
	v_or_b32_sdwa v13, v34, v12 dst_sel:DWORD dst_unused:UNUSED_PAD src0_sel:DWORD src1_sel:WORD_1
	v_or_b32_sdwa v12, v35, v12 dst_sel:DWORD dst_unused:UNUSED_PAD src0_sel:DWORD src1_sel:WORD_0
	global_store_dwordx4 v[32:33], v[6:9], off nt
	global_store_dwordx4 v[32:33], v[10:13], off offset:16 nt
	v_lshl_add_u64 v[32:33], v[32:33], 0, s[6:7]
	s_cbranch_vccnz .LBB0_1072

; DI unsigned cvtpk(float lo, float hi) { f32x2_t v = {lo, hi}; bf16x2_t b = __builtin_convertvector(v, bf16x2_t); return __builtin_bit_cast(unsigned, b); }
; DI float bflo(unsigned w) { return __uint_as_float(w << 16); }
; DI float bfhi(unsigned w) { return __uint_as_float(w & 0xffff0000u); }
; DI float silu_f(float x) { return x * __builtin_amdgcn_rcpf(1.f + __expf(-x)); }
; DI float sigmoid_f(float x) { return __builtin_amdgcn_rcpf(1.f + __expf(-x)); }
;     __device__ __forceinline__ void operator()(const f32x4 (&acc)[2][2][4][2], const Unit& u, int wr, int wc, int fr, int fq) const {
;     ...
; #pragma unroll
;             for (int m = 0; m < 4; ++m) {
;                 bf16_t* rowp = base + (size_t)(row0 + ai * HALF + m * 16) * ldc + c0 + cin;
; #pragma unroll
;                 for (int bj = 0; bj < 2; ++bj) {
;                     const f32x4 v0 = acc[ai][bj][m][0], v1 = acc[ai][bj][m][1];
;                     u32x4* p = (u32x4*)(rowp + bj * HALF);
;                     float h[8];
;                     if (mul) {
;                         const u32x4 o = ol[m][bj];
;                         h[0] = bflo(o.x) * silu_f(v0[0]); h[1] = bfhi(o.x) * silu_f(v0[1]); h[2] = bflo(o.y) * silu_f(v0[2]); h[3] = bfhi(o.y) * silu_f(v0[3]);
;                         h[4] = bflo(o.z) * silu_f(v1[0]); h[5] = bfhi(o.z) * silu_f(v1[1]); h[6] = bflo(o.w) * silu_f(v1[2]); h[7] = bfhi(o.w) * silu_f(v1[3]);
;                     } else {
;                         h[0] = sigmoid_f(v0[0]); h[1] = sigmoid_f(v0[1]); h[2] = sigmoid_f(v0[2]); h[3] = sigmoid_f(v0[3]);
;                         h[4] = sigmoid_f(v1[0]); h[5] = sigmoid_f(v1[1]); h[6] = sigmoid_f(v1[2]); h[7] = sigmoid_f(v1[3]);
;                     }
;                     u32x4 w; w.x = cvtpk(h[0], h[1]); w.y = cvtpk(h[2], h[3]); w.z = cvtpk(h[4], h[5]); w.w = cvtpk(h[6], h[7]);
;                     *p = w;
.LBB0_1786:
	v_cvt_pk_bf16_f32 v154, v180, v181
	v_cvt_pk_bf16_f32 v155, v182, v183
	v_cvt_pk_bf16_f32 v156, v184, v185
	v_cvt_pk_bf16_f32 v157, v186, v187
	global_store_dwordx4 v[178:179], v[154:157], off nt
	v_mul_f32_e32 v158, 0xbfb8aa3b, v149
	v_mul_f32_e32 v159, 0xbfb8aa3b, v142
	v_mul_f32_e32 v155, 0xbfb8aa3b, v146
	v_mul_f32_e32 v156, 0xbfb8aa3b, v147
	v_mul_f32_e32 v157, 0xbfb8aa3b, v148
	v_mul_f32_e32 v160, 0xbfb8aa3b, v143
	v_mul_f32_e32 v161, 0xbfb8aa3b, v144
	v_mul_f32_e32 v180, 0xbfb8aa3b, v145
	v_exp_f32_e32 v187, v155
	v_exp_f32_e32 v186, v156
	v_exp_f32_e32 v185, v157
	v_exp_f32_e32 v184, v158
	v_exp_f32_e32 v183, v159
	v_exp_f32_e32 v182, v160
	v_exp_f32_e32 v181, v161
	v_exp_f32_e32 v180, v180
	v_cndmask_b32_e64 v154, 0, 1, s[68:69]
	v_cmp_ne_u32_e64 s[42:43], 1, v154
	s_andn2_b64 vcc, exec, s[68:69]
	s_mov_b64 s[68:69], -1
	s_cbranch_vccnz .LBB0_1788
	v_add_f32_e32 v154, 1.0, v187
	v_add_f32_e32 v155, 1.0, v186
	v_add_f32_e32 v156, 1.0, v185
	v_add_f32_e32 v157, 1.0, v184
	v_add_f32_e32 v158, 1.0, v183
	v_add_f32_e32 v159, 1.0, v182
	v_add_f32_e32 v160, 1.0, v181
	v_add_f32_e32 v161, 1.0, v180
	v_rcp_f32_e32 v154, v154
	v_rcp_f32_e32 v155, v155
	v_rcp_f32_e32 v156, v156
	v_rcp_f32_e32 v157, v157
	v_rcp_f32_e32 v158, v158
	v_rcp_f32_e32 v159, v159
	v_rcp_f32_e32 v160, v160
	v_rcp_f32_e32 v161, v161
	s_mov_b64 s[68:69], 0

; DI unsigned cvtpk(float lo, float hi) { f32x2_t v = {lo, hi}; bf16x2_t b = __builtin_convertvector(v, bf16x2_t); return __builtin_bit_cast(unsigned, b); }
; DI float bflo(unsigned w) { return __uint_as_float(w << 16); }
; DI float bfhi(unsigned w) { return __uint_as_float(w & 0xffff0000u); }
; DI float silu_f(float x) { return x * __builtin_amdgcn_rcpf(1.f + __expf(-x)); }
; DI float sigmoid_f(float x) { return __builtin_amdgcn_rcpf(1.f + __expf(-x)); }
;     __device__ __forceinline__ void operator()(const f32x4 (&acc)[2][2][4][2], const Unit& u, int wr, int wc, int fr, int fq) const {
;     ...
; #pragma unroll
;             for (int m = 0; m < 4; ++m) {
;                 bf16_t* rowp = base + (size_t)(row0 + ai * HALF + m * 16) * ldc + c0 + cin;
; #pragma unroll
;                 for (int bj = 0; bj < 2; ++bj) {
;                     const f32x4 v0 = acc[ai][bj][m][0], v1 = acc[ai][bj][m][1];
;                     u32x4* p = (u32x4*)(rowp + bj * HALF);
;                     float h[8];
;                     if (mul) {
;                         const u32x4 o = ol[m][bj];
;                         h[0] = bflo(o.x) * silu_f(v0[0]); h[1] = bfhi(o.x) * silu_f(v0[1]); h[2] = bflo(o.y) * silu_f(v0[2]); h[3] = bfhi(o.y) * silu_f(v0[3]);
;                         h[4] = bflo(o.z) * silu_f(v1[0]); h[5] = bfhi(o.z) * silu_f(v1[1]); h[6] = bflo(o.w) * silu_f(v1[2]); h[7] = bfhi(o.w) * silu_f(v1[3]);
;                     } else {
;                         h[0] = sigmoid_f(v0[0]); h[1] = sigmoid_f(v0[1]); h[2] = sigmoid_f(v0[2]); h[3] = sigmoid_f(v0[3]);
;                         h[4] = sigmoid_f(v1[0]); h[5] = sigmoid_f(v1[1]); h[6] = sigmoid_f(v1[2]); h[7] = sigmoid_f(v1[3]);
;                     }
;                     u32x4 w; w.x = cvtpk(h[0], h[1]); w.y = cvtpk(h[2], h[3]); w.z = cvtpk(h[4], h[5]); w.w = cvtpk(h[6], h[7]);
;                     *p = w;
.LBB0_1790:
	v_cvt_pk_bf16_f32 v142, v154, v155
	v_mul_f32_e32 v146, 0xbfb8aa3b, v134
	v_mul_f32_e32 v147, 0xbfb8aa3b, v135
	v_mul_f32_e32 v148, 0xbfb8aa3b, v136
	v_mul_f32_e32 v149, 0xbfb8aa3b, v137
	v_mul_f32_e32 v154, 0xbfb8aa3b, v130
	v_mul_f32_e32 v155, 0xbfb8aa3b, v131
	v_mul_f32_e32 v180, 0xbfb8aa3b, v132
	v_mul_f32_e32 v181, 0xbfb8aa3b, v133
	v_cvt_pk_bf16_f32 v143, v156, v157
	v_cvt_pk_bf16_f32 v144, v158, v159
	v_cvt_pk_bf16_f32 v145, v160, v161
	v_exp_f32_e32 v161, v146
	v_exp_f32_e32 v160, v147
	v_exp_f32_e32 v159, v148
	v_exp_f32_e32 v158, v149
	v_exp_f32_e32 v157, v154
	v_exp_f32_e32 v156, v155
	v_exp_f32_e32 v155, v180
	v_exp_f32_e32 v154, v181
	s_and_b64 vcc, exec, s[42:43]
	s_mov_b64 s[68:69], -1
	global_store_dwordx4 v[178:179], v[142:145], off offset:256 nt
	s_cbranch_vccnz .LBB0_1792
	s_nop 0
	v_add_f32_e32 v142, 1.0, v161
	v_add_f32_e32 v143, 1.0, v160
	v_add_f32_e32 v144, 1.0, v159
	v_add_f32_e32 v145, 1.0, v158
	v_add_f32_e32 v146, 1.0, v157
	v_add_f32_e32 v147, 1.0, v156
	v_add_f32_e32 v148, 1.0, v155
	v_add_f32_e32 v149, 1.0, v154
	v_rcp_f32_e32 v142, v142
	v_rcp_f32_e32 v143, v143
	v_rcp_f32_e32 v144, v144
	v_rcp_f32_e32 v145, v145
	v_rcp_f32_e32 v146, v146
	v_rcp_f32_e32 v147, v147
	v_rcp_f32_e32 v148, v148
	v_rcp_f32_e32 v149, v149
	s_mov_b64 s[68:69], 0

; DI unsigned cvtpk(float lo, float hi) { f32x2_t v = {lo, hi}; bf16x2_t b = __builtin_convertvector(v, bf16x2_t); return __builtin_bit_cast(unsigned, b); }
; DI float bflo(unsigned w) { return __uint_as_float(w << 16); }
; DI float bfhi(unsigned w) { return __uint_as_float(w & 0xffff0000u); }
; DI float silu_f(float x) { return x * __builtin_amdgcn_rcpf(1.f + __expf(-x)); }
; DI float sigmoid_f(float x) { return __builtin_amdgcn_rcpf(1.f + __expf(-x)); }
;     __device__ __forceinline__ void operator()(const f32x4 (&acc)[2][2][4][2], const Unit& u, int wr, int wc, int fr, int fq) const {
;     ...
;             for (int m = 0; m < 4; ++m) {
;                 bf16_t* rowp = base + (size_t)(row0 + ai * HALF + m * 16) * ldc + c0 + cin;
; #pragma unroll
;                 for (int bj = 0; bj < 2; ++bj) {
;                     const f32x4 v0 = acc[ai][bj][m][0], v1 = acc[ai][bj][m][1];
;                     u32x4* p = (u32x4*)(rowp + bj * HALF);
;                     float h[8];
;                     if (mul) {
;                         const u32x4 o = ol[m][bj];
;                         h[0] = bflo(o.x) * silu_f(v0[0]); h[1] = bfhi(o.x) * silu_f(v0[1]); h[2] = bflo(o.y) * silu_f(v0[2]); h[3] = bfhi(o.y) * silu_f(v0[3]);
;                         h[4] = bflo(o.z) * silu_f(v1[0]); h[5] = bfhi(o.z) * silu_f(v1[1]); h[6] = bflo(o.w) * silu_f(v1[2]); h[7] = bfhi(o.w) * silu_f(v1[3]);
;                     } else {
;                         h[0] = sigmoid_f(v0[0]); h[1] = sigmoid_f(v0[1]); h[2] = sigmoid_f(v0[2]); h[3] = sigmoid_f(v0[3]);
;                         h[4] = sigmoid_f(v1[0]); h[5] = sigmoid_f(v1[1]); h[6] = sigmoid_f(v1[2]); h[7] = sigmoid_f(v1[3]);
;                     }
;                     u32x4 w; w.x = cvtpk(h[0], h[1]); w.y = cvtpk(h[2], h[3]); w.z = cvtpk(h[4], h[5]); w.w = cvtpk(h[6], h[7]);
;                     *p = w;
.LBB0_1794:
	v_cvt_pk_bf16_f32 v132, v142, v143
	v_cvt_pk_bf16_f32 v133, v144, v145
	v_mul_f32_e32 v136, 0xbfb8aa3b, v122
	v_mul_f32_e32 v137, 0xbfb8aa3b, v123
	v_mul_f32_e32 v142, 0xbfb8aa3b, v124
	v_mul_f32_e32 v143, 0xbfb8aa3b, v125
	v_mul_f32_e32 v144, 0xbfb8aa3b, v118
	v_mul_f32_e32 v145, 0xbfb8aa3b, v119
	v_mul_f32_e32 v156, 0xbfb8aa3b, v120
	v_mul_f32_e32 v157, 0xbfb8aa3b, v121
	v_cvt_pk_bf16_f32 v134, v146, v147
	v_cvt_pk_bf16_f32 v135, v148, v149
	v_exp_f32_e32 v155, v136
	v_exp_f32_e32 v154, v137
	v_exp_f32_e32 v149, v142
	v_exp_f32_e32 v148, v143
	v_exp_f32_e32 v147, v144
	v_exp_f32_e32 v146, v145
	v_exp_f32_e32 v145, v156
	v_exp_f32_e32 v144, v157
	v_mad_u64_u32 v[130:131], s[8:9], s64, v195, 0
	v_add3_u32 v131, v131, v175, v196
	v_lshl_add_u64 v[130:131], v[130:131], 1, v[176:177]
	s_and_b64 vcc, exec, s[42:43]
	s_mov_b64 s[68:69], -1
	global_store_dwordx4 v[130:131], v[132:135], off nt
	s_cbranch_vccnz .LBB0_1796
	s_nop 0
	v_add_f32_e32 v132, 1.0, v155
	v_add_f32_e32 v133, 1.0, v154
	v_add_f32_e32 v134, 1.0, v149
	v_add_f32_e32 v135, 1.0, v148
	v_add_f32_e32 v136, 1.0, v147
	v_add_f32_e32 v137, 1.0, v146
	v_add_f32_e32 v142, 1.0, v145
	v_add_f32_e32 v143, 1.0, v144
	v_rcp_f32_e32 v132, v132
	v_rcp_f32_e32 v133, v133
	v_rcp_f32_e32 v134, v134
	v_rcp_f32_e32 v135, v135
	v_rcp_f32_e32 v136, v136
	v_rcp_f32_e32 v137, v137
	v_rcp_f32_e32 v142, v142
	v_rcp_f32_e32 v143, v143
	s_mov_b64 s[68:69], 0

; DI unsigned cvtpk(float lo, float hi) { f32x2_t v = {lo, hi}; bf16x2_t b = __builtin_convertvector(v, bf16x2_t); return __builtin_bit_cast(unsigned, b); }
; DI float bflo(unsigned w) { return __uint_as_float(w << 16); }
; DI float bfhi(unsigned w) { return __uint_as_float(w & 0xffff0000u); }
; DI float silu_f(float x) { return x * __builtin_amdgcn_rcpf(1.f + __expf(-x)); }
; DI float sigmoid_f(float x) { return __builtin_amdgcn_rcpf(1.f + __expf(-x)); }
;     __device__ __forceinline__ void operator()(const f32x4 (&acc)[2][2][4][2], const Unit& u, int wr, int wc, int fr, int fq) const {
;     ...
; #pragma unroll
;             for (int m = 0; m < 4; ++m) {
;                 bf16_t* rowp = base + (size_t)(row0 + ai * HALF + m * 16) * ldc + c0 + cin;
; #pragma unroll
;                 for (int bj = 0; bj < 2; ++bj) {
;                     const f32x4 v0 = acc[ai][bj][m][0], v1 = acc[ai][bj][m][1];
;                     u32x4* p = (u32x4*)(rowp + bj * HALF);
;                     float h[8];
;                     if (mul) {
;                         const u32x4 o = ol[m][bj];
;                         h[0] = bflo(o.x) * silu_f(v0[0]); h[1] = bfhi(o.x) * silu_f(v0[1]); h[2] = bflo(o.y) * silu_f(v0[2]); h[3] = bfhi(o.y) * silu_f(v0[3]);
;                         h[4] = bflo(o.z) * silu_f(v1[0]); h[5] = bfhi(o.z) * silu_f(v1[1]); h[6] = bflo(o.w) * silu_f(v1[2]); h[7] = bfhi(o.w) * silu_f(v1[3]);
;                     } else {
;                         h[0] = sigmoid_f(v0[0]); h[1] = sigmoid_f(v0[1]); h[2] = sigmoid_f(v0[2]); h[3] = sigmoid_f(v0[3]);
;                         h[4] = sigmoid_f(v1[0]); h[5] = sigmoid_f(v1[1]); h[6] = sigmoid_f(v1[2]); h[7] = sigmoid_f(v1[3]);
;                     }
;                     u32x4 w; w.x = cvtpk(h[0], h[1]); w.y = cvtpk(h[2], h[3]); w.z = cvtpk(h[4], h[5]); w.w = cvtpk(h[6], h[7]);
;                     *p = w;
.LBB0_1798:
	v_cvt_pk_bf16_f32 v118, v132, v133
	v_mul_f32_e32 v122, 0xbfb8aa3b, v110
	v_mul_f32_e32 v123, 0xbfb8aa3b, v111
	v_mul_f32_e32 v124, 0xbfb8aa3b, v112
	v_mul_f32_e32 v125, 0xbfb8aa3b, v113
	v_mul_f32_e32 v132, 0xbfb8aa3b, v106
	v_mul_f32_e32 v133, 0xbfb8aa3b, v107
	v_mul_f32_e32 v144, 0xbfb8aa3b, v108
	v_mul_f32_e32 v145, 0xbfb8aa3b, v109
	v_cvt_pk_bf16_f32 v119, v134, v135
	v_cvt_pk_bf16_f32 v120, v136, v137
	v_cvt_pk_bf16_f32 v121, v142, v143
	v_exp_f32_e32 v143, v122
	v_exp_f32_e32 v142, v123
	v_exp_f32_e32 v137, v124
	v_exp_f32_e32 v136, v125
	v_exp_f32_e32 v135, v132
	v_exp_f32_e32 v134, v133
	v_exp_f32_e32 v133, v144
	v_exp_f32_e32 v132, v145
	s_and_b64 vcc, exec, s[42:43]
	s_mov_b64 s[68:69], -1
	global_store_dwordx4 v[130:131], v[118:121], off offset:256 nt
	s_cbranch_vccnz .LBB0_1800
	s_nop 0
	v_add_f32_e32 v118, 1.0, v143
	v_add_f32_e32 v119, 1.0, v142
	v_add_f32_e32 v120, 1.0, v137
	v_add_f32_e32 v121, 1.0, v136
	v_add_f32_e32 v122, 1.0, v135
	v_add_f32_e32 v123, 1.0, v134
	v_add_f32_e32 v124, 1.0, v133
	v_add_f32_e32 v125, 1.0, v132
	v_rcp_f32_e32 v118, v118
	v_rcp_f32_e32 v119, v119
	v_rcp_f32_e32 v120, v120
	v_rcp_f32_e32 v121, v121
	v_rcp_f32_e32 v122, v122
	v_rcp_f32_e32 v123, v123
	v_rcp_f32_e32 v124, v124
	v_rcp_f32_e32 v125, v125
	s_mov_b64 s[68:69], 0

; DI unsigned cvtpk(float lo, float hi) { f32x2_t v = {lo, hi}; bf16x2_t b = __builtin_convertvector(v, bf16x2_t); return __builtin_bit_cast(unsigned, b); }
; DI float bflo(unsigned w) { return __uint_as_float(w << 16); }
; DI float bfhi(unsigned w) { return __uint_as_float(w & 0xffff0000u); }
; DI float silu_f(float x) { return x * __builtin_amdgcn_rcpf(1.f + __expf(-x)); }
; DI float sigmoid_f(float x) { return __builtin_amdgcn_rcpf(1.f + __expf(-x)); }
;     __device__ __forceinline__ void operator()(const f32x4 (&acc)[2][2][4][2], const Unit& u, int wr, int wc, int fr, int fq) const {
;     ...
;             for (int m = 0; m < 4; ++m) {
;                 bf16_t* rowp = base + (size_t)(row0 + ai * HALF + m * 16) * ldc + c0 + cin;
; #pragma unroll
;                 for (int bj = 0; bj < 2; ++bj) {
;                     const f32x4 v0 = acc[ai][bj][m][0], v1 = acc[ai][bj][m][1];
;                     u32x4* p = (u32x4*)(rowp + bj * HALF);
;                     float h[8];
;                     if (mul) {
;                         const u32x4 o = ol[m][bj];
;                         h[0] = bflo(o.x) * silu_f(v0[0]); h[1] = bfhi(o.x) * silu_f(v0[1]); h[2] = bflo(o.y) * silu_f(v0[2]); h[3] = bfhi(o.y) * silu_f(v0[3]);
;                         h[4] = bflo(o.z) * silu_f(v1[0]); h[5] = bfhi(o.z) * silu_f(v1[1]); h[6] = bflo(o.w) * silu_f(v1[2]); h[7] = bfhi(o.w) * silu_f(v1[3]);
;                     } else {
;                         h[0] = sigmoid_f(v0[0]); h[1] = sigmoid_f(v0[1]); h[2] = sigmoid_f(v0[2]); h[3] = sigmoid_f(v0[3]);
;                         h[4] = sigmoid_f(v1[0]); h[5] = sigmoid_f(v1[1]); h[6] = sigmoid_f(v1[2]); h[7] = sigmoid_f(v1[3]);
;                     }
;                     u32x4 w; w.x = cvtpk(h[0], h[1]); w.y = cvtpk(h[2], h[3]); w.z = cvtpk(h[4], h[5]); w.w = cvtpk(h[6], h[7]);
;                     *p = w;
.LBB0_1802:
	v_cvt_pk_bf16_f32 v108, v118, v119
	v_cvt_pk_bf16_f32 v109, v120, v121
	v_mul_f32_e32 v112, 0xbfb8aa3b, v98
	v_mul_f32_e32 v113, 0xbfb8aa3b, v99
	v_mul_f32_e32 v118, 0xbfb8aa3b, v100
	v_mul_f32_e32 v119, 0xbfb8aa3b, v101
	v_mul_f32_e32 v120, 0xbfb8aa3b, v94
	v_mul_f32_e32 v121, 0xbfb8aa3b, v95
	v_mul_f32_e32 v132, 0xbfb8aa3b, v96
	v_mul_f32_e32 v133, 0xbfb8aa3b, v97
	v_cvt_pk_bf16_f32 v110, v122, v123
	v_cvt_pk_bf16_f32 v111, v124, v125
	v_exp_f32_e32 v131, v112
	v_exp_f32_e32 v130, v113
	v_exp_f32_e32 v125, v118
	v_exp_f32_e32 v124, v119
	v_exp_f32_e32 v123, v120
	v_exp_f32_e32 v122, v121
	v_exp_f32_e32 v121, v132
	v_exp_f32_e32 v120, v133
	v_mad_u64_u32 v[106:107], s[8:9], s64, v193, 0
	v_add3_u32 v107, v107, v175, v194
	v_lshl_add_u64 v[106:107], v[106:107], 1, v[176:177]
	s_and_b64 vcc, exec, s[42:43]
	s_mov_b64 s[68:69], -1
	global_store_dwordx4 v[106:107], v[108:111], off nt
	s_cbranch_vccnz .LBB0_1804
	s_nop 0
	v_add_f32_e32 v108, 1.0, v131
	v_add_f32_e32 v109, 1.0, v130
	v_add_f32_e32 v110, 1.0, v125
	v_add_f32_e32 v111, 1.0, v124
	v_add_f32_e32 v112, 1.0, v123
	v_add_f32_e32 v113, 1.0, v122
	v_add_f32_e32 v118, 1.0, v121
	v_add_f32_e32 v119, 1.0, v120
	v_rcp_f32_e32 v108, v108
	v_rcp_f32_e32 v109, v109
	v_rcp_f32_e32 v110, v110
	v_rcp_f32_e32 v111, v111
	v_rcp_f32_e32 v112, v112
	v_rcp_f32_e32 v113, v113
	v_rcp_f32_e32 v118, v118
	v_rcp_f32_e32 v119, v119
	s_mov_b64 s[68:69], 0

; DI unsigned cvtpk(float lo, float hi) { f32x2_t v = {lo, hi}; bf16x2_t b = __builtin_convertvector(v, bf16x2_t); return __builtin_bit_cast(unsigned, b); }
; DI float bflo(unsigned w) { return __uint_as_float(w << 16); }
; DI float bfhi(unsigned w) { return __uint_as_float(w & 0xffff0000u); }
; DI float silu_f(float x) { return x * __builtin_amdgcn_rcpf(1.f + __expf(-x)); }
; DI float sigmoid_f(float x) { return __builtin_amdgcn_rcpf(1.f + __expf(-x)); }
;     __device__ __forceinline__ void operator()(const f32x4 (&acc)[2][2][4][2], const Unit& u, int wr, int wc, int fr, int fq) const {
;     ...
; #pragma unroll
;             for (int m = 0; m < 4; ++m) {
;                 bf16_t* rowp = base + (size_t)(row0 + ai * HALF + m * 16) * ldc + c0 + cin;
; #pragma unroll
;                 for (int bj = 0; bj < 2; ++bj) {
;                     const f32x4 v0 = acc[ai][bj][m][0], v1 = acc[ai][bj][m][1];
;                     u32x4* p = (u32x4*)(rowp + bj * HALF);
;                     float h[8];
;                     if (mul) {
;                         const u32x4 o = ol[m][bj];
;                         h[0] = bflo(o.x) * silu_f(v0[0]); h[1] = bfhi(o.x) * silu_f(v0[1]); h[2] = bflo(o.y) * silu_f(v0[2]); h[3] = bfhi(o.y) * silu_f(v0[3]);
;                         h[4] = bflo(o.z) * silu_f(v1[0]); h[5] = bfhi(o.z) * silu_f(v1[1]); h[6] = bflo(o.w) * silu_f(v1[2]); h[7] = bfhi(o.w) * silu_f(v1[3]);
;                     } else {
;                         h[0] = sigmoid_f(v0[0]); h[1] = sigmoid_f(v0[1]); h[2] = sigmoid_f(v0[2]); h[3] = sigmoid_f(v0[3]);
;                         h[4] = sigmoid_f(v1[0]); h[5] = sigmoid_f(v1[1]); h[6] = sigmoid_f(v1[2]); h[7] = sigmoid_f(v1[3]);
;                     }
;                     u32x4 w; w.x = cvtpk(h[0], h[1]); w.y = cvtpk(h[2], h[3]); w.z = cvtpk(h[4], h[5]); w.w = cvtpk(h[6], h[7]);
;                     *p = w;
.LBB0_1806:
	v_cvt_pk_bf16_f32 v94, v108, v109
	v_mul_f32_e32 v98, 0xbfb8aa3b, v86
	v_mul_f32_e32 v99, 0xbfb8aa3b, v87
	v_mul_f32_e32 v100, 0xbfb8aa3b, v88
	v_mul_f32_e32 v101, 0xbfb8aa3b, v89
	v_mul_f32_e32 v108, 0xbfb8aa3b, v82
	v_mul_f32_e32 v109, 0xbfb8aa3b, v83
	v_mul_f32_e32 v120, 0xbfb8aa3b, v84
	v_mul_f32_e32 v121, 0xbfb8aa3b, v85
	v_cvt_pk_bf16_f32 v95, v110, v111
	v_cvt_pk_bf16_f32 v96, v112, v113
	v_cvt_pk_bf16_f32 v97, v118, v119
	v_exp_f32_e32 v119, v98
	v_exp_f32_e32 v118, v99
	v_exp_f32_e32 v113, v100
	v_exp_f32_e32 v112, v101
	v_exp_f32_e32 v111, v108
	v_exp_f32_e32 v110, v109
	v_exp_f32_e32 v109, v120
	v_exp_f32_e32 v108, v121
	s_and_b64 vcc, exec, s[42:43]
	s_mov_b64 s[68:69], -1
	global_store_dwordx4 v[106:107], v[94:97], off offset:256 nt
	s_cbranch_vccnz .LBB0_1808
	s_nop 0
	v_add_f32_e32 v94, 1.0, v119
	v_add_f32_e32 v95, 1.0, v118
	v_add_f32_e32 v96, 1.0, v113
	v_add_f32_e32 v97, 1.0, v112
	v_add_f32_e32 v98, 1.0, v111
	v_add_f32_e32 v99, 1.0, v110
	v_add_f32_e32 v100, 1.0, v109
	v_add_f32_e32 v101, 1.0, v108
	v_rcp_f32_e32 v94, v94
	v_rcp_f32_e32 v95, v95
	v_rcp_f32_e32 v96, v96
	v_rcp_f32_e32 v97, v97
	v_rcp_f32_e32 v98, v98
	v_rcp_f32_e32 v99, v99
	v_rcp_f32_e32 v100, v100
	v_rcp_f32_e32 v101, v101
	s_mov_b64 s[68:69], 0

; DI unsigned cvtpk(float lo, float hi) { f32x2_t v = {lo, hi}; bf16x2_t b = __builtin_convertvector(v, bf16x2_t); return __builtin_bit_cast(unsigned, b); }
; DI float bflo(unsigned w) { return __uint_as_float(w << 16); }
; DI float bfhi(unsigned w) { return __uint_as_float(w & 0xffff0000u); }
; DI float silu_f(float x) { return x * __builtin_amdgcn_rcpf(1.f + __expf(-x)); }
; DI float sigmoid_f(float x) { return __builtin_amdgcn_rcpf(1.f + __expf(-x)); }
;     __device__ __forceinline__ void operator()(const f32x4 (&acc)[2][2][4][2], const Unit& u, int wr, int wc, int fr, int fq) const {
;     ...
;             for (int m = 0; m < 4; ++m) {
;                 bf16_t* rowp = base + (size_t)(row0 + ai * HALF + m * 16) * ldc + c0 + cin;
; #pragma unroll
;                 for (int bj = 0; bj < 2; ++bj) {
;                     const f32x4 v0 = acc[ai][bj][m][0], v1 = acc[ai][bj][m][1];
;                     u32x4* p = (u32x4*)(rowp + bj * HALF);
;                     float h[8];
;                     if (mul) {
;                         const u32x4 o = ol[m][bj];
;                         h[0] = bflo(o.x) * silu_f(v0[0]); h[1] = bfhi(o.x) * silu_f(v0[1]); h[2] = bflo(o.y) * silu_f(v0[2]); h[3] = bfhi(o.y) * silu_f(v0[3]);
;                         h[4] = bflo(o.z) * silu_f(v1[0]); h[5] = bfhi(o.z) * silu_f(v1[1]); h[6] = bflo(o.w) * silu_f(v1[2]); h[7] = bfhi(o.w) * silu_f(v1[3]);
;                     } else {
;                         h[0] = sigmoid_f(v0[0]); h[1] = sigmoid_f(v0[1]); h[2] = sigmoid_f(v0[2]); h[3] = sigmoid_f(v0[3]);
;                         h[4] = sigmoid_f(v1[0]); h[5] = sigmoid_f(v1[1]); h[6] = sigmoid_f(v1[2]); h[7] = sigmoid_f(v1[3]);
;                     }
;                     u32x4 w; w.x = cvtpk(h[0], h[1]); w.y = cvtpk(h[2], h[3]); w.z = cvtpk(h[4], h[5]); w.w = cvtpk(h[6], h[7]);
;                     *p = w;
.LBB0_1810:
	v_cvt_pk_bf16_f32 v84, v94, v95
	v_cvt_pk_bf16_f32 v85, v96, v97
	v_mul_f32_e32 v88, 0xbfb8aa3b, v74
	v_mul_f32_e32 v89, 0xbfb8aa3b, v75
	v_mul_f32_e32 v94, 0xbfb8aa3b, v76
	v_mul_f32_e32 v95, 0xbfb8aa3b, v77
	v_mul_f32_e32 v96, 0xbfb8aa3b, v70
	v_mul_f32_e32 v97, 0xbfb8aa3b, v71
	v_mul_f32_e32 v108, 0xbfb8aa3b, v72
	v_mul_f32_e32 v109, 0xbfb8aa3b, v73
	v_cvt_pk_bf16_f32 v86, v98, v99
	v_cvt_pk_bf16_f32 v87, v100, v101
	v_exp_f32_e32 v107, v88
	v_exp_f32_e32 v106, v89
	v_exp_f32_e32 v101, v94
	v_exp_f32_e32 v100, v95
	v_exp_f32_e32 v99, v96
	v_exp_f32_e32 v98, v97
	v_exp_f32_e32 v97, v108
	v_exp_f32_e32 v96, v109
	v_mad_u64_u32 v[82:83], s[8:9], s64, v191, 0
	v_add3_u32 v83, v83, v175, v192
	v_lshl_add_u64 v[82:83], v[82:83], 1, v[176:177]
	s_and_b64 vcc, exec, s[42:43]
	s_mov_b64 s[68:69], -1
	global_store_dwordx4 v[82:83], v[84:87], off nt
	s_cbranch_vccnz .LBB0_1812
	s_nop 0
	v_add_f32_e32 v84, 1.0, v107
	v_add_f32_e32 v85, 1.0, v106
	v_add_f32_e32 v86, 1.0, v101
	v_add_f32_e32 v87, 1.0, v100
	v_add_f32_e32 v88, 1.0, v99
	v_add_f32_e32 v89, 1.0, v98
	v_add_f32_e32 v94, 1.0, v97
	v_add_f32_e32 v95, 1.0, v96
	v_rcp_f32_e32 v84, v84
	v_rcp_f32_e32 v85, v85
	v_rcp_f32_e32 v86, v86
	v_rcp_f32_e32 v87, v87
	v_rcp_f32_e32 v88, v88
	v_rcp_f32_e32 v89, v89
	v_rcp_f32_e32 v94, v94
	v_rcp_f32_e32 v95, v95
	s_mov_b64 s[68:69], 0

; DI unsigned cvtpk(float lo, float hi) { f32x2_t v = {lo, hi}; bf16x2_t b = __builtin_convertvector(v, bf16x2_t); return __builtin_bit_cast(unsigned, b); }
; DI float bflo(unsigned w) { return __uint_as_float(w << 16); }
; DI float bfhi(unsigned w) { return __uint_as_float(w & 0xffff0000u); }
; DI float silu_f(float x) { return x * __builtin_amdgcn_rcpf(1.f + __expf(-x)); }
; DI float sigmoid_f(float x) { return __builtin_amdgcn_rcpf(1.f + __expf(-x)); }
;     __device__ __forceinline__ void operator()(const f32x4 (&acc)[2][2][4][2], const Unit& u, int wr, int wc, int fr, int fq) const {
;     ...
;         for (int ai = 0; ai < 2; ++ai) {
;             u32x4 ol[4][2];
;             if (mul) {
; #pragma unroll
;                 for (int m = 0; m < 4; ++m)
; #pragma unroll
;                     for (int bj = 0; bj < 2; ++bj) ol[m][bj] = *(const u32x4*)(base + (size_t)(row0 + ai * HALF + m * 16) * ldc + c0 + cin + bj * HALF);
;                 asm volatile("" ::: "memory");
;             }
; #pragma unroll
;             for (int m = 0; m < 4; ++m) {
;                 bf16_t* rowp = base + (size_t)(row0 + ai * HALF + m * 16) * ldc + c0 + cin;
; #pragma unroll
;                 for (int bj = 0; bj < 2; ++bj) {
;                     const f32x4 v0 = acc[ai][bj][m][0], v1 = acc[ai][bj][m][1];
;                     u32x4* p = (u32x4*)(rowp + bj * HALF);
;                     float h[8];
;                     if (mul) {
;                         const u32x4 o = ol[m][bj];
;                         h[0] = bflo(o.x) * silu_f(v0[0]); h[1] = bfhi(o.x) * silu_f(v0[1]); h[2] = bflo(o.y) * silu_f(v0[2]); h[3] = bfhi(o.y) * silu_f(v0[3]);
;                         h[4] = bflo(o.z) * silu_f(v1[0]); h[5] = bfhi(o.z) * silu_f(v1[1]); h[6] = bflo(o.w) * silu_f(v1[2]); h[7] = bfhi(o.w) * silu_f(v1[3]);
;                     } else {
;                         h[0] = sigmoid_f(v0[0]); h[1] = sigmoid_f(v0[1]); h[2] = sigmoid_f(v0[2]); h[3] = sigmoid_f(v0[3]);
;                         h[4] = sigmoid_f(v1[0]); h[5] = sigmoid_f(v1[1]); h[6] = sigmoid_f(v1[2]); h[7] = sigmoid_f(v1[3]);
;                     }
;                     u32x4 w; w.x = cvtpk(h[0], h[1]); w.y = cvtpk(h[2], h[3]); w.z = cvtpk(h[4], h[5]); w.w = cvtpk(h[6], h[7]);
;                     *p = w;
;                 }
;             }
.LBB0_1814:
	v_cvt_pk_bf16_f32 v70, v84, v85
	v_cvt_pk_bf16_f32 v71, v86, v87
	v_cvt_pk_bf16_f32 v72, v88, v89
	v_cvt_pk_bf16_f32 v73, v94, v95
	global_store_dwordx4 v[82:83], v[70:73], off offset:256 nt
	v_add_u32_e32 v94, 0x90, v190
	v_add_u32_e32 v87, 0xa0, v190
	v_add_u32_e32 v70, 0x80, v190
	v_ashrrev_i32_e32 v71, 31, v70
	v_mul_lo_u32 v72, s64, v71
	v_mul_lo_u32 v73, s65, v70
	v_mad_u64_u32 v[70:71], s[8:9], s64, v70, 0
	v_add3_u32 v71, v71, v72, v73
	v_add_u32_e32 v84, 0xb0, v190
	s_andn2_b64 vcc, exec, s[66:67]
	v_lshl_add_u64 v[70:71], v[70:71], 1, v[176:177]
	v_ashrrev_i32_e32 v96, 31, v94
	v_mul_lo_u32 v95, s65, v94
	v_ashrrev_i32_e32 v89, 31, v87
	v_mul_lo_u32 v88, s65, v87
	v_ashrrev_i32_e32 v86, 31, v84
	v_mul_lo_u32 v85, s65, v84
	s_cbranch_vccnz .LBB0_1816
	s_waitcnt vmcnt(0)
	v_mul_lo_u32 v68, s64, v96
	v_mad_u64_u32 v[66:67], s[8:9], s64, v94, 0
	v_add3_u32 v67, v67, v68, v95
	v_lshl_add_u64 v[66:67], v[66:67], 1, v[176:177]
	global_load_dwordx4 v[150:153], v[70:71], off
	global_load_dwordx4 v[138:141], v[70:71], off offset:256
	global_load_dwordx4 v[126:129], v[66:67], off
	global_load_dwordx4 v[114:117], v[66:67], off offset:256
	v_mul_lo_u32 v68, s64, v89
	v_mad_u64_u32 v[66:67], s[8:9], s64, v87, 0
	v_add3_u32 v67, v67, v68, v88
	v_lshl_add_u64 v[66:67], v[66:67], 1, v[176:177]
	global_load_dwordx4 v[102:105], v[66:67], off
	global_load_dwordx4 v[90:93], v[66:67], off offset:256
	v_mul_lo_u32 v68, s64, v86
	v_mad_u64_u32 v[66:67], s[8:9], s64, v84, 0
	v_add3_u32 v67, v67, v68, v85
	v_lshl_add_u64 v[66:67], v[66:67], 1, v[176:177]
	global_load_dwordx4 v[78:81], v[66:67], off
	s_nop 0
	global_load_dwordx4 v[66:69], v[66:67], off offset:256

; DI unsigned cvtpk(float lo, float hi) { f32x2_t v = {lo, hi}; bf16x2_t b = __builtin_convertvector(v, bf16x2_t); return __builtin_bit_cast(unsigned, b); }
; DI float bflo(unsigned w) { return __uint_as_float(w << 16); }
; DI float bfhi(unsigned w) { return __uint_as_float(w & 0xffff0000u); }
; DI float silu_f(float x) { return x * __builtin_amdgcn_rcpf(1.f + __expf(-x)); }
; DI float sigmoid_f(float x) { return __builtin_amdgcn_rcpf(1.f + __expf(-x)); }
;     __device__ __forceinline__ void operator()(const f32x4 (&acc)[2][2][4][2], const Unit& u, int wr, int wc, int fr, int fq) const {
;     ...
; #pragma unroll
;             for (int m = 0; m < 4; ++m) {
;                 bf16_t* rowp = base + (size_t)(row0 + ai * HALF + m * 16) * ldc + c0 + cin;
; #pragma unroll
;                 for (int bj = 0; bj < 2; ++bj) {
;                     const f32x4 v0 = acc[ai][bj][m][0], v1 = acc[ai][bj][m][1];
;                     u32x4* p = (u32x4*)(rowp + bj * HALF);
;                     float h[8];
;                     if (mul) {
;                         const u32x4 o = ol[m][bj];
;                         h[0] = bflo(o.x) * silu_f(v0[0]); h[1] = bfhi(o.x) * silu_f(v0[1]); h[2] = bflo(o.y) * silu_f(v0[2]); h[3] = bfhi(o.y) * silu_f(v0[3]);
;                         h[4] = bflo(o.z) * silu_f(v1[0]); h[5] = bfhi(o.z) * silu_f(v1[1]); h[6] = bflo(o.w) * silu_f(v1[2]); h[7] = bfhi(o.w) * silu_f(v1[3]);
;                     } else {
;                         h[0] = sigmoid_f(v0[0]); h[1] = sigmoid_f(v0[1]); h[2] = sigmoid_f(v0[2]); h[3] = sigmoid_f(v0[3]);
;                         h[4] = sigmoid_f(v1[0]); h[5] = sigmoid_f(v1[1]); h[6] = sigmoid_f(v1[2]); h[7] = sigmoid_f(v1[3]);
;                     }
;                     u32x4 w; w.x = cvtpk(h[0], h[1]); w.y = cvtpk(h[2], h[3]); w.z = cvtpk(h[4], h[5]); w.w = cvtpk(h[6], h[7]);
;                     *p = w;
.LBB0_1820:
	v_cvt_pk_bf16_f32 v58, v72, v73
	v_mul_f32_e32 v62, 0xbfb8aa3b, v54
	v_mul_f32_e32 v63, 0xbfb8aa3b, v55
	v_mul_f32_e32 v64, 0xbfb8aa3b, v56
	v_mul_f32_e32 v65, 0xbfb8aa3b, v57
	v_mul_f32_e32 v72, 0xbfb8aa3b, v50
	v_mul_f32_e32 v73, 0xbfb8aa3b, v51
	v_mul_f32_e32 v97, 0xbfb8aa3b, v52
	v_mul_f32_e32 v98, 0xbfb8aa3b, v53
	v_cvt_pk_bf16_f32 v59, v74, v75
	v_cvt_pk_bf16_f32 v60, v76, v77
	v_cvt_pk_bf16_f32 v61, v82, v83
	v_exp_f32_e32 v83, v62
	v_exp_f32_e32 v82, v63
	v_exp_f32_e32 v77, v64
	v_exp_f32_e32 v76, v65
	v_exp_f32_e32 v75, v72
	v_exp_f32_e32 v74, v73
	v_exp_f32_e32 v73, v97
	v_exp_f32_e32 v72, v98
	s_and_b64 vcc, exec, s[42:43]
	s_mov_b64 s[66:67], -1
	global_store_dwordx4 v[70:71], v[58:61], off nt
	s_cbranch_vccnz .LBB0_1822
	s_nop 0
	v_add_f32_e32 v58, 1.0, v83
	v_add_f32_e32 v59, 1.0, v82
	v_add_f32_e32 v60, 1.0, v77
	v_add_f32_e32 v61, 1.0, v76
	v_add_f32_e32 v62, 1.0, v75
	v_add_f32_e32 v63, 1.0, v74
	v_add_f32_e32 v64, 1.0, v73
	v_add_f32_e32 v65, 1.0, v72
	v_rcp_f32_e32 v58, v58
	v_rcp_f32_e32 v59, v59
	v_rcp_f32_e32 v60, v60
	v_rcp_f32_e32 v61, v61
	v_rcp_f32_e32 v62, v62
	v_rcp_f32_e32 v63, v63
	v_rcp_f32_e32 v64, v64
	v_rcp_f32_e32 v65, v65
	s_mov_b64 s[66:67], 0

; DI unsigned cvtpk(float lo, float hi) { f32x2_t v = {lo, hi}; bf16x2_t b = __builtin_convertvector(v, bf16x2_t); return __builtin_bit_cast(unsigned, b); }
; DI float bflo(unsigned w) { return __uint_as_float(w << 16); }
; DI float bfhi(unsigned w) { return __uint_as_float(w & 0xffff0000u); }
; DI float silu_f(float x) { return x * __builtin_amdgcn_rcpf(1.f + __expf(-x)); }
; DI float sigmoid_f(float x) { return __builtin_amdgcn_rcpf(1.f + __expf(-x)); }
;     __device__ __forceinline__ void operator()(const f32x4 (&acc)[2][2][4][2], const Unit& u, int wr, int wc, int fr, int fq) const {
;     ...
; #pragma unroll
;             for (int m = 0; m < 4; ++m) {
;                 bf16_t* rowp = base + (size_t)(row0 + ai * HALF + m * 16) * ldc + c0 + cin;
; #pragma unroll
;                 for (int bj = 0; bj < 2; ++bj) {
;                     const f32x4 v0 = acc[ai][bj][m][0], v1 = acc[ai][bj][m][1];
;                     u32x4* p = (u32x4*)(rowp + bj * HALF);
;                     float h[8];
;                     if (mul) {
;                         const u32x4 o = ol[m][bj];
;                         h[0] = bflo(o.x) * silu_f(v0[0]); h[1] = bfhi(o.x) * silu_f(v0[1]); h[2] = bflo(o.y) * silu_f(v0[2]); h[3] = bfhi(o.y) * silu_f(v0[3]);
;                         h[4] = bflo(o.z) * silu_f(v1[0]); h[5] = bfhi(o.z) * silu_f(v1[1]); h[6] = bflo(o.w) * silu_f(v1[2]); h[7] = bfhi(o.w) * silu_f(v1[3]);
;                     } else {
;                         h[0] = sigmoid_f(v0[0]); h[1] = sigmoid_f(v0[1]); h[2] = sigmoid_f(v0[2]); h[3] = sigmoid_f(v0[3]);
;                         h[4] = sigmoid_f(v1[0]); h[5] = sigmoid_f(v1[1]); h[6] = sigmoid_f(v1[2]); h[7] = sigmoid_f(v1[3]);
;                     }
;                     u32x4 w; w.x = cvtpk(h[0], h[1]); w.y = cvtpk(h[2], h[3]); w.z = cvtpk(h[4], h[5]); w.w = cvtpk(h[6], h[7]);
;                     *p = w;
.LBB0_1824:
	v_cvt_pk_bf16_f32 v50, v58, v59
	v_mul_f32_e32 v54, 0xbfb8aa3b, v46
	v_mul_f32_e32 v55, 0xbfb8aa3b, v47
	v_mul_f32_e32 v56, 0xbfb8aa3b, v48
	v_mul_f32_e32 v57, 0xbfb8aa3b, v49
	v_mul_f32_e32 v58, 0xbfb8aa3b, v42
	v_mul_f32_e32 v59, 0xbfb8aa3b, v43
	v_mul_f32_e32 v72, 0xbfb8aa3b, v44
	v_mul_f32_e32 v73, 0xbfb8aa3b, v45
	v_cvt_pk_bf16_f32 v51, v60, v61
	v_cvt_pk_bf16_f32 v52, v62, v63
	v_cvt_pk_bf16_f32 v53, v64, v65
	v_exp_f32_e32 v65, v54
	v_exp_f32_e32 v64, v55
	v_exp_f32_e32 v63, v56
	v_exp_f32_e32 v62, v57
	v_exp_f32_e32 v61, v58
	v_exp_f32_e32 v60, v59
	v_exp_f32_e32 v59, v72
	v_exp_f32_e32 v58, v73
	s_and_b64 vcc, exec, s[42:43]
	s_mov_b64 s[66:67], -1
	global_store_dwordx4 v[70:71], v[50:53], off offset:256 nt
	s_cbranch_vccnz .LBB0_1826
	s_nop 0
	v_add_f32_e32 v50, 1.0, v65
	v_add_f32_e32 v51, 1.0, v64
	v_add_f32_e32 v52, 1.0, v63
	v_add_f32_e32 v53, 1.0, v62
	v_add_f32_e32 v54, 1.0, v61
	v_add_f32_e32 v55, 1.0, v60
	v_add_f32_e32 v56, 1.0, v59
	v_add_f32_e32 v57, 1.0, v58
	v_rcp_f32_e32 v50, v50
	v_rcp_f32_e32 v51, v51
	v_rcp_f32_e32 v52, v52
	v_rcp_f32_e32 v53, v53
	v_rcp_f32_e32 v54, v54
	v_rcp_f32_e32 v55, v55
	v_rcp_f32_e32 v56, v56
	v_rcp_f32_e32 v57, v57
	s_mov_b64 s[66:67], 0

; DI unsigned cvtpk(float lo, float hi) { f32x2_t v = {lo, hi}; bf16x2_t b = __builtin_convertvector(v, bf16x2_t); return __builtin_bit_cast(unsigned, b); }
; DI float bflo(unsigned w) { return __uint_as_float(w << 16); }
; DI float bfhi(unsigned w) { return __uint_as_float(w & 0xffff0000u); }
; DI float silu_f(float x) { return x * __builtin_amdgcn_rcpf(1.f + __expf(-x)); }
; DI float sigmoid_f(float x) { return __builtin_amdgcn_rcpf(1.f + __expf(-x)); }
;     __device__ __forceinline__ void operator()(const f32x4 (&acc)[2][2][4][2], const Unit& u, int wr, int wc, int fr, int fq) const {
;     ...
;             for (int m = 0; m < 4; ++m) {
;                 bf16_t* rowp = base + (size_t)(row0 + ai * HALF + m * 16) * ldc + c0 + cin;
; #pragma unroll
;                 for (int bj = 0; bj < 2; ++bj) {
;                     const f32x4 v0 = acc[ai][bj][m][0], v1 = acc[ai][bj][m][1];
;                     u32x4* p = (u32x4*)(rowp + bj * HALF);
;                     float h[8];
;                     if (mul) {
;                         const u32x4 o = ol[m][bj];
;                         h[0] = bflo(o.x) * silu_f(v0[0]); h[1] = bfhi(o.x) * silu_f(v0[1]); h[2] = bflo(o.y) * silu_f(v0[2]); h[3] = bfhi(o.y) * silu_f(v0[3]);
;                         h[4] = bflo(o.z) * silu_f(v1[0]); h[5] = bfhi(o.z) * silu_f(v1[1]); h[6] = bflo(o.w) * silu_f(v1[2]); h[7] = bfhi(o.w) * silu_f(v1[3]);
;                     } else {
;                         h[0] = sigmoid_f(v0[0]); h[1] = sigmoid_f(v0[1]); h[2] = sigmoid_f(v0[2]); h[3] = sigmoid_f(v0[3]);
;                         h[4] = sigmoid_f(v1[0]); h[5] = sigmoid_f(v1[1]); h[6] = sigmoid_f(v1[2]); h[7] = sigmoid_f(v1[3]);
;                     }
;                     u32x4 w; w.x = cvtpk(h[0], h[1]); w.y = cvtpk(h[2], h[3]); w.z = cvtpk(h[4], h[5]); w.w = cvtpk(h[6], h[7]);
;                     *p = w;
.LBB0_1828:
	v_mul_lo_u32 v44, s64, v96
	v_mad_u64_u32 v[42:43], s[8:9], s64, v94, 0
	v_add3_u32 v43, v43, v44, v95
	v_cvt_pk_bf16_f32 v44, v50, v51
	v_cvt_pk_bf16_f32 v45, v52, v53
	v_mul_f32_e32 v48, 0xbfb8aa3b, v38
	v_mul_f32_e32 v49, 0xbfb8aa3b, v39
	v_mul_f32_e32 v50, 0xbfb8aa3b, v40
	v_mul_f32_e32 v51, 0xbfb8aa3b, v41
	v_mul_f32_e32 v52, 0xbfb8aa3b, v34
	v_mul_f32_e32 v53, 0xbfb8aa3b, v35
	v_mul_f32_e32 v60, 0xbfb8aa3b, v36
	v_mul_f32_e32 v61, 0xbfb8aa3b, v37
	v_cvt_pk_bf16_f32 v46, v54, v55
	v_cvt_pk_bf16_f32 v47, v56, v57
	v_exp_f32_e32 v59, v48
	v_exp_f32_e32 v58, v49
	v_exp_f32_e32 v57, v50
	v_exp_f32_e32 v56, v51
	v_exp_f32_e32 v55, v52
	v_exp_f32_e32 v54, v53
	v_exp_f32_e32 v53, v60
	v_exp_f32_e32 v52, v61
	v_lshl_add_u64 v[42:43], v[42:43], 1, v[176:177]
	s_and_b64 vcc, exec, s[42:43]
	s_mov_b64 s[66:67], -1
	global_store_dwordx4 v[42:43], v[44:47], off nt
	s_cbranch_vccnz .LBB0_1830
	s_nop 0
	v_add_f32_e32 v44, 1.0, v59
	v_add_f32_e32 v45, 1.0, v58
	v_add_f32_e32 v46, 1.0, v57
	v_add_f32_e32 v47, 1.0, v56
	v_add_f32_e32 v48, 1.0, v55
	v_add_f32_e32 v49, 1.0, v54
	v_add_f32_e32 v50, 1.0, v53
	v_add_f32_e32 v51, 1.0, v52
	v_rcp_f32_e32 v44, v44
	v_rcp_f32_e32 v45, v45
	v_rcp_f32_e32 v46, v46
	v_rcp_f32_e32 v47, v47
	v_rcp_f32_e32 v48, v48
	v_rcp_f32_e32 v49, v49
	v_rcp_f32_e32 v50, v50
	v_rcp_f32_e32 v51, v51
	s_mov_b64 s[66:67], 0

; DI unsigned cvtpk(float lo, float hi) { f32x2_t v = {lo, hi}; bf16x2_t b = __builtin_convertvector(v, bf16x2_t); return __builtin_bit_cast(unsigned, b); }
; DI float bflo(unsigned w) { return __uint_as_float(w << 16); }
; DI float bfhi(unsigned w) { return __uint_as_float(w & 0xffff0000u); }
; DI float silu_f(float x) { return x * __builtin_amdgcn_rcpf(1.f + __expf(-x)); }
; DI float sigmoid_f(float x) { return __builtin_amdgcn_rcpf(1.f + __expf(-x)); }
;     __device__ __forceinline__ void operator()(const f32x4 (&acc)[2][2][4][2], const Unit& u, int wr, int wc, int fr, int fq) const {
;     ...
; #pragma unroll
;             for (int m = 0; m < 4; ++m) {
;                 bf16_t* rowp = base + (size_t)(row0 + ai * HALF + m * 16) * ldc + c0 + cin;
; #pragma unroll
;                 for (int bj = 0; bj < 2; ++bj) {
;                     const f32x4 v0 = acc[ai][bj][m][0], v1 = acc[ai][bj][m][1];
;                     u32x4* p = (u32x4*)(rowp + bj * HALF);
;                     float h[8];
;                     if (mul) {
;                         const u32x4 o = ol[m][bj];
;                         h[0] = bflo(o.x) * silu_f(v0[0]); h[1] = bfhi(o.x) * silu_f(v0[1]); h[2] = bflo(o.y) * silu_f(v0[2]); h[3] = bfhi(o.y) * silu_f(v0[3]);
;                         h[4] = bflo(o.z) * silu_f(v1[0]); h[5] = bfhi(o.z) * silu_f(v1[1]); h[6] = bflo(o.w) * silu_f(v1[2]); h[7] = bfhi(o.w) * silu_f(v1[3]);
;                     } else {
;                         h[0] = sigmoid_f(v0[0]); h[1] = sigmoid_f(v0[1]); h[2] = sigmoid_f(v0[2]); h[3] = sigmoid_f(v0[3]);
;                         h[4] = sigmoid_f(v1[0]); h[5] = sigmoid_f(v1[1]); h[6] = sigmoid_f(v1[2]); h[7] = sigmoid_f(v1[3]);
;                     }
;                     u32x4 w; w.x = cvtpk(h[0], h[1]); w.y = cvtpk(h[2], h[3]); w.z = cvtpk(h[4], h[5]); w.w = cvtpk(h[6], h[7]);
;                     *p = w;
.LBB0_1832:
	v_cvt_pk_bf16_f32 v34, v44, v45
	v_mul_f32_e32 v38, 0xbfb8aa3b, v30
	v_mul_f32_e32 v39, 0xbfb8aa3b, v31
	v_mul_f32_e32 v40, 0xbfb8aa3b, v32
	v_mul_f32_e32 v41, 0xbfb8aa3b, v33
	v_mul_f32_e32 v44, 0xbfb8aa3b, v26
	v_mul_f32_e32 v45, 0xbfb8aa3b, v27
	v_mul_f32_e32 v52, 0xbfb8aa3b, v28
	v_mul_f32_e32 v53, 0xbfb8aa3b, v29
	v_cvt_pk_bf16_f32 v35, v46, v47
	v_cvt_pk_bf16_f32 v36, v48, v49
	v_cvt_pk_bf16_f32 v37, v50, v51
	v_exp_f32_e32 v51, v38
	v_exp_f32_e32 v50, v39
	v_exp_f32_e32 v49, v40
	v_exp_f32_e32 v48, v41
	v_exp_f32_e32 v47, v44
	v_exp_f32_e32 v46, v45
	v_exp_f32_e32 v45, v52
	v_exp_f32_e32 v44, v53
	s_and_b64 vcc, exec, s[42:43]
	s_mov_b64 s[66:67], -1
	global_store_dwordx4 v[42:43], v[34:37], off offset:256 nt
	s_cbranch_vccnz .LBB0_1834
	s_nop 0
	v_add_f32_e32 v34, 1.0, v51
	v_add_f32_e32 v35, 1.0, v50
	v_add_f32_e32 v36, 1.0, v49
	v_add_f32_e32 v37, 1.0, v48
	v_add_f32_e32 v38, 1.0, v47
	v_add_f32_e32 v39, 1.0, v46
	v_add_f32_e32 v40, 1.0, v45
	v_add_f32_e32 v41, 1.0, v44
	v_rcp_f32_e32 v34, v34
	v_rcp_f32_e32 v35, v35
	v_rcp_f32_e32 v36, v36
	v_rcp_f32_e32 v37, v37
	v_rcp_f32_e32 v38, v38
	v_rcp_f32_e32 v39, v39
	v_rcp_f32_e32 v40, v40
	v_rcp_f32_e32 v41, v41
	s_mov_b64 s[66:67], 0

; DI unsigned cvtpk(float lo, float hi) { f32x2_t v = {lo, hi}; bf16x2_t b = __builtin_convertvector(v, bf16x2_t); return __builtin_bit_cast(unsigned, b); }
; DI float bflo(unsigned w) { return __uint_as_float(w << 16); }
; DI float bfhi(unsigned w) { return __uint_as_float(w & 0xffff0000u); }
; DI float silu_f(float x) { return x * __builtin_amdgcn_rcpf(1.f + __expf(-x)); }
; DI float sigmoid_f(float x) { return __builtin_amdgcn_rcpf(1.f + __expf(-x)); }
;     __device__ __forceinline__ void operator()(const f32x4 (&acc)[2][2][4][2], const Unit& u, int wr, int wc, int fr, int fq) const {
;     ...
;             for (int m = 0; m < 4; ++m) {
;                 bf16_t* rowp = base + (size_t)(row0 + ai * HALF + m * 16) * ldc + c0 + cin;
; #pragma unroll
;                 for (int bj = 0; bj < 2; ++bj) {
;                     const f32x4 v0 = acc[ai][bj][m][0], v1 = acc[ai][bj][m][1];
;                     u32x4* p = (u32x4*)(rowp + bj * HALF);
;                     float h[8];
;                     if (mul) {
;                         const u32x4 o = ol[m][bj];
;                         h[0] = bflo(o.x) * silu_f(v0[0]); h[1] = bfhi(o.x) * silu_f(v0[1]); h[2] = bflo(o.y) * silu_f(v0[2]); h[3] = bfhi(o.y) * silu_f(v0[3]);
;                         h[4] = bflo(o.z) * silu_f(v1[0]); h[5] = bfhi(o.z) * silu_f(v1[1]); h[6] = bflo(o.w) * silu_f(v1[2]); h[7] = bfhi(o.w) * silu_f(v1[3]);
;                     } else {
;                         h[0] = sigmoid_f(v0[0]); h[1] = sigmoid_f(v0[1]); h[2] = sigmoid_f(v0[2]); h[3] = sigmoid_f(v0[3]);
;                         h[4] = sigmoid_f(v1[0]); h[5] = sigmoid_f(v1[1]); h[6] = sigmoid_f(v1[2]); h[7] = sigmoid_f(v1[3]);
;                     }
;                     u32x4 w; w.x = cvtpk(h[0], h[1]); w.y = cvtpk(h[2], h[3]); w.z = cvtpk(h[4], h[5]); w.w = cvtpk(h[6], h[7]);
;                     *p = w;
.LBB0_1836:
	v_mul_lo_u32 v28, s64, v89
	v_mad_u64_u32 v[26:27], s[8:9], s64, v87, 0
	v_add3_u32 v27, v27, v28, v88
	v_cvt_pk_bf16_f32 v28, v34, v35
	v_cvt_pk_bf16_f32 v29, v36, v37
	v_mul_f32_e32 v32, 0xbfb8aa3b, v22
	v_mul_f32_e32 v33, 0xbfb8aa3b, v23
	v_mul_f32_e32 v34, 0xbfb8aa3b, v24
	v_mul_f32_e32 v35, 0xbfb8aa3b, v25
	v_mul_f32_e32 v36, 0xbfb8aa3b, v18
	v_mul_f32_e32 v37, 0xbfb8aa3b, v19
	v_mul_f32_e32 v44, 0xbfb8aa3b, v20
	v_mul_f32_e32 v45, 0xbfb8aa3b, v21
	v_cvt_pk_bf16_f32 v30, v38, v39
	v_cvt_pk_bf16_f32 v31, v40, v41
	v_exp_f32_e32 v43, v32
	v_exp_f32_e32 v42, v33
	v_exp_f32_e32 v41, v34
	v_exp_f32_e32 v40, v35
	v_exp_f32_e32 v39, v36
	v_exp_f32_e32 v38, v37
	v_exp_f32_e32 v37, v44
	v_exp_f32_e32 v36, v45
	v_lshl_add_u64 v[26:27], v[26:27], 1, v[176:177]
	s_and_b64 vcc, exec, s[42:43]
	s_mov_b64 s[66:67], -1
	global_store_dwordx4 v[26:27], v[28:31], off nt
	s_cbranch_vccnz .LBB0_1838
	s_nop 0
	v_add_f32_e32 v28, 1.0, v43
	v_add_f32_e32 v29, 1.0, v42
	v_add_f32_e32 v30, 1.0, v41
	v_add_f32_e32 v31, 1.0, v40
	v_add_f32_e32 v32, 1.0, v39
	v_add_f32_e32 v33, 1.0, v38
	v_add_f32_e32 v34, 1.0, v37
	v_add_f32_e32 v35, 1.0, v36
	v_rcp_f32_e32 v28, v28
	v_rcp_f32_e32 v29, v29
	v_rcp_f32_e32 v30, v30
	v_rcp_f32_e32 v31, v31
	v_rcp_f32_e32 v32, v32
	v_rcp_f32_e32 v33, v33
	v_rcp_f32_e32 v34, v34
	v_rcp_f32_e32 v35, v35
	s_mov_b64 s[66:67], 0

; DI unsigned cvtpk(float lo, float hi) { f32x2_t v = {lo, hi}; bf16x2_t b = __builtin_convertvector(v, bf16x2_t); return __builtin_bit_cast(unsigned, b); }
; DI float bflo(unsigned w) { return __uint_as_float(w << 16); }
; DI float bfhi(unsigned w) { return __uint_as_float(w & 0xffff0000u); }
; DI float silu_f(float x) { return x * __builtin_amdgcn_rcpf(1.f + __expf(-x)); }
; DI float sigmoid_f(float x) { return __builtin_amdgcn_rcpf(1.f + __expf(-x)); }
;     __device__ __forceinline__ void operator()(const f32x4 (&acc)[2][2][4][2], const Unit& u, int wr, int wc, int fr, int fq) const {
;     ...
; #pragma unroll
;             for (int m = 0; m < 4; ++m) {
;                 bf16_t* rowp = base + (size_t)(row0 + ai * HALF + m * 16) * ldc + c0 + cin;
; #pragma unroll
;                 for (int bj = 0; bj < 2; ++bj) {
;                     const f32x4 v0 = acc[ai][bj][m][0], v1 = acc[ai][bj][m][1];
;                     u32x4* p = (u32x4*)(rowp + bj * HALF);
;                     float h[8];
;                     if (mul) {
;                         const u32x4 o = ol[m][bj];
;                         h[0] = bflo(o.x) * silu_f(v0[0]); h[1] = bfhi(o.x) * silu_f(v0[1]); h[2] = bflo(o.y) * silu_f(v0[2]); h[3] = bfhi(o.y) * silu_f(v0[3]);
;                         h[4] = bflo(o.z) * silu_f(v1[0]); h[5] = bfhi(o.z) * silu_f(v1[1]); h[6] = bflo(o.w) * silu_f(v1[2]); h[7] = bfhi(o.w) * silu_f(v1[3]);
;                     } else {
;                         h[0] = sigmoid_f(v0[0]); h[1] = sigmoid_f(v0[1]); h[2] = sigmoid_f(v0[2]); h[3] = sigmoid_f(v0[3]);
;                         h[4] = sigmoid_f(v1[0]); h[5] = sigmoid_f(v1[1]); h[6] = sigmoid_f(v1[2]); h[7] = sigmoid_f(v1[3]);
;                     }
;                     u32x4 w; w.x = cvtpk(h[0], h[1]); w.y = cvtpk(h[2], h[3]); w.z = cvtpk(h[4], h[5]); w.w = cvtpk(h[6], h[7]);
;                     *p = w;
.LBB0_1840:
	v_cvt_pk_bf16_f32 v18, v28, v29
	v_mul_f32_e32 v22, 0xbfb8aa3b, v14
	v_mul_f32_e32 v23, 0xbfb8aa3b, v15
	v_mul_f32_e32 v24, 0xbfb8aa3b, v16
	v_mul_f32_e32 v25, 0xbfb8aa3b, v17
	v_mul_f32_e32 v28, 0xbfb8aa3b, v10
	v_mul_f32_e32 v29, 0xbfb8aa3b, v11
	v_mul_f32_e32 v36, 0xbfb8aa3b, v12
	v_mul_f32_e32 v37, 0xbfb8aa3b, v13
	v_cvt_pk_bf16_f32 v19, v30, v31
	v_cvt_pk_bf16_f32 v20, v32, v33
	v_cvt_pk_bf16_f32 v21, v34, v35
	v_exp_f32_e32 v35, v22
	v_exp_f32_e32 v34, v23
	v_exp_f32_e32 v33, v24
	v_exp_f32_e32 v32, v25
	v_exp_f32_e32 v31, v28
	v_exp_f32_e32 v30, v29
	v_exp_f32_e32 v29, v36
	v_exp_f32_e32 v28, v37
	s_and_b64 vcc, exec, s[42:43]
	s_mov_b64 s[66:67], -1
	global_store_dwordx4 v[26:27], v[18:21], off offset:256 nt
	s_cbranch_vccnz .LBB0_1842
	s_nop 0
	v_add_f32_e32 v18, 1.0, v35
	v_add_f32_e32 v19, 1.0, v34
	v_add_f32_e32 v20, 1.0, v33
	v_add_f32_e32 v21, 1.0, v32
	v_add_f32_e32 v22, 1.0, v31
	v_add_f32_e32 v23, 1.0, v30
	v_add_f32_e32 v24, 1.0, v29
	v_add_f32_e32 v25, 1.0, v28
	v_rcp_f32_e32 v18, v18
	v_rcp_f32_e32 v19, v19
	v_rcp_f32_e32 v20, v20
	v_rcp_f32_e32 v21, v21
	v_rcp_f32_e32 v22, v22
	v_rcp_f32_e32 v23, v23
	v_rcp_f32_e32 v24, v24
	v_rcp_f32_e32 v25, v25
	s_mov_b64 s[66:67], 0

; DI unsigned cvtpk(float lo, float hi) { f32x2_t v = {lo, hi}; bf16x2_t b = __builtin_convertvector(v, bf16x2_t); return __builtin_bit_cast(unsigned, b); }
; DI float bflo(unsigned w) { return __uint_as_float(w << 16); }
; DI float bfhi(unsigned w) { return __uint_as_float(w & 0xffff0000u); }
; DI float silu_f(float x) { return x * __builtin_amdgcn_rcpf(1.f + __expf(-x)); }
; DI float sigmoid_f(float x) { return __builtin_amdgcn_rcpf(1.f + __expf(-x)); }
;     __device__ __forceinline__ void operator()(const f32x4 (&acc)[2][2][4][2], const Unit& u, int wr, int wc, int fr, int fq) const {
;     ...
;             for (int m = 0; m < 4; ++m) {
;                 bf16_t* rowp = base + (size_t)(row0 + ai * HALF + m * 16) * ldc + c0 + cin;
; #pragma unroll
;                 for (int bj = 0; bj < 2; ++bj) {
;                     const f32x4 v0 = acc[ai][bj][m][0], v1 = acc[ai][bj][m][1];
;                     u32x4* p = (u32x4*)(rowp + bj * HALF);
;                     float h[8];
;                     if (mul) {
;                         const u32x4 o = ol[m][bj];
;                         h[0] = bflo(o.x) * silu_f(v0[0]); h[1] = bfhi(o.x) * silu_f(v0[1]); h[2] = bflo(o.y) * silu_f(v0[2]); h[3] = bfhi(o.y) * silu_f(v0[3]);
;                         h[4] = bflo(o.z) * silu_f(v1[0]); h[5] = bfhi(o.z) * silu_f(v1[1]); h[6] = bflo(o.w) * silu_f(v1[2]); h[7] = bfhi(o.w) * silu_f(v1[3]);
;                     } else {
;                         h[0] = sigmoid_f(v0[0]); h[1] = sigmoid_f(v0[1]); h[2] = sigmoid_f(v0[2]); h[3] = sigmoid_f(v0[3]);
;                         h[4] = sigmoid_f(v1[0]); h[5] = sigmoid_f(v1[1]); h[6] = sigmoid_f(v1[2]); h[7] = sigmoid_f(v1[3]);
;                     }
;                     u32x4 w; w.x = cvtpk(h[0], h[1]); w.y = cvtpk(h[2], h[3]); w.z = cvtpk(h[4], h[5]); w.w = cvtpk(h[6], h[7]);
;                     *p = w;
.LBB0_1844:
	v_mul_lo_u32 v12, s64, v86
	v_mad_u64_u32 v[10:11], s[8:9], s64, v84, 0
	v_add3_u32 v11, v11, v12, v85
	v_cvt_pk_bf16_f32 v12, v18, v19
	v_cvt_pk_bf16_f32 v13, v20, v21
	v_mul_f32_e32 v16, 0xbfb8aa3b, v6
	v_mul_f32_e32 v17, 0xbfb8aa3b, v7
	v_mul_f32_e32 v18, 0xbfb8aa3b, v8
	v_mul_f32_e32 v19, 0xbfb8aa3b, v9
	v_mul_f32_e32 v20, 0xbfb8aa3b, v2
	v_mul_f32_e32 v21, 0xbfb8aa3b, v3
	v_mul_f32_e32 v28, 0xbfb8aa3b, v4
	v_mul_f32_e32 v29, 0xbfb8aa3b, v5
	v_cvt_pk_bf16_f32 v14, v22, v23
	v_cvt_pk_bf16_f32 v15, v24, v25
	v_exp_f32_e32 v27, v16
	v_exp_f32_e32 v26, v17
	v_exp_f32_e32 v25, v18
	v_exp_f32_e32 v24, v19
	v_exp_f32_e32 v23, v20
	v_exp_f32_e32 v22, v21
	v_exp_f32_e32 v21, v28
	v_exp_f32_e32 v20, v29
	v_lshl_add_u64 v[10:11], v[10:11], 1, v[176:177]
	s_and_b64 vcc, exec, s[42:43]
	s_mov_b64 s[42:43], -1
	global_store_dwordx4 v[10:11], v[12:15], off nt
	s_cbranch_vccnz .LBB0_1846
	s_nop 0
	v_add_f32_e32 v12, 1.0, v27
	v_add_f32_e32 v13, 1.0, v26
	v_add_f32_e32 v14, 1.0, v25
	v_add_f32_e32 v15, 1.0, v24
	v_add_f32_e32 v16, 1.0, v23
	v_add_f32_e32 v17, 1.0, v22
	v_add_f32_e32 v18, 1.0, v21
	v_add_f32_e32 v19, 1.0, v20
	v_rcp_f32_e32 v12, v12
	v_rcp_f32_e32 v13, v13
	v_rcp_f32_e32 v14, v14
	v_rcp_f32_e32 v15, v15
	v_rcp_f32_e32 v16, v16
	v_rcp_f32_e32 v17, v17
	v_rcp_f32_e32 v18, v18
	v_rcp_f32_e32 v19, v19
	s_mov_b64 s[42:43], 0

; #define PG8_BAR __builtin_amdgcn_s_barrier()
; DI unsigned cvtpk(float lo, float hi) { f32x2_t v = {lo, hi}; bf16x2_t b = __builtin_convertvector(v, bf16x2_t); return __builtin_bit_cast(unsigned, b); }
; template <class Epi, class Sched, bool ALIGN_EPI = false, bool SP2 = false>
; __device__ __forceinline__ void gemm_phase(PG8_LAS unsigned char* lds, const Gemm g, const Sched& S, const Epi& E) {
;     ...
;         if constexpr (ALIGN_EPI) { if (wr == 0) PG8_BAR; }
;         if constexpr (!Epi::AFTER_DRAIN) { E(acc, cur, wr, wc, fr, fq); S.done(cur); }
;         if (!has_next) break;
; #pragma unroll
;         for (int a = 0; a < 2; ++a)
; #pragma unroll
;             for (int b = 0; b < 2; ++b)
; #pragma unroll
;                 for (int m = 0; m < 4; ++m)
; #pragma unroll
;                     for (int n = 0; n < 2; ++n) acc[a][b][m][n] = (f32x4){0.f, 0.f, 0.f, 0.f};
;         cur = nxt; cA = nA; cB = nB; ++ui;
;         if constexpr (ALIGN_EPI) { if (wr == 1) PG8_BAR; }
;     __device__ __forceinline__ void operator()(const f32x4 (&acc)[2][2][4][2], const Unit& u, int wr, int wc, int fr, int fq) const {
;     ...
;                     u32x4 w; w.x = cvtpk(h[0], h[1]); w.y = cvtpk(h[2], h[3]); w.z = cvtpk(h[4], h[5]); w.w = cvtpk(h[6], h[7]);
;                     *p = w;
.LBB0_1848:
	v_cvt_pk_bf16_f32 v2, v12, v13
	v_cvt_pk_bf16_f32 v3, v14, v15
	v_cvt_pk_bf16_f32 v4, v16, v17
	v_cvt_pk_bf16_f32 v5, v18, v19
	global_store_dwordx4 v[10:11], v[2:5], off offset:256 nt
	s_and_b64 vcc, exec, s[40:41]
	s_mov_b64 s[40:41], -1
	s_cbranch_vccnz .LBB0_1757
	s_andn2_b64 vcc, exec, s[48:49]
	s_cbranch_vccnz .LBB0_1756
	s_barrier
	s_branch .LBB0_1756

; DI unsigned cvtpk(float lo, float hi) { f32x2_t v = {lo, hi}; bf16x2_t b = __builtin_convertvector(v, bf16x2_t); return __builtin_bit_cast(unsigned, b); }
; DI float bflo(unsigned w) { return __uint_as_float(w << 16); }
; DI float bfhi(unsigned w) { return __uint_as_float(w & 0xffff0000u); }
;     __device__ __forceinline__ void operator()(const f32x4 (&acc)[2][2][4][2], const Unit& u, int wr, int wc, int fr, int fq) const {
;     ...
;         for (int ai = 0; ai < 2; ++ai) {
;             u32x4 gl[4][2], ol[4][2];
; #pragma unroll
;             for (int m = 0; m < 4; ++m) { const size_t row = (size_t)(row0 + ai * HALF + m * 16);
; #pragma unroll
;                 for (int bj = 0; bj < 2; ++bj) { gl[m][bj] = *(const u32x4*)(G + row * 3072 + col0 + bj * HALF); if (!FIRST) ol[m][bj] = *(const u32x4*)(MRG + row * DM + col0 + bj * HALF); } }
;             asm volatile("" ::: "memory");
; #pragma unroll
;             for (int m = 0; m < 4; ++m) {
;                 const size_t row = (size_t)(row0 + ai * HALF + m * 16);
; #pragma unroll
;                 for (int bj = 0; bj < 2; ++bj) {
;                     const f32x4 v0 = acc[ai][bj][m][0], v1 = acc[ai][bj][m][1];
;                     const u32x4 g = gl[m][bj];
;                     u32x4* p = (u32x4*)(MRG + row * DM + col0 + bj * HALF);
;                     float h[8];
;                     h[0] = bflo(g.x) * v0[0]; h[1] = bfhi(g.x) * v0[1]; h[2] = bflo(g.y) * v0[2]; h[3] = bfhi(g.y) * v0[3];
;                     h[4] = bflo(g.z) * v1[0]; h[5] = bfhi(g.z) * v1[1]; h[6] = bflo(g.w) * v1[2]; h[7] = bfhi(g.w) * v1[3];
;                     if (!FIRST) { const u32x4 o = ol[m][bj];
;                         h[0] += bflo(o.x); h[1] += bfhi(o.x); h[2] += bflo(o.y); h[3] += bfhi(o.y); h[4] += bflo(o.z); h[5] += bfhi(o.z); h[6] += bflo(o.w); h[7] += bfhi(o.w); }
;                     u32x4 w; w.x = cvtpk(h[0], h[1]); w.y = cvtpk(h[2], h[3]); w.z = cvtpk(h[4], h[5]); w.w = cvtpk(h[6], h[7]);
;                     *p = w;
;                 }
.LBB0_1930:
	v_lshl_or_b32 v130, s8, 8, v179
	v_ashrrev_i32_e32 v131, 31, v130
	v_lshlrev_b64 v[166:167], 1, v[130:131]
	v_lshl_add_u32 v168, s9, 8, v1
	v_lshl_add_u64 v[170:171], s[52:53], 0, v[166:167]
	v_mad_i64_i32 v[130:131], s[8:9], v168, s97, v[170:171]
	global_load_dwordx4 v[182:185], v[130:131], off
	global_load_dwordx4 v[186:189], v[130:131], off offset:256
	v_or_b32_e32 v176, 16, v168
	v_mad_i64_i32 v[130:131], s[8:9], v176, s97, v[170:171]
	global_load_dwordx4 v[150:153], v[130:131], off
	global_load_dwordx4 v[146:149], v[130:131], off offset:256
	v_or_b32_e32 v174, 32, v168
	v_mad_i64_i32 v[130:131], s[8:9], v174, s97, v[170:171]
	global_load_dwordx4 v[142:145], v[130:131], off
	global_load_dwordx4 v[138:141], v[130:131], off offset:256
	v_or_b32_e32 v172, 48, v168
	v_mad_i64_i32 v[130:131], s[8:9], v172, s97, v[170:171]
	global_load_dwordx4 v[134:137], v[130:131], off
	s_nop 0
	global_load_dwordx4 v[130:133], v[130:131], off offset:256
	v_ashrrev_i32_e32 v169, 31, v168
	v_lshlrev_b64 v[190:191], 11, v[168:169]
	v_lshl_add_u64 v[190:191], s[50:51], 0, v[190:191]
	v_lshl_add_u64 v[190:191], v[190:191], 0, v[166:167]
	v_ashrrev_i32_e32 v177, 31, v176
	v_ashrrev_i32_e32 v175, 31, v174
	v_ashrrev_i32_e32 v173, 31, v172
	s_mov_b64 s[60:61], -1
	s_and_b64 vcc, exec, s[40:41]
	s_waitcnt vmcnt(0)
	v_lshlrev_b32_e32 v192, 16, v182
	v_and_b32_e32 v193, 0xffff0000, v182
	v_lshlrev_b32_e32 v182, 16, v183
	v_and_b32_e32 v183, 0xffff0000, v183
	v_pk_mul_f32 v[128:129], v[128:129], v[182:183]
	v_lshlrev_b32_e32 v182, 16, v184
	v_and_b32_e32 v183, 0xffff0000, v184
	v_pk_mul_f32 v[182:183], v[122:123], v[182:183]
	v_lshlrev_b32_e32 v122, 16, v185
	v_and_b32_e32 v123, 0xffff0000, v185
	v_pk_mul_f32 v[126:127], v[126:127], v[192:193]
	v_pk_mul_f32 v[184:185], v[124:125], v[122:123]
	v_cvt_pk_bf16_f32 v122, v126, v127
	v_cvt_pk_bf16_f32 v123, v128, v129
	v_cvt_pk_bf16_f32 v124, v182, v183
	v_cvt_pk_bf16_f32 v125, v184, v185
	global_store_dwordx4 v[190:191], v[122:125], off nt
	s_nop 1
	v_lshlrev_b32_e32 v122, 16, v186
	v_and_b32_e32 v123, 0xffff0000, v186
	v_pk_mul_f32 v[118:119], v[118:119], v[122:123]
	v_lshlrev_b32_e32 v122, 16, v187
	v_and_b32_e32 v123, 0xffff0000, v187
	v_pk_mul_f32 v[120:121], v[120:121], v[122:123]
	v_lshlrev_b32_e32 v122, 16, v188
	v_and_b32_e32 v123, 0xffff0000, v188
	v_pk_mul_f32 v[122:123], v[114:115], v[122:123]
	v_lshlrev_b32_e32 v114, 16, v189
	v_and_b32_e32 v115, 0xffff0000, v189
	v_pk_mul_f32 v[124:125], v[116:117], v[114:115]
	v_cvt_pk_bf16_f32 v114, v118, v119
	v_cvt_pk_bf16_f32 v115, v120, v121
	v_cvt_pk_bf16_f32 v116, v122, v123
	v_cvt_pk_bf16_f32 v117, v124, v125
	global_store_dwordx4 v[190:191], v[114:117], off offset:256 nt
	s_nop 1
	v_lshlrev_b32_e32 v116, 16, v150
	v_and_b32_e32 v117, 0xffff0000, v150
	v_pk_mul_f32 v[110:111], v[110:111], v[116:117]
	v_lshlrev_b32_e32 v116, 16, v151
	v_and_b32_e32 v117, 0xffff0000, v151
	v_pk_mul_f32 v[112:113], v[112:113], v[116:117]
	v_lshlrev_b32_e32 v116, 16, v152
	v_and_b32_e32 v117, 0xffff0000, v152
	v_lshlrev_b64 v[114:115], 11, v[176:177]
	v_pk_mul_f32 v[116:117], v[106:107], v[116:117]
	v_lshlrev_b32_e32 v106, 16, v153
	v_and_b32_e32 v107, 0xffff0000, v153
	v_lshl_add_u64 v[114:115], s[50:51], 0, v[114:115]
	v_pk_mul_f32 v[118:119], v[108:109], v[106:107]
	v_lshl_add_u64 v[114:115], v[114:115], 0, v[166:167]
	v_cvt_pk_bf16_f32 v106, v110, v111
	v_cvt_pk_bf16_f32 v107, v112, v113
	v_cvt_pk_bf16_f32 v108, v116, v117
	v_cvt_pk_bf16_f32 v109, v118, v119
	global_store_dwordx4 v[114:115], v[106:109], off nt
	s_nop 1
	v_lshlrev_b32_e32 v106, 16, v146
	v_and_b32_e32 v107, 0xffff0000, v146
	v_pk_mul_f32 v[102:103], v[102:103], v[106:107]
	v_lshlrev_b32_e32 v106, 16, v147
	v_and_b32_e32 v107, 0xffff0000, v147
	v_pk_mul_f32 v[104:105], v[104:105], v[106:107]
	v_lshlrev_b32_e32 v106, 16, v148
	v_and_b32_e32 v107, 0xffff0000, v148
	v_pk_mul_f32 v[106:107], v[98:99], v[106:107]
	v_lshlrev_b32_e32 v98, 16, v149
	v_and_b32_e32 v99, 0xffff0000, v149
	v_pk_mul_f32 v[108:109], v[100:101], v[98:99]
	v_cvt_pk_bf16_f32 v98, v102, v103
	v_cvt_pk_bf16_f32 v99, v104, v105
	v_cvt_pk_bf16_f32 v100, v106, v107
	v_cvt_pk_bf16_f32 v101, v108, v109
	global_store_dwordx4 v[114:115], v[98:101], off offset:256 nt
	v_add_u32_e32 v104, 0xb0, v168
	v_ashrrev_i32_e32 v105, 31, v104
	v_lshlrev_b32_e32 v100, 16, v142
	v_and_b32_e32 v101, 0xffff0000, v142
	v_pk_mul_f32 v[94:95], v[94:95], v[100:101]
	v_lshlrev_b32_e32 v100, 16, v143
	v_and_b32_e32 v101, 0xffff0000, v143
	v_pk_mul_f32 v[96:97], v[96:97], v[100:101]
	v_lshlrev_b32_e32 v100, 16, v144
	v_and_b32_e32 v101, 0xffff0000, v144
	v_lshlrev_b64 v[98:99], 11, v[174:175]
	v_pk_mul_f32 v[100:101], v[90:91], v[100:101]
	v_lshlrev_b32_e32 v90, 16, v145
	v_and_b32_e32 v91, 0xffff0000, v145
	v_lshl_add_u64 v[98:99], s[50:51], 0, v[98:99]
	v_pk_mul_f32 v[102:103], v[92:93], v[90:91]
	v_lshl_add_u64 v[98:99], v[98:99], 0, v[166:167]
	v_cvt_pk_bf16_f32 v90, v94, v95
	v_cvt_pk_bf16_f32 v91, v96, v97
	v_cvt_pk_bf16_f32 v92, v100, v101
	v_cvt_pk_bf16_f32 v93, v102, v103
	global_store_dwordx4 v[98:99], v[90:93], off nt
	v_add_u32_e32 v100, 0x90, v168
	v_add_u32_e32 v102, 0xa0, v168
	v_lshlrev_b32_e32 v90, 16, v138
	v_and_b32_e32 v91, 0xffff0000, v138
	v_pk_mul_f32 v[86:87], v[86:87], v[90:91]
	v_lshlrev_b32_e32 v90, 16, v139
	v_and_b32_e32 v91, 0xffff0000, v139
	v_pk_mul_f32 v[88:89], v[88:89], v[90:91]
	v_lshlrev_b32_e32 v90, 16, v140
	v_and_b32_e32 v91, 0xffff0000, v140
	v_pk_mul_f32 v[90:91], v[82:83], v[90:91]
	v_lshlrev_b32_e32 v82, 16, v141
	v_and_b32_e32 v83, 0xffff0000, v141
	v_pk_mul_f32 v[92:93], v[84:85], v[82:83]
	v_cvt_pk_bf16_f32 v82, v86, v87
; DI unsigned cvtpk(float lo, float hi) { f32x2_t v = {lo, hi}; bf16x2_t b = __builtin_convertvector(v, bf16x2_t); return __builtin_bit_cast(unsigned, b); }
; DI float bflo(unsigned w) { return __uint_as_float(w << 16); }
; DI float bfhi(unsigned w) { return __uint_as_float(w & 0xffff0000u); }
;     __device__ __forceinline__ void operator()(const f32x4 (&acc)[2][2][4][2], const Unit& u, int wr, int wc, int fr, int fq) const {
;     ...
;                 for (int bj = 0; bj < 2; ++bj) { gl[m][bj] = *(const u32x4*)(G + row * 3072 + col0 + bj * HALF); if (!FIRST) ol[m][bj] = *(const u32x4*)(MRG + row * DM + col0 + bj * HALF); } }
;             asm volatile("" ::: "memory");
; #pragma unroll
;             for (int m = 0; m < 4; ++m) {
;                 const size_t row = (size_t)(row0 + ai * HALF + m * 16);
; #pragma unroll
;                 for (int bj = 0; bj < 2; ++bj) {
;                     const f32x4 v0 = acc[ai][bj][m][0], v1 = acc[ai][bj][m][1];
;                     const u32x4 g = gl[m][bj];
;                     u32x4* p = (u32x4*)(MRG + row * DM + col0 + bj * HALF);
;                     float h[8];
;                     h[0] = bflo(g.x) * v0[0]; h[1] = bfhi(g.x) * v0[1]; h[2] = bflo(g.y) * v0[2]; h[3] = bfhi(g.y) * v0[3];
;                     h[4] = bflo(g.z) * v1[0]; h[5] = bfhi(g.z) * v1[1]; h[6] = bflo(g.w) * v1[2]; h[7] = bfhi(g.w) * v1[3];
;                     if (!FIRST) { const u32x4 o = ol[m][bj];
;                         h[0] += bflo(o.x); h[1] += bfhi(o.x); h[2] += bflo(o.y); h[3] += bfhi(o.y); h[4] += bflo(o.z); h[5] += bfhi(o.z); h[6] += bflo(o.w); h[7] += bfhi(o.w); }
;                     u32x4 w; w.x = cvtpk(h[0], h[1]); w.y = cvtpk(h[2], h[3]); w.z = cvtpk(h[4], h[5]); w.w = cvtpk(h[6], h[7]);
;                     *p = w;
;                 }
	v_cvt_pk_bf16_f32 v83, v88, v89
	v_cvt_pk_bf16_f32 v84, v90, v91
	v_cvt_pk_bf16_f32 v85, v92, v93
	global_store_dwordx4 v[98:99], v[82:85], off offset:256 nt
	v_add_u32_e32 v98, 0x80, v168
	v_ashrrev_i32_e32 v99, 31, v98
	v_lshlrev_b32_e32 v84, 16, v134
	v_and_b32_e32 v85, 0xffff0000, v134
	v_pk_mul_f32 v[78:79], v[78:79], v[84:85]
	v_lshlrev_b32_e32 v84, 16, v135
	v_and_b32_e32 v85, 0xffff0000, v135
	v_pk_mul_f32 v[80:81], v[80:81], v[84:85]
	v_lshlrev_b32_e32 v84, 16, v136
	v_and_b32_e32 v85, 0xffff0000, v136
	v_lshlrev_b64 v[82:83], 11, v[172:173]
	v_pk_mul_f32 v[84:85], v[74:75], v[84:85]
	v_lshlrev_b32_e32 v74, 16, v137
	v_and_b32_e32 v75, 0xffff0000, v137
	v_lshl_add_u64 v[82:83], s[50:51], 0, v[82:83]
	v_pk_mul_f32 v[86:87], v[76:77], v[74:75]
	v_lshl_add_u64 v[82:83], v[82:83], 0, v[166:167]
	v_cvt_pk_bf16_f32 v74, v78, v79
	v_cvt_pk_bf16_f32 v75, v80, v81
	v_cvt_pk_bf16_f32 v76, v84, v85
	v_cvt_pk_bf16_f32 v77, v86, v87
	global_store_dwordx4 v[82:83], v[74:77], off nt
	v_ashrrev_i32_e32 v101, 31, v100
	v_ashrrev_i32_e32 v103, 31, v102
	v_lshlrev_b32_e32 v74, 16, v130
	v_and_b32_e32 v75, 0xffff0000, v130
	v_pk_mul_f32 v[70:71], v[70:71], v[74:75]
	v_lshlrev_b32_e32 v74, 16, v131
	v_and_b32_e32 v75, 0xffff0000, v131
	v_pk_mul_f32 v[72:73], v[72:73], v[74:75]
	v_lshlrev_b32_e32 v74, 16, v132
	v_and_b32_e32 v75, 0xffff0000, v132
	v_pk_mul_f32 v[74:75], v[66:67], v[74:75]
	v_lshlrev_b32_e32 v66, 16, v133
	v_and_b32_e32 v67, 0xffff0000, v133
	v_pk_mul_f32 v[76:77], v[68:69], v[66:67]
	v_cvt_pk_bf16_f32 v66, v70, v71
	v_cvt_pk_bf16_f32 v67, v72, v73
	v_cvt_pk_bf16_f32 v68, v74, v75
	v_cvt_pk_bf16_f32 v69, v76, v77
	global_store_dwordx4 v[82:83], v[66:69], off offset:256 nt
	s_nop 1
	v_mad_i64_i32 v[66:67], s[8:9], v98, s97, v[170:171]
	global_load_dwordx4 v[74:77], v[66:67], off
	global_load_dwordx4 v[78:81], v[66:67], off offset:256
	v_mad_i64_i32 v[66:67], s[8:9], v100, s97, v[170:171]
	global_load_dwordx4 v[82:85], v[66:67], off
	global_load_dwordx4 v[86:89], v[66:67], off offset:256
	v_mad_i64_i32 v[66:67], s[8:9], v102, s97, v[170:171]
	global_load_dwordx4 v[90:93], v[66:67], off
	global_load_dwordx4 v[94:97], v[66:67], off offset:256
	v_mad_i64_i32 v[66:67], s[8:9], v104, s97, v[170:171]
	global_load_dwordx4 v[70:73], v[66:67], off
	s_nop 0
	global_load_dwordx4 v[66:69], v[66:67], off offset:256
	v_lshlrev_b64 v[98:99], 11, v[98:99]
	v_lshl_add_u64 v[98:99], s[50:51], 0, v[98:99]
	v_lshl_add_u64 v[98:99], v[98:99], 0, v[166:167]
	s_waitcnt vmcnt(0)
; DI unsigned cvtpk(float lo, float hi) { f32x2_t v = {lo, hi}; bf16x2_t b = __builtin_convertvector(v, bf16x2_t); return __builtin_bit_cast(unsigned, b); }
; DI float bflo(unsigned w) { return __uint_as_float(w << 16); }
; DI float bfhi(unsigned w) { return __uint_as_float(w & 0xffff0000u); }
;     __device__ __forceinline__ void operator()(const f32x4 (&acc)[2][2][4][2], const Unit& u, int wr, int wc, int fr, int fq) const {
;     ...
;                     const f32x4 v0 = acc[ai][bj][m][0], v1 = acc[ai][bj][m][1];
;                     const u32x4 g = gl[m][bj];
;                     u32x4* p = (u32x4*)(MRG + row * DM + col0 + bj * HALF);
;                     float h[8];
;                     h[0] = bflo(g.x) * v0[0]; h[1] = bfhi(g.x) * v0[1]; h[2] = bflo(g.y) * v0[2]; h[3] = bfhi(g.y) * v0[3];
;                     h[4] = bflo(g.z) * v1[0]; h[5] = bfhi(g.z) * v1[1]; h[6] = bflo(g.w) * v1[2]; h[7] = bfhi(g.w) * v1[3];
;                     if (!FIRST) { const u32x4 o = ol[m][bj];
;                         h[0] += bflo(o.x); h[1] += bfhi(o.x); h[2] += bflo(o.y); h[3] += bfhi(o.y); h[4] += bflo(o.z); h[5] += bfhi(o.z); h[6] += bflo(o.w); h[7] += bfhi(o.w); }
;                     u32x4 w; w.x = cvtpk(h[0], h[1]); w.y = cvtpk(h[2], h[3]); w.z = cvtpk(h[4], h[5]); w.w = cvtpk(h[6], h[7]);
;                     *p = w;
;                 }
	v_lshlrev_b32_e32 v106, 16, v74
	v_and_b32_e32 v107, 0xffff0000, v74
	v_lshlrev_b32_e32 v74, 16, v75
	v_and_b32_e32 v75, 0xffff0000, v75
	v_pk_mul_f32 v[64:65], v[64:65], v[74:75]
	v_lshlrev_b32_e32 v74, 16, v76
	v_and_b32_e32 v75, 0xffff0000, v76
	v_pk_mul_f32 v[74:75], v[58:59], v[74:75]
	v_lshlrev_b32_e32 v58, 16, v77
	v_and_b32_e32 v59, 0xffff0000, v77
	v_pk_mul_f32 v[62:63], v[62:63], v[106:107]
	v_pk_mul_f32 v[76:77], v[60:61], v[58:59]
	v_cvt_pk_bf16_f32 v58, v62, v63
	v_cvt_pk_bf16_f32 v59, v64, v65
	v_cvt_pk_bf16_f32 v60, v74, v75
	v_cvt_pk_bf16_f32 v61, v76, v77
	global_store_dwordx4 v[98:99], v[58:61], off nt
	s_nop 1
	v_lshlrev_b32_e32 v58, 16, v78
	v_and_b32_e32 v59, 0xffff0000, v78
	v_pk_mul_f32 v[54:55], v[54:55], v[58:59]
	v_lshlrev_b32_e32 v58, 16, v79
	v_and_b32_e32 v59, 0xffff0000, v79
	v_pk_mul_f32 v[56:57], v[56:57], v[58:59]
	v_lshlrev_b32_e32 v58, 16, v80
	v_and_b32_e32 v59, 0xffff0000, v80
	v_pk_mul_f32 v[58:59], v[50:51], v[58:59]
	v_lshlrev_b32_e32 v50, 16, v81
	v_and_b32_e32 v51, 0xffff0000, v81
	v_pk_mul_f32 v[60:61], v[52:53], v[50:51]
	v_cvt_pk_bf16_f32 v50, v54, v55
	v_cvt_pk_bf16_f32 v51, v56, v57
	v_cvt_pk_bf16_f32 v52, v58, v59
	v_cvt_pk_bf16_f32 v53, v60, v61
	global_store_dwordx4 v[98:99], v[50:53], off offset:256 nt
	s_nop 1
	v_lshlrev_b32_e32 v52, 16, v82
	v_and_b32_e32 v53, 0xffff0000, v82
	v_pk_mul_f32 v[46:47], v[46:47], v[52:53]
	v_lshlrev_b32_e32 v52, 16, v83
	v_and_b32_e32 v53, 0xffff0000, v83
	v_pk_mul_f32 v[48:49], v[48:49], v[52:53]
	v_lshlrev_b32_e32 v52, 16, v84
	v_and_b32_e32 v53, 0xffff0000, v84
	v_lshlrev_b64 v[50:51], 11, v[100:101]
	v_pk_mul_f32 v[52:53], v[42:43], v[52:53]
	v_lshlrev_b32_e32 v42, 16, v85
	v_and_b32_e32 v43, 0xffff0000, v85
	v_lshl_add_u64 v[50:51], s[50:51], 0, v[50:51]
	v_pk_mul_f32 v[54:55], v[44:45], v[42:43]
	v_lshl_add_u64 v[50:51], v[50:51], 0, v[166:167]
	v_cvt_pk_bf16_f32 v42, v46, v47
	v_cvt_pk_bf16_f32 v43, v48, v49
	v_cvt_pk_bf16_f32 v44, v52, v53
	v_cvt_pk_bf16_f32 v45, v54, v55
	global_store_dwordx4 v[50:51], v[42:45], off nt
	s_nop 1
	v_lshlrev_b32_e32 v42, 16, v86
	v_and_b32_e32 v43, 0xffff0000, v86
	v_pk_mul_f32 v[38:39], v[38:39], v[42:43]
	v_lshlrev_b32_e32 v42, 16, v87
	v_and_b32_e32 v43, 0xffff0000, v87
	v_pk_mul_f32 v[40:41], v[40:41], v[42:43]
	v_lshlrev_b32_e32 v42, 16, v88
	v_and_b32_e32 v43, 0xffff0000, v88
	v_pk_mul_f32 v[42:43], v[34:35], v[42:43]
	v_lshlrev_b32_e32 v34, 16, v89
	v_and_b32_e32 v35, 0xffff0000, v89
	v_pk_mul_f32 v[44:45], v[36:37], v[34:35]
	v_cvt_pk_bf16_f32 v34, v38, v39
	v_cvt_pk_bf16_f32 v35, v40, v41
	v_cvt_pk_bf16_f32 v36, v42, v43
	v_cvt_pk_bf16_f32 v37, v44, v45
	global_store_dwordx4 v[50:51], v[34:37], off offset:256 nt
	s_nop 1
	v_lshlrev_b32_e32 v36, 16, v90
	v_and_b32_e32 v37, 0xffff0000, v90
	v_pk_mul_f32 v[30:31], v[30:31], v[36:37]
	v_lshlrev_b32_e32 v36, 16, v91
	v_and_b32_e32 v37, 0xffff0000, v91
	v_pk_mul_f32 v[32:33], v[32:33], v[36:37]
	v_lshlrev_b32_e32 v36, 16, v92
	v_and_b32_e32 v37, 0xffff0000, v92
	v_lshlrev_b64 v[34:35], 11, v[102:103]
	v_pk_mul_f32 v[36:37], v[26:27], v[36:37]
	v_lshlrev_b32_e32 v26, 16, v93
	v_and_b32_e32 v27, 0xffff0000, v93
	v_lshl_add_u64 v[34:35], s[50:51], 0, v[34:35]
	v_pk_mul_f32 v[38:39], v[28:29], v[26:27]
	v_lshl_add_u64 v[34:35], v[34:35], 0, v[166:167]
	v_cvt_pk_bf16_f32 v26, v30, v31
	v_cvt_pk_bf16_f32 v27, v32, v33
	v_cvt_pk_bf16_f32 v28, v36, v37
	v_cvt_pk_bf16_f32 v29, v38, v39
	global_store_dwordx4 v[34:35], v[26:29], off nt
	s_nop 1
	v_lshlrev_b32_e32 v26, 16, v94
	v_and_b32_e32 v27, 0xffff0000, v94
	v_pk_mul_f32 v[22:23], v[22:23], v[26:27]
	v_lshlrev_b32_e32 v26, 16, v95
	v_and_b32_e32 v27, 0xffff0000, v95
	v_pk_mul_f32 v[24:25], v[24:25], v[26:27]
	v_lshlrev_b32_e32 v26, 16, v96
	v_and_b32_e32 v27, 0xffff0000, v96
	v_pk_mul_f32 v[26:27], v[18:19], v[26:27]
	v_lshlrev_b32_e32 v18, 16, v97
	v_and_b32_e32 v19, 0xffff0000, v97
	v_pk_mul_f32 v[28:29], v[20:21], v[18:19]
	v_cvt_pk_bf16_f32 v18, v22, v23
	v_cvt_pk_bf16_f32 v19, v24, v25
	v_cvt_pk_bf16_f32 v20, v26, v27
	v_cvt_pk_bf16_f32 v21, v28, v29
	global_store_dwordx4 v[34:35], v[18:21], off offset:256 nt
	s_nop 1
	v_lshlrev_b32_e32 v20, 16, v70
	v_and_b32_e32 v21, 0xffff0000, v70
	v_pk_mul_f32 v[14:15], v[14:15], v[20:21]
	v_lshlrev_b32_e32 v20, 16, v71
	v_and_b32_e32 v21, 0xffff0000, v71
	v_pk_mul_f32 v[16:17], v[16:17], v[20:21]
	v_lshlrev_b32_e32 v20, 16, v72
	v_and_b32_e32 v21, 0xffff0000, v72
	v_lshlrev_b64 v[18:19], 11, v[104:105]
	v_pk_mul_f32 v[20:21], v[10:11], v[20:21]
	v_lshlrev_b32_e32 v10, 16, v73
	v_and_b32_e32 v11, 0xffff0000, v73
	v_lshl_add_u64 v[18:19], s[50:51], 0, v[18:19]
	v_pk_mul_f32 v[22:23], v[12:13], v[10:11]
	v_lshl_add_u64 v[18:19], v[18:19], 0, v[166:167]
	v_cvt_pk_bf16_f32 v10, v14, v15
	v_cvt_pk_bf16_f32 v11, v16, v17
	v_cvt_pk_bf16_f32 v12, v20, v21
	v_cvt_pk_bf16_f32 v13, v22, v23
	global_store_dwordx4 v[18:19], v[10:13], off nt
	s_nop 1
	v_lshlrev_b32_e32 v10, 16, v66
	v_and_b32_e32 v11, 0xffff0000, v66
	v_pk_mul_f32 v[6:7], v[6:7], v[10:11]
	v_lshlrev_b32_e32 v10, 16, v67
	v_and_b32_e32 v11, 0xffff0000, v67
	v_pk_mul_f32 v[8:9], v[8:9], v[10:11]
	v_lshlrev_b32_e32 v10, 16, v68
	v_and_b32_e32 v11, 0xffff0000, v68
	v_pk_mul_f32 v[10:11], v[2:3], v[10:11]
	v_lshlrev_b32_e32 v2, 16, v69
	v_and_b32_e32 v3, 0xffff0000, v69
	v_pk_mul_f32 v[12:13], v[4:5], v[2:3]
	v_cvt_pk_bf16_f32 v2, v6, v7
	v_cvt_pk_bf16_f32 v3, v8, v9
	v_cvt_pk_bf16_f32 v4, v10, v11
	v_cvt_pk_bf16_f32 v5, v12, v13
	global_store_dwordx4 v[18:19], v[2:5], off offset:256 nt
	s_cbranch_vccnz .LBB0_1913
	s_andn2_b64 vcc, exec, s[48:49]
	s_cbranch_vccnz .LBB0_1912
	s_barrier
	s_branch .LBB0_1912

; DI unsigned cvtpk(float lo, float hi) { f32x2_t v = {lo, hi}; bf16x2_t b = __builtin_convertvector(v, bf16x2_t); return __builtin_bit_cast(unsigned, b); }
; DI float bflo(unsigned w) { return __uint_as_float(w << 16); }
; DI float bfhi(unsigned w) { return __uint_as_float(w & 0xffff0000u); }
;     __device__ __forceinline__ void operator()(const f32x4 (&acc)[2][2][4][2], const Unit& u, int wr, int wc, int fr, int fq) const {
;     ...
;         for (int ai = 0; ai < 2; ++ai) {
;             u32x4 gl[4][2], ol[4][2];
; #pragma unroll
;             for (int m = 0; m < 4; ++m) { const size_t row = (size_t)(row0 + ai * HALF + m * 16);
; #pragma unroll
;                 for (int bj = 0; bj < 2; ++bj) { gl[m][bj] = *(const u32x4*)(G + row * 3072 + col0 + bj * HALF); if (!FIRST) ol[m][bj] = *(const u32x4*)(MRG + row * DM + col0 + bj * HALF); } }
;             asm volatile("" ::: "memory");
; #pragma unroll
;             for (int m = 0; m < 4; ++m) {
;                 const size_t row = (size_t)(row0 + ai * HALF + m * 16);
; #pragma unroll
;                 for (int bj = 0; bj < 2; ++bj) {
;                     const f32x4 v0 = acc[ai][bj][m][0], v1 = acc[ai][bj][m][1];
;                     const u32x4 g = gl[m][bj];
;                     u32x4* p = (u32x4*)(MRG + row * DM + col0 + bj * HALF);
;                     float h[8];
;                     h[0] = bflo(g.x) * v0[0]; h[1] = bfhi(g.x) * v0[1]; h[2] = bflo(g.y) * v0[2]; h[3] = bfhi(g.y) * v0[3];
;                     h[4] = bflo(g.z) * v1[0]; h[5] = bfhi(g.z) * v1[1]; h[6] = bflo(g.w) * v1[2]; h[7] = bfhi(g.w) * v1[3];
;                     if (!FIRST) { const u32x4 o = ol[m][bj];
;                         h[0] += bflo(o.x); h[1] += bfhi(o.x); h[2] += bflo(o.y); h[3] += bfhi(o.y); h[4] += bflo(o.z); h[5] += bfhi(o.z); h[6] += bflo(o.w); h[7] += bfhi(o.w); }
;                     u32x4 w; w.x = cvtpk(h[0], h[1]); w.y = cvtpk(h[2], h[3]); w.z = cvtpk(h[4], h[5]); w.w = cvtpk(h[6], h[7]);
;                     *p = w;
;                 }
.LBB0_1960:
	v_lshl_or_b32 v130, s8, 8, v227
	v_ashrrev_i32_e32 v131, 31, v130
	v_lshl_add_u32 v200, s9, 8, v1
	v_lshlrev_b64 v[198:199], 1, v[130:131]
	v_lshl_add_u64 v[204:205], s[52:53], 0, v[198:199]
	v_ashrrev_i32_e32 v201, 31, v200
	v_lshl_add_u64 v[202:203], s[50:51], 0, v[198:199]
	v_mad_i64_i32 v[130:131], s[8:9], v200, s97, v[204:205]
	v_lshlrev_b64 v[238:239], 11, v[200:201]
	v_lshl_add_u64 v[132:133], v[202:203], 0, v[238:239]
	global_load_dwordx4 v[230:233], v[130:131], off
	global_load_dwordx4 v[234:237], v[132:133], off
	global_load_dwordx4 v[182:185], v[130:131], off offset:256
	global_load_dwordx4 v[178:181], v[132:133], off offset:256
	v_or_b32_e32 v130, 16, v200
	v_ashrrev_i32_e32 v131, 31, v130
	v_mad_i64_i32 v[132:133], s[8:9], v130, s97, v[204:205]
	v_lshlrev_b64 v[210:211], 11, v[130:131]
	v_lshl_add_u64 v[130:131], v[202:203], 0, v[210:211]
	global_load_dwordx4 v[174:177], v[132:133], off
	global_load_dwordx4 v[170:173], v[130:131], off
	global_load_dwordx4 v[166:169], v[132:133], off offset:256
	global_load_dwordx4 v[162:165], v[130:131], off offset:256
	v_or_b32_e32 v130, 32, v200
	v_ashrrev_i32_e32 v131, 31, v130
	v_mad_i64_i32 v[132:133], s[8:9], v130, s97, v[204:205]
	v_lshlrev_b64 v[208:209], 11, v[130:131]
	v_lshl_add_u64 v[130:131], v[202:203], 0, v[208:209]
	global_load_dwordx4 v[158:161], v[132:133], off
	global_load_dwordx4 v[154:157], v[130:131], off
	global_load_dwordx4 v[146:149], v[132:133], off offset:256
	global_load_dwordx4 v[138:141], v[130:131], off offset:256
	v_or_b32_e32 v130, 48, v200
	v_ashrrev_i32_e32 v131, 31, v130
	v_lshlrev_b64 v[206:207], 11, v[130:131]
	v_mad_i64_i32 v[132:133], s[8:9], v130, s97, v[204:205]
	v_lshl_add_u64 v[130:131], v[202:203], 0, v[206:207]
	global_load_dwordx4 v[150:153], v[132:133], off
	global_load_dwordx4 v[142:145], v[130:131], off
	global_load_dwordx4 v[134:137], v[132:133], off offset:256
	s_nop 0
	global_load_dwordx4 v[130:133], v[130:131], off offset:256
	v_lshl_add_u64 v[238:239], s[50:51], 0, v[238:239]
	v_lshl_add_u64 v[238:239], v[238:239], 0, v[198:199]
	s_mov_b64 s[60:61], -1
	s_and_b64 vcc, exec, s[40:41]
	s_waitcnt vmcnt(0)
	v_lshlrev_b32_e32 v240, 16, v230
	v_and_b32_e32 v241, 0xffff0000, v230
	v_lshlrev_b32_e32 v242, 16, v234
	v_and_b32_e32 v243, 0xffff0000, v234
	v_lshlrev_b32_e32 v230, 16, v231
	v_and_b32_e32 v231, 0xffff0000, v231
	v_lshlrev_b32_e32 v234, 16, v235
	v_and_b32_e32 v235, 0xffff0000, v235
	v_pk_fma_f32 v[128:129], v[128:129], v[230:231], v[234:235]
	v_lshlrev_b32_e32 v230, 16, v232
	v_and_b32_e32 v231, 0xffff0000, v232
	v_lshlrev_b32_e32 v234, 16, v236
	v_and_b32_e32 v235, 0xffff0000, v236
	v_pk_fma_f32 v[230:231], v[122:123], v[230:231], v[234:235]
	v_lshlrev_b32_e32 v122, 16, v233
	v_and_b32_e32 v123, 0xffff0000, v233
	v_lshlrev_b32_e32 v232, 16, v237
	v_and_b32_e32 v233, 0xffff0000, v237
	v_pk_fma_f32 v[126:127], v[126:127], v[240:241], v[242:243]
	v_pk_fma_f32 v[232:233], v[124:125], v[122:123], v[232:233]
	v_cvt_pk_bf16_f32 v122, v126, v127
	v_cvt_pk_bf16_f32 v123, v128, v129
	v_cvt_pk_bf16_f32 v124, v230, v231
	v_cvt_pk_bf16_f32 v125, v232, v233
	global_store_dwordx4 v[238:239], v[122:125], off nt
	s_nop 1
	v_lshlrev_b32_e32 v122, 16, v182
	v_and_b32_e32 v123, 0xffff0000, v182
	v_lshlrev_b32_e32 v124, 16, v178
	v_and_b32_e32 v125, 0xffff0000, v178
	v_pk_fma_f32 v[118:119], v[118:119], v[122:123], v[124:125]
	v_lshlrev_b32_e32 v122, 16, v183
	v_and_b32_e32 v123, 0xffff0000, v183
	v_lshlrev_b32_e32 v124, 16, v179
	v_and_b32_e32 v125, 0xffff0000, v179
	v_pk_fma_f32 v[120:121], v[120:121], v[122:123], v[124:125]
	v_lshlrev_b32_e32 v122, 16, v184
	v_and_b32_e32 v123, 0xffff0000, v184
	v_lshlrev_b32_e32 v124, 16, v180
	v_and_b32_e32 v125, 0xffff0000, v180
	v_pk_fma_f32 v[122:123], v[114:115], v[122:123], v[124:125]
	v_lshlrev_b32_e32 v114, 16, v185
	v_and_b32_e32 v115, 0xffff0000, v185
	v_lshlrev_b32_e32 v124, 16, v181
	v_and_b32_e32 v125, 0xffff0000, v181
	v_pk_fma_f32 v[124:125], v[116:117], v[114:115], v[124:125]
	v_cvt_pk_bf16_f32 v114, v118, v119
	v_cvt_pk_bf16_f32 v115, v120, v121
	v_cvt_pk_bf16_f32 v116, v122, v123
	v_cvt_pk_bf16_f32 v117, v124, v125
	global_store_dwordx4 v[238:239], v[114:117], off offset:256 nt
	v_lshlrev_b32_e32 v118, 16, v170
	v_and_b32_e32 v119, 0xffff0000, v170
	v_lshlrev_b32_e32 v116, 16, v174
	v_and_b32_e32 v117, 0xffff0000, v174
	v_pk_fma_f32 v[110:111], v[110:111], v[116:117], v[118:119]
	v_lshlrev_b32_e32 v116, 16, v175
	v_and_b32_e32 v117, 0xffff0000, v175
	v_lshlrev_b32_e32 v118, 16, v171
	v_and_b32_e32 v119, 0xffff0000, v171
	v_pk_fma_f32 v[112:113], v[112:113], v[116:117], v[118:119]
	v_lshlrev_b32_e32 v116, 16, v176
	v_and_b32_e32 v117, 0xffff0000, v176
	v_lshlrev_b32_e32 v118, 16, v172
	v_and_b32_e32 v119, 0xffff0000, v172
	v_pk_fma_f32 v[116:117], v[106:107], v[116:117], v[118:119]
	v_lshlrev_b32_e32 v106, 16, v177
	v_and_b32_e32 v107, 0xffff0000, v177
	v_lshlrev_b32_e32 v118, 16, v173
	v_and_b32_e32 v119, 0xffff0000, v173
	v_lshl_add_u64 v[114:115], s[50:51], 0, v[210:211]
	v_pk_fma_f32 v[118:119], v[108:109], v[106:107], v[118:119]
	v_lshl_add_u64 v[114:115], v[114:115], 0, v[198:199]
	v_cvt_pk_bf16_f32 v106, v110, v111
	v_cvt_pk_bf16_f32 v107, v112, v113
	v_cvt_pk_bf16_f32 v108, v116, v117
	v_cvt_pk_bf16_f32 v109, v118, v119
	global_store_dwordx4 v[114:115], v[106:109], off nt
	s_nop 1
	v_lshlrev_b32_e32 v106, 16, v166
	v_and_b32_e32 v107, 0xffff0000, v166
	v_lshlrev_b32_e32 v108, 16, v162
	v_and_b32_e32 v109, 0xffff0000, v162
	v_pk_fma_f32 v[102:103], v[102:103], v[106:107], v[108:109]
	v_lshlrev_b32_e32 v106, 16, v167
	v_and_b32_e32 v107, 0xffff0000, v167
	v_lshlrev_b32_e32 v108, 16, v163
; DI unsigned cvtpk(float lo, float hi) { f32x2_t v = {lo, hi}; bf16x2_t b = __builtin_convertvector(v, bf16x2_t); return __builtin_bit_cast(unsigned, b); }
; DI float bflo(unsigned w) { return __uint_as_float(w << 16); }
; DI float bfhi(unsigned w) { return __uint_as_float(w & 0xffff0000u); }
;     __device__ __forceinline__ void operator()(const f32x4 (&acc)[2][2][4][2], const Unit& u, int wr, int wc, int fr, int fq) const {
;     ...
;                 for (int bj = 0; bj < 2; ++bj) { gl[m][bj] = *(const u32x4*)(G + row * 3072 + col0 + bj * HALF); if (!FIRST) ol[m][bj] = *(const u32x4*)(MRG + row * DM + col0 + bj * HALF); } }
;             asm volatile("" ::: "memory");
; #pragma unroll
;             for (int m = 0; m < 4; ++m) {
;                 const size_t row = (size_t)(row0 + ai * HALF + m * 16);
; #pragma unroll
;                 for (int bj = 0; bj < 2; ++bj) {
;                     const f32x4 v0 = acc[ai][bj][m][0], v1 = acc[ai][bj][m][1];
;                     const u32x4 g = gl[m][bj];
;                     u32x4* p = (u32x4*)(MRG + row * DM + col0 + bj * HALF);
;                     float h[8];
;                     h[0] = bflo(g.x) * v0[0]; h[1] = bfhi(g.x) * v0[1]; h[2] = bflo(g.y) * v0[2]; h[3] = bfhi(g.y) * v0[3];
;                     h[4] = bflo(g.z) * v1[0]; h[5] = bfhi(g.z) * v1[1]; h[6] = bflo(g.w) * v1[2]; h[7] = bfhi(g.w) * v1[3];
;                     if (!FIRST) { const u32x4 o = ol[m][bj];
;                         h[0] += bflo(o.x); h[1] += bfhi(o.x); h[2] += bflo(o.y); h[3] += bfhi(o.y); h[4] += bflo(o.z); h[5] += bfhi(o.z); h[6] += bflo(o.w); h[7] += bfhi(o.w); }
;                     u32x4 w; w.x = cvtpk(h[0], h[1]); w.y = cvtpk(h[2], h[3]); w.z = cvtpk(h[4], h[5]); w.w = cvtpk(h[6], h[7]);
;                     *p = w;
;                 }
	v_and_b32_e32 v109, 0xffff0000, v163
	v_pk_fma_f32 v[104:105], v[104:105], v[106:107], v[108:109]
	v_lshlrev_b32_e32 v106, 16, v168
	v_and_b32_e32 v107, 0xffff0000, v168
	v_lshlrev_b32_e32 v108, 16, v164
	v_and_b32_e32 v109, 0xffff0000, v164
	v_pk_fma_f32 v[106:107], v[98:99], v[106:107], v[108:109]
	v_lshlrev_b32_e32 v98, 16, v169
	v_and_b32_e32 v99, 0xffff0000, v169
	v_lshlrev_b32_e32 v108, 16, v165
	v_and_b32_e32 v109, 0xffff0000, v165
	v_pk_fma_f32 v[108:109], v[100:101], v[98:99], v[108:109]
	v_cvt_pk_bf16_f32 v98, v102, v103
	v_cvt_pk_bf16_f32 v99, v104, v105
	v_cvt_pk_bf16_f32 v100, v106, v107
	v_cvt_pk_bf16_f32 v101, v108, v109
	global_store_dwordx4 v[114:115], v[98:101], off offset:256 nt
	v_lshlrev_b32_e32 v102, 16, v154
	v_and_b32_e32 v103, 0xffff0000, v154
	v_lshlrev_b32_e32 v100, 16, v158
	v_and_b32_e32 v101, 0xffff0000, v158
	v_pk_fma_f32 v[94:95], v[94:95], v[100:101], v[102:103]
	v_lshlrev_b32_e32 v100, 16, v159
	v_and_b32_e32 v101, 0xffff0000, v159
	v_lshlrev_b32_e32 v102, 16, v155
	v_and_b32_e32 v103, 0xffff0000, v155
	v_pk_fma_f32 v[96:97], v[96:97], v[100:101], v[102:103]
	v_lshlrev_b32_e32 v100, 16, v160
	v_and_b32_e32 v101, 0xffff0000, v160
	v_lshlrev_b32_e32 v102, 16, v156
	v_and_b32_e32 v103, 0xffff0000, v156
	v_pk_fma_f32 v[100:101], v[90:91], v[100:101], v[102:103]
	v_lshlrev_b32_e32 v90, 16, v161
	v_and_b32_e32 v91, 0xffff0000, v161
	v_lshlrev_b32_e32 v102, 16, v157
	v_and_b32_e32 v103, 0xffff0000, v157
	v_lshl_add_u64 v[98:99], s[50:51], 0, v[208:209]
	v_pk_fma_f32 v[102:103], v[92:93], v[90:91], v[102:103]
	v_lshl_add_u64 v[98:99], v[98:99], 0, v[198:199]
	v_cvt_pk_bf16_f32 v90, v94, v95
	v_cvt_pk_bf16_f32 v91, v96, v97
	v_cvt_pk_bf16_f32 v92, v100, v101
	v_cvt_pk_bf16_f32 v93, v102, v103
	global_store_dwordx4 v[98:99], v[90:93], off nt
	s_nop 1
	v_lshlrev_b32_e32 v90, 16, v146
	v_and_b32_e32 v91, 0xffff0000, v146
	v_lshlrev_b32_e32 v92, 16, v138
	v_and_b32_e32 v93, 0xffff0000, v138
	v_pk_fma_f32 v[86:87], v[86:87], v[90:91], v[92:93]
	v_lshlrev_b32_e32 v90, 16, v147
	v_and_b32_e32 v91, 0xffff0000, v147
	v_lshlrev_b32_e32 v92, 16, v139
	v_and_b32_e32 v93, 0xffff0000, v139
	v_pk_fma_f32 v[88:89], v[88:89], v[90:91], v[92:93]
	v_lshlrev_b32_e32 v90, 16, v148
	v_and_b32_e32 v91, 0xffff0000, v148
	v_lshlrev_b32_e32 v92, 16, v140
	v_and_b32_e32 v93, 0xffff0000, v140
	v_pk_fma_f32 v[90:91], v[82:83], v[90:91], v[92:93]
	v_lshlrev_b32_e32 v82, 16, v149
	v_and_b32_e32 v83, 0xffff0000, v149
	v_lshlrev_b32_e32 v92, 16, v141
	v_and_b32_e32 v93, 0xffff0000, v141
	v_pk_fma_f32 v[92:93], v[84:85], v[82:83], v[92:93]
	v_cvt_pk_bf16_f32 v82, v86, v87
	v_cvt_pk_bf16_f32 v83, v88, v89
	v_cvt_pk_bf16_f32 v84, v90, v91
	v_cvt_pk_bf16_f32 v85, v92, v93
	global_store_dwordx4 v[98:99], v[82:85], off offset:256 nt
	v_lshlrev_b32_e32 v86, 16, v142
	v_and_b32_e32 v87, 0xffff0000, v142
	v_lshlrev_b32_e32 v84, 16, v150
	v_and_b32_e32 v85, 0xffff0000, v150
	v_pk_fma_f32 v[78:79], v[78:79], v[84:85], v[86:87]
	v_lshlrev_b32_e32 v84, 16, v151
	v_and_b32_e32 v85, 0xffff0000, v151
	v_lshlrev_b32_e32 v86, 16, v143
	v_and_b32_e32 v87, 0xffff0000, v143
	v_pk_fma_f32 v[80:81], v[80:81], v[84:85], v[86:87]
	v_lshlrev_b32_e32 v84, 16, v152
	v_and_b32_e32 v85, 0xffff0000, v152
	v_lshlrev_b32_e32 v86, 16, v144
	v_and_b32_e32 v87, 0xffff0000, v144
	v_pk_fma_f32 v[84:85], v[74:75], v[84:85], v[86:87]
	v_lshlrev_b32_e32 v74, 16, v153
	v_and_b32_e32 v75, 0xffff0000, v153
	v_lshlrev_b32_e32 v86, 16, v145
	v_and_b32_e32 v87, 0xffff0000, v145
	v_lshl_add_u64 v[82:83], s[50:51], 0, v[206:207]
	v_pk_fma_f32 v[86:87], v[76:77], v[74:75], v[86:87]
	v_lshl_add_u64 v[82:83], v[82:83], 0, v[198:199]
	v_cvt_pk_bf16_f32 v74, v78, v79
	v_cvt_pk_bf16_f32 v75, v80, v81
	v_cvt_pk_bf16_f32 v76, v84, v85
	v_cvt_pk_bf16_f32 v77, v86, v87
	global_store_dwordx4 v[82:83], v[74:77], off nt
	s_nop 1
	v_lshlrev_b32_e32 v74, 16, v134
	v_and_b32_e32 v75, 0xffff0000, v134
	v_lshlrev_b32_e32 v76, 16, v130
	v_and_b32_e32 v77, 0xffff0000, v130
	v_pk_fma_f32 v[70:71], v[70:71], v[74:75], v[76:77]
	v_lshlrev_b32_e32 v74, 16, v135
	v_and_b32_e32 v75, 0xffff0000, v135
	v_lshlrev_b32_e32 v76, 16, v131
	v_and_b32_e32 v77, 0xffff0000, v131
	v_pk_fma_f32 v[72:73], v[72:73], v[74:75], v[76:77]
	v_lshlrev_b32_e32 v74, 16, v136
	v_and_b32_e32 v75, 0xffff0000, v136
	v_lshlrev_b32_e32 v76, 16, v132
	v_and_b32_e32 v77, 0xffff0000, v132
	v_pk_fma_f32 v[74:75], v[66:67], v[74:75], v[76:77]
	v_lshlrev_b32_e32 v66, 16, v137
	v_and_b32_e32 v67, 0xffff0000, v137
	v_lshlrev_b32_e32 v76, 16, v133
	v_and_b32_e32 v77, 0xffff0000, v133
	v_pk_fma_f32 v[76:77], v[68:69], v[66:67], v[76:77]
	v_cvt_pk_bf16_f32 v66, v70, v71
	v_cvt_pk_bf16_f32 v67, v72, v73
	v_cvt_pk_bf16_f32 v68, v74, v75
	v_cvt_pk_bf16_f32 v69, v76, v77
	global_store_dwordx4 v[82:83], v[66:69], off offset:256 nt
	s_nop 1
	v_add_u32_e32 v66, 0x80, v200
	v_ashrrev_i32_e32 v67, 31, v66
	v_mad_i64_i32 v[68:69], s[8:9], v66, s97, v[204:205]
	v_lshlrev_b64 v[132:133], 11, v[66:67]
	v_lshl_add_u64 v[66:67], v[202:203], 0, v[132:133]
	global_load_dwordx4 v[100:103], v[68:69], off
	global_load_dwordx4 v[104:107], v[66:67], off
	global_load_dwordx4 v[108:111], v[68:69], off offset:256
	global_load_dwordx4 v[112:115], v[66:67], off offset:256
	v_add_u32_e32 v66, 0x90, v200
	v_ashrrev_i32_e32 v67, 31, v66
	v_mad_i64_i32 v[68:69], s[8:9], v66, s97, v[204:205]
	v_lshlrev_b64 v[134:135], 11, v[66:67]
	v_lshl_add_u64 v[66:67], v[202:203], 0, v[134:135]
	global_load_dwordx4 v[116:119], v[68:69], off
	global_load_dwordx4 v[120:123], v[66:67], off
	global_load_dwordx4 v[124:127], v[68:69], off offset:256
	global_load_dwordx4 v[128:131], v[66:67], off offset:256
	v_add_u32_e32 v66, 0xa0, v200
	v_ashrrev_i32_e32 v67, 31, v66
	v_mad_i64_i32 v[68:69], s[8:9], v66, s97, v[204:205]
	v_lshlrev_b64 v[136:137], 11, v[66:67]
	v_lshl_add_u64 v[66:67], v[202:203], 0, v[136:137]
	global_load_dwordx4 v[94:97], v[68:69], off
	global_load_dwordx4 v[90:93], v[66:67], off
	global_load_dwordx4 v[86:89], v[68:69], off offset:256
	global_load_dwordx4 v[82:85], v[66:67], off offset:256
	v_add_u32_e32 v66, 0xb0, v200
	v_ashrrev_i32_e32 v67, 31, v66
	v_lshlrev_b64 v[98:99], 11, v[66:67]
	v_mad_i64_i32 v[68:69], s[8:9], v66, s97, v[204:205]
	v_lshl_add_u64 v[66:67], v[202:203], 0, v[98:99]
	global_load_dwordx4 v[78:81], v[68:69], off
	global_load_dwordx4 v[74:77], v[66:67], off
	global_load_dwordx4 v[70:73], v[68:69], off offset:256
	s_nop 0
	global_load_dwordx4 v[66:69], v[66:67], off offset:256
	v_lshl_add_u64 v[132:133], s[50:51], 0, v[132:133]
	v_lshl_add_u64 v[132:133], v[132:133], 0, v[198:199]
	s_waitcnt vmcnt(0)
; DI unsigned cvtpk(float lo, float hi) { f32x2_t v = {lo, hi}; bf16x2_t b = __builtin_convertvector(v, bf16x2_t); return __builtin_bit_cast(unsigned, b); }
; DI float bflo(unsigned w) { return __uint_as_float(w << 16); }
; DI float bfhi(unsigned w) { return __uint_as_float(w & 0xffff0000u); }
;     __device__ __forceinline__ void operator()(const f32x4 (&acc)[2][2][4][2], const Unit& u, int wr, int wc, int fr, int fq) const {
;     ...
;                 for (int bj = 0; bj < 2; ++bj) {
;                     const f32x4 v0 = acc[ai][bj][m][0], v1 = acc[ai][bj][m][1];
;                     const u32x4 g = gl[m][bj];
;                     u32x4* p = (u32x4*)(MRG + row * DM + col0 + bj * HALF);
;                     float h[8];
;                     h[0] = bflo(g.x) * v0[0]; h[1] = bfhi(g.x) * v0[1]; h[2] = bflo(g.y) * v0[2]; h[3] = bfhi(g.y) * v0[3];
;                     h[4] = bflo(g.z) * v1[0]; h[5] = bfhi(g.z) * v1[1]; h[6] = bflo(g.w) * v1[2]; h[7] = bfhi(g.w) * v1[3];
;                     if (!FIRST) { const u32x4 o = ol[m][bj];
;                         h[0] += bflo(o.x); h[1] += bfhi(o.x); h[2] += bflo(o.y); h[3] += bfhi(o.y); h[4] += bflo(o.z); h[5] += bfhi(o.z); h[6] += bflo(o.w); h[7] += bfhi(o.w); }
;                     u32x4 w; w.x = cvtpk(h[0], h[1]); w.y = cvtpk(h[2], h[3]); w.z = cvtpk(h[4], h[5]); w.w = cvtpk(h[6], h[7]);
;                     *p = w;
;                 }
	v_lshlrev_b32_e32 v138, 16, v100
	v_and_b32_e32 v139, 0xffff0000, v100
	v_lshlrev_b32_e32 v140, 16, v104
	v_and_b32_e32 v141, 0xffff0000, v104
	v_lshlrev_b32_e32 v100, 16, v101
	v_and_b32_e32 v101, 0xffff0000, v101
	v_lshlrev_b32_e32 v104, 16, v105
	v_and_b32_e32 v105, 0xffff0000, v105
	v_pk_fma_f32 v[64:65], v[64:65], v[100:101], v[104:105]
	v_lshlrev_b32_e32 v100, 16, v102
	v_and_b32_e32 v101, 0xffff0000, v102
	v_lshlrev_b32_e32 v104, 16, v106
	v_and_b32_e32 v105, 0xffff0000, v106
	v_pk_fma_f32 v[100:101], v[58:59], v[100:101], v[104:105]
	v_lshlrev_b32_e32 v58, 16, v103
	v_and_b32_e32 v59, 0xffff0000, v103
	v_lshlrev_b32_e32 v102, 16, v107
	v_and_b32_e32 v103, 0xffff0000, v107
	v_pk_fma_f32 v[62:63], v[62:63], v[138:139], v[140:141]
	v_pk_fma_f32 v[102:103], v[60:61], v[58:59], v[102:103]
	v_cvt_pk_bf16_f32 v58, v62, v63
	v_cvt_pk_bf16_f32 v59, v64, v65
	v_cvt_pk_bf16_f32 v60, v100, v101
	v_cvt_pk_bf16_f32 v61, v102, v103
	global_store_dwordx4 v[132:133], v[58:61], off nt
	s_nop 1
	v_lshlrev_b32_e32 v58, 16, v108
	v_and_b32_e32 v59, 0xffff0000, v108
	v_lshlrev_b32_e32 v60, 16, v112
	v_and_b32_e32 v61, 0xffff0000, v112
	v_pk_fma_f32 v[54:55], v[54:55], v[58:59], v[60:61]
	v_lshlrev_b32_e32 v58, 16, v109
	v_and_b32_e32 v59, 0xffff0000, v109
	v_lshlrev_b32_e32 v60, 16, v113
	v_and_b32_e32 v61, 0xffff0000, v113
	v_pk_fma_f32 v[56:57], v[56:57], v[58:59], v[60:61]
	v_lshlrev_b32_e32 v58, 16, v110
	v_and_b32_e32 v59, 0xffff0000, v110
	v_lshlrev_b32_e32 v60, 16, v114
	v_and_b32_e32 v61, 0xffff0000, v114
	v_pk_fma_f32 v[58:59], v[50:51], v[58:59], v[60:61]
	v_lshlrev_b32_e32 v50, 16, v111
	v_and_b32_e32 v51, 0xffff0000, v111
	v_lshlrev_b32_e32 v60, 16, v115
	v_and_b32_e32 v61, 0xffff0000, v115
	v_pk_fma_f32 v[60:61], v[52:53], v[50:51], v[60:61]
	v_cvt_pk_bf16_f32 v50, v54, v55
	v_cvt_pk_bf16_f32 v51, v56, v57
	v_cvt_pk_bf16_f32 v52, v58, v59
	v_cvt_pk_bf16_f32 v53, v60, v61
	global_store_dwordx4 v[132:133], v[50:53], off offset:256 nt
	v_lshlrev_b32_e32 v54, 16, v120
	v_and_b32_e32 v55, 0xffff0000, v120
	v_lshlrev_b32_e32 v52, 16, v116
	v_and_b32_e32 v53, 0xffff0000, v116
	v_pk_fma_f32 v[46:47], v[46:47], v[52:53], v[54:55]
	v_lshlrev_b32_e32 v52, 16, v117
	v_and_b32_e32 v53, 0xffff0000, v117
	v_lshlrev_b32_e32 v54, 16, v121
	v_and_b32_e32 v55, 0xffff0000, v121
	v_pk_fma_f32 v[48:49], v[48:49], v[52:53], v[54:55]
	v_lshlrev_b32_e32 v52, 16, v118
	v_and_b32_e32 v53, 0xffff0000, v118
	v_lshlrev_b32_e32 v54, 16, v122
	v_and_b32_e32 v55, 0xffff0000, v122
	v_pk_fma_f32 v[52:53], v[42:43], v[52:53], v[54:55]
	v_lshlrev_b32_e32 v42, 16, v119
	v_and_b32_e32 v43, 0xffff0000, v119
	v_lshlrev_b32_e32 v54, 16, v123
	v_and_b32_e32 v55, 0xffff0000, v123
	v_lshl_add_u64 v[50:51], s[50:51], 0, v[134:135]
	v_pk_fma_f32 v[54:55], v[44:45], v[42:43], v[54:55]
	v_lshl_add_u64 v[50:51], v[50:51], 0, v[198:199]
	v_cvt_pk_bf16_f32 v42, v46, v47
	v_cvt_pk_bf16_f32 v43, v48, v49
	v_cvt_pk_bf16_f32 v44, v52, v53
	v_cvt_pk_bf16_f32 v45, v54, v55
	global_store_dwordx4 v[50:51], v[42:45], off nt
	s_nop 1
	v_lshlrev_b32_e32 v42, 16, v124
	v_and_b32_e32 v43, 0xffff0000, v124
	v_lshlrev_b32_e32 v44, 16, v128
	v_and_b32_e32 v45, 0xffff0000, v128
	v_pk_fma_f32 v[38:39], v[38:39], v[42:43], v[44:45]
	v_lshlrev_b32_e32 v42, 16, v125
	v_and_b32_e32 v43, 0xffff0000, v125
	v_lshlrev_b32_e32 v44, 16, v129
	v_and_b32_e32 v45, 0xffff0000, v129
	v_pk_fma_f32 v[40:41], v[40:41], v[42:43], v[44:45]
	v_lshlrev_b32_e32 v42, 16, v126
	v_and_b32_e32 v43, 0xffff0000, v126
	v_lshlrev_b32_e32 v44, 16, v130
	v_and_b32_e32 v45, 0xffff0000, v130
	v_pk_fma_f32 v[42:43], v[34:35], v[42:43], v[44:45]
	v_lshlrev_b32_e32 v34, 16, v127
	v_and_b32_e32 v35, 0xffff0000, v127
	v_lshlrev_b32_e32 v44, 16, v131
	v_and_b32_e32 v45, 0xffff0000, v131
	v_pk_fma_f32 v[44:45], v[36:37], v[34:35], v[44:45]
	v_cvt_pk_bf16_f32 v34, v38, v39
	v_cvt_pk_bf16_f32 v35, v40, v41
	v_cvt_pk_bf16_f32 v36, v42, v43
	v_cvt_pk_bf16_f32 v37, v44, v45
	global_store_dwordx4 v[50:51], v[34:37], off offset:256 nt
	v_lshlrev_b32_e32 v38, 16, v90
; DI unsigned cvtpk(float lo, float hi) { f32x2_t v = {lo, hi}; bf16x2_t b = __builtin_convertvector(v, bf16x2_t); return __builtin_bit_cast(unsigned, b); }
; DI float bflo(unsigned w) { return __uint_as_float(w << 16); }
; DI float bfhi(unsigned w) { return __uint_as_float(w & 0xffff0000u); }
;     __device__ __forceinline__ void operator()(const f32x4 (&acc)[2][2][4][2], const Unit& u, int wr, int wc, int fr, int fq) const {
;     ...
;                 for (int bj = 0; bj < 2; ++bj) {
;                     const f32x4 v0 = acc[ai][bj][m][0], v1 = acc[ai][bj][m][1];
;                     const u32x4 g = gl[m][bj];
;                     u32x4* p = (u32x4*)(MRG + row * DM + col0 + bj * HALF);
;                     float h[8];
;                     h[0] = bflo(g.x) * v0[0]; h[1] = bfhi(g.x) * v0[1]; h[2] = bflo(g.y) * v0[2]; h[3] = bfhi(g.y) * v0[3];
;                     h[4] = bflo(g.z) * v1[0]; h[5] = bfhi(g.z) * v1[1]; h[6] = bflo(g.w) * v1[2]; h[7] = bfhi(g.w) * v1[3];
;                     if (!FIRST) { const u32x4 o = ol[m][bj];
;                         h[0] += bflo(o.x); h[1] += bfhi(o.x); h[2] += bflo(o.y); h[3] += bfhi(o.y); h[4] += bflo(o.z); h[5] += bfhi(o.z); h[6] += bflo(o.w); h[7] += bfhi(o.w); }
;                     u32x4 w; w.x = cvtpk(h[0], h[1]); w.y = cvtpk(h[2], h[3]); w.z = cvtpk(h[4], h[5]); w.w = cvtpk(h[6], h[7]);
;                     *p = w;
;                 }
	v_and_b32_e32 v39, 0xffff0000, v90
	v_lshlrev_b32_e32 v36, 16, v94
	v_and_b32_e32 v37, 0xffff0000, v94
	v_pk_fma_f32 v[30:31], v[30:31], v[36:37], v[38:39]
	v_lshlrev_b32_e32 v36, 16, v95
	v_and_b32_e32 v37, 0xffff0000, v95
	v_lshlrev_b32_e32 v38, 16, v91
	v_and_b32_e32 v39, 0xffff0000, v91
	v_pk_fma_f32 v[32:33], v[32:33], v[36:37], v[38:39]
	v_lshlrev_b32_e32 v36, 16, v96
	v_and_b32_e32 v37, 0xffff0000, v96
	v_lshlrev_b32_e32 v38, 16, v92
	v_and_b32_e32 v39, 0xffff0000, v92
	v_pk_fma_f32 v[36:37], v[26:27], v[36:37], v[38:39]
	v_lshlrev_b32_e32 v26, 16, v97
	v_and_b32_e32 v27, 0xffff0000, v97
	v_lshlrev_b32_e32 v38, 16, v93
	v_and_b32_e32 v39, 0xffff0000, v93
	v_lshl_add_u64 v[34:35], s[50:51], 0, v[136:137]
	v_pk_fma_f32 v[38:39], v[28:29], v[26:27], v[38:39]
	v_lshl_add_u64 v[34:35], v[34:35], 0, v[198:199]
	v_cvt_pk_bf16_f32 v26, v30, v31
	v_cvt_pk_bf16_f32 v27, v32, v33
	v_cvt_pk_bf16_f32 v28, v36, v37
	v_cvt_pk_bf16_f32 v29, v38, v39
	global_store_dwordx4 v[34:35], v[26:29], off nt
	s_nop 1
	v_lshlrev_b32_e32 v26, 16, v86
	v_and_b32_e32 v27, 0xffff0000, v86
	v_lshlrev_b32_e32 v28, 16, v82
	v_and_b32_e32 v29, 0xffff0000, v82
	v_pk_fma_f32 v[22:23], v[22:23], v[26:27], v[28:29]
	v_lshlrev_b32_e32 v26, 16, v87
	v_and_b32_e32 v27, 0xffff0000, v87
	v_lshlrev_b32_e32 v28, 16, v83
	v_and_b32_e32 v29, 0xffff0000, v83
	v_pk_fma_f32 v[24:25], v[24:25], v[26:27], v[28:29]
	v_lshlrev_b32_e32 v26, 16, v88
	v_and_b32_e32 v27, 0xffff0000, v88
	v_lshlrev_b32_e32 v28, 16, v84
	v_and_b32_e32 v29, 0xffff0000, v84
	v_pk_fma_f32 v[26:27], v[18:19], v[26:27], v[28:29]
	v_lshlrev_b32_e32 v18, 16, v89
	v_and_b32_e32 v19, 0xffff0000, v89
	v_lshlrev_b32_e32 v28, 16, v85
	v_and_b32_e32 v29, 0xffff0000, v85
	v_pk_fma_f32 v[28:29], v[20:21], v[18:19], v[28:29]
	v_cvt_pk_bf16_f32 v18, v22, v23
	v_cvt_pk_bf16_f32 v19, v24, v25
	v_cvt_pk_bf16_f32 v20, v26, v27
	v_cvt_pk_bf16_f32 v21, v28, v29
	global_store_dwordx4 v[34:35], v[18:21], off offset:256 nt
	v_lshlrev_b32_e32 v22, 16, v74
	v_and_b32_e32 v23, 0xffff0000, v74
	v_lshlrev_b32_e32 v20, 16, v78
	v_and_b32_e32 v21, 0xffff0000, v78
	v_pk_fma_f32 v[14:15], v[14:15], v[20:21], v[22:23]
	v_lshlrev_b32_e32 v20, 16, v79
	v_and_b32_e32 v21, 0xffff0000, v79
	v_lshlrev_b32_e32 v22, 16, v75
	v_and_b32_e32 v23, 0xffff0000, v75
	v_pk_fma_f32 v[16:17], v[16:17], v[20:21], v[22:23]
	v_lshlrev_b32_e32 v20, 16, v80
	v_and_b32_e32 v21, 0xffff0000, v80
	v_lshlrev_b32_e32 v22, 16, v76
	v_and_b32_e32 v23, 0xffff0000, v76
	v_pk_fma_f32 v[20:21], v[10:11], v[20:21], v[22:23]
	v_lshlrev_b32_e32 v10, 16, v81
	v_and_b32_e32 v11, 0xffff0000, v81
	v_lshlrev_b32_e32 v22, 16, v77
	v_and_b32_e32 v23, 0xffff0000, v77
	v_lshl_add_u64 v[18:19], s[50:51], 0, v[98:99]
	v_pk_fma_f32 v[22:23], v[12:13], v[10:11], v[22:23]
	v_lshl_add_u64 v[18:19], v[18:19], 0, v[198:199]
	v_cvt_pk_bf16_f32 v10, v14, v15
	v_cvt_pk_bf16_f32 v11, v16, v17
	v_cvt_pk_bf16_f32 v12, v20, v21
	v_cvt_pk_bf16_f32 v13, v22, v23
	global_store_dwordx4 v[18:19], v[10:13], off nt
	s_nop 1
	v_lshlrev_b32_e32 v10, 16, v70
	v_and_b32_e32 v11, 0xffff0000, v70
	v_lshlrev_b32_e32 v12, 16, v66
	v_and_b32_e32 v13, 0xffff0000, v66
	v_pk_fma_f32 v[6:7], v[6:7], v[10:11], v[12:13]
	v_lshlrev_b32_e32 v10, 16, v71
	v_and_b32_e32 v11, 0xffff0000, v71
	v_lshlrev_b32_e32 v12, 16, v67
	v_and_b32_e32 v13, 0xffff0000, v67
	v_pk_fma_f32 v[8:9], v[8:9], v[10:11], v[12:13]
	v_lshlrev_b32_e32 v10, 16, v72
	v_and_b32_e32 v11, 0xffff0000, v72
	v_lshlrev_b32_e32 v12, 16, v68
	v_and_b32_e32 v13, 0xffff0000, v68
	v_pk_fma_f32 v[10:11], v[2:3], v[10:11], v[12:13]
	v_lshlrev_b32_e32 v2, 16, v73
	v_and_b32_e32 v3, 0xffff0000, v73
	v_lshlrev_b32_e32 v12, 16, v69
	v_and_b32_e32 v13, 0xffff0000, v69
	v_pk_fma_f32 v[12:13], v[4:5], v[2:3], v[12:13]
	v_cvt_pk_bf16_f32 v2, v6, v7
	v_cvt_pk_bf16_f32 v3, v8, v9
	v_cvt_pk_bf16_f32 v4, v10, v11
	v_cvt_pk_bf16_f32 v5, v12, v13
	global_store_dwordx4 v[18:19], v[2:5], off offset:256 nt
	s_cbranch_vccnz .LBB0_1943
	s_andn2_b64 vcc, exec, s[48:49]
	s_cbranch_vccnz .LBB0_1942
	s_barrier
	s_branch .LBB0_1942

;     __device__ __forceinline__ void operator()(const f32x4 (&acc)[2][2][4][2], const Unit& u, int wr, int wc, int fr, int fq) const {
;     ...
;         for (int ai = 0; ai < 2; ++ai) {
;             f32x4 x[4][2][2];
; #pragma unroll
;             for (int m = 0; m < 4; ++m) { const size_t off = (size_t)(row0 + ai * HALF + m * 16) * DM + col0;
; #pragma unroll
;                 for (int bj = 0; bj < 2; ++bj)
; #pragma unroll
;                     for (int n = 0; n < 2; ++n) x[m][bj][n] = *(const f32x4*)(Yin + off + bj * HALF + n * 16); }
;             asm volatile("" ::: "memory");
; #pragma unroll
;             for (int m = 0; m < 4; ++m) { const size_t off = (size_t)(row0 + ai * HALF + m * 16) * DM + col0;
; #pragma unroll
;                 for (int bj = 0; bj < 2; ++bj)
; #pragma unroll
;                     for (int n = 0; n < 2; ++n) *(f32x4*)(Y + off + bj * HALF + n * 16) = x[m][bj][n] * ALPHA + acc[ai][bj][m][n] * s; }
;             asm volatile("" ::: "memory");
.LBB0_2072:
	v_lshl_or_b32 v132, s8, 8, v163
	v_lshl_add_u32 v130, s9, 8, v1
	v_ashrrev_i32_e32 v133, 31, v132
	v_lshlrev_b64 v[154:155], 2, v[132:133]
	v_ashrrev_i32_e32 v131, 31, v130
	v_lshl_add_u64 v[156:157], s[44:45], 0, v[154:155]
	v_lshlrev_b64 v[158:159], 12, v[130:131]
	v_lshl_add_u64 v[132:133], v[156:157], 0, v[158:159]
	global_load_dwordx4 v[166:169], v[132:133], off
	global_load_dwordx4 v[170:173], v[132:133], off offset:64
	global_load_dwordx4 v[174:177], v[132:133], off offset:512
	global_load_dwordx4 v[178:181], v[132:133], off offset:576
	v_or_b32_e32 v132, 16, v130
	v_ashrrev_i32_e32 v133, 31, v132
	v_lshlrev_b64 v[210:211], 12, v[132:133]
	v_lshl_add_u64 v[132:133], v[156:157], 0, v[210:211]
	global_load_dwordx4 v[182:185], v[132:133], off
	global_load_dwordx4 v[186:189], v[132:133], off offset:64
	global_load_dwordx4 v[190:193], v[132:133], off offset:512
	global_load_dwordx4 v[194:197], v[132:133], off offset:576
	v_or_b32_e32 v132, 32, v130
	v_ashrrev_i32_e32 v133, 31, v132
	v_lshlrev_b64 v[230:231], 12, v[132:133]
	v_or_b32_e32 v130, 48, v130
	v_lshl_add_u64 v[132:133], v[156:157], 0, v[230:231]
	v_ashrrev_i32_e32 v131, 31, v130
	global_load_dwordx4 v[198:201], v[132:133], off
	global_load_dwordx4 v[202:205], v[132:133], off offset:64
	global_load_dwordx4 v[206:209], v[132:133], off offset:512
	global_load_dwordx4 v[142:145], v[132:133], off offset:576
	v_lshlrev_b64 v[160:161], 12, v[130:131]
	v_lshl_add_u64 v[130:131], v[156:157], 0, v[160:161]
	global_load_dwordx4 v[226:229], v[130:131], off
	global_load_dwordx4 v[138:141], v[130:131], off offset:64
	global_load_dwordx4 v[134:137], v[130:131], off offset:512
	s_nop 0
	global_load_dwordx4 v[130:133], v[130:131], off offset:576
	s_mov_b64 s[8:9], 0x80000
	s_mov_b64 s[58:59], -1
	s_and_b64 vcc, exec, s[40:41]
	s_waitcnt vmcnt(0)
	v_pk_fma_f32 v[126:127], v[166:167], s[96:97], v[126:127] op_sel_hi:[1,0,1]
	v_lshl_add_u64 v[166:167], s[44:45], 0, v[158:159]
	v_lshl_add_u64 v[166:167], v[166:167], 0, v[154:155]
	v_pk_fma_f32 v[116:117], v[180:181], s[96:97], v[116:117] op_sel_hi:[1,0,1]
	v_pk_fma_f32 v[114:115], v[178:179], s[96:97], v[114:115] op_sel_hi:[1,0,1]
	global_store_dwordx4 v[166:167], v[114:117], off offset:576 nt
	v_pk_fma_f32 v[128:129], v[168:169], s[96:97], v[128:129] op_sel_hi:[1,0,1]
	v_pk_fma_f32 v[124:125], v[172:173], s[96:97], v[124:125] op_sel_hi:[1,0,1]
	v_lshl_add_u64 v[114:115], s[44:45], 0, v[210:211]
	v_lshl_add_u64 v[114:115], v[114:115], 0, v[154:155]
	v_pk_fma_f32 v[100:101], v[196:197], s[96:97], v[100:101] op_sel_hi:[1,0,1]
	v_pk_fma_f32 v[98:99], v[194:195], s[96:97], v[98:99] op_sel_hi:[1,0,1]
	global_store_dwordx4 v[114:115], v[98:101], off offset:576 nt
	v_pk_fma_f32 v[122:123], v[170:171], s[96:97], v[122:123] op_sel_hi:[1,0,1]
	v_pk_fma_f32 v[120:121], v[176:177], s[96:97], v[120:121] op_sel_hi:[1,0,1]
	v_lshl_add_u64 v[98:99], s[44:45], 0, v[230:231]
	v_lshl_add_u64 v[98:99], v[98:99], 0, v[154:155]
	v_pk_fma_f32 v[84:85], v[144:145], s[96:97], v[84:85] op_sel_hi:[1,0,1]
	v_pk_fma_f32 v[82:83], v[142:143], s[96:97], v[82:83] op_sel_hi:[1,0,1]
	global_store_dwordx4 v[98:99], v[82:85], off offset:576 nt
	v_pk_fma_f32 v[118:119], v[174:175], s[96:97], v[118:119] op_sel_hi:[1,0,1]
	v_pk_fma_f32 v[112:113], v[184:185], s[96:97], v[112:113] op_sel_hi:[1,0,1]
	v_lshl_add_u64 v[82:83], s[44:45], 0, v[160:161]
	v_pk_fma_f32 v[110:111], v[182:183], s[96:97], v[110:111] op_sel_hi:[1,0,1]
	v_pk_fma_f32 v[108:109], v[188:189], s[96:97], v[108:109] op_sel_hi:[1,0,1]
	v_pk_fma_f32 v[106:107], v[186:187], s[96:97], v[106:107] op_sel_hi:[1,0,1]
	v_pk_fma_f32 v[104:105], v[192:193], s[96:97], v[104:105] op_sel_hi:[1,0,1]
	v_pk_fma_f32 v[102:103], v[190:191], s[96:97], v[102:103] op_sel_hi:[1,0,1]
	v_pk_fma_f32 v[96:97], v[200:201], s[96:97], v[96:97] op_sel_hi:[1,0,1]
	v_pk_fma_f32 v[94:95], v[198:199], s[96:97], v[94:95] op_sel_hi:[1,0,1]
	v_pk_fma_f32 v[92:93], v[204:205], s[96:97], v[92:93] op_sel_hi:[1,0,1]
	v_pk_fma_f32 v[90:91], v[202:203], s[96:97], v[90:91] op_sel_hi:[1,0,1]
	v_pk_fma_f32 v[88:89], v[208:209], s[96:97], v[88:89] op_sel_hi:[1,0,1]
	v_pk_fma_f32 v[86:87], v[206:207], s[96:97], v[86:87] op_sel_hi:[1,0,1]
	v_pk_fma_f32 v[80:81], v[228:229], s[96:97], v[80:81] op_sel_hi:[1,0,1]
	v_pk_fma_f32 v[78:79], v[226:227], s[96:97], v[78:79] op_sel_hi:[1,0,1]
	v_lshl_add_u64 v[82:83], v[82:83], 0, v[154:155]
	v_pk_fma_f32 v[76:77], v[140:141], s[96:97], v[76:77] op_sel_hi:[1,0,1]
	v_pk_fma_f32 v[74:75], v[138:139], s[96:97], v[74:75] op_sel_hi:[1,0,1]
	v_pk_fma_f32 v[72:73], v[136:137], s[96:97], v[72:73] op_sel_hi:[1,0,1]
	v_pk_fma_f32 v[70:71], v[134:135], s[96:97], v[70:71] op_sel_hi:[1,0,1]
	v_pk_fma_f32 v[68:69], v[132:133], s[96:97], v[68:69] op_sel_hi:[1,0,1]
	v_pk_fma_f32 v[66:67], v[130:131], s[96:97], v[66:67] op_sel_hi:[1,0,1]
	global_store_dwordx4 v[166:167], v[126:129], off nt
	global_store_dwordx4 v[166:167], v[122:125], off offset:64 nt
	global_store_dwordx4 v[166:167], v[118:121], off offset:512 nt
	global_store_dwordx4 v[114:115], v[110:113], off nt
	global_store_dwordx4 v[114:115], v[106:109], off offset:64 nt
	global_store_dwordx4 v[114:115], v[102:105], off offset:512 nt
	global_store_dwordx4 v[98:99], v[94:97], off nt
	global_store_dwordx4 v[98:99], v[90:93], off offset:64 nt
	global_store_dwordx4 v[98:99], v[86:89], off offset:512 nt
	global_store_dwordx4 v[82:83], v[78:81], off nt
	global_store_dwordx4 v[82:83], v[74:77], off offset:64 nt
	global_store_dwordx4 v[82:83], v[70:73], off offset:512 nt
	global_store_dwordx4 v[82:83], v[66:69], off offset:576 nt
	v_lshl_add_u64 v[132:133], v[158:159], 0, s[8:9]
	s_mov_b64 s[8:9], 0x90000
	v_lshl_add_u64 v[66:67], v[156:157], 0, v[132:133]
	global_load_dwordx4 v[84:87], v[66:67], off
	global_load_dwordx4 v[88:91], v[66:67], off offset:64
	global_load_dwordx4 v[92:95], v[66:67], off offset:512
	global_load_dwordx4 v[96:99], v[66:67], off offset:576
	v_lshl_add_u64 v[134:135], v[158:159], 0, s[8:9]
	v_lshl_add_u64 v[66:67], v[156:157], 0, v[134:135]
	s_mov_b64 s[8:9], 0xa0000
	global_load_dwordx4 v[100:103], v[66:67], off
	global_load_dwordx4 v[104:107], v[66:67], off offset:64
	global_load_dwordx4 v[108:111], v[66:67], off offset:512
	global_load_dwordx4 v[112:115], v[66:67], off offset:576
	v_lshl_add_u64 v[136:137], v[158:159], 0, s[8:9]
	v_lshl_add_u64 v[66:67], v[156:157], 0, v[136:137]
	s_mov_b64 s[8:9], 0xb0000
	global_load_dwordx4 v[116:119], v[66:67], off
	global_load_dwordx4 v[120:123], v[66:67], off offset:64
	global_load_dwordx4 v[124:127], v[66:67], off offset:512
	global_load_dwordx4 v[78:81], v[66:67], off offset:576
	v_lshl_add_u64 v[82:83], v[158:159], 0, s[8:9]
	v_lshl_add_u64 v[66:67], v[156:157], 0, v[82:83]
	global_load_dwordx4 v[128:131], v[66:67], off
	global_load_dwordx4 v[74:77], v[66:67], off offset:64
	global_load_dwordx4 v[70:73], v[66:67], off offset:512
	s_nop 0
	global_load_dwordx4 v[66:69], v[66:67], off offset:576
	s_waitcnt vmcnt(0)
;     __device__ __forceinline__ void operator()(const f32x4 (&acc)[2][2][4][2], const Unit& u, int wr, int wc, int fr, int fq) const {
;     ...
;             for (int m = 0; m < 4; ++m) { const size_t off = (size_t)(row0 + ai * HALF + m * 16) * DM + col0;
; #pragma unroll
;                 for (int bj = 0; bj < 2; ++bj)
; #pragma unroll
;                     for (int n = 0; n < 2; ++n) *(f32x4*)(Y + off + bj * HALF + n * 16) = x[m][bj][n] * ALPHA + acc[ai][bj][m][n] * s; }
;             asm volatile("" ::: "memory");
	v_pk_fma_f32 v[62:63], v[84:85], s[96:97], v[62:63] op_sel_hi:[1,0,1]
	v_lshl_add_u64 v[84:85], s[44:45], 0, v[132:133]
	v_lshl_add_u64 v[84:85], v[84:85], 0, v[154:155]
	v_pk_fma_f32 v[52:53], v[98:99], s[96:97], v[52:53] op_sel_hi:[1,0,1]
	v_pk_fma_f32 v[50:51], v[96:97], s[96:97], v[50:51] op_sel_hi:[1,0,1]
	global_store_dwordx4 v[84:85], v[50:53], off offset:576 nt
	v_pk_fma_f32 v[64:65], v[86:87], s[96:97], v[64:65] op_sel_hi:[1,0,1]
	v_pk_fma_f32 v[36:37], v[114:115], s[96:97], v[36:37] op_sel_hi:[1,0,1]
	v_lshl_add_u64 v[50:51], s[44:45], 0, v[134:135]
	v_lshl_add_u64 v[50:51], v[50:51], 0, v[154:155]
	v_pk_fma_f32 v[34:35], v[112:113], s[96:97], v[34:35] op_sel_hi:[1,0,1]
	global_store_dwordx4 v[50:51], v[34:37], off offset:576 nt
	v_pk_fma_f32 v[20:21], v[80:81], s[96:97], v[20:21] op_sel_hi:[1,0,1]
	v_pk_fma_f32 v[18:19], v[78:79], s[96:97], v[18:19] op_sel_hi:[1,0,1]
	v_lshl_add_u64 v[34:35], s[44:45], 0, v[136:137]
	v_lshl_add_u64 v[34:35], v[34:35], 0, v[154:155]
	global_store_dwordx4 v[34:35], v[18:21], off offset:576 nt
	v_pk_fma_f32 v[60:61], v[90:91], s[96:97], v[60:61] op_sel_hi:[1,0,1]
	v_pk_fma_f32 v[58:59], v[88:89], s[96:97], v[58:59] op_sel_hi:[1,0,1]
	v_lshl_add_u64 v[18:19], s[44:45], 0, v[82:83]
	v_pk_fma_f32 v[56:57], v[94:95], s[96:97], v[56:57] op_sel_hi:[1,0,1]
	v_pk_fma_f32 v[54:55], v[92:93], s[96:97], v[54:55] op_sel_hi:[1,0,1]
	v_pk_fma_f32 v[48:49], v[102:103], s[96:97], v[48:49] op_sel_hi:[1,0,1]
	v_pk_fma_f32 v[46:47], v[100:101], s[96:97], v[46:47] op_sel_hi:[1,0,1]
	v_pk_fma_f32 v[44:45], v[106:107], s[96:97], v[44:45] op_sel_hi:[1,0,1]
	v_pk_fma_f32 v[42:43], v[104:105], s[96:97], v[42:43] op_sel_hi:[1,0,1]
	v_pk_fma_f32 v[40:41], v[110:111], s[96:97], v[40:41] op_sel_hi:[1,0,1]
	v_pk_fma_f32 v[38:39], v[108:109], s[96:97], v[38:39] op_sel_hi:[1,0,1]
	v_pk_fma_f32 v[32:33], v[118:119], s[96:97], v[32:33] op_sel_hi:[1,0,1]
	v_pk_fma_f32 v[30:31], v[116:117], s[96:97], v[30:31] op_sel_hi:[1,0,1]
	v_pk_fma_f32 v[28:29], v[122:123], s[96:97], v[28:29] op_sel_hi:[1,0,1]
	v_pk_fma_f32 v[26:27], v[120:121], s[96:97], v[26:27] op_sel_hi:[1,0,1]
	v_pk_fma_f32 v[24:25], v[126:127], s[96:97], v[24:25] op_sel_hi:[1,0,1]
	v_pk_fma_f32 v[22:23], v[124:125], s[96:97], v[22:23] op_sel_hi:[1,0,1]
	v_pk_fma_f32 v[16:17], v[130:131], s[96:97], v[16:17] op_sel_hi:[1,0,1]
	v_pk_fma_f32 v[14:15], v[128:129], s[96:97], v[14:15] op_sel_hi:[1,0,1]
	v_lshl_add_u64 v[18:19], v[18:19], 0, v[154:155]
	v_pk_fma_f32 v[12:13], v[76:77], s[96:97], v[12:13] op_sel_hi:[1,0,1]
	v_pk_fma_f32 v[10:11], v[74:75], s[96:97], v[10:11] op_sel_hi:[1,0,1]
	v_pk_fma_f32 v[8:9], v[72:73], s[96:97], v[8:9] op_sel_hi:[1,0,1]
	v_pk_fma_f32 v[6:7], v[70:71], s[96:97], v[6:7] op_sel_hi:[1,0,1]
	v_pk_fma_f32 v[4:5], v[68:69], s[96:97], v[4:5] op_sel_hi:[1,0,1]
	v_pk_fma_f32 v[2:3], v[66:67], s[96:97], v[2:3] op_sel_hi:[1,0,1]
	global_store_dwordx4 v[84:85], v[62:65], off nt
	global_store_dwordx4 v[84:85], v[58:61], off offset:64 nt
	global_store_dwordx4 v[84:85], v[54:57], off offset:512 nt
	global_store_dwordx4 v[50:51], v[46:49], off nt
	global_store_dwordx4 v[50:51], v[42:45], off offset:64 nt
	global_store_dwordx4 v[50:51], v[38:41], off offset:512 nt
	global_store_dwordx4 v[34:35], v[30:33], off nt
	global_store_dwordx4 v[34:35], v[26:29], off offset:64 nt
	global_store_dwordx4 v[34:35], v[22:25], off offset:512 nt
	global_store_dwordx4 v[18:19], v[14:17], off nt
	global_store_dwordx4 v[18:19], v[10:13], off offset:64 nt
	global_store_dwordx4 v[18:19], v[6:9], off offset:512 nt
	global_store_dwordx4 v[18:19], v[2:5], off offset:576 nt
	s_cbranch_vccnz .LBB0_2055
	s_andn2_b64 vcc, exec, s[50:51]
	s_cbranch_vccnz .LBB0_2054
	s_barrier
	s_branch .LBB0_2054

;     __device__ __forceinline__ void operator()(const f32x4 (&acc)[2][2][4][2], const Unit& u, int wr, int wc, int fr, int fq) const {
;     ...
;         for (int ai = 0; ai < 2; ++ai) {
;             f32x4 x[4][2][2];
; #pragma unroll
;             for (int m = 0; m < 4; ++m) { const size_t off = (size_t)(row0 + ai * HALF + m * 16) * DM + col0;
; #pragma unroll
;                 for (int bj = 0; bj < 2; ++bj)
; #pragma unroll
;                     for (int n = 0; n < 2; ++n) x[m][bj][n] = *(const f32x4*)(Yin + off + bj * HALF + n * 16); }
;             asm volatile("" ::: "memory");
; #pragma unroll
;             for (int m = 0; m < 4; ++m) { const size_t off = (size_t)(row0 + ai * HALF + m * 16) * DM + col0;
; #pragma unroll
;                 for (int bj = 0; bj < 2; ++bj)
; #pragma unroll
;                     for (int n = 0; n < 2; ++n) *(f32x4*)(Y + off + bj * HALF + n * 16) = x[m][bj][n] * ALPHA + acc[ai][bj][m][n] * s; }
;             asm volatile("" ::: "memory");
.LBB0_2342:
	v_lshl_or_b32 v4, s8, 8, v163
	v_lshl_add_u32 v2, s9, 8, v1
	v_ashrrev_i32_e32 v5, 31, v4
	v_lshlrev_b64 v[94:95], 2, v[4:5]
	v_ashrrev_i32_e32 v3, 31, v2
	v_lshl_add_u64 v[156:157], s[44:45], 0, v[94:95]
	v_lshlrev_b64 v[158:159], 12, v[2:3]
	v_lshl_add_u64 v[4:5], v[156:157], 0, v[158:159]
	global_load_dwordx4 v[166:169], v[4:5], off
	global_load_dwordx4 v[170:173], v[4:5], off offset:64
	global_load_dwordx4 v[174:177], v[4:5], off offset:512
	global_load_dwordx4 v[178:181], v[4:5], off offset:576
	v_or_b32_e32 v4, 16, v2
	v_ashrrev_i32_e32 v5, 31, v4
	v_lshlrev_b64 v[210:211], 12, v[4:5]
	v_lshl_add_u64 v[4:5], v[156:157], 0, v[210:211]
	global_load_dwordx4 v[182:185], v[4:5], off
	global_load_dwordx4 v[186:189], v[4:5], off offset:64
	global_load_dwordx4 v[190:193], v[4:5], off offset:512
	global_load_dwordx4 v[194:197], v[4:5], off offset:576
	v_or_b32_e32 v4, 32, v2
	v_ashrrev_i32_e32 v5, 31, v4
	v_or_b32_e32 v2, 48, v2
	v_lshlrev_b64 v[230:231], 12, v[4:5]
	v_ashrrev_i32_e32 v3, 31, v2
	v_lshl_add_u64 v[4:5], v[156:157], 0, v[230:231]
	v_lshlrev_b64 v[160:161], 12, v[2:3]
	global_load_dwordx4 v[198:201], v[4:5], off
	global_load_dwordx4 v[202:205], v[4:5], off offset:64
	global_load_dwordx4 v[206:209], v[4:5], off offset:512
	global_load_dwordx4 v[14:17], v[4:5], off offset:576
	v_lshl_add_u64 v[2:3], v[156:157], 0, v[160:161]
	global_load_dwordx4 v[226:229], v[2:3], off
	global_load_dwordx4 v[10:13], v[2:3], off offset:64
	global_load_dwordx4 v[6:9], v[2:3], off offset:512
	s_nop 0
	global_load_dwordx4 v[2:5], v[2:3], off offset:576
	s_mov_b64 s[8:9], 0x80000
	s_mov_b64 s[58:59], -1
	s_and_b64 vcc, exec, s[40:41]
	s_waitcnt vmcnt(0)
	v_pk_fma_f32 v[168:169], v[168:169], s[96:97], v[144:145] op_sel_hi:[1,0,1]
	v_pk_fma_f32 v[166:167], v[166:167], s[96:97], v[146:147] op_sel_hi:[1,0,1]
	v_lshl_add_u64 v[144:145], s[44:45], 0, v[158:159]
	v_pk_fma_f32 v[146:147], v[172:173], s[96:97], v[128:129] op_sel_hi:[1,0,1]
	v_lshl_add_u64 v[128:129], s[44:45], 0, v[210:211]
	v_lshl_add_u64 v[232:233], v[144:145], 0, v[94:95]
	v_pk_fma_f32 v[144:145], v[170:171], s[96:97], v[138:139] op_sel_hi:[1,0,1]
	v_pk_fma_f32 v[140:141], v[184:185], s[96:97], v[140:141] op_sel_hi:[1,0,1]
	v_pk_fma_f32 v[138:139], v[182:183], s[96:97], v[142:143] op_sel_hi:[1,0,1]
	v_lshl_add_u64 v[128:129], v[128:129], 0, v[94:95]
	global_store_dwordx4 v[128:129], v[138:141], off nt
	global_store_dwordx4 v[232:233], v[144:147], off offset:64 nt
	global_store_dwordx4 v[232:233], v[166:169], off nt
	v_pk_fma_f32 v[140:141], v[188:189], s[96:97], v[112:113] op_sel_hi:[1,0,1]
	v_pk_fma_f32 v[138:139], v[186:187], s[96:97], v[114:115] op_sel_hi:[1,0,1]
	v_pk_fma_f32 v[114:115], v[192:193], s[96:97], v[120:121] op_sel_hi:[1,0,1]
	v_pk_fma_f32 v[112:113], v[190:191], s[96:97], v[122:123] op_sel_hi:[1,0,1]
	global_store_dwordx4 v[128:129], v[112:115], off offset:512 nt
	v_pk_fma_f32 v[146:147], v[176:177], s[96:97], v[148:149] op_sel_hi:[1,0,1]
	v_pk_fma_f32 v[144:145], v[174:175], s[96:97], v[150:151] op_sel_hi:[1,0,1]
	v_pk_fma_f32 v[114:115], v[196:197], s[96:97], v[124:125] op_sel_hi:[1,0,1]
	v_pk_fma_f32 v[112:113], v[194:195], s[96:97], v[126:127] op_sel_hi:[1,0,1]
	global_store_dwordx4 v[128:129], v[112:115], off offset:576 nt
	v_pk_fma_f32 v[16:17], v[16:17], s[96:97], v[108:109] op_sel_hi:[1,0,1]
	v_pk_fma_f32 v[14:15], v[14:15], s[96:97], v[110:111] op_sel_hi:[1,0,1]
	v_pk_fma_f32 v[114:115], v[200:201], s[96:97], v[116:117] op_sel_hi:[1,0,1]
	v_lshl_add_u64 v[116:117], s[44:45], 0, v[230:231]
	v_pk_fma_f32 v[112:113], v[198:199], s[96:97], v[118:119] op_sel_hi:[1,0,1]
	v_lshl_add_u64 v[116:117], v[116:117], 0, v[94:95]
	global_store_dwordx4 v[116:117], v[112:115], off nt
	global_store_dwordx4 v[232:233], v[144:147], off offset:512 nt
	global_store_dwordx4 v[116:117], v[14:17], off offset:576 nt
	v_pk_fma_f32 v[114:115], v[204:205], s[96:97], v[96:97] op_sel_hi:[1,0,1]
	v_pk_fma_f32 v[112:113], v[202:203], s[96:97], v[98:99] op_sel_hi:[1,0,1]
	v_pk_fma_f32 v[98:99], v[208:209], s[96:97], v[104:105] op_sel_hi:[1,0,1]
	v_pk_fma_f32 v[96:97], v[206:207], s[96:97], v[106:107] op_sel_hi:[1,0,1]
	global_store_dwordx4 v[116:117], v[96:99], off offset:512 nt
	v_pk_fma_f32 v[146:147], v[180:181], s[96:97], v[152:153] op_sel_hi:[1,0,1]
	v_pk_fma_f32 v[144:145], v[178:179], s[96:97], v[154:155] op_sel_hi:[1,0,1]
	v_lshl_add_u64 v[96:97], s[44:45], 0, v[160:161]
	v_pk_fma_f32 v[16:17], v[228:229], s[96:97], v[100:101] op_sel_hi:[1,0,1]
	v_pk_fma_f32 v[14:15], v[226:227], s[96:97], v[102:103] op_sel_hi:[1,0,1]
	v_lshl_add_u64 v[96:97], v[96:97], 0, v[94:95]
	v_pk_fma_f32 v[12:13], v[12:13], s[96:97], v[92:93] op_sel_hi:[1,0,1]
	v_pk_fma_f32 v[10:11], v[10:11], s[96:97], v[90:91] op_sel_hi:[1,0,1]
	v_pk_fma_f32 v[8:9], v[8:9], s[96:97], v[88:89] op_sel_hi:[1,0,1]
	v_pk_fma_f32 v[6:7], v[6:7], s[96:97], v[86:87] op_sel_hi:[1,0,1]
	v_pk_fma_f32 v[4:5], v[4:5], s[96:97], v[84:85] op_sel_hi:[1,0,1]
	v_pk_fma_f32 v[2:3], v[2:3], s[96:97], v[82:83] op_sel_hi:[1,0,1]
	global_store_dwordx4 v[232:233], v[144:147], off offset:576 nt
	global_store_dwordx4 v[128:129], v[138:141], off offset:64 nt
	global_store_dwordx4 v[116:117], v[112:115], off offset:64 nt
	global_store_dwordx4 v[96:97], v[14:17], off nt
	global_store_dwordx4 v[96:97], v[10:13], off offset:64 nt
	global_store_dwordx4 v[96:97], v[6:9], off offset:512 nt
	global_store_dwordx4 v[96:97], v[2:5], off offset:576 nt
	v_lshl_add_u64 v[92:93], v[158:159], 0, s[8:9]
	s_mov_b64 s[8:9], 0x90000
	v_lshl_add_u64 v[2:3], v[156:157], 0, v[92:93]
	global_load_dwordx4 v[84:87], v[2:3], off
	global_load_dwordx4 v[88:91], v[2:3], off offset:64
	global_load_dwordx4 v[96:99], v[2:3], off offset:512
	global_load_dwordx4 v[100:103], v[2:3], off offset:576
	v_lshl_add_u64 v[128:129], v[158:159], 0, s[8:9]
	v_lshl_add_u64 v[2:3], v[156:157], 0, v[128:129]
	global_load_dwordx4 v[104:107], v[2:3], off
	global_load_dwordx4 v[108:111], v[2:3], off offset:64
	global_load_dwordx4 v[112:115], v[2:3], off offset:512
	global_load_dwordx4 v[116:119], v[2:3], off offset:576
	s_mov_b64 s[8:9], 0xa0000
	v_lshl_add_u64 v[146:147], v[158:159], 0, s[8:9]
	s_mov_b64 s[8:9], 0xb0000
	v_lshl_add_u64 v[2:3], v[156:157], 0, v[146:147]
	v_lshl_add_u64 v[82:83], v[158:159], 0, s[8:9]
	global_load_dwordx4 v[120:123], v[2:3], off
	global_load_dwordx4 v[124:127], v[2:3], off offset:64
	global_load_dwordx4 v[138:141], v[2:3], off offset:512
	global_load_dwordx4 v[14:17], v[2:3], off offset:576
	v_lshl_add_u64 v[2:3], v[156:157], 0, v[82:83]
	global_load_dwordx4 v[142:145], v[2:3], off
	global_load_dwordx4 v[10:13], v[2:3], off offset:64
	global_load_dwordx4 v[6:9], v[2:3], off offset:512
	s_nop 0
	global_load_dwordx4 v[2:5], v[2:3], off offset:576
	s_waitcnt vmcnt(0)
;     __device__ __forceinline__ void operator()(const f32x4 (&acc)[2][2][4][2], const Unit& u, int wr, int wc, int fr, int fq) const {
;     ...
;             for (int m = 0; m < 4; ++m) { const size_t off = (size_t)(row0 + ai * HALF + m * 16) * DM + col0;
; #pragma unroll
;                 for (int bj = 0; bj < 2; ++bj)
; #pragma unroll
;                     for (int n = 0; n < 2; ++n) *(f32x4*)(Y + off + bj * HALF + n * 16) = x[m][bj][n] * ALPHA + acc[ai][bj][m][n] * s; }
;             asm volatile("" ::: "memory");
	v_pk_fma_f32 v[86:87], v[86:87], s[96:97], v[70:71] op_sel_hi:[1,0,1]
	v_lshl_add_u64 v[70:71], s[44:45], 0, v[92:93]
	v_pk_fma_f32 v[84:85], v[84:85], s[96:97], v[72:73] op_sel_hi:[1,0,1]
	v_lshl_add_u64 v[92:93], v[70:71], 0, v[94:95]
	v_pk_fma_f32 v[72:73], v[90:91], s[96:97], v[62:63] op_sel_hi:[1,0,1]
	v_pk_fma_f32 v[70:71], v[88:89], s[96:97], v[64:65] op_sel_hi:[1,0,1]
	v_pk_fma_f32 v[64:65], v[98:99], s[96:97], v[74:75] op_sel_hi:[1,0,1]
	v_pk_fma_f32 v[62:63], v[96:97], s[96:97], v[76:77] op_sel_hi:[1,0,1]
	global_store_dwordx4 v[92:93], v[62:65], off offset:512 nt
	global_store_dwordx4 v[92:93], v[84:87], off nt
	global_store_dwordx4 v[92:93], v[70:73], off offset:64 nt
	v_pk_fma_f32 v[64:65], v[102:103], s[96:97], v[78:79] op_sel_hi:[1,0,1]
	v_pk_fma_f32 v[62:63], v[100:101], s[96:97], v[80:81] op_sel_hi:[1,0,1]
	global_store_dwordx4 v[92:93], v[62:65], off offset:576 nt
	v_pk_fma_f32 v[16:17], v[16:17], s[96:97], v[42:43] op_sel_hi:[1,0,1]
	v_pk_fma_f32 v[14:15], v[14:15], s[96:97], v[44:45] op_sel_hi:[1,0,1]
	v_pk_fma_f32 v[64:65], v[106:107], s[96:97], v[66:67] op_sel_hi:[1,0,1]
	v_lshl_add_u64 v[66:67], s[44:45], 0, v[128:129]
	v_pk_fma_f32 v[62:63], v[104:105], s[96:97], v[68:69] op_sel_hi:[1,0,1]
	v_lshl_add_u64 v[66:67], v[66:67], 0, v[94:95]
	global_store_dwordx4 v[66:67], v[62:65], off nt
	v_pk_fma_f32 v[12:13], v[12:13], s[96:97], v[26:27] op_sel_hi:[1,0,1]
	v_pk_fma_f32 v[10:11], v[10:11], s[96:97], v[24:25] op_sel_hi:[1,0,1]
	v_pk_fma_f32 v[64:65], v[110:111], s[96:97], v[46:47] op_sel_hi:[1,0,1]
	v_pk_fma_f32 v[62:63], v[108:109], s[96:97], v[48:49] op_sel_hi:[1,0,1]
	v_pk_fma_f32 v[48:49], v[114:115], s[96:97], v[54:55] op_sel_hi:[1,0,1]
	v_pk_fma_f32 v[46:47], v[112:113], s[96:97], v[56:57] op_sel_hi:[1,0,1]
	global_store_dwordx4 v[66:67], v[46:49], off offset:512 nt
	v_pk_fma_f32 v[8:9], v[8:9], s[96:97], v[28:29] op_sel_hi:[1,0,1]
	v_pk_fma_f32 v[6:7], v[6:7], s[96:97], v[22:23] op_sel_hi:[1,0,1]
	v_pk_fma_f32 v[48:49], v[118:119], s[96:97], v[58:59] op_sel_hi:[1,0,1]
	v_pk_fma_f32 v[46:47], v[116:117], s[96:97], v[60:61] op_sel_hi:[1,0,1]
	global_store_dwordx4 v[66:67], v[46:49], off offset:576 nt
	v_pk_fma_f32 v[4:5], v[4:5], s[96:97], v[20:21] op_sel_hi:[1,0,1]
	v_pk_fma_f32 v[2:3], v[2:3], s[96:97], v[18:19] op_sel_hi:[1,0,1]
	v_pk_fma_f32 v[48:49], v[122:123], s[96:97], v[50:51] op_sel_hi:[1,0,1]
	v_lshl_add_u64 v[50:51], s[44:45], 0, v[146:147]
	v_pk_fma_f32 v[46:47], v[120:121], s[96:97], v[52:53] op_sel_hi:[1,0,1]
	v_lshl_add_u64 v[50:51], v[50:51], 0, v[94:95]
	global_store_dwordx4 v[50:51], v[46:49], off nt
	global_store_dwordx4 v[50:51], v[14:17], off offset:576 nt
	global_store_dwordx4 v[66:67], v[62:65], off offset:64 nt
	v_pk_fma_f32 v[48:49], v[126:127], s[96:97], v[30:31] op_sel_hi:[1,0,1]
	v_pk_fma_f32 v[46:47], v[124:125], s[96:97], v[32:33] op_sel_hi:[1,0,1]
	v_pk_fma_f32 v[32:33], v[140:141], s[96:97], v[38:39] op_sel_hi:[1,0,1]
	v_pk_fma_f32 v[30:31], v[138:139], s[96:97], v[40:41] op_sel_hi:[1,0,1]
	global_store_dwordx4 v[50:51], v[30:33], off offset:512 nt
	v_pk_fma_f32 v[16:17], v[144:145], s[96:97], v[34:35] op_sel_hi:[1,0,1]
	v_pk_fma_f32 v[14:15], v[142:143], s[96:97], v[36:37] op_sel_hi:[1,0,1]
	v_lshl_add_u64 v[30:31], s[44:45], 0, v[82:83]
	v_lshl_add_u64 v[30:31], v[30:31], 0, v[94:95]
	global_store_dwordx4 v[50:51], v[46:49], off offset:64 nt
	global_store_dwordx4 v[30:31], v[14:17], off nt
	global_store_dwordx4 v[30:31], v[10:13], off offset:64 nt
	global_store_dwordx4 v[30:31], v[6:9], off offset:512 nt
	global_store_dwordx4 v[30:31], v[2:5], off offset:576 nt
	s_cbranch_vccnz .LBB0_2325
	s_andn2_b64 vcc, exec, s[50:51]
	s_cbranch_vccnz .LBB0_2324
	s_barrier
	s_branch .LBB0_2324
